# peeled last K-iteration of every GEMM tile: ks=1 fragment reads prefetched into the second register set
# speedup vs baseline: 1.0082x; 1.0039x over previous
.LBB0_259:
	s_and_b32 s8, s7, 0x4000
	s_xor_b32 s9, s8, 0x4000
	s_lshl_b32 s9, s9, 1
	s_add_i32 s9, s9, 32
	s_add_u32 s90, s52, s4
	s_addc_u32 s91, s53, s5
	s_add_i32 m0, s9, s82
	s_lshl_b32 s8, s8, 1
	global_load_lds_dwordx4 v184, s[90:91]
	s_add_i32 m0, s9, s83
	s_add_i32 s8, s8, 32
	global_load_lds_dwordx4 v185, s[90:91]
	s_add_i32 m0, s9, s84
	v_lshl_add_u32 v64, v120, 1, s8
	global_load_lds_dwordx4 v186, s[90:91]
	s_add_i32 m0, s9, s85
	v_lshl_add_u32 v95, v121, 1, s8
	global_load_lds_dwordx4 v187, s[90:91]
	s_add_i32 m0, s9, s86
	v_add_u32_e32 v166, v64, v142
	global_load_lds_dwordx4 v188, s[90:91]
	s_add_i32 m0, s9, s87
	v_add_u32_e32 v174, v95, v142
	global_load_lds_dwordx4 v189, s[90:91]
	s_add_i32 m0, s9, s88
	s_addk_i32 s7, 0x4000
	global_load_lds_dwordx4 v190, s[90:91]
	s_add_i32 m0, s9, s89
	s_add_u32 s4, s4, 0x80
	s_addc_u32 s5, s5, 0
	global_load_lds_dwordx4 v191, s[90:91]
	ds_read_b128 v[146:149], v166
	ds_read_b128 v[154:157], v174 offset:16384
	ds_read_b128 v[158:161], v174 offset:18432
	ds_read_b128 v[170:173], v174 offset:20480
	ds_read_b128 v[174:177], v174 offset:22528
	ds_read_b128 v[150:153], v166 offset:2048
	ds_read_b128 v[162:165], v166 offset:4096
	ds_read_b128 v[166:169], v166 offset:6144
	v_add_u32_e32 v64, v64, v143
	v_add_u32_e32 v95, v95, v143
	ds_read_b128 v[204:207], v64
	ds_read_b128 v[208:211], v95 offset:16384
	ds_read_b128 v[212:215], v95 offset:18432
	ds_read_b128 v[216:219], v95 offset:20480
	ds_read_b128 v[220:223], v95 offset:22528
	ds_read_b128 v[224:227], v64 offset:2048
	ds_read_b128 v[228:231], v64 offset:4096
	ds_read_b128 v[232:235], v64 offset:6144
	s_setprio 1
	s_waitcnt lgkmcnt(11)
	v_mfma_f32_16x16x32_bf16 v[60:63], v[146:149], v[154:157], v[60:63]
	v_mfma_f32_16x16x32_bf16 v[56:59], v[146:149], v[158:161], v[56:59]
	v_mfma_f32_16x16x32_bf16 v[52:55], v[146:149], v[170:173], v[52:55]
	v_mfma_f32_16x16x32_bf16 v[48:51], v[146:149], v[174:177], v[48:51]
	s_waitcnt lgkmcnt(10)
	v_mfma_f32_16x16x32_bf16 v[44:47], v[150:153], v[154:157], v[44:47]
	v_mfma_f32_16x16x32_bf16 v[40:43], v[150:153], v[158:161], v[40:43]
	v_mfma_f32_16x16x32_bf16 v[36:39], v[150:153], v[170:173], v[36:39]
	v_mfma_f32_16x16x32_bf16 v[32:35], v[150:153], v[174:177], v[32:35]
	s_waitcnt lgkmcnt(9)
	v_mfma_f32_16x16x32_bf16 v[28:31], v[162:165], v[154:157], v[28:31]
	v_mfma_f32_16x16x32_bf16 v[24:27], v[162:165], v[158:161], v[24:27]
	v_mfma_f32_16x16x32_bf16 v[20:23], v[162:165], v[170:173], v[20:23]
	v_mfma_f32_16x16x32_bf16 v[16:19], v[162:165], v[174:177], v[16:19]
	s_waitcnt lgkmcnt(8)
	v_mfma_f32_16x16x32_bf16 v[12:15], v[166:169], v[154:157], v[12:15]
	v_mfma_f32_16x16x32_bf16 v[8:11], v[166:169], v[158:161], v[8:11]
	v_mfma_f32_16x16x32_bf16 v[4:7], v[166:169], v[170:173], v[4:7]
	v_mfma_f32_16x16x32_bf16 v[0:3], v[166:169], v[174:177], v[0:3]
	s_waitcnt lgkmcnt(3)
	v_mfma_f32_16x16x32_bf16 v[60:63], v[204:207], v[208:211], v[60:63]
	v_mfma_f32_16x16x32_bf16 v[56:59], v[204:207], v[212:215], v[56:59]
	v_mfma_f32_16x16x32_bf16 v[52:55], v[204:207], v[216:219], v[52:55]
	v_mfma_f32_16x16x32_bf16 v[48:51], v[204:207], v[220:223], v[48:51]
	s_waitcnt lgkmcnt(2)
	v_mfma_f32_16x16x32_bf16 v[44:47], v[224:227], v[208:211], v[44:47]
	v_mfma_f32_16x16x32_bf16 v[40:43], v[224:227], v[212:215], v[40:43]
	v_mfma_f32_16x16x32_bf16 v[36:39], v[224:227], v[216:219], v[36:39]
	v_mfma_f32_16x16x32_bf16 v[32:35], v[224:227], v[220:223], v[32:35]
	s_waitcnt lgkmcnt(1)
	v_mfma_f32_16x16x32_bf16 v[28:31], v[228:231], v[208:211], v[28:31]
	v_mfma_f32_16x16x32_bf16 v[24:27], v[228:231], v[212:215], v[24:27]
	v_mfma_f32_16x16x32_bf16 v[20:23], v[228:231], v[216:219], v[20:23]
	v_mfma_f32_16x16x32_bf16 v[16:19], v[228:231], v[220:223], v[16:19]
	s_waitcnt lgkmcnt(0)
	v_mfma_f32_16x16x32_bf16 v[12:15], v[232:235], v[208:211], v[12:15]
	v_mfma_f32_16x16x32_bf16 v[8:11], v[232:235], v[212:215], v[8:11]
	v_mfma_f32_16x16x32_bf16 v[4:7], v[232:235], v[216:219], v[4:7]
	v_mfma_f32_16x16x32_bf16 v[0:3], v[232:235], v[220:223], v[0:3]
	s_setprio 0
	s_cmpk_eq_i32 s4, 0x780
	s_waitcnt vmcnt(0)
	s_barrier
	s_cbranch_scc0 .LBB0_259
	ds_read_b128 v[96:99], v122 offset:55296
	ds_read_b128 v[100:103], v122 offset:53248
	ds_read_b128 v[104:107], v123 offset:38912
	ds_read_b128 v[108:111], v123 offset:36864
	ds_read_b128 v[146:149], v122 offset:51200
	ds_read_b128 v[150:153], v122 offset:49152
	ds_read_b128 v[154:157], v123 offset:34816
	ds_read_b128 v[158:161], v123 offset:32768
	ds_read_b128 v[204:207], v124 offset:32768
	ds_read_b128 v[208:211], v124 offset:34816
	ds_read_b128 v[212:215], v125 offset:49152
	ds_read_b128 v[216:219], v125 offset:51200
	ds_read_b128 v[220:223], v124 offset:36864
	ds_read_b128 v[224:227], v124 offset:38912
	ds_read_b128 v[228:231], v125 offset:53248
	ds_read_b128 v[232:235], v125 offset:55296
	s_setprio 1
	s_waitcnt lgkmcnt(11)
	v_mfma_f32_16x16x32_bf16 v[24:27], v[108:111], v[146:149], v[24:27]
	v_mfma_f32_16x16x32_bf16 v[20:23], v[108:111], v[100:103], v[20:23]
	v_mfma_f32_16x16x32_bf16 v[16:19], v[108:111], v[96:99], v[16:19]
	s_waitcnt lgkmcnt(8)
	v_mfma_f32_16x16x32_bf16 v[60:63], v[158:161], v[150:153], v[60:63]
	v_mfma_f32_16x16x32_bf16 v[56:59], v[158:161], v[146:149], v[56:59]
	v_mfma_f32_16x16x32_bf16 v[52:55], v[158:161], v[100:103], v[52:55]
	v_mfma_f32_16x16x32_bf16 v[48:51], v[158:161], v[96:99], v[48:51]
	v_mfma_f32_16x16x32_bf16 v[44:47], v[154:157], v[150:153], v[44:47]
	v_mfma_f32_16x16x32_bf16 v[40:43], v[154:157], v[146:149], v[40:43]
	v_mfma_f32_16x16x32_bf16 v[36:39], v[154:157], v[100:103], v[36:39]
	v_mfma_f32_16x16x32_bf16 v[32:35], v[154:157], v[96:99], v[32:35]
	v_mfma_f32_16x16x32_bf16 v[28:31], v[108:111], v[150:153], v[28:31]
	v_mfma_f32_16x16x32_bf16 v[12:15], v[104:107], v[150:153], v[12:15]
	v_mfma_f32_16x16x32_bf16 v[8:11], v[104:107], v[146:149], v[8:11]
	v_mfma_f32_16x16x32_bf16 v[4:7], v[104:107], v[100:103], v[4:7]
	v_mfma_f32_16x16x32_bf16 v[0:3], v[104:107], v[96:99], v[0:3]
	s_waitcnt lgkmcnt(3)
	v_mfma_f32_16x16x32_bf16 v[24:27], v[220:223], v[216:219], v[24:27]
	s_waitcnt lgkmcnt(1)
	v_mfma_f32_16x16x32_bf16 v[20:23], v[220:223], v[228:231], v[20:23]
	s_waitcnt lgkmcnt(0)
	v_mfma_f32_16x16x32_bf16 v[16:19], v[220:223], v[232:235], v[16:19]
	v_mfma_f32_16x16x32_bf16 v[60:63], v[204:207], v[212:215], v[60:63]
	v_mfma_f32_16x16x32_bf16 v[56:59], v[204:207], v[216:219], v[56:59]
	v_mfma_f32_16x16x32_bf16 v[52:55], v[204:207], v[228:231], v[52:55]
	v_mfma_f32_16x16x32_bf16 v[48:51], v[204:207], v[232:235], v[48:51]
	v_mfma_f32_16x16x32_bf16 v[44:47], v[208:211], v[212:215], v[44:47]
	v_mfma_f32_16x16x32_bf16 v[40:43], v[208:211], v[216:219], v[40:43]
	v_mfma_f32_16x16x32_bf16 v[36:39], v[208:211], v[228:231], v[36:39]
	v_mfma_f32_16x16x32_bf16 v[32:35], v[208:211], v[232:235], v[32:35]
	v_mfma_f32_16x16x32_bf16 v[28:31], v[220:223], v[212:215], v[28:31]
	v_mfma_f32_16x16x32_bf16 v[12:15], v[224:227], v[212:215], v[12:15]
	v_mfma_f32_16x16x32_bf16 v[8:11], v[224:227], v[216:219], v[8:11]
	v_mfma_f32_16x16x32_bf16 v[4:7], v[224:227], v[228:231], v[4:7]
	v_mfma_f32_16x16x32_bf16 v[0:3], v[224:227], v[232:235], v[0:3]
	s_setprio 0
	s_barrier
	ds_write2_b32 v126, v60, v56 offset1:16
	ds_write2_b32 v126, v61, v57 offset0:132 offset1:148
	v_add_u32_e32 v56, 0x400, v126
	ds_write2_b32 v56, v62, v58 offset0:8 offset1:24
	ds_write2_b32 v56, v63, v59 offset0:140 offset1:156
	ds_write2_b32 v126, v52, v48 offset0:32 offset1:48
	ds_write2_b32 v126, v53, v49 offset0:164 offset1:180
	ds_write2_b32 v56, v54, v50 offset0:40 offset1:56
	ds_write2_b32 v56, v55, v51 offset0:172 offset1:188
	v_add_u32_e32 v48, 0x2000, v126
	ds_write2_b32 v48, v44, v40 offset0:64 offset1:80
	ds_write2_b32 v48, v45, v41 offset0:196 offset1:212
	v_add_u32_e32 v40, 0x2400, v126
	ds_write2_b32 v40, v46, v42 offset0:72 offset1:88
	ds_write2_b32 v40, v47, v43 offset0:204 offset1:220
	ds_write2_b32 v48, v36, v32 offset0:96 offset1:112
	ds_write2_b32 v48, v37, v33 offset0:228 offset1:244
	ds_write2_b32 v40, v38, v34 offset0:104 offset1:120
	ds_write2_b32 v40, v39, v35 offset0:236 offset1:252
	v_add_u32_e32 v32, 0x4000, v126
	ds_write2_b32 v32, v28, v24 offset0:128 offset1:144
	v_add_u32_e32 v24, 0x4400, v126
	ds_write2_b32 v24, v29, v25 offset0:4 offset1:20
	ds_write2_b32 v24, v30, v26 offset0:136 offset1:152
	v_add_u32_e32 v25, 0x4800, v126
	ds_write2_b32 v25, v31, v27 offset0:12 offset1:28
	ds_write2_b32 v32, v20, v16 offset0:160 offset1:176
	ds_write2_b32 v24, v21, v17 offset0:36 offset1:52
	ds_write2_b32 v24, v22, v18 offset0:168 offset1:184
	ds_write2_b32 v25, v23, v19 offset0:44 offset1:60
	v_add_u32_e32 v16, 0x6000, v126
	ds_write2_b32 v16, v12, v8 offset0:192 offset1:208
	v_add_u32_e32 v8, 0x6400, v126
	ds_write2_b32 v8, v13, v9 offset0:68 offset1:84
	ds_write2_b32 v8, v14, v10 offset0:200 offset1:216
	v_add_u32_e32 v9, 0x6800, v126
	v_or_b32_e32 v64, s6, v127
	ds_write2_b32 v9, v15, v11 offset0:76 offset1:92
	ds_write2_b32 v16, v4, v0 offset0:224 offset1:240
	ds_write2_b32 v8, v5, v1 offset0:100 offset1:116
	ds_write2_b32 v8, v6, v2 offset0:232 offset1:248
	ds_write2_b32 v9, v7, v3 offset0:108 offset1:124
	v_ashrrev_i32_e32 v1, 31, v64
	v_mov_b32_e32 v0, v64
	v_lshlrev_b64 v[2:3], 1, v[64:65]
	v_lshl_add_u64 v[20:21], v[0:1], 1, s[10:11]
	v_mov_b32_e32 v0, s15
	v_mov_b32_e32 v1, s13
	v_cmp_gt_i32_e64 s[8:9], s38, v64
	v_lshl_add_u64 v[16:17], s[18:19], 0, v[2:3]
	v_lshl_add_u64 v[18:19], s[16:17], 0, v[2:3]
	v_cndmask_b32_e64 v1, v0, v1, s[8:9]
	v_mov_b32_e32 v0, s14
	v_mov_b32_e32 v2, s12
	v_cndmask_b32_e64 v0, v0, v2, s[8:9]
	v_mov_b32_e32 v95, v65
	v_cmp_lt_i32_e64 s[4:5], s39, v64
	v_cmp_lt_i32_e64 s[6:7], s40, v64
	v_lshl_add_u64 v[22:23], v[0:1], 0, v[94:95]
	v_add_u32_e32 v24, s30, v135
	s_mov_b32 s45, 0
	s_waitcnt lgkmcnt(0)
	s_barrier
	s_branch .LBB0_263

.LBB0_278:
	s_and_b32 s8, s7, 0x4000
	s_xor_b32 s9, s8, 0x4000
	s_lshl_b32 s9, s9, 1
	s_add_i32 s9, s9, 32
	s_add_u32 s90, s52, s4
	s_addc_u32 s91, s53, s5
	s_add_i32 m0, s9, s82
	s_lshl_b32 s8, s8, 1
	global_load_lds_dwordx4 v184, s[90:91]
	s_add_i32 m0, s9, s83
	s_add_i32 s8, s8, 32
	global_load_lds_dwordx4 v185, s[90:91]
	s_add_i32 m0, s9, s84
	v_lshl_add_u32 v64, v121, 1, s8
	global_load_lds_dwordx4 v186, s[90:91]
	s_add_i32 m0, s9, s85
	v_lshl_add_u32 v95, v122, 1, s8
	global_load_lds_dwordx4 v187, s[90:91]
	s_add_i32 m0, s9, s86
	v_add_u32_e32 v164, v64, v139
	global_load_lds_dwordx4 v188, s[90:91]
	s_add_i32 m0, s9, s87
	v_add_u32_e32 v172, v95, v139
	global_load_lds_dwordx4 v189, s[90:91]
	s_add_i32 m0, s9, s88
	s_addk_i32 s7, 0x4000
	global_load_lds_dwordx4 v190, s[90:91]
	s_add_i32 m0, s9, s89
	s_add_u32 s4, s4, 0x80
	s_addc_u32 s5, s5, 0
	global_load_lds_dwordx4 v191, s[90:91]
	ds_read_b128 v[144:147], v164
	ds_read_b128 v[152:155], v172 offset:16384
	ds_read_b128 v[156:159], v172 offset:18432
	ds_read_b128 v[168:171], v172 offset:20480
	ds_read_b128 v[172:175], v172 offset:22528
	ds_read_b128 v[148:151], v164 offset:2048
	ds_read_b128 v[160:163], v164 offset:4096
	ds_read_b128 v[164:167], v164 offset:6144
	v_add_u32_e32 v64, v64, v140
	v_add_u32_e32 v95, v95, v140
	ds_read_b128 v[204:207], v64
	ds_read_b128 v[208:211], v95 offset:16384
	ds_read_b128 v[212:215], v95 offset:18432
	ds_read_b128 v[216:219], v95 offset:20480
	ds_read_b128 v[220:223], v95 offset:22528
	ds_read_b128 v[224:227], v64 offset:2048
	ds_read_b128 v[228:231], v64 offset:4096
	ds_read_b128 v[232:235], v64 offset:6144
	s_setprio 1
	s_waitcnt lgkmcnt(11)
	v_mfma_f32_16x16x32_bf16 v[60:63], v[144:147], v[152:155], v[60:63]
	v_mfma_f32_16x16x32_bf16 v[56:59], v[144:147], v[156:159], v[56:59]
	v_mfma_f32_16x16x32_bf16 v[52:55], v[144:147], v[168:171], v[52:55]
	v_mfma_f32_16x16x32_bf16 v[48:51], v[144:147], v[172:175], v[48:51]
	s_waitcnt lgkmcnt(10)
	v_mfma_f32_16x16x32_bf16 v[44:47], v[148:151], v[152:155], v[44:47]
	v_mfma_f32_16x16x32_bf16 v[40:43], v[148:151], v[156:159], v[40:43]
	v_mfma_f32_16x16x32_bf16 v[36:39], v[148:151], v[168:171], v[36:39]
	v_mfma_f32_16x16x32_bf16 v[32:35], v[148:151], v[172:175], v[32:35]
	s_waitcnt lgkmcnt(9)
	v_mfma_f32_16x16x32_bf16 v[28:31], v[160:163], v[152:155], v[28:31]
	v_mfma_f32_16x16x32_bf16 v[24:27], v[160:163], v[156:159], v[24:27]
	v_mfma_f32_16x16x32_bf16 v[20:23], v[160:163], v[168:171], v[20:23]
	v_mfma_f32_16x16x32_bf16 v[16:19], v[160:163], v[172:175], v[16:19]
	s_waitcnt lgkmcnt(8)
	v_mfma_f32_16x16x32_bf16 v[12:15], v[164:167], v[152:155], v[12:15]
	v_mfma_f32_16x16x32_bf16 v[8:11], v[164:167], v[156:159], v[8:11]
	v_mfma_f32_16x16x32_bf16 v[4:7], v[164:167], v[168:171], v[4:7]
	v_mfma_f32_16x16x32_bf16 v[0:3], v[164:167], v[172:175], v[0:3]
	s_waitcnt lgkmcnt(3)
	v_mfma_f32_16x16x32_bf16 v[60:63], v[204:207], v[208:211], v[60:63]
	v_mfma_f32_16x16x32_bf16 v[56:59], v[204:207], v[212:215], v[56:59]
	v_mfma_f32_16x16x32_bf16 v[52:55], v[204:207], v[216:219], v[52:55]
	v_mfma_f32_16x16x32_bf16 v[48:51], v[204:207], v[220:223], v[48:51]
	s_waitcnt lgkmcnt(2)
	v_mfma_f32_16x16x32_bf16 v[44:47], v[224:227], v[208:211], v[44:47]
	v_mfma_f32_16x16x32_bf16 v[40:43], v[224:227], v[212:215], v[40:43]
	v_mfma_f32_16x16x32_bf16 v[36:39], v[224:227], v[216:219], v[36:39]
	v_mfma_f32_16x16x32_bf16 v[32:35], v[224:227], v[220:223], v[32:35]
	s_waitcnt lgkmcnt(1)
	v_mfma_f32_16x16x32_bf16 v[28:31], v[228:231], v[208:211], v[28:31]
	v_mfma_f32_16x16x32_bf16 v[24:27], v[228:231], v[212:215], v[24:27]
	v_mfma_f32_16x16x32_bf16 v[20:23], v[228:231], v[216:219], v[20:23]
	v_mfma_f32_16x16x32_bf16 v[16:19], v[228:231], v[220:223], v[16:19]
	s_waitcnt lgkmcnt(0)
	v_mfma_f32_16x16x32_bf16 v[12:15], v[232:235], v[208:211], v[12:15]
	v_mfma_f32_16x16x32_bf16 v[8:11], v[232:235], v[212:215], v[8:11]
	v_mfma_f32_16x16x32_bf16 v[4:7], v[232:235], v[216:219], v[4:7]
	v_mfma_f32_16x16x32_bf16 v[0:3], v[232:235], v[220:223], v[0:3]
	s_setprio 0
	s_cmpk_eq_i32 s4, 0x780
	s_waitcnt vmcnt(0)
	s_barrier
	s_cbranch_scc0 .LBB0_278
	ds_read_b128 v[96:99], v123 offset:55296
	ds_read_b128 v[100:103], v123 offset:53248
	ds_read_b128 v[104:107], v124 offset:38912
	ds_read_b128 v[108:111], v124 offset:36864
	ds_read_b128 v[144:147], v123 offset:51200
	ds_read_b128 v[148:151], v123 offset:49152
	ds_read_b128 v[152:155], v124 offset:34816
	ds_read_b128 v[156:159], v124 offset:32768
	ds_read_b128 v[204:207], v125 offset:32768
	ds_read_b128 v[208:211], v125 offset:34816
	ds_read_b128 v[212:215], v126 offset:49152
	ds_read_b128 v[216:219], v126 offset:51200
	ds_read_b128 v[220:223], v125 offset:36864
	ds_read_b128 v[224:227], v125 offset:38912
	ds_read_b128 v[228:231], v126 offset:53248
	ds_read_b128 v[232:235], v126 offset:55296
	s_setprio 1
	s_waitcnt lgkmcnt(11)
	v_mfma_f32_16x16x32_bf16 v[24:27], v[108:111], v[144:147], v[24:27]
	v_mfma_f32_16x16x32_bf16 v[20:23], v[108:111], v[100:103], v[20:23]
	v_mfma_f32_16x16x32_bf16 v[16:19], v[108:111], v[96:99], v[16:19]
	s_waitcnt lgkmcnt(8)
	v_mfma_f32_16x16x32_bf16 v[60:63], v[156:159], v[148:151], v[60:63]
	v_mfma_f32_16x16x32_bf16 v[56:59], v[156:159], v[144:147], v[56:59]
	v_mfma_f32_16x16x32_bf16 v[52:55], v[156:159], v[100:103], v[52:55]
	v_mfma_f32_16x16x32_bf16 v[48:51], v[156:159], v[96:99], v[48:51]
	v_mfma_f32_16x16x32_bf16 v[44:47], v[152:155], v[148:151], v[44:47]
	v_mfma_f32_16x16x32_bf16 v[40:43], v[152:155], v[144:147], v[40:43]
	v_mfma_f32_16x16x32_bf16 v[36:39], v[152:155], v[100:103], v[36:39]
	v_mfma_f32_16x16x32_bf16 v[32:35], v[152:155], v[96:99], v[32:35]
	v_mfma_f32_16x16x32_bf16 v[28:31], v[108:111], v[148:151], v[28:31]
	v_mfma_f32_16x16x32_bf16 v[12:15], v[104:107], v[148:151], v[12:15]
	v_mfma_f32_16x16x32_bf16 v[8:11], v[104:107], v[144:147], v[8:11]
	v_mfma_f32_16x16x32_bf16 v[4:7], v[104:107], v[100:103], v[4:7]
	v_mfma_f32_16x16x32_bf16 v[0:3], v[104:107], v[96:99], v[0:3]
	s_waitcnt lgkmcnt(3)
	v_mfma_f32_16x16x32_bf16 v[24:27], v[220:223], v[216:219], v[24:27]
	s_waitcnt lgkmcnt(1)
	v_mfma_f32_16x16x32_bf16 v[20:23], v[220:223], v[228:231], v[20:23]
	s_waitcnt lgkmcnt(0)
	v_mfma_f32_16x16x32_bf16 v[16:19], v[220:223], v[232:235], v[16:19]
	v_mfma_f32_16x16x32_bf16 v[60:63], v[204:207], v[212:215], v[60:63]
	v_mfma_f32_16x16x32_bf16 v[56:59], v[204:207], v[216:219], v[56:59]
	v_mfma_f32_16x16x32_bf16 v[52:55], v[204:207], v[228:231], v[52:55]
	v_mfma_f32_16x16x32_bf16 v[48:51], v[204:207], v[232:235], v[48:51]
	v_mfma_f32_16x16x32_bf16 v[44:47], v[208:211], v[212:215], v[44:47]
	v_mfma_f32_16x16x32_bf16 v[40:43], v[208:211], v[216:219], v[40:43]
	v_mfma_f32_16x16x32_bf16 v[36:39], v[208:211], v[228:231], v[36:39]
	v_mfma_f32_16x16x32_bf16 v[32:35], v[208:211], v[232:235], v[32:35]
	v_mfma_f32_16x16x32_bf16 v[28:31], v[220:223], v[212:215], v[28:31]
	v_mfma_f32_16x16x32_bf16 v[12:15], v[224:227], v[212:215], v[12:15]
	v_mfma_f32_16x16x32_bf16 v[8:11], v[224:227], v[216:219], v[8:11]
	v_mfma_f32_16x16x32_bf16 v[4:7], v[224:227], v[228:231], v[4:7]
	v_mfma_f32_16x16x32_bf16 v[0:3], v[224:227], v[232:235], v[0:3]
	s_setprio 0
	s_barrier
	ds_write2_b32 v127, v60, v56 offset1:16
	ds_write2_b32 v127, v61, v57 offset0:132 offset1:148
	v_add_u32_e32 v56, 0x400, v127
	ds_write2_b32 v56, v62, v58 offset0:8 offset1:24
	ds_write2_b32 v56, v63, v59 offset0:140 offset1:156
	ds_write2_b32 v127, v52, v48 offset0:32 offset1:48
	ds_write2_b32 v127, v53, v49 offset0:164 offset1:180
	ds_write2_b32 v56, v54, v50 offset0:40 offset1:56
	ds_write2_b32 v56, v55, v51 offset0:172 offset1:188
	v_add_u32_e32 v48, 0x2000, v127
	ds_write2_b32 v48, v44, v40 offset0:64 offset1:80
	ds_write2_b32 v48, v45, v41 offset0:196 offset1:212
	v_add_u32_e32 v40, 0x2400, v127
	ds_write2_b32 v40, v46, v42 offset0:72 offset1:88
	ds_write2_b32 v40, v47, v43 offset0:204 offset1:220
	ds_write2_b32 v48, v36, v32 offset0:96 offset1:112
	ds_write2_b32 v48, v37, v33 offset0:228 offset1:244
	ds_write2_b32 v40, v38, v34 offset0:104 offset1:120
	ds_write2_b32 v40, v39, v35 offset0:236 offset1:252
	v_add_u32_e32 v32, 0x4000, v127
	ds_write2_b32 v32, v28, v24 offset0:128 offset1:144
	v_add_u32_e32 v24, 0x4400, v127
	ds_write2_b32 v24, v29, v25 offset0:4 offset1:20
	ds_write2_b32 v24, v30, v26 offset0:136 offset1:152
	v_add_u32_e32 v25, 0x4800, v127
	ds_write2_b32 v25, v31, v27 offset0:12 offset1:28
	ds_write2_b32 v32, v20, v16 offset0:160 offset1:176
	ds_write2_b32 v24, v21, v17 offset0:36 offset1:52
	ds_write2_b32 v24, v22, v18 offset0:168 offset1:184
	ds_write2_b32 v25, v23, v19 offset0:44 offset1:60
	v_add_u32_e32 v16, 0x6000, v127
	ds_write2_b32 v16, v12, v8 offset0:192 offset1:208
	v_add_u32_e32 v8, 0x6400, v127
	ds_write2_b32 v8, v13, v9 offset0:68 offset1:84
	ds_write2_b32 v8, v14, v10 offset0:200 offset1:216
	v_add_u32_e32 v9, 0x6800, v127
	v_or_b32_e32 v64, s6, v128
	ds_write2_b32 v9, v15, v11 offset0:76 offset1:92
	ds_write2_b32 v16, v4, v0 offset0:224 offset1:240
	ds_write2_b32 v8, v5, v1 offset0:100 offset1:116
	ds_write2_b32 v8, v6, v2 offset0:232 offset1:248
	ds_write2_b32 v9, v7, v3 offset0:108 offset1:124
	v_ashrrev_i32_e32 v1, 31, v64
	v_mov_b32_e32 v0, v64
	v_lshlrev_b64 v[2:3], 1, v[64:65]
	v_lshl_add_u64 v[20:21], v[0:1], 1, s[10:11]
	v_mov_b32_e32 v0, s15
	v_mov_b32_e32 v1, s13
	v_cmp_gt_i32_e64 s[8:9], s24, v64
	v_lshl_add_u64 v[16:17], s[18:19], 0, v[2:3]
	v_lshl_add_u64 v[18:19], s[16:17], 0, v[2:3]
	v_cndmask_b32_e64 v1, v0, v1, s[8:9]
	v_mov_b32_e32 v0, s14
	v_mov_b32_e32 v2, s12
	v_cndmask_b32_e64 v0, v0, v2, s[8:9]
	v_mov_b32_e32 v95, v65
	v_cmp_lt_i32_e64 s[4:5], s26, v64
	v_cmp_lt_i32_e64 s[6:7], s27, v64
	v_lshl_add_u64 v[22:23], v[0:1], 0, v[94:95]
	v_add_u32_e32 v24, v132, v143
	s_mov_b32 s35, 0
	s_waitcnt lgkmcnt(0)
	s_barrier
	s_branch .LBB0_282

.LBB0_423:
	s_and_b32 s25, s24, 0x4000
	s_xor_b32 s26, s25, 0x4000
	s_lshl_b32 s26, s26, 1
	s_add_i32 s26, s26, 32
	s_add_u32 s90, s52, s14
	s_addc_u32 s91, s53, s15
	s_add_i32 m0, s26, s82
	s_lshl_b32 s25, s25, 1
	global_load_lds_dwordx4 v188, s[90:91]
	s_add_i32 m0, s26, s83
	s_add_i32 s25, s25, 32
	global_load_lds_dwordx4 v189, s[90:91]
	s_add_i32 m0, s26, s84
	v_add3_u32 v170, s25, v114, v135
	global_load_lds_dwordx4 v190, s[90:91]
	s_add_i32 m0, s26, s85
	v_add3_u32 v171, s25, v115, v135
	global_load_lds_dwordx4 v191, s[90:91]
	s_add_i32 m0, s26, s86
	v_add_u32_e32 v158, v170, v136
	global_load_lds_dwordx4 v192, s[90:91]
	s_add_i32 m0, s26, s87
	v_add_u32_e32 v166, v171, v136
	global_load_lds_dwordx4 v193, s[90:91]
	s_add_i32 m0, s26, s88
	s_addk_i32 s24, 0x4000
	global_load_lds_dwordx4 v194, s[90:91]
	s_add_i32 m0, s26, s89
	s_add_u32 s14, s14, 0x80
	s_addc_u32 s15, s15, 0
	global_load_lds_dwordx4 v195, s[90:91]
	ds_read_b128 v[138:141], v158
	ds_read_b128 v[146:149], v166 offset:16384
	ds_read_b128 v[150:153], v166 offset:18432
	ds_read_b128 v[162:165], v166 offset:20480
	ds_read_b128 v[166:169], v166 offset:22528
	ds_read_b128 v[142:145], v158 offset:2048
	ds_read_b128 v[154:157], v158 offset:4096
	ds_read_b128 v[158:161], v158 offset:6144
	v_add_u32_e32 v236, v170, v137
	v_add_u32_e32 v237, v171, v137
	ds_read_b128 v[204:207], v236
	ds_read_b128 v[208:211], v237 offset:16384
	ds_read_b128 v[212:215], v237 offset:18432
	ds_read_b128 v[216:219], v237 offset:20480
	ds_read_b128 v[220:223], v237 offset:22528
	ds_read_b128 v[224:227], v236 offset:2048
	ds_read_b128 v[228:231], v236 offset:4096
	ds_read_b128 v[232:235], v236 offset:6144
	s_setprio 1
	s_waitcnt lgkmcnt(11)
	v_mfma_f32_16x16x32_bf16 v[60:63], v[138:141], v[146:149], v[60:63]
	v_mfma_f32_16x16x32_bf16 v[56:59], v[138:141], v[150:153], v[56:59]
	v_mfma_f32_16x16x32_bf16 v[52:55], v[138:141], v[162:165], v[52:55]
	v_mfma_f32_16x16x32_bf16 v[48:51], v[138:141], v[166:169], v[48:51]
	s_waitcnt lgkmcnt(10)
	v_mfma_f32_16x16x32_bf16 v[44:47], v[142:145], v[146:149], v[44:47]
	v_mfma_f32_16x16x32_bf16 v[40:43], v[142:145], v[150:153], v[40:43]
	v_mfma_f32_16x16x32_bf16 v[36:39], v[142:145], v[162:165], v[36:39]
	v_mfma_f32_16x16x32_bf16 v[32:35], v[142:145], v[166:169], v[32:35]
	s_waitcnt lgkmcnt(9)
	v_mfma_f32_16x16x32_bf16 v[28:31], v[154:157], v[146:149], v[28:31]
	v_mfma_f32_16x16x32_bf16 v[24:27], v[154:157], v[150:153], v[24:27]
	v_mfma_f32_16x16x32_bf16 v[20:23], v[154:157], v[162:165], v[20:23]
	v_mfma_f32_16x16x32_bf16 v[16:19], v[154:157], v[166:169], v[16:19]
	s_waitcnt lgkmcnt(8)
	v_mfma_f32_16x16x32_bf16 v[12:15], v[158:161], v[146:149], v[12:15]
	v_mfma_f32_16x16x32_bf16 v[8:11], v[158:161], v[150:153], v[8:11]
	v_mfma_f32_16x16x32_bf16 v[4:7], v[158:161], v[162:165], v[4:7]
	v_mfma_f32_16x16x32_bf16 v[0:3], v[158:161], v[166:169], v[0:3]
	s_waitcnt lgkmcnt(3)
	v_mfma_f32_16x16x32_bf16 v[60:63], v[204:207], v[208:211], v[60:63]
	v_mfma_f32_16x16x32_bf16 v[56:59], v[204:207], v[212:215], v[56:59]
	v_mfma_f32_16x16x32_bf16 v[52:55], v[204:207], v[216:219], v[52:55]
	v_mfma_f32_16x16x32_bf16 v[48:51], v[204:207], v[220:223], v[48:51]
	s_waitcnt lgkmcnt(2)
	v_mfma_f32_16x16x32_bf16 v[44:47], v[224:227], v[208:211], v[44:47]
	v_mfma_f32_16x16x32_bf16 v[40:43], v[224:227], v[212:215], v[40:43]
	v_mfma_f32_16x16x32_bf16 v[36:39], v[224:227], v[216:219], v[36:39]
	v_mfma_f32_16x16x32_bf16 v[32:35], v[224:227], v[220:223], v[32:35]
	s_waitcnt lgkmcnt(1)
	v_mfma_f32_16x16x32_bf16 v[28:31], v[228:231], v[208:211], v[28:31]
	v_mfma_f32_16x16x32_bf16 v[24:27], v[228:231], v[212:215], v[24:27]
	v_mfma_f32_16x16x32_bf16 v[20:23], v[228:231], v[216:219], v[20:23]
	v_mfma_f32_16x16x32_bf16 v[16:19], v[228:231], v[220:223], v[16:19]
	s_waitcnt lgkmcnt(0)
	v_mfma_f32_16x16x32_bf16 v[12:15], v[232:235], v[208:211], v[12:15]
	v_mfma_f32_16x16x32_bf16 v[8:11], v[232:235], v[212:215], v[8:11]
	v_mfma_f32_16x16x32_bf16 v[4:7], v[232:235], v[216:219], v[4:7]
	v_mfma_f32_16x16x32_bf16 v[0:3], v[232:235], v[220:223], v[0:3]
	s_setprio 0
	s_cmpk_eq_i32 s14, 0x780
	s_waitcnt vmcnt(0)
	s_barrier
	s_cbranch_scc0 .LBB0_423
	ds_read_b128 v[90:93], v118 offset:55296
	ds_read_b128 v[94:97], v118 offset:53248
	ds_read_b128 v[98:101], v119 offset:38912
	ds_read_b128 v[102:105], v119 offset:36864
	ds_read_b128 v[138:141], v118 offset:51200
	ds_read_b128 v[142:145], v118 offset:49152
	ds_read_b128 v[146:149], v119 offset:34816
	ds_read_b128 v[150:153], v119 offset:32768
	ds_read_b128 v[204:207], v120 offset:32768
	ds_read_b128 v[208:211], v120 offset:34816
	ds_read_b128 v[212:215], v121 offset:49152
	ds_read_b128 v[216:219], v121 offset:51200
	ds_read_b128 v[220:223], v120 offset:36864
	ds_read_b128 v[224:227], v120 offset:38912
	ds_read_b128 v[228:231], v121 offset:53248
	ds_read_b128 v[232:235], v121 offset:55296
	s_setprio 1
	s_waitcnt lgkmcnt(13)
	v_mfma_f32_16x16x32_bf16 v[4:7], v[98:101], v[94:97], v[4:7]
	v_mfma_f32_16x16x32_bf16 v[0:3], v[98:101], v[90:93], v[0:3]
	s_waitcnt lgkmcnt(8)
	v_mfma_f32_16x16x32_bf16 v[60:63], v[150:153], v[142:145], v[60:63]
	v_mfma_f32_16x16x32_bf16 v[56:59], v[150:153], v[138:141], v[56:59]
	v_mfma_f32_16x16x32_bf16 v[52:55], v[150:153], v[94:97], v[52:55]
	v_mfma_f32_16x16x32_bf16 v[48:51], v[150:153], v[90:93], v[48:51]
	v_mfma_f32_16x16x32_bf16 v[44:47], v[146:149], v[142:145], v[44:47]
	v_mfma_f32_16x16x32_bf16 v[40:43], v[146:149], v[138:141], v[40:43]
	v_mfma_f32_16x16x32_bf16 v[36:39], v[146:149], v[94:97], v[36:39]
	v_mfma_f32_16x16x32_bf16 v[32:35], v[146:149], v[90:93], v[32:35]
	v_mfma_f32_16x16x32_bf16 v[28:31], v[102:105], v[142:145], v[28:31]
	v_mfma_f32_16x16x32_bf16 v[24:27], v[102:105], v[138:141], v[24:27]
	v_mfma_f32_16x16x32_bf16 v[20:23], v[102:105], v[94:97], v[20:23]
	v_mfma_f32_16x16x32_bf16 v[16:19], v[102:105], v[90:93], v[16:19]
	v_mfma_f32_16x16x32_bf16 v[12:15], v[98:101], v[142:145], v[12:15]
	v_mfma_f32_16x16x32_bf16 v[8:11], v[98:101], v[138:141], v[8:11]
	s_waitcnt lgkmcnt(1)
	v_mfma_f32_16x16x32_bf16 v[4:7], v[224:227], v[228:231], v[4:7]
	s_waitcnt lgkmcnt(0)
	v_mfma_f32_16x16x32_bf16 v[0:3], v[224:227], v[232:235], v[0:3]
	v_mfma_f32_16x16x32_bf16 v[60:63], v[204:207], v[212:215], v[60:63]
	v_mfma_f32_16x16x32_bf16 v[56:59], v[204:207], v[216:219], v[56:59]
	v_mfma_f32_16x16x32_bf16 v[52:55], v[204:207], v[228:231], v[52:55]
	v_mfma_f32_16x16x32_bf16 v[48:51], v[204:207], v[232:235], v[48:51]
	v_mfma_f32_16x16x32_bf16 v[44:47], v[208:211], v[212:215], v[44:47]
	v_mfma_f32_16x16x32_bf16 v[40:43], v[208:211], v[216:219], v[40:43]
	v_mfma_f32_16x16x32_bf16 v[36:39], v[208:211], v[228:231], v[36:39]
	v_mfma_f32_16x16x32_bf16 v[32:35], v[208:211], v[232:235], v[32:35]
	v_mfma_f32_16x16x32_bf16 v[28:31], v[220:223], v[212:215], v[28:31]
	v_mfma_f32_16x16x32_bf16 v[24:27], v[220:223], v[216:219], v[24:27]
	v_mfma_f32_16x16x32_bf16 v[20:23], v[220:223], v[228:231], v[20:23]
	v_mfma_f32_16x16x32_bf16 v[16:19], v[220:223], v[232:235], v[16:19]
	v_mfma_f32_16x16x32_bf16 v[12:15], v[224:227], v[212:215], v[12:15]
	v_mfma_f32_16x16x32_bf16 v[8:11], v[224:227], v[216:219], v[8:11]
	s_setprio 0
	s_barrier
	ds_write2_b32 v116, v60, v56 offset1:16
	ds_write2_b32 v116, v61, v57 offset0:132 offset1:148
	v_add_u32_e32 v56, 0x400, v116
	ds_write2_b32 v56, v62, v58 offset0:8 offset1:24
	ds_write2_b32 v56, v63, v59 offset0:140 offset1:156
	ds_write2_b32 v116, v52, v48 offset0:32 offset1:48
	ds_write2_b32 v116, v53, v49 offset0:164 offset1:180
	ds_write2_b32 v56, v54, v50 offset0:40 offset1:56
	ds_write2_b32 v56, v55, v51 offset0:172 offset1:188
	v_add_u32_e32 v48, 0x2000, v116
	ds_write2_b32 v48, v44, v40 offset0:64 offset1:80
	ds_write2_b32 v48, v45, v41 offset0:196 offset1:212
	v_add_u32_e32 v40, 0x2400, v116
	ds_write2_b32 v40, v46, v42 offset0:72 offset1:88
	ds_write2_b32 v40, v47, v43 offset0:204 offset1:220
	ds_write2_b32 v48, v36, v32 offset0:96 offset1:112
	ds_write2_b32 v48, v37, v33 offset0:228 offset1:244
	ds_write2_b32 v40, v38, v34 offset0:104 offset1:120
	ds_write2_b32 v40, v39, v35 offset0:236 offset1:252
	v_add_u32_e32 v32, 0x4000, v116
	ds_write2_b32 v32, v28, v24 offset0:128 offset1:144
	v_add_u32_e32 v24, 0x4400, v116
	ds_write2_b32 v24, v29, v25 offset0:4 offset1:20
	ds_write2_b32 v24, v30, v26 offset0:136 offset1:152
	v_add_u32_e32 v25, 0x4800, v116
	ds_write2_b32 v25, v31, v27 offset0:12 offset1:28
	ds_write2_b32 v32, v20, v16 offset0:160 offset1:176
	ds_write2_b32 v24, v21, v17 offset0:36 offset1:52
	ds_write2_b32 v24, v22, v18 offset0:168 offset1:184
	ds_write2_b32 v25, v23, v19 offset0:44 offset1:60
	v_add_u32_e32 v16, 0x6000, v116
	ds_write2_b32 v16, v12, v8 offset0:192 offset1:208
	v_add_u32_e32 v8, 0x6400, v116
	ds_write2_b32 v8, v13, v9 offset0:68 offset1:84
	ds_write2_b32 v8, v14, v10 offset0:200 offset1:216
	v_add_u32_e32 v9, 0x6800, v116
	ds_write2_b32 v9, v15, v11 offset0:76 offset1:92
	ds_write2_b32 v16, v4, v0 offset0:224 offset1:240
	ds_write2_b32 v8, v5, v1 offset0:100 offset1:116
	ds_write2_b32 v8, v6, v2 offset0:232 offset1:248
	ds_write2_b32 v9, v7, v3 offset0:108 offset1:124
	v_or_b32_e32 v0, s23, v117
	v_ashrrev_i32_e32 v1, 31, v0
	v_lshlrev_b64 v[2:3], 2, v[0:1]
	v_lshl_add_u64 v[0:1], s[12:13], 0, v[2:3]
	v_lshl_add_u64 v[2:3], s[8:9], 0, v[2:3]
	v_add_u32_e32 v4, s22, v128
	s_mov_b32 s14, 0
	s_waitcnt lgkmcnt(0)
	s_barrier

.LBB0_432:
	s_and_b32 s26, s25, 0x4000
	s_xor_b32 s27, s26, 0x4000
	s_lshl_b32 s27, s27, 1
	s_add_i32 s27, s27, 32
	s_add_u32 s90, s52, s14
	s_addc_u32 s91, s53, s15
	s_add_i32 m0, s27, s82
	s_lshl_b32 s26, s26, 1
	global_load_lds_dwordx4 v188, s[90:91]
	s_add_i32 m0, s27, s83
	s_add_i32 s26, s26, 32
	global_load_lds_dwordx4 v189, s[90:91]
	s_add_i32 m0, s27, s84
	v_add3_u32 v139, s26, v113, v136
	global_load_lds_dwordx4 v190, s[90:91]
	s_add_i32 m0, s27, s85
	v_add3_u32 v172, s26, v114, v136
	global_load_lds_dwordx4 v191, s[90:91]
	s_add_i32 m0, s27, s86
	v_add_u32_e32 v160, v139, v137
	global_load_lds_dwordx4 v192, s[90:91]
	s_add_i32 m0, s27, s87
	v_add_u32_e32 v168, v172, v137
	global_load_lds_dwordx4 v193, s[90:91]
	s_add_i32 m0, s27, s88
	s_addk_i32 s25, 0x4000
	global_load_lds_dwordx4 v194, s[90:91]
	s_add_i32 m0, s27, s89
	s_add_u32 s14, s14, 0x80
	s_addc_u32 s15, s15, 0
	global_load_lds_dwordx4 v195, s[90:91]
	ds_read_b128 v[140:143], v160
	ds_read_b128 v[148:151], v168 offset:16384
	ds_read_b128 v[152:155], v168 offset:18432
	ds_read_b128 v[164:167], v168 offset:20480
	ds_read_b128 v[168:171], v168 offset:22528
	ds_read_b128 v[144:147], v160 offset:2048
	ds_read_b128 v[156:159], v160 offset:4096
	ds_read_b128 v[160:163], v160 offset:6144
	v_add_u32_e32 v139, v139, v138
	v_add_u32_e32 v236, v172, v138
	ds_read_b128 v[204:207], v139
	ds_read_b128 v[208:211], v236 offset:16384
	ds_read_b128 v[212:215], v236 offset:18432
	ds_read_b128 v[216:219], v236 offset:20480
	ds_read_b128 v[220:223], v236 offset:22528
	ds_read_b128 v[224:227], v139 offset:2048
	ds_read_b128 v[228:231], v139 offset:4096
	ds_read_b128 v[232:235], v139 offset:6144
	s_setprio 1
	s_waitcnt lgkmcnt(11)
	v_mfma_f32_16x16x32_bf16 v[60:63], v[140:143], v[148:151], v[60:63]
	v_mfma_f32_16x16x32_bf16 v[56:59], v[140:143], v[152:155], v[56:59]
	v_mfma_f32_16x16x32_bf16 v[52:55], v[140:143], v[164:167], v[52:55]
	v_mfma_f32_16x16x32_bf16 v[48:51], v[140:143], v[168:171], v[48:51]
	s_waitcnt lgkmcnt(10)
	v_mfma_f32_16x16x32_bf16 v[44:47], v[144:147], v[148:151], v[44:47]
	v_mfma_f32_16x16x32_bf16 v[40:43], v[144:147], v[152:155], v[40:43]
	v_mfma_f32_16x16x32_bf16 v[36:39], v[144:147], v[164:167], v[36:39]
	v_mfma_f32_16x16x32_bf16 v[32:35], v[144:147], v[168:171], v[32:35]
	s_waitcnt lgkmcnt(9)
	v_mfma_f32_16x16x32_bf16 v[28:31], v[156:159], v[148:151], v[28:31]
	v_mfma_f32_16x16x32_bf16 v[24:27], v[156:159], v[152:155], v[24:27]
	v_mfma_f32_16x16x32_bf16 v[20:23], v[156:159], v[164:167], v[20:23]
	v_mfma_f32_16x16x32_bf16 v[16:19], v[156:159], v[168:171], v[16:19]
	s_waitcnt lgkmcnt(8)
	v_mfma_f32_16x16x32_bf16 v[12:15], v[160:163], v[148:151], v[12:15]
	v_mfma_f32_16x16x32_bf16 v[8:11], v[160:163], v[152:155], v[8:11]
	v_mfma_f32_16x16x32_bf16 v[4:7], v[160:163], v[164:167], v[4:7]
	v_mfma_f32_16x16x32_bf16 v[0:3], v[160:163], v[168:171], v[0:3]
	s_waitcnt lgkmcnt(3)
	v_mfma_f32_16x16x32_bf16 v[60:63], v[204:207], v[208:211], v[60:63]
	v_mfma_f32_16x16x32_bf16 v[56:59], v[204:207], v[212:215], v[56:59]
	v_mfma_f32_16x16x32_bf16 v[52:55], v[204:207], v[216:219], v[52:55]
	v_mfma_f32_16x16x32_bf16 v[48:51], v[204:207], v[220:223], v[48:51]
	s_waitcnt lgkmcnt(2)
	v_mfma_f32_16x16x32_bf16 v[44:47], v[224:227], v[208:211], v[44:47]
	v_mfma_f32_16x16x32_bf16 v[40:43], v[224:227], v[212:215], v[40:43]
	v_mfma_f32_16x16x32_bf16 v[36:39], v[224:227], v[216:219], v[36:39]
	v_mfma_f32_16x16x32_bf16 v[32:35], v[224:227], v[220:223], v[32:35]
	s_waitcnt lgkmcnt(1)
	v_mfma_f32_16x16x32_bf16 v[28:31], v[228:231], v[208:211], v[28:31]
	v_mfma_f32_16x16x32_bf16 v[24:27], v[228:231], v[212:215], v[24:27]
	v_mfma_f32_16x16x32_bf16 v[20:23], v[228:231], v[216:219], v[20:23]
	v_mfma_f32_16x16x32_bf16 v[16:19], v[228:231], v[220:223], v[16:19]
	s_waitcnt lgkmcnt(0)
	v_mfma_f32_16x16x32_bf16 v[12:15], v[232:235], v[208:211], v[12:15]
	v_mfma_f32_16x16x32_bf16 v[8:11], v[232:235], v[212:215], v[8:11]
	v_mfma_f32_16x16x32_bf16 v[4:7], v[232:235], v[216:219], v[4:7]
	v_mfma_f32_16x16x32_bf16 v[0:3], v[232:235], v[220:223], v[0:3]
	s_setprio 0
	s_cmpk_eq_i32 s14, 0x780
	s_waitcnt vmcnt(0)
	s_barrier
	s_cbranch_scc0 .LBB0_432
	ds_read_b128 v[88:91], v117 offset:55296
	ds_read_b128 v[92:95], v117 offset:53248
	ds_read_b128 v[96:99], v118 offset:38912
	ds_read_b128 v[100:103], v118 offset:36864
	ds_read_b128 v[140:143], v117 offset:51200
	ds_read_b128 v[144:147], v117 offset:49152
	ds_read_b128 v[148:151], v118 offset:34816
	ds_read_b128 v[152:155], v118 offset:32768
	ds_read_b128 v[204:207], v119 offset:32768
	ds_read_b128 v[208:211], v119 offset:34816
	ds_read_b128 v[212:215], v120 offset:49152
	ds_read_b128 v[216:219], v120 offset:51200
	ds_read_b128 v[220:223], v119 offset:36864
	ds_read_b128 v[224:227], v119 offset:38912
	ds_read_b128 v[228:231], v120 offset:53248
	ds_read_b128 v[232:235], v120 offset:55296
	s_setprio 1
	s_waitcnt lgkmcnt(13)
	v_mfma_f32_16x16x32_bf16 v[4:7], v[96:99], v[92:95], v[4:7]
	v_mfma_f32_16x16x32_bf16 v[0:3], v[96:99], v[88:91], v[0:3]
	s_waitcnt lgkmcnt(8)
	v_mfma_f32_16x16x32_bf16 v[60:63], v[152:155], v[144:147], v[60:63]
	v_mfma_f32_16x16x32_bf16 v[56:59], v[152:155], v[140:143], v[56:59]
	v_mfma_f32_16x16x32_bf16 v[52:55], v[152:155], v[92:95], v[52:55]
	v_mfma_f32_16x16x32_bf16 v[48:51], v[152:155], v[88:91], v[48:51]
	v_mfma_f32_16x16x32_bf16 v[44:47], v[148:151], v[144:147], v[44:47]
	v_mfma_f32_16x16x32_bf16 v[40:43], v[148:151], v[140:143], v[40:43]
	v_mfma_f32_16x16x32_bf16 v[36:39], v[148:151], v[92:95], v[36:39]
	v_mfma_f32_16x16x32_bf16 v[32:35], v[148:151], v[88:91], v[32:35]
	v_mfma_f32_16x16x32_bf16 v[28:31], v[100:103], v[144:147], v[28:31]
	v_mfma_f32_16x16x32_bf16 v[24:27], v[100:103], v[140:143], v[24:27]
	v_mfma_f32_16x16x32_bf16 v[20:23], v[100:103], v[92:95], v[20:23]
	v_mfma_f32_16x16x32_bf16 v[16:19], v[100:103], v[88:91], v[16:19]
	v_mfma_f32_16x16x32_bf16 v[12:15], v[96:99], v[144:147], v[12:15]
	v_mfma_f32_16x16x32_bf16 v[8:11], v[96:99], v[140:143], v[8:11]
	s_waitcnt lgkmcnt(1)
	v_mfma_f32_16x16x32_bf16 v[4:7], v[224:227], v[228:231], v[4:7]
	s_waitcnt lgkmcnt(0)
	v_mfma_f32_16x16x32_bf16 v[0:3], v[224:227], v[232:235], v[0:3]
	v_mfma_f32_16x16x32_bf16 v[60:63], v[204:207], v[212:215], v[60:63]
	v_mfma_f32_16x16x32_bf16 v[56:59], v[204:207], v[216:219], v[56:59]
	v_mfma_f32_16x16x32_bf16 v[52:55], v[204:207], v[228:231], v[52:55]
	v_mfma_f32_16x16x32_bf16 v[48:51], v[204:207], v[232:235], v[48:51]
	v_mfma_f32_16x16x32_bf16 v[44:47], v[208:211], v[212:215], v[44:47]
	v_mfma_f32_16x16x32_bf16 v[40:43], v[208:211], v[216:219], v[40:43]
	v_mfma_f32_16x16x32_bf16 v[36:39], v[208:211], v[228:231], v[36:39]
	v_mfma_f32_16x16x32_bf16 v[32:35], v[208:211], v[232:235], v[32:35]
	v_mfma_f32_16x16x32_bf16 v[28:31], v[220:223], v[212:215], v[28:31]
	v_mfma_f32_16x16x32_bf16 v[24:27], v[220:223], v[216:219], v[24:27]
	v_mfma_f32_16x16x32_bf16 v[20:23], v[220:223], v[228:231], v[20:23]
	v_mfma_f32_16x16x32_bf16 v[16:19], v[220:223], v[232:235], v[16:19]
	v_mfma_f32_16x16x32_bf16 v[12:15], v[224:227], v[212:215], v[12:15]
	v_mfma_f32_16x16x32_bf16 v[8:11], v[224:227], v[216:219], v[8:11]
	s_setprio 0
	s_barrier
	ds_write2_b32 v115, v60, v56 offset1:16
	ds_write2_b32 v115, v61, v57 offset0:132 offset1:148
	v_add_u32_e32 v56, 0x400, v115
	ds_write2_b32 v56, v62, v58 offset0:8 offset1:24
	ds_write2_b32 v56, v63, v59 offset0:140 offset1:156
	ds_write2_b32 v115, v52, v48 offset0:32 offset1:48
	ds_write2_b32 v115, v53, v49 offset0:164 offset1:180
	ds_write2_b32 v56, v54, v50 offset0:40 offset1:56
	ds_write2_b32 v56, v55, v51 offset0:172 offset1:188
	v_add_u32_e32 v48, 0x2000, v115
	ds_write2_b32 v48, v44, v40 offset0:64 offset1:80
	ds_write2_b32 v48, v45, v41 offset0:196 offset1:212
	v_add_u32_e32 v40, 0x2400, v115
	ds_write2_b32 v40, v46, v42 offset0:72 offset1:88
	ds_write2_b32 v40, v47, v43 offset0:204 offset1:220
	ds_write2_b32 v48, v36, v32 offset0:96 offset1:112
	ds_write2_b32 v48, v37, v33 offset0:228 offset1:244
	ds_write2_b32 v40, v38, v34 offset0:104 offset1:120
	ds_write2_b32 v40, v39, v35 offset0:236 offset1:252
	v_add_u32_e32 v32, 0x4000, v115
	ds_write2_b32 v32, v28, v24 offset0:128 offset1:144
	v_add_u32_e32 v24, 0x4400, v115
	ds_write2_b32 v24, v29, v25 offset0:4 offset1:20
	ds_write2_b32 v24, v30, v26 offset0:136 offset1:152
	v_add_u32_e32 v25, 0x4800, v115
	ds_write2_b32 v25, v31, v27 offset0:12 offset1:28
	ds_write2_b32 v32, v20, v16 offset0:160 offset1:176
	ds_write2_b32 v24, v21, v17 offset0:36 offset1:52
	ds_write2_b32 v24, v22, v18 offset0:168 offset1:184
	ds_write2_b32 v25, v23, v19 offset0:44 offset1:60
	v_add_u32_e32 v16, 0x6000, v115
	ds_write2_b32 v16, v12, v8 offset0:192 offset1:208
	v_add_u32_e32 v8, 0x6400, v115
	ds_write2_b32 v8, v13, v9 offset0:68 offset1:84
	ds_write2_b32 v8, v14, v10 offset0:200 offset1:216
	v_add_u32_e32 v9, 0x6800, v115
	ds_write2_b32 v9, v15, v11 offset0:76 offset1:92
	ds_write2_b32 v16, v4, v0 offset0:224 offset1:240
	ds_write2_b32 v8, v5, v1 offset0:100 offset1:116
	ds_write2_b32 v8, v6, v2 offset0:232 offset1:248
	ds_write2_b32 v9, v7, v3 offset0:108 offset1:124
	v_or_b32_e32 v0, s23, v116
	v_ashrrev_i32_e32 v1, 31, v0
	v_lshlrev_b64 v[2:3], 2, v[0:1]
	v_lshl_add_u64 v[0:1], s[12:13], 0, v[2:3]
	v_lshl_add_u64 v[2:3], s[8:9], 0, v[2:3]
	v_add_u32_e32 v4, s24, v129
	s_mov_b32 s14, 0
	s_waitcnt lgkmcnt(0)
	s_barrier

.LBB0_443:
	s_and_b32 s25, s24, 0x4000
	s_xor_b32 s26, s25, 0x4000
	s_lshl_b32 s26, s26, 1
	s_add_i32 s26, s26, 32
	s_add_u32 s90, s52, s10
	s_addc_u32 s91, s53, s11
	s_add_i32 m0, s26, s82
	s_lshl_b32 s25, s25, 1
	global_load_lds_dwordx4 v189, s[90:91]
	s_add_i32 m0, s26, s83
	s_add_i32 s25, s25, 32
	global_load_lds_dwordx4 v190, s[90:91]
	s_add_i32 m0, s26, s84
	v_lshlrev_b32_e32 v70, 1, v129
	global_load_lds_dwordx4 v191, s[90:91]
	s_add_i32 m0, s26, s85
	v_add3_u32 v151, s25, v124, v70
	global_load_lds_dwordx4 v192, s[90:91]
	s_add_i32 m0, s26, s86
	v_lshlrev_b32_e32 v152, 1, v117
	global_load_lds_dwordx4 v193, s[90:91]
	s_add_i32 m0, s26, s87
	v_add3_u32 v70, s25, v125, v70
	global_load_lds_dwordx4 v194, s[90:91]
	s_add_i32 m0, s26, s88
	v_add_u32_e32 v172, v151, v152
	global_load_lds_dwordx4 v195, s[90:91]
	s_add_i32 m0, s26, s89
	v_add_u32_e32 v181, v70, v152
	global_load_lds_dwordx4 v196, s[90:91]
	ds_read_b128 v[152:155], v172
	ds_read_b128 v[160:163], v181 offset:16384
	ds_read_b128 v[164:167], v181 offset:18432
	ds_read_b128 v[176:179], v181 offset:20480
	ds_read_b128 v[182:185], v181 offset:22528
	ds_read_b128 v[156:159], v172 offset:2048
	ds_read_b128 v[168:171], v172 offset:4096
	ds_read_b128 v[172:175], v172 offset:6144
	v_lshlrev_b32_e32 v236, 1, v116
	v_add_u32_e32 v151, v151, v236
	v_add_u32_e32 v70, v70, v236
	ds_read_b128 v[204:207], v151
	ds_read_b128 v[208:211], v70 offset:16384
	ds_read_b128 v[212:215], v70 offset:18432
	ds_read_b128 v[216:219], v70 offset:20480
	ds_read_b128 v[220:223], v70 offset:22528
	ds_read_b128 v[224:227], v151 offset:2048
	ds_read_b128 v[228:231], v151 offset:4096
	ds_read_b128 v[232:235], v151 offset:6144
	s_setprio 1
	s_waitcnt lgkmcnt(11)
	v_mfma_f32_16x16x32_bf16 v[60:63], v[152:155], v[160:163], v[60:63]
	v_mfma_f32_16x16x32_bf16 v[56:59], v[152:155], v[164:167], v[56:59]
	v_mfma_f32_16x16x32_bf16 v[52:55], v[152:155], v[176:179], v[52:55]
	v_mfma_f32_16x16x32_bf16 v[48:51], v[152:155], v[182:185], v[48:51]
	s_waitcnt lgkmcnt(10)
	v_mfma_f32_16x16x32_bf16 v[44:47], v[156:159], v[160:163], v[44:47]
	v_mfma_f32_16x16x32_bf16 v[40:43], v[156:159], v[164:167], v[40:43]
	v_mfma_f32_16x16x32_bf16 v[36:39], v[156:159], v[176:179], v[36:39]
	v_mfma_f32_16x16x32_bf16 v[32:35], v[156:159], v[182:185], v[32:35]
	s_waitcnt lgkmcnt(9)
	v_mfma_f32_16x16x32_bf16 v[28:31], v[168:171], v[160:163], v[28:31]
	v_mfma_f32_16x16x32_bf16 v[24:27], v[168:171], v[164:167], v[24:27]
	v_mfma_f32_16x16x32_bf16 v[20:23], v[168:171], v[176:179], v[20:23]
	v_mfma_f32_16x16x32_bf16 v[16:19], v[168:171], v[182:185], v[16:19]
	s_waitcnt lgkmcnt(8)
	v_mfma_f32_16x16x32_bf16 v[12:15], v[172:175], v[160:163], v[12:15]
	v_mfma_f32_16x16x32_bf16 v[8:11], v[172:175], v[164:167], v[8:11]
	v_mfma_f32_16x16x32_bf16 v[4:7], v[172:175], v[176:179], v[4:7]
	v_mfma_f32_16x16x32_bf16 v[0:3], v[172:175], v[182:185], v[0:3]
	s_waitcnt lgkmcnt(3)
	v_mfma_f32_16x16x32_bf16 v[60:63], v[204:207], v[208:211], v[60:63]
	v_mfma_f32_16x16x32_bf16 v[56:59], v[204:207], v[212:215], v[56:59]
	v_mfma_f32_16x16x32_bf16 v[52:55], v[204:207], v[216:219], v[52:55]
	v_mfma_f32_16x16x32_bf16 v[48:51], v[204:207], v[220:223], v[48:51]
	s_waitcnt lgkmcnt(2)
	v_mfma_f32_16x16x32_bf16 v[44:47], v[224:227], v[208:211], v[44:47]
	v_mfma_f32_16x16x32_bf16 v[40:43], v[224:227], v[212:215], v[40:43]
	v_mfma_f32_16x16x32_bf16 v[36:39], v[224:227], v[216:219], v[36:39]
	v_mfma_f32_16x16x32_bf16 v[32:35], v[224:227], v[220:223], v[32:35]
	s_waitcnt lgkmcnt(1)
	v_mfma_f32_16x16x32_bf16 v[28:31], v[228:231], v[208:211], v[28:31]
	v_mfma_f32_16x16x32_bf16 v[24:27], v[228:231], v[212:215], v[24:27]
	v_mfma_f32_16x16x32_bf16 v[20:23], v[228:231], v[216:219], v[20:23]
	v_mfma_f32_16x16x32_bf16 v[16:19], v[228:231], v[220:223], v[16:19]
	s_waitcnt lgkmcnt(0)
	v_mfma_f32_16x16x32_bf16 v[12:15], v[232:235], v[208:211], v[12:15]
	v_mfma_f32_16x16x32_bf16 v[8:11], v[232:235], v[212:215], v[8:11]
	v_mfma_f32_16x16x32_bf16 v[4:7], v[232:235], v[216:219], v[4:7]
	v_mfma_f32_16x16x32_bf16 v[0:3], v[232:235], v[220:223], v[0:3]
	s_setprio 0
	s_add_u32 s10, s10, 0x80
	s_addc_u32 s11, s11, 0
	s_addk_i32 s24, 0x4000
	s_cmpk_eq_i32 s10, 0x780
	s_waitcnt vmcnt(0)
	s_barrier
	s_cbranch_scc0 .LBB0_443
	ds_read_b128 v[96:99], v69 offset:32768
	ds_read_b128 v[100:103], v69 offset:34816
	ds_read_b128 v[104:107], v135 offset:49152
	ds_read_b128 v[108:111], v135 offset:51200
	ds_read_b128 v[152:155], v69 offset:36864
	ds_read_b128 v[156:159], v69 offset:38912
	ds_read_b128 v[160:163], v135 offset:53248
	ds_read_b128 v[164:167], v135 offset:55296
	ds_read_b128 v[204:207], v136 offset:32768
	ds_read_b128 v[208:211], v136 offset:34816
	ds_read_b128 v[212:215], v137 offset:49152
	ds_read_b128 v[216:219], v137 offset:51200
	ds_read_b128 v[220:223], v136 offset:36864
	ds_read_b128 v[224:227], v136 offset:38912
	ds_read_b128 v[228:231], v137 offset:53248
	ds_read_b128 v[232:235], v137 offset:55296
	s_setprio 1
	s_waitcnt lgkmcnt(9)
	v_mfma_f32_16x16x32_bf16 v[4:7], v[156:159], v[160:163], v[4:7]
	s_waitcnt lgkmcnt(8)
	v_mfma_f32_16x16x32_bf16 v[0:3], v[156:159], v[164:167], v[0:3]
	v_mfma_f32_16x16x32_bf16 v[60:63], v[96:99], v[104:107], v[60:63]
	v_mfma_f32_16x16x32_bf16 v[56:59], v[96:99], v[108:111], v[56:59]
	v_mfma_f32_16x16x32_bf16 v[52:55], v[96:99], v[160:163], v[52:55]
	v_mfma_f32_16x16x32_bf16 v[48:51], v[96:99], v[164:167], v[48:51]
	v_mfma_f32_16x16x32_bf16 v[44:47], v[100:103], v[104:107], v[44:47]
	v_mfma_f32_16x16x32_bf16 v[40:43], v[100:103], v[108:111], v[40:43]
	v_mfma_f32_16x16x32_bf16 v[36:39], v[100:103], v[160:163], v[36:39]
	v_mfma_f32_16x16x32_bf16 v[32:35], v[100:103], v[164:167], v[32:35]
	v_mfma_f32_16x16x32_bf16 v[28:31], v[152:155], v[104:107], v[28:31]
	v_mfma_f32_16x16x32_bf16 v[24:27], v[152:155], v[108:111], v[24:27]
	v_mfma_f32_16x16x32_bf16 v[20:23], v[152:155], v[160:163], v[20:23]
	v_mfma_f32_16x16x32_bf16 v[16:19], v[152:155], v[164:167], v[16:19]
	v_mfma_f32_16x16x32_bf16 v[12:15], v[156:159], v[104:107], v[12:15]
	v_mfma_f32_16x16x32_bf16 v[8:11], v[156:159], v[108:111], v[8:11]
	s_waitcnt lgkmcnt(1)
	v_mfma_f32_16x16x32_bf16 v[4:7], v[224:227], v[228:231], v[4:7]
	s_waitcnt lgkmcnt(0)
	v_mfma_f32_16x16x32_bf16 v[0:3], v[224:227], v[232:235], v[0:3]
	v_mfma_f32_16x16x32_bf16 v[60:63], v[204:207], v[212:215], v[60:63]
	v_mfma_f32_16x16x32_bf16 v[56:59], v[204:207], v[216:219], v[56:59]
	v_mfma_f32_16x16x32_bf16 v[52:55], v[204:207], v[228:231], v[52:55]
	v_mfma_f32_16x16x32_bf16 v[48:51], v[204:207], v[232:235], v[48:51]
	v_mfma_f32_16x16x32_bf16 v[44:47], v[208:211], v[212:215], v[44:47]
	v_mfma_f32_16x16x32_bf16 v[40:43], v[208:211], v[216:219], v[40:43]
	v_mfma_f32_16x16x32_bf16 v[36:39], v[208:211], v[228:231], v[36:39]
	v_mfma_f32_16x16x32_bf16 v[32:35], v[208:211], v[232:235], v[32:35]
	v_mfma_f32_16x16x32_bf16 v[28:31], v[220:223], v[212:215], v[28:31]
	v_mfma_f32_16x16x32_bf16 v[24:27], v[220:223], v[216:219], v[24:27]
	v_mfma_f32_16x16x32_bf16 v[20:23], v[220:223], v[228:231], v[20:23]
	v_mfma_f32_16x16x32_bf16 v[16:19], v[220:223], v[232:235], v[16:19]
	v_mfma_f32_16x16x32_bf16 v[12:15], v[224:227], v[212:215], v[12:15]
	v_mfma_f32_16x16x32_bf16 v[8:11], v[224:227], v[216:219], v[8:11]
	s_setprio 0
	s_barrier
	ds_write2_b32 v134, v60, v56 offset1:16
	ds_write2_b32 v134, v61, v57 offset0:132 offset1:148
	v_add_u32_e32 v56, 0x400, v134
	ds_write2_b32 v56, v62, v58 offset0:8 offset1:24
	ds_write2_b32 v56, v63, v59 offset0:140 offset1:156
	ds_write2_b32 v134, v52, v48 offset0:32 offset1:48
	ds_write2_b32 v134, v53, v49 offset0:164 offset1:180
	ds_write2_b32 v56, v54, v50 offset0:40 offset1:56
	ds_write2_b32 v56, v55, v51 offset0:172 offset1:188
	v_add_u32_e32 v48, 0x2000, v134
	ds_write2_b32 v48, v44, v40 offset0:64 offset1:80
	ds_write2_b32 v48, v45, v41 offset0:196 offset1:212
	v_add_u32_e32 v40, 0x2400, v134
	ds_write2_b32 v40, v46, v42 offset0:72 offset1:88
	ds_write2_b32 v40, v47, v43 offset0:204 offset1:220
	ds_write2_b32 v48, v36, v32 offset0:96 offset1:112
	ds_write2_b32 v48, v37, v33 offset0:228 offset1:244
	ds_write2_b32 v40, v38, v34 offset0:104 offset1:120
	ds_write2_b32 v40, v39, v35 offset0:236 offset1:252
	v_add_u32_e32 v32, 0x4000, v134
	ds_write2_b32 v32, v28, v24 offset0:128 offset1:144
	v_add_u32_e32 v24, 0x4400, v134
	ds_write2_b32 v24, v29, v25 offset0:4 offset1:20
	ds_write2_b32 v24, v30, v26 offset0:136 offset1:152
	v_add_u32_e32 v25, 0x4800, v134
	ds_write2_b32 v25, v31, v27 offset0:12 offset1:28
	ds_write2_b32 v32, v20, v16 offset0:160 offset1:176
	ds_write2_b32 v24, v21, v17 offset0:36 offset1:52
	ds_write2_b32 v24, v22, v18 offset0:168 offset1:184
	ds_write2_b32 v25, v23, v19 offset0:44 offset1:60
	v_add_u32_e32 v16, 0x6000, v134
	ds_write2_b32 v16, v12, v8 offset0:192 offset1:208
	v_add_u32_e32 v8, 0x6400, v134
	ds_write2_b32 v8, v13, v9 offset0:68 offset1:84
	ds_write2_b32 v8, v14, v10 offset0:200 offset1:216
	v_add_u32_e32 v9, 0x6800, v134
	ds_write2_b32 v9, v15, v11 offset0:76 offset1:92
	ds_write2_b32 v16, v4, v0 offset0:224 offset1:240
	ds_write2_b32 v8, v5, v1 offset0:100 offset1:116
	ds_write2_b32 v8, v6, v2 offset0:232 offset1:248
	ds_write2_b32 v9, v7, v3 offset0:108 offset1:124
	v_or_b32_e32 v0, s22, v113
	v_lshlrev_b32_e32 v70, 2, v0
	v_lshl_add_u64 v[0:1], s[12:13], 0, v[70:71]
	v_lshl_add_u64 v[2:3], s[8:9], 0, v[70:71]
	v_add_u32_e32 v4, s23, v146
	s_mov_b32 s10, 0
	s_waitcnt lgkmcnt(0)
	s_barrier

.LBB0_605:
	s_and_b32 s18, s17, 0x4000
	s_xor_b32 s19, s18, 0x4000
	s_lshl_b32 s19, s19, 1
	s_add_i32 s19, s19, 32
	s_add_u32 s90, s52, s10
	s_addc_u32 s91, s53, s11
	s_add_i32 m0, s19, s82
	s_lshl_b32 s18, s18, 1
	global_load_lds_dwordx4 v184, s[90:91]
	s_add_i32 m0, s19, s83
	s_add_i32 s18, s18, 32
	global_load_lds_dwordx4 v185, s[90:91]
	s_add_i32 m0, s19, s84
	v_lshl_add_u32 v137, v114, 1, s18
	global_load_lds_dwordx4 v186, s[90:91]
	s_add_i32 m0, s19, s85
	v_lshl_add_u32 v170, v115, 1, s18
	global_load_lds_dwordx4 v187, s[90:91]
	s_add_i32 m0, s19, s86
	v_add_u32_e32 v158, v137, v135
	global_load_lds_dwordx4 v188, s[90:91]
	s_add_i32 m0, s19, s87
	v_add_u32_e32 v166, v170, v135
	global_load_lds_dwordx4 v189, s[90:91]
	s_add_i32 m0, s19, s88
	s_addk_i32 s17, 0x4000
	global_load_lds_dwordx4 v190, s[90:91]
	s_add_i32 m0, s19, s89
	s_add_u32 s10, s10, 0x80
	s_addc_u32 s11, s11, 0
	global_load_lds_dwordx4 v191, s[90:91]
	ds_read_b128 v[138:141], v158
	ds_read_b128 v[146:149], v166 offset:16384
	ds_read_b128 v[150:153], v166 offset:18432
	ds_read_b128 v[162:165], v166 offset:20480
	ds_read_b128 v[166:169], v166 offset:22528
	ds_read_b128 v[142:145], v158 offset:2048
	ds_read_b128 v[154:157], v158 offset:4096
	ds_read_b128 v[158:161], v158 offset:6144
	v_add_u32_e32 v137, v137, v136
	v_add_u32_e32 v236, v170, v136
	ds_read_b128 v[204:207], v137
	ds_read_b128 v[208:211], v236 offset:16384
	ds_read_b128 v[212:215], v236 offset:18432
	ds_read_b128 v[216:219], v236 offset:20480
	ds_read_b128 v[220:223], v236 offset:22528
	ds_read_b128 v[224:227], v137 offset:2048
	ds_read_b128 v[228:231], v137 offset:4096
	ds_read_b128 v[232:235], v137 offset:6144
	s_setprio 1
	s_waitcnt lgkmcnt(11)
	v_mfma_f32_16x16x32_bf16 v[60:63], v[138:141], v[146:149], v[60:63]
	v_mfma_f32_16x16x32_bf16 v[56:59], v[138:141], v[150:153], v[56:59]
	v_mfma_f32_16x16x32_bf16 v[52:55], v[138:141], v[162:165], v[52:55]
	v_mfma_f32_16x16x32_bf16 v[48:51], v[138:141], v[166:169], v[48:51]
	s_waitcnt lgkmcnt(10)
	v_mfma_f32_16x16x32_bf16 v[44:47], v[142:145], v[146:149], v[44:47]
	v_mfma_f32_16x16x32_bf16 v[40:43], v[142:145], v[150:153], v[40:43]
	v_mfma_f32_16x16x32_bf16 v[36:39], v[142:145], v[162:165], v[36:39]
	v_mfma_f32_16x16x32_bf16 v[32:35], v[142:145], v[166:169], v[32:35]
	s_waitcnt lgkmcnt(9)
	v_mfma_f32_16x16x32_bf16 v[28:31], v[154:157], v[146:149], v[28:31]
	v_mfma_f32_16x16x32_bf16 v[24:27], v[154:157], v[150:153], v[24:27]
	v_mfma_f32_16x16x32_bf16 v[20:23], v[154:157], v[162:165], v[20:23]
	v_mfma_f32_16x16x32_bf16 v[16:19], v[154:157], v[166:169], v[16:19]
	s_waitcnt lgkmcnt(8)
	v_mfma_f32_16x16x32_bf16 v[12:15], v[158:161], v[146:149], v[12:15]
	v_mfma_f32_16x16x32_bf16 v[8:11], v[158:161], v[150:153], v[8:11]
	v_mfma_f32_16x16x32_bf16 v[4:7], v[158:161], v[162:165], v[4:7]
	v_mfma_f32_16x16x32_bf16 v[0:3], v[158:161], v[166:169], v[0:3]
	s_waitcnt lgkmcnt(3)
	v_mfma_f32_16x16x32_bf16 v[60:63], v[204:207], v[208:211], v[60:63]
	v_mfma_f32_16x16x32_bf16 v[56:59], v[204:207], v[212:215], v[56:59]
	v_mfma_f32_16x16x32_bf16 v[52:55], v[204:207], v[216:219], v[52:55]
	v_mfma_f32_16x16x32_bf16 v[48:51], v[204:207], v[220:223], v[48:51]
	s_waitcnt lgkmcnt(2)
	v_mfma_f32_16x16x32_bf16 v[44:47], v[224:227], v[208:211], v[44:47]
	v_mfma_f32_16x16x32_bf16 v[40:43], v[224:227], v[212:215], v[40:43]
	v_mfma_f32_16x16x32_bf16 v[36:39], v[224:227], v[216:219], v[36:39]
	v_mfma_f32_16x16x32_bf16 v[32:35], v[224:227], v[220:223], v[32:35]
	s_waitcnt lgkmcnt(1)
	v_mfma_f32_16x16x32_bf16 v[28:31], v[228:231], v[208:211], v[28:31]
	v_mfma_f32_16x16x32_bf16 v[24:27], v[228:231], v[212:215], v[24:27]
	v_mfma_f32_16x16x32_bf16 v[20:23], v[228:231], v[216:219], v[20:23]
	v_mfma_f32_16x16x32_bf16 v[16:19], v[228:231], v[220:223], v[16:19]
	s_waitcnt lgkmcnt(0)
	v_mfma_f32_16x16x32_bf16 v[12:15], v[232:235], v[208:211], v[12:15]
	v_mfma_f32_16x16x32_bf16 v[8:11], v[232:235], v[212:215], v[8:11]
	v_mfma_f32_16x16x32_bf16 v[4:7], v[232:235], v[216:219], v[4:7]
	v_mfma_f32_16x16x32_bf16 v[0:3], v[232:235], v[220:223], v[0:3]
	s_setprio 0
	s_cmpk_eq_i32 s10, 0x780
	s_waitcnt vmcnt(0)
	s_barrier
	s_cbranch_scc0 .LBB0_605
	ds_read_b128 v[90:93], v116 offset:55296
	ds_read_b128 v[94:97], v116 offset:53248
	ds_read_b128 v[98:101], v117 offset:38912
	ds_read_b128 v[102:105], v117 offset:36864
	ds_read_b128 v[138:141], v116 offset:51200
	ds_read_b128 v[142:145], v116 offset:49152
	ds_read_b128 v[146:149], v117 offset:34816
	ds_read_b128 v[150:153], v117 offset:32768
	ds_read_b128 v[204:207], v118 offset:32768
	ds_read_b128 v[208:211], v118 offset:34816
	ds_read_b128 v[212:215], v119 offset:49152
	ds_read_b128 v[216:219], v119 offset:51200
	ds_read_b128 v[220:223], v118 offset:36864
	ds_read_b128 v[224:227], v118 offset:38912
	ds_read_b128 v[228:231], v119 offset:53248
	ds_read_b128 v[232:235], v119 offset:55296
	s_setprio 1
	s_waitcnt lgkmcnt(13)
	v_mfma_f32_16x16x32_bf16 v[0:3], v[98:101], v[90:93], v[0:3]
	s_waitcnt lgkmcnt(8)
	v_mfma_f32_16x16x32_bf16 v[60:63], v[150:153], v[142:145], v[60:63]
	v_mfma_f32_16x16x32_bf16 v[56:59], v[150:153], v[138:141], v[56:59]
	v_mfma_f32_16x16x32_bf16 v[52:55], v[150:153], v[94:97], v[52:55]
	v_mfma_f32_16x16x32_bf16 v[48:51], v[150:153], v[90:93], v[48:51]
	v_mfma_f32_16x16x32_bf16 v[44:47], v[146:149], v[142:145], v[44:47]
	v_mfma_f32_16x16x32_bf16 v[40:43], v[146:149], v[138:141], v[40:43]
	v_mfma_f32_16x16x32_bf16 v[36:39], v[146:149], v[94:97], v[36:39]
	v_mfma_f32_16x16x32_bf16 v[32:35], v[146:149], v[90:93], v[32:35]
	v_mfma_f32_16x16x32_bf16 v[28:31], v[102:105], v[142:145], v[28:31]
	v_mfma_f32_16x16x32_bf16 v[24:27], v[102:105], v[138:141], v[24:27]
	v_mfma_f32_16x16x32_bf16 v[20:23], v[102:105], v[94:97], v[20:23]
	v_mfma_f32_16x16x32_bf16 v[16:19], v[102:105], v[90:93], v[16:19]
	v_mfma_f32_16x16x32_bf16 v[12:15], v[98:101], v[142:145], v[12:15]
	v_mfma_f32_16x16x32_bf16 v[8:11], v[98:101], v[138:141], v[8:11]
	v_mfma_f32_16x16x32_bf16 v[4:7], v[98:101], v[94:97], v[4:7]
	s_waitcnt lgkmcnt(0)
	v_mfma_f32_16x16x32_bf16 v[0:3], v[224:227], v[232:235], v[0:3]
	v_mfma_f32_16x16x32_bf16 v[60:63], v[204:207], v[212:215], v[60:63]
	v_mfma_f32_16x16x32_bf16 v[56:59], v[204:207], v[216:219], v[56:59]
	v_mfma_f32_16x16x32_bf16 v[52:55], v[204:207], v[228:231], v[52:55]
	v_mfma_f32_16x16x32_bf16 v[48:51], v[204:207], v[232:235], v[48:51]
	v_mfma_f32_16x16x32_bf16 v[44:47], v[208:211], v[212:215], v[44:47]
	v_mfma_f32_16x16x32_bf16 v[40:43], v[208:211], v[216:219], v[40:43]
	v_mfma_f32_16x16x32_bf16 v[36:39], v[208:211], v[228:231], v[36:39]
	v_mfma_f32_16x16x32_bf16 v[32:35], v[208:211], v[232:235], v[32:35]
	v_mfma_f32_16x16x32_bf16 v[28:31], v[220:223], v[212:215], v[28:31]
	v_mfma_f32_16x16x32_bf16 v[24:27], v[220:223], v[216:219], v[24:27]
	v_mfma_f32_16x16x32_bf16 v[20:23], v[220:223], v[228:231], v[20:23]
	v_mfma_f32_16x16x32_bf16 v[16:19], v[220:223], v[232:235], v[16:19]
	v_mfma_f32_16x16x32_bf16 v[12:15], v[224:227], v[212:215], v[12:15]
	v_mfma_f32_16x16x32_bf16 v[8:11], v[224:227], v[216:219], v[8:11]
	v_mfma_f32_16x16x32_bf16 v[4:7], v[224:227], v[228:231], v[4:7]
	s_setprio 0
	s_barrier
	ds_write2_b32 v120, v60, v56 offset1:16
	ds_write2_b32 v120, v61, v57 offset0:132 offset1:148
	v_add_u32_e32 v56, 0x400, v120
	ds_write2_b32 v56, v62, v58 offset0:8 offset1:24
	ds_write2_b32 v56, v63, v59 offset0:140 offset1:156
	ds_write2_b32 v120, v52, v48 offset0:32 offset1:48
	ds_write2_b32 v120, v53, v49 offset0:164 offset1:180
	ds_write2_b32 v56, v54, v50 offset0:40 offset1:56
	ds_write2_b32 v56, v55, v51 offset0:172 offset1:188
	v_add_u32_e32 v48, 0x2000, v120
	ds_write2_b32 v48, v44, v40 offset0:64 offset1:80
	ds_write2_b32 v48, v45, v41 offset0:196 offset1:212
	v_add_u32_e32 v40, 0x2400, v120
	ds_write2_b32 v40, v46, v42 offset0:72 offset1:88
	ds_write2_b32 v40, v47, v43 offset0:204 offset1:220
	ds_write2_b32 v48, v36, v32 offset0:96 offset1:112
	ds_write2_b32 v48, v37, v33 offset0:228 offset1:244
	ds_write2_b32 v40, v38, v34 offset0:104 offset1:120
	ds_write2_b32 v40, v39, v35 offset0:236 offset1:252
	v_add_u32_e32 v32, 0x4000, v120
	ds_write2_b32 v32, v28, v24 offset0:128 offset1:144
	v_add_u32_e32 v24, 0x4400, v120
	ds_write2_b32 v24, v29, v25 offset0:4 offset1:20
	ds_write2_b32 v24, v30, v26 offset0:136 offset1:152
	v_add_u32_e32 v25, 0x4800, v120
	ds_write2_b32 v25, v31, v27 offset0:12 offset1:28
	ds_write2_b32 v32, v20, v16 offset0:160 offset1:176
	ds_write2_b32 v24, v21, v17 offset0:36 offset1:52
	ds_write2_b32 v24, v22, v18 offset0:168 offset1:184
	ds_write2_b32 v25, v23, v19 offset0:44 offset1:60
	v_add_u32_e32 v16, 0x6000, v120
	ds_write2_b32 v16, v12, v8 offset0:192 offset1:208
	v_add_u32_e32 v8, 0x6400, v120
	ds_write2_b32 v8, v13, v9 offset0:68 offset1:84
	ds_write2_b32 v8, v14, v10 offset0:200 offset1:216
	v_add_u32_e32 v9, 0x6800, v120
	ds_write2_b32 v9, v15, v11 offset0:76 offset1:92
	ds_write2_b32 v16, v4, v0 offset0:224 offset1:240
	ds_write2_b32 v8, v5, v1 offset0:100 offset1:116
	ds_write2_b32 v8, v6, v2 offset0:232 offset1:248
	ds_write2_b32 v9, v7, v3 offset0:108 offset1:124
	v_or_b32_e32 v0, s16, v121
	v_ashrrev_i32_e32 v1, 31, v0
	v_lshl_add_u64 v[0:1], v[0:1], 1, s[4:5]
	v_add_u32_e32 v2, s15, v128
	s_mov_b32 s10, 0
	s_waitcnt lgkmcnt(0)
	s_barrier

.LBB0_616:
	s_and_b32 s15, s14, 0x4000
	s_xor_b32 s16, s15, 0x4000
	s_lshl_b32 s16, s16, 1
	s_add_i32 s16, s16, 32
	s_add_u32 s90, s52, s6
	s_addc_u32 s91, s53, s7
	s_add_i32 m0, s16, s82
	s_lshl_b32 s15, s15, 1
	global_load_lds_dwordx4 v184, s[90:91]
	s_add_i32 m0, s16, s83
	s_add_i32 s15, s15, 32
	global_load_lds_dwordx4 v185, s[90:91]
	s_add_i32 m0, s16, s84
	v_lshl_add_u32 v137, v113, 1, s15
	global_load_lds_dwordx4 v186, s[90:91]
	s_add_i32 m0, s16, s85
	v_lshl_add_u32 v170, v114, 1, s15
	global_load_lds_dwordx4 v187, s[90:91]
	s_add_i32 m0, s16, s86
	v_add_u32_e32 v158, v137, v135
	global_load_lds_dwordx4 v188, s[90:91]
	s_add_i32 m0, s16, s87
	v_add_u32_e32 v166, v170, v135
	global_load_lds_dwordx4 v189, s[90:91]
	s_add_i32 m0, s16, s88
	s_addk_i32 s14, 0x4000
	global_load_lds_dwordx4 v190, s[90:91]
	s_add_i32 m0, s16, s89
	s_add_u32 s6, s6, 0x80
	s_addc_u32 s7, s7, 0
	global_load_lds_dwordx4 v191, s[90:91]
	ds_read_b128 v[138:141], v158
	ds_read_b128 v[146:149], v166 offset:16384
	ds_read_b128 v[150:153], v166 offset:18432
	ds_read_b128 v[162:165], v166 offset:20480
	ds_read_b128 v[166:169], v166 offset:22528
	ds_read_b128 v[142:145], v158 offset:2048
	ds_read_b128 v[154:157], v158 offset:4096
	ds_read_b128 v[158:161], v158 offset:6144
	v_add_u32_e32 v137, v137, v136
	v_add_u32_e32 v236, v170, v136
	ds_read_b128 v[204:207], v137
	ds_read_b128 v[208:211], v236 offset:16384
	ds_read_b128 v[212:215], v236 offset:18432
	ds_read_b128 v[216:219], v236 offset:20480
	ds_read_b128 v[220:223], v236 offset:22528
	ds_read_b128 v[224:227], v137 offset:2048
	ds_read_b128 v[228:231], v137 offset:4096
	ds_read_b128 v[232:235], v137 offset:6144
	s_setprio 1
	s_waitcnt lgkmcnt(11)
	v_mfma_f32_16x16x32_bf16 v[60:63], v[138:141], v[146:149], v[60:63]
	v_mfma_f32_16x16x32_bf16 v[56:59], v[138:141], v[150:153], v[56:59]
	v_mfma_f32_16x16x32_bf16 v[52:55], v[138:141], v[162:165], v[52:55]
	v_mfma_f32_16x16x32_bf16 v[48:51], v[138:141], v[166:169], v[48:51]
	s_waitcnt lgkmcnt(10)
	v_mfma_f32_16x16x32_bf16 v[44:47], v[142:145], v[146:149], v[44:47]
	v_mfma_f32_16x16x32_bf16 v[40:43], v[142:145], v[150:153], v[40:43]
	v_mfma_f32_16x16x32_bf16 v[36:39], v[142:145], v[162:165], v[36:39]
	v_mfma_f32_16x16x32_bf16 v[32:35], v[142:145], v[166:169], v[32:35]
	s_waitcnt lgkmcnt(9)
	v_mfma_f32_16x16x32_bf16 v[28:31], v[154:157], v[146:149], v[28:31]
	v_mfma_f32_16x16x32_bf16 v[24:27], v[154:157], v[150:153], v[24:27]
	v_mfma_f32_16x16x32_bf16 v[20:23], v[154:157], v[162:165], v[20:23]
	v_mfma_f32_16x16x32_bf16 v[16:19], v[154:157], v[166:169], v[16:19]
	s_waitcnt lgkmcnt(8)
	v_mfma_f32_16x16x32_bf16 v[12:15], v[158:161], v[146:149], v[12:15]
	v_mfma_f32_16x16x32_bf16 v[8:11], v[158:161], v[150:153], v[8:11]
	v_mfma_f32_16x16x32_bf16 v[4:7], v[158:161], v[162:165], v[4:7]
	v_mfma_f32_16x16x32_bf16 v[0:3], v[158:161], v[166:169], v[0:3]
	s_waitcnt lgkmcnt(3)
	v_mfma_f32_16x16x32_bf16 v[60:63], v[204:207], v[208:211], v[60:63]
	v_mfma_f32_16x16x32_bf16 v[56:59], v[204:207], v[212:215], v[56:59]
	v_mfma_f32_16x16x32_bf16 v[52:55], v[204:207], v[216:219], v[52:55]
	v_mfma_f32_16x16x32_bf16 v[48:51], v[204:207], v[220:223], v[48:51]
	s_waitcnt lgkmcnt(2)
	v_mfma_f32_16x16x32_bf16 v[44:47], v[224:227], v[208:211], v[44:47]
	v_mfma_f32_16x16x32_bf16 v[40:43], v[224:227], v[212:215], v[40:43]
	v_mfma_f32_16x16x32_bf16 v[36:39], v[224:227], v[216:219], v[36:39]
	v_mfma_f32_16x16x32_bf16 v[32:35], v[224:227], v[220:223], v[32:35]
	s_waitcnt lgkmcnt(1)
	v_mfma_f32_16x16x32_bf16 v[28:31], v[228:231], v[208:211], v[28:31]
	v_mfma_f32_16x16x32_bf16 v[24:27], v[228:231], v[212:215], v[24:27]
	v_mfma_f32_16x16x32_bf16 v[20:23], v[228:231], v[216:219], v[20:23]
	v_mfma_f32_16x16x32_bf16 v[16:19], v[228:231], v[220:223], v[16:19]
	s_waitcnt lgkmcnt(0)
	v_mfma_f32_16x16x32_bf16 v[12:15], v[232:235], v[208:211], v[12:15]
	v_mfma_f32_16x16x32_bf16 v[8:11], v[232:235], v[212:215], v[8:11]
	v_mfma_f32_16x16x32_bf16 v[4:7], v[232:235], v[216:219], v[4:7]
	v_mfma_f32_16x16x32_bf16 v[0:3], v[232:235], v[220:223], v[0:3]
	s_setprio 0
	s_cmpk_eq_i32 s6, 0x780
	s_waitcnt vmcnt(0)
	s_barrier
	s_cbranch_scc0 .LBB0_616
	ds_read_b128 v[88:91], v115 offset:55296
	ds_read_b128 v[92:95], v115 offset:53248
	ds_read_b128 v[96:99], v116 offset:38912
	ds_read_b128 v[100:103], v116 offset:36864
	ds_read_b128 v[138:141], v115 offset:51200
	ds_read_b128 v[142:145], v115 offset:49152
	ds_read_b128 v[146:149], v116 offset:34816
	ds_read_b128 v[150:153], v116 offset:32768
	ds_read_b128 v[204:207], v117 offset:32768
	ds_read_b128 v[208:211], v117 offset:34816
	ds_read_b128 v[212:215], v118 offset:49152
	ds_read_b128 v[216:219], v118 offset:51200
	ds_read_b128 v[220:223], v117 offset:36864
	ds_read_b128 v[224:227], v117 offset:38912
	ds_read_b128 v[228:231], v118 offset:53248
	ds_read_b128 v[232:235], v118 offset:55296
	s_setprio 1
	s_waitcnt lgkmcnt(13)
	v_mfma_f32_16x16x32_bf16 v[0:3], v[96:99], v[88:91], v[0:3]
	s_waitcnt lgkmcnt(8)
	v_mfma_f32_16x16x32_bf16 v[60:63], v[150:153], v[142:145], v[60:63]
	v_mfma_f32_16x16x32_bf16 v[56:59], v[150:153], v[138:141], v[56:59]
	v_mfma_f32_16x16x32_bf16 v[52:55], v[150:153], v[92:95], v[52:55]
	v_mfma_f32_16x16x32_bf16 v[48:51], v[150:153], v[88:91], v[48:51]
	v_mfma_f32_16x16x32_bf16 v[44:47], v[146:149], v[142:145], v[44:47]
	v_mfma_f32_16x16x32_bf16 v[40:43], v[146:149], v[138:141], v[40:43]
	v_mfma_f32_16x16x32_bf16 v[36:39], v[146:149], v[92:95], v[36:39]
	v_mfma_f32_16x16x32_bf16 v[32:35], v[146:149], v[88:91], v[32:35]
	v_mfma_f32_16x16x32_bf16 v[28:31], v[100:103], v[142:145], v[28:31]
	v_mfma_f32_16x16x32_bf16 v[24:27], v[100:103], v[138:141], v[24:27]
	v_mfma_f32_16x16x32_bf16 v[20:23], v[100:103], v[92:95], v[20:23]
	v_mfma_f32_16x16x32_bf16 v[16:19], v[100:103], v[88:91], v[16:19]
	v_mfma_f32_16x16x32_bf16 v[12:15], v[96:99], v[142:145], v[12:15]
	v_mfma_f32_16x16x32_bf16 v[8:11], v[96:99], v[138:141], v[8:11]
	v_mfma_f32_16x16x32_bf16 v[4:7], v[96:99], v[92:95], v[4:7]
	s_waitcnt lgkmcnt(0)
	v_mfma_f32_16x16x32_bf16 v[0:3], v[224:227], v[232:235], v[0:3]
	v_mfma_f32_16x16x32_bf16 v[60:63], v[204:207], v[212:215], v[60:63]
	v_mfma_f32_16x16x32_bf16 v[56:59], v[204:207], v[216:219], v[56:59]
	v_mfma_f32_16x16x32_bf16 v[52:55], v[204:207], v[228:231], v[52:55]
	v_mfma_f32_16x16x32_bf16 v[48:51], v[204:207], v[232:235], v[48:51]
	v_mfma_f32_16x16x32_bf16 v[44:47], v[208:211], v[212:215], v[44:47]
	v_mfma_f32_16x16x32_bf16 v[40:43], v[208:211], v[216:219], v[40:43]
	v_mfma_f32_16x16x32_bf16 v[36:39], v[208:211], v[228:231], v[36:39]
	v_mfma_f32_16x16x32_bf16 v[32:35], v[208:211], v[232:235], v[32:35]
	v_mfma_f32_16x16x32_bf16 v[28:31], v[220:223], v[212:215], v[28:31]
	v_mfma_f32_16x16x32_bf16 v[24:27], v[220:223], v[216:219], v[24:27]
	v_mfma_f32_16x16x32_bf16 v[20:23], v[220:223], v[228:231], v[20:23]
	v_mfma_f32_16x16x32_bf16 v[16:19], v[220:223], v[232:235], v[16:19]
	v_mfma_f32_16x16x32_bf16 v[12:15], v[224:227], v[212:215], v[12:15]
	v_mfma_f32_16x16x32_bf16 v[8:11], v[224:227], v[216:219], v[8:11]
	v_mfma_f32_16x16x32_bf16 v[4:7], v[224:227], v[228:231], v[4:7]
	s_setprio 0
	s_barrier
	ds_write2_b32 v119, v60, v56 offset1:16
	ds_write2_b32 v119, v61, v57 offset0:132 offset1:148
	v_add_u32_e32 v56, 0x400, v119
	ds_write2_b32 v56, v62, v58 offset0:8 offset1:24
	ds_write2_b32 v56, v63, v59 offset0:140 offset1:156
	ds_write2_b32 v119, v52, v48 offset0:32 offset1:48
	ds_write2_b32 v119, v53, v49 offset0:164 offset1:180
	ds_write2_b32 v56, v54, v50 offset0:40 offset1:56
	ds_write2_b32 v56, v55, v51 offset0:172 offset1:188
	v_add_u32_e32 v48, 0x2000, v119
	ds_write2_b32 v48, v44, v40 offset0:64 offset1:80
	ds_write2_b32 v48, v45, v41 offset0:196 offset1:212
	v_add_u32_e32 v40, 0x2400, v119
	ds_write2_b32 v40, v46, v42 offset0:72 offset1:88
	ds_write2_b32 v40, v47, v43 offset0:204 offset1:220
	ds_write2_b32 v48, v36, v32 offset0:96 offset1:112
	ds_write2_b32 v48, v37, v33 offset0:228 offset1:244
	ds_write2_b32 v40, v38, v34 offset0:104 offset1:120
	ds_write2_b32 v40, v39, v35 offset0:236 offset1:252
	v_add_u32_e32 v32, 0x4000, v119
	ds_write2_b32 v32, v28, v24 offset0:128 offset1:144
	v_add_u32_e32 v24, 0x4400, v119
	ds_write2_b32 v24, v29, v25 offset0:4 offset1:20
	ds_write2_b32 v24, v30, v26 offset0:136 offset1:152
	v_add_u32_e32 v25, 0x4800, v119
	ds_write2_b32 v25, v31, v27 offset0:12 offset1:28
	ds_write2_b32 v32, v20, v16 offset0:160 offset1:176
	ds_write2_b32 v24, v21, v17 offset0:36 offset1:52
	ds_write2_b32 v24, v22, v18 offset0:168 offset1:184
	ds_write2_b32 v25, v23, v19 offset0:44 offset1:60
	v_add_u32_e32 v16, 0x6000, v119
	ds_write2_b32 v16, v12, v8 offset0:192 offset1:208
	v_add_u32_e32 v8, 0x6400, v119
	ds_write2_b32 v8, v13, v9 offset0:68 offset1:84
	ds_write2_b32 v8, v14, v10 offset0:200 offset1:216
	v_add_u32_e32 v9, 0x6800, v119
	ds_write2_b32 v9, v15, v11 offset0:76 offset1:92
	ds_write2_b32 v16, v4, v0 offset0:224 offset1:240
	ds_write2_b32 v8, v5, v1 offset0:100 offset1:116
	ds_write2_b32 v8, v6, v2 offset0:232 offset1:248
	ds_write2_b32 v9, v7, v3 offset0:108 offset1:124
	v_or_b32_e32 v0, s12, v120
	v_ashrrev_i32_e32 v1, 31, v0
	v_lshl_add_u64 v[0:1], v[0:1], 1, s[4:5]
	v_add_u32_e32 v2, s13, v128
	s_mov_b32 s6, 0
	s_waitcnt lgkmcnt(0)
	s_barrier

.LBB0_682:
	s_and_b32 s25, s24, 0x4000
	s_xor_b32 s26, s25, 0x4000
	s_lshl_b32 s26, s26, 1
	s_add_i32 s26, s26, 32
	s_add_u32 s90, s52, s14
	s_addc_u32 s91, s53, s15
	s_add_i32 m0, s26, s82
	s_lshl_b32 s25, s25, 1
	global_load_lds_dwordx4 v192, s[90:91]
	s_add_i32 m0, s26, s83
	s_add_i32 s25, s25, 32
	global_load_lds_dwordx4 v193, s[90:91]
	s_add_i32 m0, s26, s84
	v_add3_u32 v170, s25, v114, v135
	global_load_lds_dwordx4 v194, s[90:91]
	s_add_i32 m0, s26, s85
	v_add3_u32 v171, s25, v115, v135
	global_load_lds_dwordx4 v195, s[90:91]
	s_add_i32 m0, s26, s86
	v_add_u32_e32 v158, v170, v136
	global_load_lds_dwordx4 v196, s[90:91]
	s_add_i32 m0, s26, s87
	v_add_u32_e32 v166, v171, v136
	global_load_lds_dwordx4 v197, s[90:91]
	s_add_i32 m0, s26, s88
	s_addk_i32 s24, 0x4000
	global_load_lds_dwordx4 v198, s[90:91]
	s_add_i32 m0, s26, s89
	s_add_u32 s14, s14, 0x80
	s_addc_u32 s15, s15, 0
	global_load_lds_dwordx4 v199, s[90:91]
	ds_read_b128 v[138:141], v158
	ds_read_b128 v[146:149], v166 offset:16384
	ds_read_b128 v[150:153], v166 offset:18432
	ds_read_b128 v[162:165], v166 offset:20480
	ds_read_b128 v[166:169], v166 offset:22528
	ds_read_b128 v[142:145], v158 offset:2048
	ds_read_b128 v[154:157], v158 offset:4096
	ds_read_b128 v[158:161], v158 offset:6144
	v_add_u32_e32 v236, v170, v137
	v_add_u32_e32 v237, v171, v137
	ds_read_b128 v[204:207], v236
	ds_read_b128 v[208:211], v237 offset:16384
	ds_read_b128 v[212:215], v237 offset:18432
	ds_read_b128 v[216:219], v237 offset:20480
	ds_read_b128 v[220:223], v237 offset:22528
	ds_read_b128 v[224:227], v236 offset:2048
	ds_read_b128 v[228:231], v236 offset:4096
	ds_read_b128 v[232:235], v236 offset:6144
	s_setprio 1
	s_waitcnt lgkmcnt(11)
	v_mfma_f32_16x16x32_bf16 v[60:63], v[138:141], v[146:149], v[60:63]
	v_mfma_f32_16x16x32_bf16 v[56:59], v[138:141], v[150:153], v[56:59]
	v_mfma_f32_16x16x32_bf16 v[52:55], v[138:141], v[162:165], v[52:55]
	v_mfma_f32_16x16x32_bf16 v[48:51], v[138:141], v[166:169], v[48:51]
	s_waitcnt lgkmcnt(10)
	v_mfma_f32_16x16x32_bf16 v[44:47], v[142:145], v[146:149], v[44:47]
	v_mfma_f32_16x16x32_bf16 v[40:43], v[142:145], v[150:153], v[40:43]
	v_mfma_f32_16x16x32_bf16 v[36:39], v[142:145], v[162:165], v[36:39]
	v_mfma_f32_16x16x32_bf16 v[32:35], v[142:145], v[166:169], v[32:35]
	s_waitcnt lgkmcnt(9)
	v_mfma_f32_16x16x32_bf16 v[28:31], v[154:157], v[146:149], v[28:31]
	v_mfma_f32_16x16x32_bf16 v[24:27], v[154:157], v[150:153], v[24:27]
	v_mfma_f32_16x16x32_bf16 v[20:23], v[154:157], v[162:165], v[20:23]
	v_mfma_f32_16x16x32_bf16 v[16:19], v[154:157], v[166:169], v[16:19]
	s_waitcnt lgkmcnt(8)
	v_mfma_f32_16x16x32_bf16 v[12:15], v[158:161], v[146:149], v[12:15]
	v_mfma_f32_16x16x32_bf16 v[8:11], v[158:161], v[150:153], v[8:11]
	v_mfma_f32_16x16x32_bf16 v[4:7], v[158:161], v[162:165], v[4:7]
	v_mfma_f32_16x16x32_bf16 v[0:3], v[158:161], v[166:169], v[0:3]
	s_waitcnt lgkmcnt(3)
	v_mfma_f32_16x16x32_bf16 v[60:63], v[204:207], v[208:211], v[60:63]
	v_mfma_f32_16x16x32_bf16 v[56:59], v[204:207], v[212:215], v[56:59]
	v_mfma_f32_16x16x32_bf16 v[52:55], v[204:207], v[216:219], v[52:55]
	v_mfma_f32_16x16x32_bf16 v[48:51], v[204:207], v[220:223], v[48:51]
	s_waitcnt lgkmcnt(2)
	v_mfma_f32_16x16x32_bf16 v[44:47], v[224:227], v[208:211], v[44:47]
	v_mfma_f32_16x16x32_bf16 v[40:43], v[224:227], v[212:215], v[40:43]
	v_mfma_f32_16x16x32_bf16 v[36:39], v[224:227], v[216:219], v[36:39]
	v_mfma_f32_16x16x32_bf16 v[32:35], v[224:227], v[220:223], v[32:35]
	s_waitcnt lgkmcnt(1)
	v_mfma_f32_16x16x32_bf16 v[28:31], v[228:231], v[208:211], v[28:31]
	v_mfma_f32_16x16x32_bf16 v[24:27], v[228:231], v[212:215], v[24:27]
	v_mfma_f32_16x16x32_bf16 v[20:23], v[228:231], v[216:219], v[20:23]
	v_mfma_f32_16x16x32_bf16 v[16:19], v[228:231], v[220:223], v[16:19]
	s_waitcnt lgkmcnt(0)
	v_mfma_f32_16x16x32_bf16 v[12:15], v[232:235], v[208:211], v[12:15]
	v_mfma_f32_16x16x32_bf16 v[8:11], v[232:235], v[212:215], v[8:11]
	v_mfma_f32_16x16x32_bf16 v[4:7], v[232:235], v[216:219], v[4:7]
	v_mfma_f32_16x16x32_bf16 v[0:3], v[232:235], v[220:223], v[0:3]
	s_setprio 0
	s_cmpk_eq_i32 s14, 0x1f80
	s_waitcnt vmcnt(0)
	s_barrier
	s_cbranch_scc0 .LBB0_682
	ds_read_b128 v[90:93], v118 offset:55296
	ds_read_b128 v[94:97], v118 offset:53248
	ds_read_b128 v[98:101], v119 offset:38912
	ds_read_b128 v[102:105], v119 offset:36864
	ds_read_b128 v[138:141], v118 offset:51200
	ds_read_b128 v[142:145], v118 offset:49152
	ds_read_b128 v[146:149], v119 offset:34816
	ds_read_b128 v[150:153], v119 offset:32768
	ds_read_b128 v[204:207], v120 offset:32768
	ds_read_b128 v[208:211], v120 offset:34816
	ds_read_b128 v[212:215], v121 offset:49152
	ds_read_b128 v[216:219], v121 offset:51200
	ds_read_b128 v[220:223], v120 offset:36864
	ds_read_b128 v[224:227], v120 offset:38912
	ds_read_b128 v[228:231], v121 offset:53248
	ds_read_b128 v[232:235], v121 offset:55296
	s_setprio 1
	s_waitcnt lgkmcnt(13)
	v_mfma_f32_16x16x32_bf16 v[4:7], v[98:101], v[94:97], v[4:7]
	v_mfma_f32_16x16x32_bf16 v[0:3], v[98:101], v[90:93], v[0:3]
	s_waitcnt lgkmcnt(8)
	v_mfma_f32_16x16x32_bf16 v[60:63], v[150:153], v[142:145], v[60:63]
	v_mfma_f32_16x16x32_bf16 v[56:59], v[150:153], v[138:141], v[56:59]
	v_mfma_f32_16x16x32_bf16 v[52:55], v[150:153], v[94:97], v[52:55]
	v_mfma_f32_16x16x32_bf16 v[48:51], v[150:153], v[90:93], v[48:51]
	v_mfma_f32_16x16x32_bf16 v[44:47], v[146:149], v[142:145], v[44:47]
	v_mfma_f32_16x16x32_bf16 v[40:43], v[146:149], v[138:141], v[40:43]
	v_mfma_f32_16x16x32_bf16 v[36:39], v[146:149], v[94:97], v[36:39]
	v_mfma_f32_16x16x32_bf16 v[32:35], v[146:149], v[90:93], v[32:35]
	v_mfma_f32_16x16x32_bf16 v[28:31], v[102:105], v[142:145], v[28:31]
	v_mfma_f32_16x16x32_bf16 v[24:27], v[102:105], v[138:141], v[24:27]
	v_mfma_f32_16x16x32_bf16 v[20:23], v[102:105], v[94:97], v[20:23]
	v_mfma_f32_16x16x32_bf16 v[16:19], v[102:105], v[90:93], v[16:19]
	v_mfma_f32_16x16x32_bf16 v[12:15], v[98:101], v[142:145], v[12:15]
	v_mfma_f32_16x16x32_bf16 v[8:11], v[98:101], v[138:141], v[8:11]
	s_waitcnt lgkmcnt(1)
	v_mfma_f32_16x16x32_bf16 v[4:7], v[224:227], v[228:231], v[4:7]
	s_waitcnt lgkmcnt(0)
	v_mfma_f32_16x16x32_bf16 v[0:3], v[224:227], v[232:235], v[0:3]
	v_mfma_f32_16x16x32_bf16 v[60:63], v[204:207], v[212:215], v[60:63]
	v_mfma_f32_16x16x32_bf16 v[56:59], v[204:207], v[216:219], v[56:59]
	v_mfma_f32_16x16x32_bf16 v[52:55], v[204:207], v[228:231], v[52:55]
	v_mfma_f32_16x16x32_bf16 v[48:51], v[204:207], v[232:235], v[48:51]
	v_mfma_f32_16x16x32_bf16 v[44:47], v[208:211], v[212:215], v[44:47]
	v_mfma_f32_16x16x32_bf16 v[40:43], v[208:211], v[216:219], v[40:43]
	v_mfma_f32_16x16x32_bf16 v[36:39], v[208:211], v[228:231], v[36:39]
	v_mfma_f32_16x16x32_bf16 v[32:35], v[208:211], v[232:235], v[32:35]
	v_mfma_f32_16x16x32_bf16 v[28:31], v[220:223], v[212:215], v[28:31]
	v_mfma_f32_16x16x32_bf16 v[24:27], v[220:223], v[216:219], v[24:27]
	v_mfma_f32_16x16x32_bf16 v[20:23], v[220:223], v[228:231], v[20:23]
	v_mfma_f32_16x16x32_bf16 v[16:19], v[220:223], v[232:235], v[16:19]
	v_mfma_f32_16x16x32_bf16 v[12:15], v[224:227], v[212:215], v[12:15]
	v_mfma_f32_16x16x32_bf16 v[8:11], v[224:227], v[216:219], v[8:11]
	s_setprio 0
	s_barrier
	ds_write2_b32 v116, v60, v56 offset1:16
	ds_write2_b32 v116, v61, v57 offset0:132 offset1:148
	v_add_u32_e32 v56, 0x400, v116
	ds_write2_b32 v56, v62, v58 offset0:8 offset1:24
	ds_write2_b32 v56, v63, v59 offset0:140 offset1:156
	ds_write2_b32 v116, v52, v48 offset0:32 offset1:48
	ds_write2_b32 v116, v53, v49 offset0:164 offset1:180
	ds_write2_b32 v56, v54, v50 offset0:40 offset1:56
	ds_write2_b32 v56, v55, v51 offset0:172 offset1:188
	v_add_u32_e32 v48, 0x2000, v116
	ds_write2_b32 v48, v44, v40 offset0:64 offset1:80
	ds_write2_b32 v48, v45, v41 offset0:196 offset1:212
	v_add_u32_e32 v40, 0x2400, v116
	ds_write2_b32 v40, v46, v42 offset0:72 offset1:88
	ds_write2_b32 v40, v47, v43 offset0:204 offset1:220
	ds_write2_b32 v48, v36, v32 offset0:96 offset1:112
	ds_write2_b32 v48, v37, v33 offset0:228 offset1:244
	ds_write2_b32 v40, v38, v34 offset0:104 offset1:120
	ds_write2_b32 v40, v39, v35 offset0:236 offset1:252
	v_add_u32_e32 v32, 0x4000, v116
	ds_write2_b32 v32, v28, v24 offset0:128 offset1:144
	v_add_u32_e32 v24, 0x4400, v116
	ds_write2_b32 v24, v29, v25 offset0:4 offset1:20
	ds_write2_b32 v24, v30, v26 offset0:136 offset1:152
	v_add_u32_e32 v25, 0x4800, v116
	ds_write2_b32 v25, v31, v27 offset0:12 offset1:28
	ds_write2_b32 v32, v20, v16 offset0:160 offset1:176
	ds_write2_b32 v24, v21, v17 offset0:36 offset1:52
	ds_write2_b32 v24, v22, v18 offset0:168 offset1:184
	ds_write2_b32 v25, v23, v19 offset0:44 offset1:60
	v_add_u32_e32 v16, 0x6000, v116
	ds_write2_b32 v16, v12, v8 offset0:192 offset1:208
	v_add_u32_e32 v8, 0x6400, v116
	ds_write2_b32 v8, v13, v9 offset0:68 offset1:84
	ds_write2_b32 v8, v14, v10 offset0:200 offset1:216
	v_add_u32_e32 v9, 0x6800, v116
	ds_write2_b32 v9, v15, v11 offset0:76 offset1:92
	ds_write2_b32 v16, v4, v0 offset0:224 offset1:240
	ds_write2_b32 v8, v5, v1 offset0:100 offset1:116
	ds_write2_b32 v8, v6, v2 offset0:232 offset1:248
	ds_write2_b32 v9, v7, v3 offset0:108 offset1:124
	v_or_b32_e32 v0, s23, v117
	v_ashrrev_i32_e32 v1, 31, v0
	v_lshlrev_b64 v[2:3], 2, v[0:1]
	v_lshl_add_u64 v[0:1], s[12:13], 0, v[2:3]
	v_lshl_add_u64 v[2:3], s[10:11], 0, v[2:3]
	v_add_u32_e32 v4, s22, v128
	s_mov_b32 s14, 0
	s_waitcnt lgkmcnt(0)
	s_barrier

.LBB0_691:
	s_and_b32 s26, s25, 0x4000
	s_xor_b32 s27, s26, 0x4000
	s_lshl_b32 s27, s27, 1
	s_add_i32 s27, s27, 32
	s_add_u32 s90, s52, s14
	s_addc_u32 s91, s53, s15
	s_add_i32 m0, s27, s82
	s_lshl_b32 s26, s26, 1
	global_load_lds_dwordx4 v192, s[90:91]
	s_add_i32 m0, s27, s83
	s_add_i32 s26, s26, 32
	global_load_lds_dwordx4 v193, s[90:91]
	s_add_i32 m0, s27, s84
	v_add3_u32 v139, s26, v113, v136
	global_load_lds_dwordx4 v194, s[90:91]
	s_add_i32 m0, s27, s85
	v_add3_u32 v172, s26, v114, v136
	global_load_lds_dwordx4 v195, s[90:91]
	s_add_i32 m0, s27, s86
	v_add_u32_e32 v160, v139, v137
	global_load_lds_dwordx4 v196, s[90:91]
	s_add_i32 m0, s27, s87
	v_add_u32_e32 v168, v172, v137
	global_load_lds_dwordx4 v197, s[90:91]
	s_add_i32 m0, s27, s88
	s_addk_i32 s25, 0x4000
	global_load_lds_dwordx4 v198, s[90:91]
	s_add_i32 m0, s27, s89
	s_add_u32 s14, s14, 0x80
	s_addc_u32 s15, s15, 0
	global_load_lds_dwordx4 v199, s[90:91]
	ds_read_b128 v[140:143], v160
	ds_read_b128 v[148:151], v168 offset:16384
	ds_read_b128 v[152:155], v168 offset:18432
	ds_read_b128 v[164:167], v168 offset:20480
	ds_read_b128 v[168:171], v168 offset:22528
	ds_read_b128 v[144:147], v160 offset:2048
	ds_read_b128 v[156:159], v160 offset:4096
	ds_read_b128 v[160:163], v160 offset:6144
	v_add_u32_e32 v139, v139, v138
	v_add_u32_e32 v236, v172, v138
	ds_read_b128 v[204:207], v139
	ds_read_b128 v[208:211], v236 offset:16384
	ds_read_b128 v[212:215], v236 offset:18432
	ds_read_b128 v[216:219], v236 offset:20480
	ds_read_b128 v[220:223], v236 offset:22528
	ds_read_b128 v[224:227], v139 offset:2048
	ds_read_b128 v[228:231], v139 offset:4096
	ds_read_b128 v[232:235], v139 offset:6144
	s_setprio 1
	s_waitcnt lgkmcnt(11)
	v_mfma_f32_16x16x32_bf16 v[60:63], v[140:143], v[148:151], v[60:63]
	v_mfma_f32_16x16x32_bf16 v[56:59], v[140:143], v[152:155], v[56:59]
	v_mfma_f32_16x16x32_bf16 v[52:55], v[140:143], v[164:167], v[52:55]
	v_mfma_f32_16x16x32_bf16 v[48:51], v[140:143], v[168:171], v[48:51]
	s_waitcnt lgkmcnt(10)
	v_mfma_f32_16x16x32_bf16 v[44:47], v[144:147], v[148:151], v[44:47]
	v_mfma_f32_16x16x32_bf16 v[40:43], v[144:147], v[152:155], v[40:43]
	v_mfma_f32_16x16x32_bf16 v[36:39], v[144:147], v[164:167], v[36:39]
	v_mfma_f32_16x16x32_bf16 v[32:35], v[144:147], v[168:171], v[32:35]
	s_waitcnt lgkmcnt(9)
	v_mfma_f32_16x16x32_bf16 v[28:31], v[156:159], v[148:151], v[28:31]
	v_mfma_f32_16x16x32_bf16 v[24:27], v[156:159], v[152:155], v[24:27]
	v_mfma_f32_16x16x32_bf16 v[20:23], v[156:159], v[164:167], v[20:23]
	v_mfma_f32_16x16x32_bf16 v[16:19], v[156:159], v[168:171], v[16:19]
	s_waitcnt lgkmcnt(8)
	v_mfma_f32_16x16x32_bf16 v[12:15], v[160:163], v[148:151], v[12:15]
	v_mfma_f32_16x16x32_bf16 v[8:11], v[160:163], v[152:155], v[8:11]
	v_mfma_f32_16x16x32_bf16 v[4:7], v[160:163], v[164:167], v[4:7]
	v_mfma_f32_16x16x32_bf16 v[0:3], v[160:163], v[168:171], v[0:3]
	s_waitcnt lgkmcnt(3)
	v_mfma_f32_16x16x32_bf16 v[60:63], v[204:207], v[208:211], v[60:63]
	v_mfma_f32_16x16x32_bf16 v[56:59], v[204:207], v[212:215], v[56:59]
	v_mfma_f32_16x16x32_bf16 v[52:55], v[204:207], v[216:219], v[52:55]
	v_mfma_f32_16x16x32_bf16 v[48:51], v[204:207], v[220:223], v[48:51]
	s_waitcnt lgkmcnt(2)
	v_mfma_f32_16x16x32_bf16 v[44:47], v[224:227], v[208:211], v[44:47]
	v_mfma_f32_16x16x32_bf16 v[40:43], v[224:227], v[212:215], v[40:43]
	v_mfma_f32_16x16x32_bf16 v[36:39], v[224:227], v[216:219], v[36:39]
	v_mfma_f32_16x16x32_bf16 v[32:35], v[224:227], v[220:223], v[32:35]
	s_waitcnt lgkmcnt(1)
	v_mfma_f32_16x16x32_bf16 v[28:31], v[228:231], v[208:211], v[28:31]
	v_mfma_f32_16x16x32_bf16 v[24:27], v[228:231], v[212:215], v[24:27]
	v_mfma_f32_16x16x32_bf16 v[20:23], v[228:231], v[216:219], v[20:23]
	v_mfma_f32_16x16x32_bf16 v[16:19], v[228:231], v[220:223], v[16:19]
	s_waitcnt lgkmcnt(0)
	v_mfma_f32_16x16x32_bf16 v[12:15], v[232:235], v[208:211], v[12:15]
	v_mfma_f32_16x16x32_bf16 v[8:11], v[232:235], v[212:215], v[8:11]
	v_mfma_f32_16x16x32_bf16 v[4:7], v[232:235], v[216:219], v[4:7]
	v_mfma_f32_16x16x32_bf16 v[0:3], v[232:235], v[220:223], v[0:3]
	s_setprio 0
	s_cmpk_eq_i32 s14, 0x1f80
	s_waitcnt vmcnt(0)
	s_barrier
	s_cbranch_scc0 .LBB0_691
	ds_read_b128 v[88:91], v117 offset:55296
	ds_read_b128 v[92:95], v117 offset:53248
	ds_read_b128 v[96:99], v118 offset:38912
	ds_read_b128 v[100:103], v118 offset:36864
	ds_read_b128 v[140:143], v117 offset:51200
	ds_read_b128 v[144:147], v117 offset:49152
	ds_read_b128 v[148:151], v118 offset:34816
	ds_read_b128 v[152:155], v118 offset:32768
	ds_read_b128 v[204:207], v119 offset:32768
	ds_read_b128 v[208:211], v119 offset:34816
	ds_read_b128 v[212:215], v120 offset:49152
	ds_read_b128 v[216:219], v120 offset:51200
	ds_read_b128 v[220:223], v119 offset:36864
	ds_read_b128 v[224:227], v119 offset:38912
	ds_read_b128 v[228:231], v120 offset:53248
	ds_read_b128 v[232:235], v120 offset:55296
	s_setprio 1
	s_waitcnt lgkmcnt(13)
	v_mfma_f32_16x16x32_bf16 v[4:7], v[96:99], v[92:95], v[4:7]
	v_mfma_f32_16x16x32_bf16 v[0:3], v[96:99], v[88:91], v[0:3]
	s_waitcnt lgkmcnt(8)
	v_mfma_f32_16x16x32_bf16 v[60:63], v[152:155], v[144:147], v[60:63]
	v_mfma_f32_16x16x32_bf16 v[56:59], v[152:155], v[140:143], v[56:59]
	v_mfma_f32_16x16x32_bf16 v[52:55], v[152:155], v[92:95], v[52:55]
	v_mfma_f32_16x16x32_bf16 v[48:51], v[152:155], v[88:91], v[48:51]
	v_mfma_f32_16x16x32_bf16 v[44:47], v[148:151], v[144:147], v[44:47]
	v_mfma_f32_16x16x32_bf16 v[40:43], v[148:151], v[140:143], v[40:43]
	v_mfma_f32_16x16x32_bf16 v[36:39], v[148:151], v[92:95], v[36:39]
	v_mfma_f32_16x16x32_bf16 v[32:35], v[148:151], v[88:91], v[32:35]
	v_mfma_f32_16x16x32_bf16 v[28:31], v[100:103], v[144:147], v[28:31]
	v_mfma_f32_16x16x32_bf16 v[24:27], v[100:103], v[140:143], v[24:27]
	v_mfma_f32_16x16x32_bf16 v[20:23], v[100:103], v[92:95], v[20:23]
	v_mfma_f32_16x16x32_bf16 v[16:19], v[100:103], v[88:91], v[16:19]
	v_mfma_f32_16x16x32_bf16 v[12:15], v[96:99], v[144:147], v[12:15]
	v_mfma_f32_16x16x32_bf16 v[8:11], v[96:99], v[140:143], v[8:11]
	s_waitcnt lgkmcnt(1)
	v_mfma_f32_16x16x32_bf16 v[4:7], v[224:227], v[228:231], v[4:7]
	s_waitcnt lgkmcnt(0)
	v_mfma_f32_16x16x32_bf16 v[0:3], v[224:227], v[232:235], v[0:3]
	v_mfma_f32_16x16x32_bf16 v[60:63], v[204:207], v[212:215], v[60:63]
	v_mfma_f32_16x16x32_bf16 v[56:59], v[204:207], v[216:219], v[56:59]
	v_mfma_f32_16x16x32_bf16 v[52:55], v[204:207], v[228:231], v[52:55]
	v_mfma_f32_16x16x32_bf16 v[48:51], v[204:207], v[232:235], v[48:51]
	v_mfma_f32_16x16x32_bf16 v[44:47], v[208:211], v[212:215], v[44:47]
	v_mfma_f32_16x16x32_bf16 v[40:43], v[208:211], v[216:219], v[40:43]
	v_mfma_f32_16x16x32_bf16 v[36:39], v[208:211], v[228:231], v[36:39]
	v_mfma_f32_16x16x32_bf16 v[32:35], v[208:211], v[232:235], v[32:35]
	v_mfma_f32_16x16x32_bf16 v[28:31], v[220:223], v[212:215], v[28:31]
	v_mfma_f32_16x16x32_bf16 v[24:27], v[220:223], v[216:219], v[24:27]
	v_mfma_f32_16x16x32_bf16 v[20:23], v[220:223], v[228:231], v[20:23]
	v_mfma_f32_16x16x32_bf16 v[16:19], v[220:223], v[232:235], v[16:19]
	v_mfma_f32_16x16x32_bf16 v[12:15], v[224:227], v[212:215], v[12:15]
	v_mfma_f32_16x16x32_bf16 v[8:11], v[224:227], v[216:219], v[8:11]
	s_setprio 0
	s_barrier
	ds_write2_b32 v115, v60, v56 offset1:16
	ds_write2_b32 v115, v61, v57 offset0:132 offset1:148
	v_add_u32_e32 v56, 0x400, v115
	ds_write2_b32 v56, v62, v58 offset0:8 offset1:24
	ds_write2_b32 v56, v63, v59 offset0:140 offset1:156
	ds_write2_b32 v115, v52, v48 offset0:32 offset1:48
	ds_write2_b32 v115, v53, v49 offset0:164 offset1:180
	ds_write2_b32 v56, v54, v50 offset0:40 offset1:56
	ds_write2_b32 v56, v55, v51 offset0:172 offset1:188
	v_add_u32_e32 v48, 0x2000, v115
	ds_write2_b32 v48, v44, v40 offset0:64 offset1:80
	ds_write2_b32 v48, v45, v41 offset0:196 offset1:212
	v_add_u32_e32 v40, 0x2400, v115
	ds_write2_b32 v40, v46, v42 offset0:72 offset1:88
	ds_write2_b32 v40, v47, v43 offset0:204 offset1:220
	ds_write2_b32 v48, v36, v32 offset0:96 offset1:112
	ds_write2_b32 v48, v37, v33 offset0:228 offset1:244
	ds_write2_b32 v40, v38, v34 offset0:104 offset1:120
	ds_write2_b32 v40, v39, v35 offset0:236 offset1:252
	v_add_u32_e32 v32, 0x4000, v115
	ds_write2_b32 v32, v28, v24 offset0:128 offset1:144
	v_add_u32_e32 v24, 0x4400, v115
	ds_write2_b32 v24, v29, v25 offset0:4 offset1:20
	ds_write2_b32 v24, v30, v26 offset0:136 offset1:152
	v_add_u32_e32 v25, 0x4800, v115
	ds_write2_b32 v25, v31, v27 offset0:12 offset1:28
	ds_write2_b32 v32, v20, v16 offset0:160 offset1:176
	ds_write2_b32 v24, v21, v17 offset0:36 offset1:52
	ds_write2_b32 v24, v22, v18 offset0:168 offset1:184
	ds_write2_b32 v25, v23, v19 offset0:44 offset1:60
	v_add_u32_e32 v16, 0x6000, v115
	ds_write2_b32 v16, v12, v8 offset0:192 offset1:208
	v_add_u32_e32 v8, 0x6400, v115
	ds_write2_b32 v8, v13, v9 offset0:68 offset1:84
	ds_write2_b32 v8, v14, v10 offset0:200 offset1:216
	v_add_u32_e32 v9, 0x6800, v115
	ds_write2_b32 v9, v15, v11 offset0:76 offset1:92
	ds_write2_b32 v16, v4, v0 offset0:224 offset1:240
	ds_write2_b32 v8, v5, v1 offset0:100 offset1:116
	ds_write2_b32 v8, v6, v2 offset0:232 offset1:248
	ds_write2_b32 v9, v7, v3 offset0:108 offset1:124
	v_or_b32_e32 v0, s23, v116
	v_ashrrev_i32_e32 v1, 31, v0
	v_lshlrev_b64 v[2:3], 2, v[0:1]
	v_lshl_add_u64 v[0:1], s[12:13], 0, v[2:3]
	v_lshl_add_u64 v[2:3], s[10:11], 0, v[2:3]
	v_add_u32_e32 v4, s24, v129
	s_mov_b32 s14, 0
	s_waitcnt lgkmcnt(0)
	s_barrier

.LBB0_702:
	s_and_b32 s27, s26, 0x4000
	s_xor_b32 s28, s27, 0x4000
	s_lshl_b32 s28, s28, 1
	s_add_i32 s28, s28, 32
	s_add_u32 s90, s52, s14
	s_addc_u32 s91, s53, s15
	s_add_i32 m0, s28, s82
	s_lshl_b32 s27, s27, 1
	global_load_lds_dwordx4 v193, s[90:91]
	s_add_i32 m0, s28, s83
	s_add_i32 s27, s27, 32
	global_load_lds_dwordx4 v194, s[90:91]
	s_add_i32 m0, s28, s84
	v_lshlrev_b32_e32 v72, 1, v131
	global_load_lds_dwordx4 v195, s[90:91]
	s_add_i32 m0, s28, s85
	v_add3_u32 v178, s27, v129, v72
	global_load_lds_dwordx4 v196, s[90:91]
	s_add_i32 m0, s28, s86
	v_lshlrev_b32_e32 v154, 1, v121
	global_load_lds_dwordx4 v197, s[90:91]
	s_add_i32 m0, s28, s87
	v_add3_u32 v72, s27, v130, v72
	global_load_lds_dwordx4 v198, s[90:91]
	s_add_i32 m0, s28, s88
	v_add_u32_e32 v174, v178, v154
	global_load_lds_dwordx4 v199, s[90:91]
	s_add_i32 m0, s28, s89
	v_add_u32_e32 v179, v72, v154
	global_load_lds_dwordx4 v200, s[90:91]
	ds_read_b128 v[154:157], v174
	ds_read_b128 v[162:165], v179 offset:16384
	ds_read_b128 v[166:169], v179 offset:18432
	ds_read_b128 v[182:185], v179 offset:20480
	ds_read_b128 v[186:189], v179 offset:22528
	ds_read_b128 v[158:161], v174 offset:2048
	ds_read_b128 v[170:173], v174 offset:4096
	ds_read_b128 v[174:177], v174 offset:6144
	v_lshlrev_b32_e32 v236, 1, v122
	v_add_u32_e32 v237, v178, v236
	v_add_u32_e32 v72, v72, v236
	ds_read_b128 v[204:207], v237
	ds_read_b128 v[208:211], v72 offset:16384
	ds_read_b128 v[212:215], v72 offset:18432
	ds_read_b128 v[216:219], v72 offset:20480
	ds_read_b128 v[220:223], v72 offset:22528
	ds_read_b128 v[224:227], v237 offset:2048
	ds_read_b128 v[228:231], v237 offset:4096
	ds_read_b128 v[232:235], v237 offset:6144
	s_setprio 1
	s_waitcnt lgkmcnt(11)
	v_mfma_f32_16x16x32_bf16 v[60:63], v[154:157], v[162:165], v[60:63]
	v_mfma_f32_16x16x32_bf16 v[56:59], v[154:157], v[166:169], v[56:59]
	v_mfma_f32_16x16x32_bf16 v[52:55], v[154:157], v[182:185], v[52:55]
	v_mfma_f32_16x16x32_bf16 v[48:51], v[154:157], v[186:189], v[48:51]
	s_waitcnt lgkmcnt(10)
	v_mfma_f32_16x16x32_bf16 v[44:47], v[158:161], v[162:165], v[44:47]
	v_mfma_f32_16x16x32_bf16 v[40:43], v[158:161], v[166:169], v[40:43]
	v_mfma_f32_16x16x32_bf16 v[36:39], v[158:161], v[182:185], v[36:39]
	v_mfma_f32_16x16x32_bf16 v[32:35], v[158:161], v[186:189], v[32:35]
	s_waitcnt lgkmcnt(9)
	v_mfma_f32_16x16x32_bf16 v[28:31], v[170:173], v[162:165], v[28:31]
	v_mfma_f32_16x16x32_bf16 v[24:27], v[170:173], v[166:169], v[24:27]
	v_mfma_f32_16x16x32_bf16 v[20:23], v[170:173], v[182:185], v[20:23]
	v_mfma_f32_16x16x32_bf16 v[16:19], v[170:173], v[186:189], v[16:19]
	s_waitcnt lgkmcnt(8)
	v_mfma_f32_16x16x32_bf16 v[12:15], v[174:177], v[162:165], v[12:15]
	v_mfma_f32_16x16x32_bf16 v[8:11], v[174:177], v[166:169], v[8:11]
	v_mfma_f32_16x16x32_bf16 v[4:7], v[174:177], v[182:185], v[4:7]
	v_mfma_f32_16x16x32_bf16 v[0:3], v[174:177], v[186:189], v[0:3]
	s_waitcnt lgkmcnt(3)
	v_mfma_f32_16x16x32_bf16 v[60:63], v[204:207], v[208:211], v[60:63]
	v_mfma_f32_16x16x32_bf16 v[56:59], v[204:207], v[212:215], v[56:59]
	v_mfma_f32_16x16x32_bf16 v[52:55], v[204:207], v[216:219], v[52:55]
	v_mfma_f32_16x16x32_bf16 v[48:51], v[204:207], v[220:223], v[48:51]
	s_waitcnt lgkmcnt(2)
	v_mfma_f32_16x16x32_bf16 v[44:47], v[224:227], v[208:211], v[44:47]
	v_mfma_f32_16x16x32_bf16 v[40:43], v[224:227], v[212:215], v[40:43]
	v_mfma_f32_16x16x32_bf16 v[36:39], v[224:227], v[216:219], v[36:39]
	v_mfma_f32_16x16x32_bf16 v[32:35], v[224:227], v[220:223], v[32:35]
	s_waitcnt lgkmcnt(1)
	v_mfma_f32_16x16x32_bf16 v[28:31], v[228:231], v[208:211], v[28:31]
	v_mfma_f32_16x16x32_bf16 v[24:27], v[228:231], v[212:215], v[24:27]
	v_mfma_f32_16x16x32_bf16 v[20:23], v[228:231], v[216:219], v[20:23]
	v_mfma_f32_16x16x32_bf16 v[16:19], v[228:231], v[220:223], v[16:19]
	s_waitcnt lgkmcnt(0)
	v_mfma_f32_16x16x32_bf16 v[12:15], v[232:235], v[208:211], v[12:15]
	v_mfma_f32_16x16x32_bf16 v[8:11], v[232:235], v[212:215], v[8:11]
	v_mfma_f32_16x16x32_bf16 v[4:7], v[232:235], v[216:219], v[4:7]
	v_mfma_f32_16x16x32_bf16 v[0:3], v[232:235], v[220:223], v[0:3]
	s_setprio 0
	s_add_u32 s14, s14, 0x80
	s_addc_u32 s15, s15, 0
	s_addk_i32 s26, 0x4000
	s_cmpk_eq_i32 s14, 0x1f80
	s_waitcnt vmcnt(0)
	s_barrier
	s_cbranch_scc0 .LBB0_702
	ds_read_b128 v[98:101], v71 offset:32768
	ds_read_b128 v[102:105], v71 offset:34816
	ds_read_b128 v[106:109], v138 offset:49152
	ds_read_b128 v[110:113], v138 offset:51200
	ds_read_b128 v[154:157], v71 offset:36864
	ds_read_b128 v[158:161], v71 offset:38912
	ds_read_b128 v[162:165], v138 offset:53248
	ds_read_b128 v[166:169], v138 offset:55296
	ds_read_b128 v[204:207], v139 offset:32768
	ds_read_b128 v[208:211], v139 offset:34816
	ds_read_b128 v[212:215], v140 offset:49152
	ds_read_b128 v[216:219], v140 offset:51200
	ds_read_b128 v[220:223], v139 offset:36864
	ds_read_b128 v[224:227], v139 offset:38912
	ds_read_b128 v[228:231], v140 offset:53248
	ds_read_b128 v[232:235], v140 offset:55296
	s_setprio 1
	s_waitcnt lgkmcnt(9)
	v_mfma_f32_16x16x32_bf16 v[4:7], v[158:161], v[162:165], v[4:7]
	s_waitcnt lgkmcnt(8)
	v_mfma_f32_16x16x32_bf16 v[0:3], v[158:161], v[166:169], v[0:3]
	v_mfma_f32_16x16x32_bf16 v[60:63], v[98:101], v[106:109], v[60:63]
	v_mfma_f32_16x16x32_bf16 v[56:59], v[98:101], v[110:113], v[56:59]
	v_mfma_f32_16x16x32_bf16 v[52:55], v[98:101], v[162:165], v[52:55]
	v_mfma_f32_16x16x32_bf16 v[48:51], v[98:101], v[166:169], v[48:51]
	v_mfma_f32_16x16x32_bf16 v[44:47], v[102:105], v[106:109], v[44:47]
	v_mfma_f32_16x16x32_bf16 v[40:43], v[102:105], v[110:113], v[40:43]
	v_mfma_f32_16x16x32_bf16 v[36:39], v[102:105], v[162:165], v[36:39]
	v_mfma_f32_16x16x32_bf16 v[32:35], v[102:105], v[166:169], v[32:35]
	v_mfma_f32_16x16x32_bf16 v[28:31], v[154:157], v[106:109], v[28:31]
	v_mfma_f32_16x16x32_bf16 v[24:27], v[154:157], v[110:113], v[24:27]
	v_mfma_f32_16x16x32_bf16 v[20:23], v[154:157], v[162:165], v[20:23]
	v_mfma_f32_16x16x32_bf16 v[16:19], v[154:157], v[166:169], v[16:19]
	v_mfma_f32_16x16x32_bf16 v[12:15], v[158:161], v[106:109], v[12:15]
	v_mfma_f32_16x16x32_bf16 v[8:11], v[158:161], v[110:113], v[8:11]
	s_waitcnt lgkmcnt(1)
	v_mfma_f32_16x16x32_bf16 v[4:7], v[224:227], v[228:231], v[4:7]
	s_waitcnt lgkmcnt(0)
	v_mfma_f32_16x16x32_bf16 v[0:3], v[224:227], v[232:235], v[0:3]
	v_mfma_f32_16x16x32_bf16 v[60:63], v[204:207], v[212:215], v[60:63]
	v_mfma_f32_16x16x32_bf16 v[56:59], v[204:207], v[216:219], v[56:59]
	v_mfma_f32_16x16x32_bf16 v[52:55], v[204:207], v[228:231], v[52:55]
	v_mfma_f32_16x16x32_bf16 v[48:51], v[204:207], v[232:235], v[48:51]
	v_mfma_f32_16x16x32_bf16 v[44:47], v[208:211], v[212:215], v[44:47]
	v_mfma_f32_16x16x32_bf16 v[40:43], v[208:211], v[216:219], v[40:43]
	v_mfma_f32_16x16x32_bf16 v[36:39], v[208:211], v[228:231], v[36:39]
	v_mfma_f32_16x16x32_bf16 v[32:35], v[208:211], v[232:235], v[32:35]
	v_mfma_f32_16x16x32_bf16 v[28:31], v[220:223], v[212:215], v[28:31]
	v_mfma_f32_16x16x32_bf16 v[24:27], v[220:223], v[216:219], v[24:27]
	v_mfma_f32_16x16x32_bf16 v[20:23], v[220:223], v[228:231], v[20:23]
	v_mfma_f32_16x16x32_bf16 v[16:19], v[220:223], v[232:235], v[16:19]
	v_mfma_f32_16x16x32_bf16 v[12:15], v[224:227], v[212:215], v[12:15]
	v_mfma_f32_16x16x32_bf16 v[8:11], v[224:227], v[216:219], v[8:11]
	s_setprio 0
	s_barrier
	ds_write2_b32 v136, v60, v56 offset1:16
	ds_write2_b32 v136, v61, v57 offset0:132 offset1:148
	v_add_u32_e32 v56, 0x400, v136
	ds_write2_b32 v56, v62, v58 offset0:8 offset1:24
	ds_write2_b32 v56, v63, v59 offset0:140 offset1:156
	ds_write2_b32 v136, v52, v48 offset0:32 offset1:48
	ds_write2_b32 v136, v53, v49 offset0:164 offset1:180
	ds_write2_b32 v56, v54, v50 offset0:40 offset1:56
	ds_write2_b32 v56, v55, v51 offset0:172 offset1:188
	v_add_u32_e32 v48, 0x2000, v136
	ds_write2_b32 v48, v44, v40 offset0:64 offset1:80
	ds_write2_b32 v48, v45, v41 offset0:196 offset1:212
	v_add_u32_e32 v40, 0x2400, v136
	ds_write2_b32 v40, v46, v42 offset0:72 offset1:88
	ds_write2_b32 v40, v47, v43 offset0:204 offset1:220
	ds_write2_b32 v48, v36, v32 offset0:96 offset1:112
	ds_write2_b32 v48, v37, v33 offset0:228 offset1:244
	ds_write2_b32 v40, v38, v34 offset0:104 offset1:120
	ds_write2_b32 v40, v39, v35 offset0:236 offset1:252
	v_add_u32_e32 v32, 0x4000, v136
	ds_write2_b32 v32, v28, v24 offset0:128 offset1:144
	v_add_u32_e32 v24, 0x4400, v136
	ds_write2_b32 v24, v29, v25 offset0:4 offset1:20
	ds_write2_b32 v24, v30, v26 offset0:136 offset1:152
	v_add_u32_e32 v25, 0x4800, v136
	ds_write2_b32 v25, v31, v27 offset0:12 offset1:28
	ds_write2_b32 v32, v20, v16 offset0:160 offset1:176
	ds_write2_b32 v24, v21, v17 offset0:36 offset1:52
	ds_write2_b32 v24, v22, v18 offset0:168 offset1:184
	ds_write2_b32 v25, v23, v19 offset0:44 offset1:60
	v_add_u32_e32 v16, 0x6000, v136
	ds_write2_b32 v16, v12, v8 offset0:192 offset1:208
	v_add_u32_e32 v8, 0x6400, v136
	ds_write2_b32 v8, v13, v9 offset0:68 offset1:84
	ds_write2_b32 v8, v14, v10 offset0:200 offset1:216
	v_add_u32_e32 v9, 0x6800, v136
	ds_write2_b32 v9, v15, v11 offset0:76 offset1:92
	ds_write2_b32 v16, v4, v0 offset0:224 offset1:240
	ds_write2_b32 v8, v5, v1 offset0:100 offset1:116
	ds_write2_b32 v8, v6, v2 offset0:232 offset1:248
	ds_write2_b32 v9, v7, v3 offset0:108 offset1:124
	v_or_b32_e32 v0, s24, v137
	v_lshlrev_b32_e32 v72, 2, v0
	v_lshl_add_u64 v[0:1], s[12:13], 0, v[72:73]
	v_lshl_add_u64 v[2:3], s[10:11], 0, v[72:73]
	v_add_u32_e32 v4, s25, v149
	s_mov_b32 s14, 0
	s_waitcnt lgkmcnt(0)
	s_barrier

.LBB0_708:
	s_and_b32 s6, s11, 0x4000
	s_xor_b32 s7, s6, 0x4000
	s_lshl_b32 s7, s7, 1
	s_add_i32 s7, s7, 32
	s_add_u32 s90, s52, s4
	s_addc_u32 s91, s53, s5
	s_add_i32 m0, s7, s82
	s_lshl_b32 s6, s6, 1
	global_load_lds_dwordx4 v192, s[90:91]
	s_add_i32 m0, s7, s83
	s_add_i32 s6, s6, 32
	global_load_lds_dwordx4 v193, s[90:91]
	s_add_i32 m0, s7, s84
	v_lshlrev_b32_e32 v85, 1, v80
	global_load_lds_dwordx4 v194, s[90:91]
	s_add_i32 m0, s7, s85
	v_add3_u32 v112, s6, v81, v85
	global_load_lds_dwordx4 v195, s[90:91]
	s_add_i32 m0, s7, s86
	v_lshlrev_b32_e32 v86, 1, v121
	global_load_lds_dwordx4 v196, s[90:91]
	s_add_i32 m0, s7, s87
	v_add3_u32 v113, s6, v82, v85
	global_load_lds_dwordx4 v197, s[90:91]
	s_add_i32 m0, s7, s88
	v_add_u32_e32 v87, v112, v86
	global_load_lds_dwordx4 v198, s[90:91]
	s_add_i32 m0, s7, s89
	v_add_u32_e32 v123, v113, v86
	global_load_lds_dwordx4 v199, s[90:91]
	ds_read_b128 v[88:91], v87
	ds_read_b128 v[96:99], v123 offset:16384
	ds_read_b128 v[100:103], v123 offset:18432
	ds_read_b128 v[124:127], v123 offset:20480
	ds_read_b128 v[128:131], v123 offset:22528
	ds_read_b128 v[92:95], v87 offset:2048
	ds_read_b128 v[104:107], v87 offset:4096
	ds_read_b128 v[108:111], v87 offset:6144
	v_lshlrev_b32_e32 v87, 1, v122
	v_add_u32_e32 v236, v112, v87
	v_add_u32_e32 v112, v113, v87
	ds_read_b128 v[204:207], v236
	ds_read_b128 v[208:211], v112 offset:16384
	ds_read_b128 v[212:215], v112 offset:18432
	ds_read_b128 v[216:219], v112 offset:20480
	ds_read_b128 v[220:223], v112 offset:22528
	ds_read_b128 v[224:227], v236 offset:2048
	ds_read_b128 v[228:231], v236 offset:4096
	ds_read_b128 v[232:235], v236 offset:6144
	s_setprio 1
	s_waitcnt lgkmcnt(11)
	v_mfma_f32_16x16x32_bf16 v[60:63], v[88:91], v[96:99], v[60:63]
	v_mfma_f32_16x16x32_bf16 v[56:59], v[88:91], v[100:103], v[56:59]
	v_mfma_f32_16x16x32_bf16 v[52:55], v[88:91], v[124:127], v[52:55]
	v_mfma_f32_16x16x32_bf16 v[48:51], v[88:91], v[128:131], v[48:51]
	s_waitcnt lgkmcnt(10)
	v_mfma_f32_16x16x32_bf16 v[44:47], v[92:95], v[96:99], v[44:47]
	v_mfma_f32_16x16x32_bf16 v[40:43], v[92:95], v[100:103], v[40:43]
	v_mfma_f32_16x16x32_bf16 v[36:39], v[92:95], v[124:127], v[36:39]
	v_mfma_f32_16x16x32_bf16 v[32:35], v[92:95], v[128:131], v[32:35]
	s_waitcnt lgkmcnt(9)
	v_mfma_f32_16x16x32_bf16 v[28:31], v[104:107], v[96:99], v[28:31]
	v_mfma_f32_16x16x32_bf16 v[24:27], v[104:107], v[100:103], v[24:27]
	v_mfma_f32_16x16x32_bf16 v[20:23], v[104:107], v[124:127], v[20:23]
	v_mfma_f32_16x16x32_bf16 v[16:19], v[104:107], v[128:131], v[16:19]
	s_waitcnt lgkmcnt(8)
	v_mfma_f32_16x16x32_bf16 v[12:15], v[108:111], v[96:99], v[12:15]
	v_mfma_f32_16x16x32_bf16 v[8:11], v[108:111], v[100:103], v[8:11]
	v_mfma_f32_16x16x32_bf16 v[4:7], v[108:111], v[124:127], v[4:7]
	v_mfma_f32_16x16x32_bf16 v[0:3], v[108:111], v[128:131], v[0:3]
	s_waitcnt lgkmcnt(3)
	v_mfma_f32_16x16x32_bf16 v[60:63], v[204:207], v[208:211], v[60:63]
	v_mfma_f32_16x16x32_bf16 v[56:59], v[204:207], v[212:215], v[56:59]
	v_mfma_f32_16x16x32_bf16 v[52:55], v[204:207], v[216:219], v[52:55]
	v_mfma_f32_16x16x32_bf16 v[48:51], v[204:207], v[220:223], v[48:51]
	s_waitcnt lgkmcnt(2)
	v_mfma_f32_16x16x32_bf16 v[44:47], v[224:227], v[208:211], v[44:47]
	v_mfma_f32_16x16x32_bf16 v[40:43], v[224:227], v[212:215], v[40:43]
	v_mfma_f32_16x16x32_bf16 v[36:39], v[224:227], v[216:219], v[36:39]
	v_mfma_f32_16x16x32_bf16 v[32:35], v[224:227], v[220:223], v[32:35]
	s_waitcnt lgkmcnt(1)
	v_mfma_f32_16x16x32_bf16 v[28:31], v[228:231], v[208:211], v[28:31]
	v_mfma_f32_16x16x32_bf16 v[24:27], v[228:231], v[212:215], v[24:27]
	v_mfma_f32_16x16x32_bf16 v[20:23], v[228:231], v[216:219], v[20:23]
	v_mfma_f32_16x16x32_bf16 v[16:19], v[228:231], v[220:223], v[16:19]
	s_waitcnt lgkmcnt(0)
	v_mfma_f32_16x16x32_bf16 v[12:15], v[232:235], v[208:211], v[12:15]
	v_mfma_f32_16x16x32_bf16 v[8:11], v[232:235], v[212:215], v[8:11]
	v_mfma_f32_16x16x32_bf16 v[4:7], v[232:235], v[216:219], v[4:7]
	v_mfma_f32_16x16x32_bf16 v[0:3], v[232:235], v[220:223], v[0:3]
	s_setprio 0
	s_add_u32 s4, s4, 0x80
	s_addc_u32 s5, s5, 0
	s_addk_i32 s11, 0x4000
	s_cmpk_eq_i32 s4, 0x780
	s_waitcnt vmcnt(0)
	s_barrier
	s_cbranch_scc0 .LBB0_708
	v_add3_u32 v84, 32, v81, v85
	v_add3_u32 v85, 32, v82, v85
	v_add_u32_e32 v88, v84, v86
	v_add_u32_e32 v86, v85, v86
	ds_read_b128 v[64:67], v88 offset:32768
	ds_read_b128 v[68:71], v88 offset:34816
	ds_read_b128 v[72:75], v86 offset:49152
	ds_read_b128 v[76:79], v86 offset:51200
	ds_read_b128 v[80:83], v88 offset:36864
	ds_read_b128 v[88:91], v88 offset:38912
	ds_read_b128 v[92:95], v86 offset:53248
	ds_read_b128 v[96:99], v86 offset:55296
	v_add_u32_e32 v84, v84, v87
	v_add_u32_e32 v236, v85, v87
	ds_read_b128 v[204:207], v84 offset:32768
	ds_read_b128 v[208:211], v84 offset:34816
	ds_read_b128 v[212:215], v236 offset:49152
	ds_read_b128 v[216:219], v236 offset:51200
	ds_read_b128 v[220:223], v84 offset:36864
	ds_read_b128 v[224:227], v84 offset:38912
	ds_read_b128 v[228:231], v236 offset:53248
	ds_read_b128 v[232:235], v236 offset:55296
	s_setprio 1
	s_waitcnt lgkmcnt(8)
	v_mfma_f32_16x16x32_bf16 v[0:3], v[88:91], v[96:99], v[0:3]
	v_mfma_f32_16x16x32_bf16 v[60:63], v[64:67], v[72:75], v[60:63]
	v_mfma_f32_16x16x32_bf16 v[56:59], v[64:67], v[76:79], v[56:59]
	v_mfma_f32_16x16x32_bf16 v[52:55], v[64:67], v[92:95], v[52:55]
	v_mfma_f32_16x16x32_bf16 v[48:51], v[64:67], v[96:99], v[48:51]
	v_mfma_f32_16x16x32_bf16 v[44:47], v[68:71], v[72:75], v[44:47]
	v_mfma_f32_16x16x32_bf16 v[40:43], v[68:71], v[76:79], v[40:43]
	v_mfma_f32_16x16x32_bf16 v[36:39], v[68:71], v[92:95], v[36:39]
	v_mfma_f32_16x16x32_bf16 v[32:35], v[68:71], v[96:99], v[32:35]
	v_mfma_f32_16x16x32_bf16 v[28:31], v[80:83], v[72:75], v[28:31]
	v_mfma_f32_16x16x32_bf16 v[24:27], v[80:83], v[76:79], v[24:27]
	v_mfma_f32_16x16x32_bf16 v[20:23], v[80:83], v[92:95], v[20:23]
	v_mfma_f32_16x16x32_bf16 v[16:19], v[80:83], v[96:99], v[16:19]
	v_mfma_f32_16x16x32_bf16 v[12:15], v[88:91], v[72:75], v[12:15]
	v_mfma_f32_16x16x32_bf16 v[8:11], v[88:91], v[76:79], v[8:11]
	v_mfma_f32_16x16x32_bf16 v[4:7], v[88:91], v[92:95], v[4:7]
	s_waitcnt lgkmcnt(0)
	v_mfma_f32_16x16x32_bf16 v[0:3], v[224:227], v[232:235], v[0:3]
	v_mfma_f32_16x16x32_bf16 v[60:63], v[204:207], v[212:215], v[60:63]
	v_mfma_f32_16x16x32_bf16 v[56:59], v[204:207], v[216:219], v[56:59]
	v_mfma_f32_16x16x32_bf16 v[52:55], v[204:207], v[228:231], v[52:55]
	v_mfma_f32_16x16x32_bf16 v[48:51], v[204:207], v[232:235], v[48:51]
	v_mfma_f32_16x16x32_bf16 v[44:47], v[208:211], v[212:215], v[44:47]
	v_mfma_f32_16x16x32_bf16 v[40:43], v[208:211], v[216:219], v[40:43]
	v_mfma_f32_16x16x32_bf16 v[36:39], v[208:211], v[228:231], v[36:39]
	v_mfma_f32_16x16x32_bf16 v[32:35], v[208:211], v[232:235], v[32:35]
	v_mfma_f32_16x16x32_bf16 v[28:31], v[220:223], v[212:215], v[28:31]
	v_mfma_f32_16x16x32_bf16 v[24:27], v[220:223], v[216:219], v[24:27]
	v_mfma_f32_16x16x32_bf16 v[20:23], v[220:223], v[228:231], v[20:23]
	v_mfma_f32_16x16x32_bf16 v[16:19], v[220:223], v[232:235], v[16:19]
	v_mfma_f32_16x16x32_bf16 v[12:15], v[224:227], v[212:215], v[12:15]
	v_mfma_f32_16x16x32_bf16 v[8:11], v[224:227], v[216:219], v[8:11]
	v_mfma_f32_16x16x32_bf16 v[4:7], v[224:227], v[228:231], v[4:7]
	s_setprio 0
	v_lshl_or_b32 v64, v114, 2, v116
	v_mul_u32_u24_e32 v64, 0x210, v64
	v_add3_u32 v64, v115, v117, v64
	s_barrier
	ds_write2_b32 v64, v60, v56 offset1:16
	ds_write2_b32 v64, v61, v57 offset0:132 offset1:148
	v_add_u32_e32 v56, 0x400, v64
	ds_write2_b32 v56, v62, v58 offset0:8 offset1:24
	ds_write2_b32 v56, v63, v59 offset0:140 offset1:156
	ds_write2_b32 v64, v52, v48 offset0:32 offset1:48
	ds_write2_b32 v64, v53, v49 offset0:164 offset1:180
	ds_write2_b32 v56, v54, v50 offset0:40 offset1:56
	ds_write2_b32 v56, v55, v51 offset0:172 offset1:188
	v_add_u32_e32 v48, 0x2000, v64
	ds_write2_b32 v48, v44, v40 offset0:64 offset1:80
	ds_write2_b32 v48, v45, v41 offset0:196 offset1:212
	v_add_u32_e32 v40, 0x2400, v64
	ds_write2_b32 v40, v46, v42 offset0:72 offset1:88
	ds_write2_b32 v40, v47, v43 offset0:204 offset1:220
	ds_write2_b32 v48, v36, v32 offset0:96 offset1:112
	ds_write2_b32 v48, v37, v33 offset0:228 offset1:244
	ds_write2_b32 v40, v38, v34 offset0:104 offset1:120
	ds_write2_b32 v40, v39, v35 offset0:236 offset1:252
	v_add_u32_e32 v32, 0x4000, v64
	ds_write2_b32 v32, v28, v24 offset0:128 offset1:144
	v_add_u32_e32 v24, 0x4400, v64
	ds_write2_b32 v24, v29, v25 offset0:4 offset1:20
	ds_write2_b32 v24, v30, v26 offset0:136 offset1:152
	v_add_u32_e32 v25, 0x4800, v64
	ds_write2_b32 v25, v31, v27 offset0:12 offset1:28
	ds_write2_b32 v32, v20, v16 offset0:160 offset1:176
	ds_write2_b32 v24, v21, v17 offset0:36 offset1:52
	ds_write2_b32 v24, v22, v18 offset0:168 offset1:184
	ds_write2_b32 v25, v23, v19 offset0:44 offset1:60
	v_add_u32_e32 v16, 0x6000, v64
	ds_write2_b32 v16, v12, v8 offset0:192 offset1:208
	v_add_u32_e32 v8, 0x6400, v64
	ds_write2_b32 v8, v13, v9 offset0:68 offset1:84
	ds_write2_b32 v8, v14, v10 offset0:200 offset1:216
	v_add_u32_e32 v9, 0x6800, v64
	ds_write2_b32 v9, v15, v11 offset0:76 offset1:92
	ds_write2_b32 v16, v4, v0 offset0:224 offset1:240
	ds_write2_b32 v8, v5, v1 offset0:100 offset1:116
	ds_write2_b32 v8, v6, v2 offset0:232 offset1:248
	ds_write2_b32 v9, v7, v3 offset0:108 offset1:124
	v_lshlrev_b32_e32 v0, 4, v180
	v_and_b32_e32 v0, 0x70, v0
	s_lshl_b32 s5, s14, 23
	v_or_b32_e32 v0, s9, v0
	s_add_u32 s6, s12, s5
	s_addc_u32 s7, s13, 0
	v_lshlrev_b32_e32 v0, 2, v0
	v_mov_b32_e32 v1, 0
	v_lshrrev_b32_e32 v2, 3, v180
	v_and_b32_e32 v4, 7, v180
	v_lshl_add_u64 v[0:1], s[6:7], 0, v[0:1]
	s_mov_b64 s[6:7], 0x11600000
	v_mul_u32_u24_e32 v3, 0x210, v2
	v_lshlrev_b32_e32 v4, 6, v4
	s_mov_b32 s4, 0
	v_lshl_add_u64 v[0:1], v[0:1], 0, s[6:7]
	v_add3_u32 v3, v3, v4, 32
	s_mov_b32 s5, 0x38e38e39
	s_mov_b32 s6, 0x1ffffee
	s_movk_i32 s7, 0xf800
	s_waitcnt lgkmcnt(0)
	s_barrier

.LBB0_1814:
	s_and_b32 s27, s26, 0x4000
	s_xor_b32 s28, s27, 0x4000
	s_lshl_b32 s28, s28, 1
	s_add_i32 s28, s28, 32
	s_add_u32 s90, s52, s16
	s_addc_u32 s91, s53, s17
	s_add_i32 m0, s28, s82
	s_lshl_b32 s27, s27, 1
	global_load_lds_dwordx4 v188, s[90:91]
	s_add_i32 m0, s28, s83
	s_add_i32 s27, s27, 32
	global_load_lds_dwordx4 v189, s[90:91]
	s_add_i32 m0, s28, s84
	v_add3_u32 v170, s27, v114, v135
	global_load_lds_dwordx4 v190, s[90:91]
	s_add_i32 m0, s28, s85
	v_add3_u32 v171, s27, v115, v135
	global_load_lds_dwordx4 v191, s[90:91]
	s_add_i32 m0, s28, s86
	v_add_u32_e32 v158, v170, v136
	global_load_lds_dwordx4 v192, s[90:91]
	s_add_i32 m0, s28, s87
	v_add_u32_e32 v166, v171, v136
	global_load_lds_dwordx4 v193, s[90:91]
	s_add_i32 m0, s28, s88
	s_addk_i32 s26, 0x4000
	global_load_lds_dwordx4 v194, s[90:91]
	s_add_i32 m0, s28, s89
	s_add_u32 s16, s16, 0x80
	s_addc_u32 s17, s17, 0
	global_load_lds_dwordx4 v195, s[90:91]
	ds_read_b128 v[138:141], v158
	ds_read_b128 v[146:149], v166 offset:16384
	ds_read_b128 v[150:153], v166 offset:18432
	ds_read_b128 v[162:165], v166 offset:20480
	ds_read_b128 v[166:169], v166 offset:22528
	ds_read_b128 v[142:145], v158 offset:2048
	ds_read_b128 v[154:157], v158 offset:4096
	ds_read_b128 v[158:161], v158 offset:6144
	v_add_u32_e32 v236, v170, v137
	v_add_u32_e32 v237, v171, v137
	ds_read_b128 v[204:207], v236
	ds_read_b128 v[208:211], v237 offset:16384
	ds_read_b128 v[212:215], v237 offset:18432
	ds_read_b128 v[216:219], v237 offset:20480
	ds_read_b128 v[220:223], v237 offset:22528
	ds_read_b128 v[224:227], v236 offset:2048
	ds_read_b128 v[228:231], v236 offset:4096
	ds_read_b128 v[232:235], v236 offset:6144
	s_setprio 1
	s_waitcnt lgkmcnt(11)
	v_mfma_f32_16x16x32_bf16 v[60:63], v[138:141], v[146:149], v[60:63]
	v_mfma_f32_16x16x32_bf16 v[56:59], v[138:141], v[150:153], v[56:59]
	v_mfma_f32_16x16x32_bf16 v[52:55], v[138:141], v[162:165], v[52:55]
	v_mfma_f32_16x16x32_bf16 v[48:51], v[138:141], v[166:169], v[48:51]
	s_waitcnt lgkmcnt(10)
	v_mfma_f32_16x16x32_bf16 v[44:47], v[142:145], v[146:149], v[44:47]
	v_mfma_f32_16x16x32_bf16 v[40:43], v[142:145], v[150:153], v[40:43]
	v_mfma_f32_16x16x32_bf16 v[36:39], v[142:145], v[162:165], v[36:39]
	v_mfma_f32_16x16x32_bf16 v[32:35], v[142:145], v[166:169], v[32:35]
	s_waitcnt lgkmcnt(9)
	v_mfma_f32_16x16x32_bf16 v[28:31], v[154:157], v[146:149], v[28:31]
	v_mfma_f32_16x16x32_bf16 v[24:27], v[154:157], v[150:153], v[24:27]
	v_mfma_f32_16x16x32_bf16 v[20:23], v[154:157], v[162:165], v[20:23]
	v_mfma_f32_16x16x32_bf16 v[16:19], v[154:157], v[166:169], v[16:19]
	s_waitcnt lgkmcnt(8)
	v_mfma_f32_16x16x32_bf16 v[12:15], v[158:161], v[146:149], v[12:15]
	v_mfma_f32_16x16x32_bf16 v[8:11], v[158:161], v[150:153], v[8:11]
	v_mfma_f32_16x16x32_bf16 v[4:7], v[158:161], v[162:165], v[4:7]
	v_mfma_f32_16x16x32_bf16 v[0:3], v[158:161], v[166:169], v[0:3]
	s_waitcnt lgkmcnt(3)
	v_mfma_f32_16x16x32_bf16 v[60:63], v[204:207], v[208:211], v[60:63]
	v_mfma_f32_16x16x32_bf16 v[56:59], v[204:207], v[212:215], v[56:59]
	v_mfma_f32_16x16x32_bf16 v[52:55], v[204:207], v[216:219], v[52:55]
	v_mfma_f32_16x16x32_bf16 v[48:51], v[204:207], v[220:223], v[48:51]
	s_waitcnt lgkmcnt(2)
	v_mfma_f32_16x16x32_bf16 v[44:47], v[224:227], v[208:211], v[44:47]
	v_mfma_f32_16x16x32_bf16 v[40:43], v[224:227], v[212:215], v[40:43]
	v_mfma_f32_16x16x32_bf16 v[36:39], v[224:227], v[216:219], v[36:39]
	v_mfma_f32_16x16x32_bf16 v[32:35], v[224:227], v[220:223], v[32:35]
	s_waitcnt lgkmcnt(1)
	v_mfma_f32_16x16x32_bf16 v[28:31], v[228:231], v[208:211], v[28:31]
	v_mfma_f32_16x16x32_bf16 v[24:27], v[228:231], v[212:215], v[24:27]
	v_mfma_f32_16x16x32_bf16 v[20:23], v[228:231], v[216:219], v[20:23]
	v_mfma_f32_16x16x32_bf16 v[16:19], v[228:231], v[220:223], v[16:19]
	s_waitcnt lgkmcnt(0)
	v_mfma_f32_16x16x32_bf16 v[12:15], v[232:235], v[208:211], v[12:15]
	v_mfma_f32_16x16x32_bf16 v[8:11], v[232:235], v[212:215], v[8:11]
	v_mfma_f32_16x16x32_bf16 v[4:7], v[232:235], v[216:219], v[4:7]
	v_mfma_f32_16x16x32_bf16 v[0:3], v[232:235], v[220:223], v[0:3]
	s_setprio 0
	s_cmpk_eq_i32 s16, 0x780
	s_waitcnt vmcnt(0)
	s_barrier
	s_cbranch_scc0 .LBB0_1814
	ds_read_b128 v[90:93], v118 offset:55296
	ds_read_b128 v[94:97], v118 offset:53248
	ds_read_b128 v[98:101], v119 offset:38912
	ds_read_b128 v[102:105], v119 offset:36864
	ds_read_b128 v[138:141], v118 offset:51200
	ds_read_b128 v[142:145], v118 offset:49152
	ds_read_b128 v[146:149], v119 offset:34816
	ds_read_b128 v[150:153], v119 offset:32768
	ds_read_b128 v[204:207], v120 offset:32768
	ds_read_b128 v[208:211], v120 offset:34816
	ds_read_b128 v[212:215], v121 offset:49152
	ds_read_b128 v[216:219], v121 offset:51200
	ds_read_b128 v[220:223], v120 offset:36864
	ds_read_b128 v[224:227], v120 offset:38912
	ds_read_b128 v[228:231], v121 offset:53248
	ds_read_b128 v[232:235], v121 offset:55296
	s_setprio 1
	s_waitcnt lgkmcnt(13)
	v_mfma_f32_16x16x32_bf16 v[4:7], v[98:101], v[94:97], v[4:7]
	v_mfma_f32_16x16x32_bf16 v[0:3], v[98:101], v[90:93], v[0:3]
	s_waitcnt lgkmcnt(8)
	v_mfma_f32_16x16x32_bf16 v[60:63], v[150:153], v[142:145], v[60:63]
	v_mfma_f32_16x16x32_bf16 v[56:59], v[150:153], v[138:141], v[56:59]
	v_mfma_f32_16x16x32_bf16 v[52:55], v[150:153], v[94:97], v[52:55]
	v_mfma_f32_16x16x32_bf16 v[48:51], v[150:153], v[90:93], v[48:51]
	v_mfma_f32_16x16x32_bf16 v[44:47], v[146:149], v[142:145], v[44:47]
	v_mfma_f32_16x16x32_bf16 v[40:43], v[146:149], v[138:141], v[40:43]
	v_mfma_f32_16x16x32_bf16 v[36:39], v[146:149], v[94:97], v[36:39]
	v_mfma_f32_16x16x32_bf16 v[32:35], v[146:149], v[90:93], v[32:35]
	v_mfma_f32_16x16x32_bf16 v[28:31], v[102:105], v[142:145], v[28:31]
	v_mfma_f32_16x16x32_bf16 v[24:27], v[102:105], v[138:141], v[24:27]
	v_mfma_f32_16x16x32_bf16 v[20:23], v[102:105], v[94:97], v[20:23]
	v_mfma_f32_16x16x32_bf16 v[16:19], v[102:105], v[90:93], v[16:19]
	v_mfma_f32_16x16x32_bf16 v[12:15], v[98:101], v[142:145], v[12:15]
	v_mfma_f32_16x16x32_bf16 v[8:11], v[98:101], v[138:141], v[8:11]
	s_waitcnt lgkmcnt(1)
	v_mfma_f32_16x16x32_bf16 v[4:7], v[224:227], v[228:231], v[4:7]
	s_waitcnt lgkmcnt(0)
	v_mfma_f32_16x16x32_bf16 v[0:3], v[224:227], v[232:235], v[0:3]
	v_mfma_f32_16x16x32_bf16 v[60:63], v[204:207], v[212:215], v[60:63]
	v_mfma_f32_16x16x32_bf16 v[56:59], v[204:207], v[216:219], v[56:59]
	v_mfma_f32_16x16x32_bf16 v[52:55], v[204:207], v[228:231], v[52:55]
	v_mfma_f32_16x16x32_bf16 v[48:51], v[204:207], v[232:235], v[48:51]
	v_mfma_f32_16x16x32_bf16 v[44:47], v[208:211], v[212:215], v[44:47]
	v_mfma_f32_16x16x32_bf16 v[40:43], v[208:211], v[216:219], v[40:43]
	v_mfma_f32_16x16x32_bf16 v[36:39], v[208:211], v[228:231], v[36:39]
	v_mfma_f32_16x16x32_bf16 v[32:35], v[208:211], v[232:235], v[32:35]
	v_mfma_f32_16x16x32_bf16 v[28:31], v[220:223], v[212:215], v[28:31]
	v_mfma_f32_16x16x32_bf16 v[24:27], v[220:223], v[216:219], v[24:27]
	v_mfma_f32_16x16x32_bf16 v[20:23], v[220:223], v[228:231], v[20:23]
	v_mfma_f32_16x16x32_bf16 v[16:19], v[220:223], v[232:235], v[16:19]
	v_mfma_f32_16x16x32_bf16 v[12:15], v[224:227], v[212:215], v[12:15]
	v_mfma_f32_16x16x32_bf16 v[8:11], v[224:227], v[216:219], v[8:11]
	s_setprio 0
	s_barrier
	ds_write2_b32 v116, v60, v56 offset1:16
	ds_write2_b32 v116, v61, v57 offset0:132 offset1:148
	v_add_u32_e32 v56, 0x400, v116
	ds_write2_b32 v56, v62, v58 offset0:8 offset1:24
	ds_write2_b32 v56, v63, v59 offset0:140 offset1:156
	ds_write2_b32 v116, v52, v48 offset0:32 offset1:48
	ds_write2_b32 v116, v53, v49 offset0:164 offset1:180
	ds_write2_b32 v56, v54, v50 offset0:40 offset1:56
	ds_write2_b32 v56, v55, v51 offset0:172 offset1:188
	v_add_u32_e32 v48, 0x2000, v116
	ds_write2_b32 v48, v44, v40 offset0:64 offset1:80
	ds_write2_b32 v48, v45, v41 offset0:196 offset1:212
	v_add_u32_e32 v40, 0x2400, v116
	ds_write2_b32 v40, v46, v42 offset0:72 offset1:88
	ds_write2_b32 v40, v47, v43 offset0:204 offset1:220
	ds_write2_b32 v48, v36, v32 offset0:96 offset1:112
	ds_write2_b32 v48, v37, v33 offset0:228 offset1:244
	ds_write2_b32 v40, v38, v34 offset0:104 offset1:120
	ds_write2_b32 v40, v39, v35 offset0:236 offset1:252
	v_add_u32_e32 v32, 0x4000, v116
	ds_write2_b32 v32, v28, v24 offset0:128 offset1:144
	v_add_u32_e32 v24, 0x4400, v116
	ds_write2_b32 v24, v29, v25 offset0:4 offset1:20
	ds_write2_b32 v24, v30, v26 offset0:136 offset1:152
	v_add_u32_e32 v25, 0x4800, v116
	ds_write2_b32 v25, v31, v27 offset0:12 offset1:28
	ds_write2_b32 v32, v20, v16 offset0:160 offset1:176
	ds_write2_b32 v24, v21, v17 offset0:36 offset1:52
	ds_write2_b32 v24, v22, v18 offset0:168 offset1:184
	ds_write2_b32 v25, v23, v19 offset0:44 offset1:60
	v_add_u32_e32 v16, 0x6000, v116
	ds_write2_b32 v16, v12, v8 offset0:192 offset1:208
	v_add_u32_e32 v8, 0x6400, v116
	ds_write2_b32 v8, v13, v9 offset0:68 offset1:84
	ds_write2_b32 v8, v14, v10 offset0:200 offset1:216
	v_add_u32_e32 v9, 0x6800, v116
	ds_write2_b32 v9, v15, v11 offset0:76 offset1:92
	ds_write2_b32 v16, v4, v0 offset0:224 offset1:240
	ds_write2_b32 v8, v5, v1 offset0:100 offset1:116
	ds_write2_b32 v8, v6, v2 offset0:232 offset1:248
	ds_write2_b32 v9, v7, v3 offset0:108 offset1:124
	v_or_b32_e32 v0, s25, v117
	v_ashrrev_i32_e32 v1, 31, v0
	v_lshlrev_b64 v[2:3], 2, v[0:1]
	v_lshl_add_u64 v[0:1], s[14:15], 0, v[2:3]
	v_lshl_add_u64 v[2:3], s[10:11], 0, v[2:3]
	v_add_u32_e32 v4, s24, v128
	s_mov_b32 s16, 0
	s_waitcnt lgkmcnt(0)
	s_barrier

.LBB0_1823:
	s_and_b32 s28, s27, 0x4000
	s_xor_b32 s29, s28, 0x4000
	s_lshl_b32 s29, s29, 1
	s_add_i32 s29, s29, 32
	s_add_u32 s90, s52, s16
	s_addc_u32 s91, s53, s17
	s_add_i32 m0, s29, s82
	s_lshl_b32 s28, s28, 1
	global_load_lds_dwordx4 v188, s[90:91]
	s_add_i32 m0, s29, s83
	s_add_i32 s28, s28, 32
	global_load_lds_dwordx4 v189, s[90:91]
	s_add_i32 m0, s29, s84
	v_add3_u32 v139, s28, v113, v136
	global_load_lds_dwordx4 v190, s[90:91]
	s_add_i32 m0, s29, s85
	v_add3_u32 v172, s28, v114, v136
	global_load_lds_dwordx4 v191, s[90:91]
	s_add_i32 m0, s29, s86
	v_add_u32_e32 v160, v139, v137
	global_load_lds_dwordx4 v192, s[90:91]
	s_add_i32 m0, s29, s87
	v_add_u32_e32 v168, v172, v137
	global_load_lds_dwordx4 v193, s[90:91]
	s_add_i32 m0, s29, s88
	s_addk_i32 s27, 0x4000
	global_load_lds_dwordx4 v194, s[90:91]
	s_add_i32 m0, s29, s89
	s_add_u32 s16, s16, 0x80
	s_addc_u32 s17, s17, 0
	global_load_lds_dwordx4 v195, s[90:91]
	ds_read_b128 v[140:143], v160
	ds_read_b128 v[148:151], v168 offset:16384
	ds_read_b128 v[152:155], v168 offset:18432
	ds_read_b128 v[164:167], v168 offset:20480
	ds_read_b128 v[168:171], v168 offset:22528
	ds_read_b128 v[144:147], v160 offset:2048
	ds_read_b128 v[156:159], v160 offset:4096
	ds_read_b128 v[160:163], v160 offset:6144
	v_add_u32_e32 v139, v139, v138
	v_add_u32_e32 v236, v172, v138
	ds_read_b128 v[204:207], v139
	ds_read_b128 v[208:211], v236 offset:16384
	ds_read_b128 v[212:215], v236 offset:18432
	ds_read_b128 v[216:219], v236 offset:20480
	ds_read_b128 v[220:223], v236 offset:22528
	ds_read_b128 v[224:227], v139 offset:2048
	ds_read_b128 v[228:231], v139 offset:4096
	ds_read_b128 v[232:235], v139 offset:6144
	s_setprio 1
	s_waitcnt lgkmcnt(11)
	v_mfma_f32_16x16x32_bf16 v[60:63], v[140:143], v[148:151], v[60:63]
	v_mfma_f32_16x16x32_bf16 v[56:59], v[140:143], v[152:155], v[56:59]
	v_mfma_f32_16x16x32_bf16 v[52:55], v[140:143], v[164:167], v[52:55]
	v_mfma_f32_16x16x32_bf16 v[48:51], v[140:143], v[168:171], v[48:51]
	s_waitcnt lgkmcnt(10)
	v_mfma_f32_16x16x32_bf16 v[44:47], v[144:147], v[148:151], v[44:47]
	v_mfma_f32_16x16x32_bf16 v[40:43], v[144:147], v[152:155], v[40:43]
	v_mfma_f32_16x16x32_bf16 v[36:39], v[144:147], v[164:167], v[36:39]
	v_mfma_f32_16x16x32_bf16 v[32:35], v[144:147], v[168:171], v[32:35]
	s_waitcnt lgkmcnt(9)
	v_mfma_f32_16x16x32_bf16 v[28:31], v[156:159], v[148:151], v[28:31]
	v_mfma_f32_16x16x32_bf16 v[24:27], v[156:159], v[152:155], v[24:27]
	v_mfma_f32_16x16x32_bf16 v[20:23], v[156:159], v[164:167], v[20:23]
	v_mfma_f32_16x16x32_bf16 v[16:19], v[156:159], v[168:171], v[16:19]
	s_waitcnt lgkmcnt(8)
	v_mfma_f32_16x16x32_bf16 v[12:15], v[160:163], v[148:151], v[12:15]
	v_mfma_f32_16x16x32_bf16 v[8:11], v[160:163], v[152:155], v[8:11]
	v_mfma_f32_16x16x32_bf16 v[4:7], v[160:163], v[164:167], v[4:7]
	v_mfma_f32_16x16x32_bf16 v[0:3], v[160:163], v[168:171], v[0:3]
	s_waitcnt lgkmcnt(3)
	v_mfma_f32_16x16x32_bf16 v[60:63], v[204:207], v[208:211], v[60:63]
	v_mfma_f32_16x16x32_bf16 v[56:59], v[204:207], v[212:215], v[56:59]
	v_mfma_f32_16x16x32_bf16 v[52:55], v[204:207], v[216:219], v[52:55]
	v_mfma_f32_16x16x32_bf16 v[48:51], v[204:207], v[220:223], v[48:51]
	s_waitcnt lgkmcnt(2)
	v_mfma_f32_16x16x32_bf16 v[44:47], v[224:227], v[208:211], v[44:47]
	v_mfma_f32_16x16x32_bf16 v[40:43], v[224:227], v[212:215], v[40:43]
	v_mfma_f32_16x16x32_bf16 v[36:39], v[224:227], v[216:219], v[36:39]
	v_mfma_f32_16x16x32_bf16 v[32:35], v[224:227], v[220:223], v[32:35]
	s_waitcnt lgkmcnt(1)
	v_mfma_f32_16x16x32_bf16 v[28:31], v[228:231], v[208:211], v[28:31]
	v_mfma_f32_16x16x32_bf16 v[24:27], v[228:231], v[212:215], v[24:27]
	v_mfma_f32_16x16x32_bf16 v[20:23], v[228:231], v[216:219], v[20:23]
	v_mfma_f32_16x16x32_bf16 v[16:19], v[228:231], v[220:223], v[16:19]
	s_waitcnt lgkmcnt(0)
	v_mfma_f32_16x16x32_bf16 v[12:15], v[232:235], v[208:211], v[12:15]
	v_mfma_f32_16x16x32_bf16 v[8:11], v[232:235], v[212:215], v[8:11]
	v_mfma_f32_16x16x32_bf16 v[4:7], v[232:235], v[216:219], v[4:7]
	v_mfma_f32_16x16x32_bf16 v[0:3], v[232:235], v[220:223], v[0:3]
	s_setprio 0
	s_cmpk_eq_i32 s16, 0x780
	s_waitcnt vmcnt(0)
	s_barrier
	s_cbranch_scc0 .LBB0_1823
	ds_read_b128 v[88:91], v117 offset:55296
	ds_read_b128 v[92:95], v117 offset:53248
	ds_read_b128 v[96:99], v118 offset:38912
	ds_read_b128 v[100:103], v118 offset:36864
	ds_read_b128 v[140:143], v117 offset:51200
	ds_read_b128 v[144:147], v117 offset:49152
	ds_read_b128 v[148:151], v118 offset:34816
	ds_read_b128 v[152:155], v118 offset:32768
	ds_read_b128 v[204:207], v119 offset:32768
	ds_read_b128 v[208:211], v119 offset:34816
	ds_read_b128 v[212:215], v120 offset:49152
	ds_read_b128 v[216:219], v120 offset:51200
	ds_read_b128 v[220:223], v119 offset:36864
	ds_read_b128 v[224:227], v119 offset:38912
	ds_read_b128 v[228:231], v120 offset:53248
	ds_read_b128 v[232:235], v120 offset:55296
	s_setprio 1
	s_waitcnt lgkmcnt(13)
	v_mfma_f32_16x16x32_bf16 v[4:7], v[96:99], v[92:95], v[4:7]
	v_mfma_f32_16x16x32_bf16 v[0:3], v[96:99], v[88:91], v[0:3]
	s_waitcnt lgkmcnt(8)
	v_mfma_f32_16x16x32_bf16 v[60:63], v[152:155], v[144:147], v[60:63]
	v_mfma_f32_16x16x32_bf16 v[56:59], v[152:155], v[140:143], v[56:59]
	v_mfma_f32_16x16x32_bf16 v[52:55], v[152:155], v[92:95], v[52:55]
	v_mfma_f32_16x16x32_bf16 v[48:51], v[152:155], v[88:91], v[48:51]
	v_mfma_f32_16x16x32_bf16 v[44:47], v[148:151], v[144:147], v[44:47]
	v_mfma_f32_16x16x32_bf16 v[40:43], v[148:151], v[140:143], v[40:43]
	v_mfma_f32_16x16x32_bf16 v[36:39], v[148:151], v[92:95], v[36:39]
	v_mfma_f32_16x16x32_bf16 v[32:35], v[148:151], v[88:91], v[32:35]
	v_mfma_f32_16x16x32_bf16 v[28:31], v[100:103], v[144:147], v[28:31]
	v_mfma_f32_16x16x32_bf16 v[24:27], v[100:103], v[140:143], v[24:27]
	v_mfma_f32_16x16x32_bf16 v[20:23], v[100:103], v[92:95], v[20:23]
	v_mfma_f32_16x16x32_bf16 v[16:19], v[100:103], v[88:91], v[16:19]
	v_mfma_f32_16x16x32_bf16 v[12:15], v[96:99], v[144:147], v[12:15]
	v_mfma_f32_16x16x32_bf16 v[8:11], v[96:99], v[140:143], v[8:11]
	s_waitcnt lgkmcnt(1)
	v_mfma_f32_16x16x32_bf16 v[4:7], v[224:227], v[228:231], v[4:7]
	s_waitcnt lgkmcnt(0)
	v_mfma_f32_16x16x32_bf16 v[0:3], v[224:227], v[232:235], v[0:3]
	v_mfma_f32_16x16x32_bf16 v[60:63], v[204:207], v[212:215], v[60:63]
	v_mfma_f32_16x16x32_bf16 v[56:59], v[204:207], v[216:219], v[56:59]
	v_mfma_f32_16x16x32_bf16 v[52:55], v[204:207], v[228:231], v[52:55]
	v_mfma_f32_16x16x32_bf16 v[48:51], v[204:207], v[232:235], v[48:51]
	v_mfma_f32_16x16x32_bf16 v[44:47], v[208:211], v[212:215], v[44:47]
	v_mfma_f32_16x16x32_bf16 v[40:43], v[208:211], v[216:219], v[40:43]
	v_mfma_f32_16x16x32_bf16 v[36:39], v[208:211], v[228:231], v[36:39]
	v_mfma_f32_16x16x32_bf16 v[32:35], v[208:211], v[232:235], v[32:35]
	v_mfma_f32_16x16x32_bf16 v[28:31], v[220:223], v[212:215], v[28:31]
	v_mfma_f32_16x16x32_bf16 v[24:27], v[220:223], v[216:219], v[24:27]
	v_mfma_f32_16x16x32_bf16 v[20:23], v[220:223], v[228:231], v[20:23]
	v_mfma_f32_16x16x32_bf16 v[16:19], v[220:223], v[232:235], v[16:19]
	v_mfma_f32_16x16x32_bf16 v[12:15], v[224:227], v[212:215], v[12:15]
	v_mfma_f32_16x16x32_bf16 v[8:11], v[224:227], v[216:219], v[8:11]
	s_setprio 0
	s_barrier
	ds_write2_b32 v115, v60, v56 offset1:16
	ds_write2_b32 v115, v61, v57 offset0:132 offset1:148
	v_add_u32_e32 v56, 0x400, v115
	ds_write2_b32 v56, v62, v58 offset0:8 offset1:24
	ds_write2_b32 v56, v63, v59 offset0:140 offset1:156
	ds_write2_b32 v115, v52, v48 offset0:32 offset1:48
	ds_write2_b32 v115, v53, v49 offset0:164 offset1:180
	ds_write2_b32 v56, v54, v50 offset0:40 offset1:56
	ds_write2_b32 v56, v55, v51 offset0:172 offset1:188
	v_add_u32_e32 v48, 0x2000, v115
	ds_write2_b32 v48, v44, v40 offset0:64 offset1:80
	ds_write2_b32 v48, v45, v41 offset0:196 offset1:212
	v_add_u32_e32 v40, 0x2400, v115
	ds_write2_b32 v40, v46, v42 offset0:72 offset1:88
	ds_write2_b32 v40, v47, v43 offset0:204 offset1:220
	ds_write2_b32 v48, v36, v32 offset0:96 offset1:112
	ds_write2_b32 v48, v37, v33 offset0:228 offset1:244
	ds_write2_b32 v40, v38, v34 offset0:104 offset1:120
	ds_write2_b32 v40, v39, v35 offset0:236 offset1:252
	v_add_u32_e32 v32, 0x4000, v115
	ds_write2_b32 v32, v28, v24 offset0:128 offset1:144
	v_add_u32_e32 v24, 0x4400, v115
	ds_write2_b32 v24, v29, v25 offset0:4 offset1:20
	ds_write2_b32 v24, v30, v26 offset0:136 offset1:152
	v_add_u32_e32 v25, 0x4800, v115
	ds_write2_b32 v25, v31, v27 offset0:12 offset1:28
	ds_write2_b32 v32, v20, v16 offset0:160 offset1:176
	ds_write2_b32 v24, v21, v17 offset0:36 offset1:52
	ds_write2_b32 v24, v22, v18 offset0:168 offset1:184
	ds_write2_b32 v25, v23, v19 offset0:44 offset1:60
	v_add_u32_e32 v16, 0x6000, v115
	ds_write2_b32 v16, v12, v8 offset0:192 offset1:208
	v_add_u32_e32 v8, 0x6400, v115
	ds_write2_b32 v8, v13, v9 offset0:68 offset1:84
	ds_write2_b32 v8, v14, v10 offset0:200 offset1:216
	v_add_u32_e32 v9, 0x6800, v115
	ds_write2_b32 v9, v15, v11 offset0:76 offset1:92
	ds_write2_b32 v16, v4, v0 offset0:224 offset1:240
	ds_write2_b32 v8, v5, v1 offset0:100 offset1:116
	ds_write2_b32 v8, v6, v2 offset0:232 offset1:248
	ds_write2_b32 v9, v7, v3 offset0:108 offset1:124
	v_or_b32_e32 v0, s25, v116
	v_ashrrev_i32_e32 v1, 31, v0
	v_lshlrev_b64 v[2:3], 2, v[0:1]
	v_lshl_add_u64 v[0:1], s[14:15], 0, v[2:3]
	v_lshl_add_u64 v[2:3], s[10:11], 0, v[2:3]
	v_add_u32_e32 v4, s26, v129
	s_mov_b32 s16, 0
	s_waitcnt lgkmcnt(0)
	s_barrier

.LBB0_1834:
	s_and_b32 s27, s26, 0x4000
	s_xor_b32 s28, s27, 0x4000
	s_lshl_b32 s28, s28, 1
	s_add_i32 s28, s28, 32
	s_add_u32 s90, s52, s12
	s_addc_u32 s91, s53, s13
	s_add_i32 m0, s28, s82
	s_lshl_b32 s27, s27, 1
	global_load_lds_dwordx4 v189, s[90:91]
	s_add_i32 m0, s28, s83
	s_add_i32 s27, s27, 32
	global_load_lds_dwordx4 v190, s[90:91]
	s_add_i32 m0, s28, s84
	v_lshlrev_b32_e32 v70, 1, v129
	global_load_lds_dwordx4 v191, s[90:91]
	s_add_i32 m0, s28, s85
	v_add3_u32 v151, s27, v124, v70
	global_load_lds_dwordx4 v192, s[90:91]
	s_add_i32 m0, s28, s86
	v_add3_u32 v70, s27, v125, v70
	global_load_lds_dwordx4 v193, s[90:91]
	s_add_i32 m0, s28, s87
	v_lshlrev_b32_e32 v152, 1, v117
	global_load_lds_dwordx4 v194, s[90:91]
	s_add_i32 m0, s28, s88
	v_add_u32_e32 v172, v151, v152
	global_load_lds_dwordx4 v195, s[90:91]
	s_add_i32 m0, s28, s89
	v_add_u32_e32 v182, v70, v152
	global_load_lds_dwordx4 v196, s[90:91]
	ds_read_b128 v[152:155], v172
	ds_read_b128 v[160:163], v182 offset:16384
	ds_read_b128 v[164:167], v182 offset:18432
	ds_read_b128 v[176:179], v182 offset:20480
	ds_read_b128 v[182:185], v182 offset:22528
	ds_read_b128 v[156:159], v172 offset:2048
	ds_read_b128 v[168:171], v172 offset:4096
	ds_read_b128 v[172:175], v172 offset:6144
	v_lshlrev_b32_e32 v236, 1, v116
	v_add_u32_e32 v151, v151, v236
	v_add_u32_e32 v70, v70, v236
	ds_read_b128 v[204:207], v151
	ds_read_b128 v[208:211], v70 offset:16384
	ds_read_b128 v[212:215], v70 offset:18432
	ds_read_b128 v[216:219], v70 offset:20480
	ds_read_b128 v[220:223], v70 offset:22528
	ds_read_b128 v[224:227], v151 offset:2048
	ds_read_b128 v[228:231], v151 offset:4096
	ds_read_b128 v[232:235], v151 offset:6144
	s_setprio 1
	s_waitcnt lgkmcnt(11)
	v_mfma_f32_16x16x32_bf16 v[60:63], v[152:155], v[160:163], v[60:63]
	v_mfma_f32_16x16x32_bf16 v[56:59], v[152:155], v[164:167], v[56:59]
	v_mfma_f32_16x16x32_bf16 v[52:55], v[152:155], v[176:179], v[52:55]
	v_mfma_f32_16x16x32_bf16 v[48:51], v[152:155], v[182:185], v[48:51]
	s_waitcnt lgkmcnt(10)
	v_mfma_f32_16x16x32_bf16 v[44:47], v[156:159], v[160:163], v[44:47]
	v_mfma_f32_16x16x32_bf16 v[40:43], v[156:159], v[164:167], v[40:43]
	v_mfma_f32_16x16x32_bf16 v[36:39], v[156:159], v[176:179], v[36:39]
	v_mfma_f32_16x16x32_bf16 v[32:35], v[156:159], v[182:185], v[32:35]
	s_waitcnt lgkmcnt(9)
	v_mfma_f32_16x16x32_bf16 v[28:31], v[168:171], v[160:163], v[28:31]
	v_mfma_f32_16x16x32_bf16 v[24:27], v[168:171], v[164:167], v[24:27]
	v_mfma_f32_16x16x32_bf16 v[20:23], v[168:171], v[176:179], v[20:23]
	v_mfma_f32_16x16x32_bf16 v[16:19], v[168:171], v[182:185], v[16:19]
	s_waitcnt lgkmcnt(8)
	v_mfma_f32_16x16x32_bf16 v[12:15], v[172:175], v[160:163], v[12:15]
	v_mfma_f32_16x16x32_bf16 v[8:11], v[172:175], v[164:167], v[8:11]
	v_mfma_f32_16x16x32_bf16 v[4:7], v[172:175], v[176:179], v[4:7]
	v_mfma_f32_16x16x32_bf16 v[0:3], v[172:175], v[182:185], v[0:3]
	s_waitcnt lgkmcnt(3)
	v_mfma_f32_16x16x32_bf16 v[60:63], v[204:207], v[208:211], v[60:63]
	v_mfma_f32_16x16x32_bf16 v[56:59], v[204:207], v[212:215], v[56:59]
	v_mfma_f32_16x16x32_bf16 v[52:55], v[204:207], v[216:219], v[52:55]
	v_mfma_f32_16x16x32_bf16 v[48:51], v[204:207], v[220:223], v[48:51]
	s_waitcnt lgkmcnt(2)
	v_mfma_f32_16x16x32_bf16 v[44:47], v[224:227], v[208:211], v[44:47]
	v_mfma_f32_16x16x32_bf16 v[40:43], v[224:227], v[212:215], v[40:43]
	v_mfma_f32_16x16x32_bf16 v[36:39], v[224:227], v[216:219], v[36:39]
	v_mfma_f32_16x16x32_bf16 v[32:35], v[224:227], v[220:223], v[32:35]
	s_waitcnt lgkmcnt(1)
	v_mfma_f32_16x16x32_bf16 v[28:31], v[228:231], v[208:211], v[28:31]
	v_mfma_f32_16x16x32_bf16 v[24:27], v[228:231], v[212:215], v[24:27]
	v_mfma_f32_16x16x32_bf16 v[20:23], v[228:231], v[216:219], v[20:23]
	v_mfma_f32_16x16x32_bf16 v[16:19], v[228:231], v[220:223], v[16:19]
	s_waitcnt lgkmcnt(0)
	v_mfma_f32_16x16x32_bf16 v[12:15], v[232:235], v[208:211], v[12:15]
	v_mfma_f32_16x16x32_bf16 v[8:11], v[232:235], v[212:215], v[8:11]
	v_mfma_f32_16x16x32_bf16 v[4:7], v[232:235], v[216:219], v[4:7]
	v_mfma_f32_16x16x32_bf16 v[0:3], v[232:235], v[220:223], v[0:3]
	s_setprio 0
	s_add_u32 s12, s12, 0x80
	s_addc_u32 s13, s13, 0
	s_addk_i32 s26, 0x4000
	s_cmpk_eq_i32 s12, 0x780
	s_waitcnt vmcnt(0)
	s_barrier
	s_cbranch_scc0 .LBB0_1834
	ds_read_b128 v[96:99], v69 offset:32768
	ds_read_b128 v[100:103], v69 offset:34816
	ds_read_b128 v[104:107], v135 offset:49152
	ds_read_b128 v[108:111], v135 offset:51200
	ds_read_b128 v[152:155], v69 offset:36864
	ds_read_b128 v[156:159], v69 offset:38912
	ds_read_b128 v[160:163], v135 offset:53248
	ds_read_b128 v[164:167], v135 offset:55296
	ds_read_b128 v[204:207], v136 offset:32768
	ds_read_b128 v[208:211], v136 offset:34816
	ds_read_b128 v[212:215], v137 offset:49152
	ds_read_b128 v[216:219], v137 offset:51200
	ds_read_b128 v[220:223], v136 offset:36864
	ds_read_b128 v[224:227], v136 offset:38912
	ds_read_b128 v[228:231], v137 offset:53248
	ds_read_b128 v[232:235], v137 offset:55296
	s_setprio 1
	s_waitcnt lgkmcnt(9)
	v_mfma_f32_16x16x32_bf16 v[4:7], v[156:159], v[160:163], v[4:7]
	s_waitcnt lgkmcnt(8)
	v_mfma_f32_16x16x32_bf16 v[0:3], v[156:159], v[164:167], v[0:3]
	v_mfma_f32_16x16x32_bf16 v[60:63], v[96:99], v[104:107], v[60:63]
	v_mfma_f32_16x16x32_bf16 v[56:59], v[96:99], v[108:111], v[56:59]
	v_mfma_f32_16x16x32_bf16 v[52:55], v[96:99], v[160:163], v[52:55]
	v_mfma_f32_16x16x32_bf16 v[48:51], v[96:99], v[164:167], v[48:51]
	v_mfma_f32_16x16x32_bf16 v[44:47], v[100:103], v[104:107], v[44:47]
	v_mfma_f32_16x16x32_bf16 v[40:43], v[100:103], v[108:111], v[40:43]
	v_mfma_f32_16x16x32_bf16 v[36:39], v[100:103], v[160:163], v[36:39]
	v_mfma_f32_16x16x32_bf16 v[32:35], v[100:103], v[164:167], v[32:35]
	v_mfma_f32_16x16x32_bf16 v[28:31], v[152:155], v[104:107], v[28:31]
	v_mfma_f32_16x16x32_bf16 v[24:27], v[152:155], v[108:111], v[24:27]
	v_mfma_f32_16x16x32_bf16 v[20:23], v[152:155], v[160:163], v[20:23]
	v_mfma_f32_16x16x32_bf16 v[16:19], v[152:155], v[164:167], v[16:19]
	v_mfma_f32_16x16x32_bf16 v[12:15], v[156:159], v[104:107], v[12:15]
	v_mfma_f32_16x16x32_bf16 v[8:11], v[156:159], v[108:111], v[8:11]
	s_waitcnt lgkmcnt(1)
	v_mfma_f32_16x16x32_bf16 v[4:7], v[224:227], v[228:231], v[4:7]
	s_waitcnt lgkmcnt(0)
	v_mfma_f32_16x16x32_bf16 v[0:3], v[224:227], v[232:235], v[0:3]
	v_mfma_f32_16x16x32_bf16 v[60:63], v[204:207], v[212:215], v[60:63]
	v_mfma_f32_16x16x32_bf16 v[56:59], v[204:207], v[216:219], v[56:59]
	v_mfma_f32_16x16x32_bf16 v[52:55], v[204:207], v[228:231], v[52:55]
	v_mfma_f32_16x16x32_bf16 v[48:51], v[204:207], v[232:235], v[48:51]
	v_mfma_f32_16x16x32_bf16 v[44:47], v[208:211], v[212:215], v[44:47]
	v_mfma_f32_16x16x32_bf16 v[40:43], v[208:211], v[216:219], v[40:43]
	v_mfma_f32_16x16x32_bf16 v[36:39], v[208:211], v[228:231], v[36:39]
	v_mfma_f32_16x16x32_bf16 v[32:35], v[208:211], v[232:235], v[32:35]
	v_mfma_f32_16x16x32_bf16 v[28:31], v[220:223], v[212:215], v[28:31]
	v_mfma_f32_16x16x32_bf16 v[24:27], v[220:223], v[216:219], v[24:27]
	v_mfma_f32_16x16x32_bf16 v[20:23], v[220:223], v[228:231], v[20:23]
	v_mfma_f32_16x16x32_bf16 v[16:19], v[220:223], v[232:235], v[16:19]
	v_mfma_f32_16x16x32_bf16 v[12:15], v[224:227], v[212:215], v[12:15]
	v_mfma_f32_16x16x32_bf16 v[8:11], v[224:227], v[216:219], v[8:11]
	s_setprio 0
	s_barrier
	ds_write2_b32 v134, v60, v56 offset1:16
	ds_write2_b32 v134, v61, v57 offset0:132 offset1:148
	v_add_u32_e32 v56, 0x400, v134
	ds_write2_b32 v56, v62, v58 offset0:8 offset1:24
	ds_write2_b32 v56, v63, v59 offset0:140 offset1:156
	ds_write2_b32 v134, v52, v48 offset0:32 offset1:48
	ds_write2_b32 v134, v53, v49 offset0:164 offset1:180
	ds_write2_b32 v56, v54, v50 offset0:40 offset1:56
	ds_write2_b32 v56, v55, v51 offset0:172 offset1:188
	v_add_u32_e32 v48, 0x2000, v134
	ds_write2_b32 v48, v44, v40 offset0:64 offset1:80
	ds_write2_b32 v48, v45, v41 offset0:196 offset1:212
	v_add_u32_e32 v40, 0x2400, v134
	ds_write2_b32 v40, v46, v42 offset0:72 offset1:88
	ds_write2_b32 v40, v47, v43 offset0:204 offset1:220
	ds_write2_b32 v48, v36, v32 offset0:96 offset1:112
	ds_write2_b32 v48, v37, v33 offset0:228 offset1:244
	ds_write2_b32 v40, v38, v34 offset0:104 offset1:120
	ds_write2_b32 v40, v39, v35 offset0:236 offset1:252
	v_add_u32_e32 v32, 0x4000, v134
	ds_write2_b32 v32, v28, v24 offset0:128 offset1:144
	v_add_u32_e32 v24, 0x4400, v134
	ds_write2_b32 v24, v29, v25 offset0:4 offset1:20
	ds_write2_b32 v24, v30, v26 offset0:136 offset1:152
	v_add_u32_e32 v25, 0x4800, v134
	ds_write2_b32 v25, v31, v27 offset0:12 offset1:28
	ds_write2_b32 v32, v20, v16 offset0:160 offset1:176
	ds_write2_b32 v24, v21, v17 offset0:36 offset1:52
	ds_write2_b32 v24, v22, v18 offset0:168 offset1:184
	ds_write2_b32 v25, v23, v19 offset0:44 offset1:60
	v_add_u32_e32 v16, 0x6000, v134
	ds_write2_b32 v16, v12, v8 offset0:192 offset1:208
	v_add_u32_e32 v8, 0x6400, v134
	ds_write2_b32 v8, v13, v9 offset0:68 offset1:84
	ds_write2_b32 v8, v14, v10 offset0:200 offset1:216
	v_add_u32_e32 v9, 0x6800, v134
	ds_write2_b32 v9, v15, v11 offset0:76 offset1:92
	ds_write2_b32 v16, v4, v0 offset0:224 offset1:240
	ds_write2_b32 v8, v5, v1 offset0:100 offset1:116
	ds_write2_b32 v8, v6, v2 offset0:232 offset1:248
	ds_write2_b32 v9, v7, v3 offset0:108 offset1:124
	v_or_b32_e32 v0, s24, v113
	v_lshlrev_b32_e32 v70, 2, v0
	v_lshl_add_u64 v[0:1], s[14:15], 0, v[70:71]
	v_lshl_add_u64 v[2:3], s[10:11], 0, v[70:71]
	v_add_u32_e32 v4, s25, v146
	s_mov_b32 s12, 0
	s_waitcnt lgkmcnt(0)
	s_barrier

.LBB0_1998:
	s_and_b32 s20, s19, 0x4000
	s_xor_b32 s21, s20, 0x4000
	s_lshl_b32 s21, s21, 1
	s_add_i32 s21, s21, 32
	s_add_u32 s90, s52, s12
	s_addc_u32 s91, s53, s13
	s_add_i32 m0, s21, s82
	s_lshl_b32 s20, s20, 1
	global_load_lds_dwordx4 v184, s[90:91]
	s_add_i32 m0, s21, s83
	s_add_i32 s20, s20, 32
	global_load_lds_dwordx4 v185, s[90:91]
	s_add_i32 m0, s21, s84
	v_lshl_add_u32 v137, v114, 1, s20
	global_load_lds_dwordx4 v186, s[90:91]
	s_add_i32 m0, s21, s85
	v_lshl_add_u32 v170, v115, 1, s20
	global_load_lds_dwordx4 v187, s[90:91]
	s_add_i32 m0, s21, s86
	v_add_u32_e32 v158, v137, v135
	global_load_lds_dwordx4 v188, s[90:91]
	s_add_i32 m0, s21, s87
	v_add_u32_e32 v166, v170, v135
	global_load_lds_dwordx4 v189, s[90:91]
	s_add_i32 m0, s21, s88
	s_addk_i32 s19, 0x4000
	global_load_lds_dwordx4 v190, s[90:91]
	s_add_i32 m0, s21, s89
	s_add_u32 s12, s12, 0x80
	s_addc_u32 s13, s13, 0
	global_load_lds_dwordx4 v191, s[90:91]
	ds_read_b128 v[138:141], v158
	ds_read_b128 v[146:149], v166 offset:16384
	ds_read_b128 v[150:153], v166 offset:18432
	ds_read_b128 v[162:165], v166 offset:20480
	ds_read_b128 v[166:169], v166 offset:22528
	ds_read_b128 v[142:145], v158 offset:2048
	ds_read_b128 v[154:157], v158 offset:4096
	ds_read_b128 v[158:161], v158 offset:6144
	v_add_u32_e32 v137, v137, v136
	v_add_u32_e32 v236, v170, v136
	ds_read_b128 v[204:207], v137
	ds_read_b128 v[208:211], v236 offset:16384
	ds_read_b128 v[212:215], v236 offset:18432
	ds_read_b128 v[216:219], v236 offset:20480
	ds_read_b128 v[220:223], v236 offset:22528
	ds_read_b128 v[224:227], v137 offset:2048
	ds_read_b128 v[228:231], v137 offset:4096
	ds_read_b128 v[232:235], v137 offset:6144
	s_setprio 1
	s_waitcnt lgkmcnt(11)
	v_mfma_f32_16x16x32_bf16 v[60:63], v[138:141], v[146:149], v[60:63]
	v_mfma_f32_16x16x32_bf16 v[56:59], v[138:141], v[150:153], v[56:59]
	v_mfma_f32_16x16x32_bf16 v[52:55], v[138:141], v[162:165], v[52:55]
	v_mfma_f32_16x16x32_bf16 v[48:51], v[138:141], v[166:169], v[48:51]
	s_waitcnt lgkmcnt(10)
	v_mfma_f32_16x16x32_bf16 v[44:47], v[142:145], v[146:149], v[44:47]
	v_mfma_f32_16x16x32_bf16 v[40:43], v[142:145], v[150:153], v[40:43]
	v_mfma_f32_16x16x32_bf16 v[36:39], v[142:145], v[162:165], v[36:39]
	v_mfma_f32_16x16x32_bf16 v[32:35], v[142:145], v[166:169], v[32:35]
	s_waitcnt lgkmcnt(9)
	v_mfma_f32_16x16x32_bf16 v[28:31], v[154:157], v[146:149], v[28:31]
	v_mfma_f32_16x16x32_bf16 v[24:27], v[154:157], v[150:153], v[24:27]
	v_mfma_f32_16x16x32_bf16 v[20:23], v[154:157], v[162:165], v[20:23]
	v_mfma_f32_16x16x32_bf16 v[16:19], v[154:157], v[166:169], v[16:19]
	s_waitcnt lgkmcnt(8)
	v_mfma_f32_16x16x32_bf16 v[12:15], v[158:161], v[146:149], v[12:15]
	v_mfma_f32_16x16x32_bf16 v[8:11], v[158:161], v[150:153], v[8:11]
	v_mfma_f32_16x16x32_bf16 v[4:7], v[158:161], v[162:165], v[4:7]
	v_mfma_f32_16x16x32_bf16 v[0:3], v[158:161], v[166:169], v[0:3]
	s_waitcnt lgkmcnt(3)
	v_mfma_f32_16x16x32_bf16 v[60:63], v[204:207], v[208:211], v[60:63]
	v_mfma_f32_16x16x32_bf16 v[56:59], v[204:207], v[212:215], v[56:59]
	v_mfma_f32_16x16x32_bf16 v[52:55], v[204:207], v[216:219], v[52:55]
	v_mfma_f32_16x16x32_bf16 v[48:51], v[204:207], v[220:223], v[48:51]
	s_waitcnt lgkmcnt(2)
	v_mfma_f32_16x16x32_bf16 v[44:47], v[224:227], v[208:211], v[44:47]
	v_mfma_f32_16x16x32_bf16 v[40:43], v[224:227], v[212:215], v[40:43]
	v_mfma_f32_16x16x32_bf16 v[36:39], v[224:227], v[216:219], v[36:39]
	v_mfma_f32_16x16x32_bf16 v[32:35], v[224:227], v[220:223], v[32:35]
	s_waitcnt lgkmcnt(1)
	v_mfma_f32_16x16x32_bf16 v[28:31], v[228:231], v[208:211], v[28:31]
	v_mfma_f32_16x16x32_bf16 v[24:27], v[228:231], v[212:215], v[24:27]
	v_mfma_f32_16x16x32_bf16 v[20:23], v[228:231], v[216:219], v[20:23]
	v_mfma_f32_16x16x32_bf16 v[16:19], v[228:231], v[220:223], v[16:19]
	s_waitcnt lgkmcnt(0)
	v_mfma_f32_16x16x32_bf16 v[12:15], v[232:235], v[208:211], v[12:15]
	v_mfma_f32_16x16x32_bf16 v[8:11], v[232:235], v[212:215], v[8:11]
	v_mfma_f32_16x16x32_bf16 v[4:7], v[232:235], v[216:219], v[4:7]
	v_mfma_f32_16x16x32_bf16 v[0:3], v[232:235], v[220:223], v[0:3]
	s_setprio 0
	s_cmpk_eq_i32 s12, 0x780
	s_waitcnt vmcnt(0)
	s_barrier
	s_cbranch_scc0 .LBB0_1998
	ds_read_b128 v[90:93], v116 offset:55296
	ds_read_b128 v[94:97], v116 offset:53248
	ds_read_b128 v[98:101], v117 offset:38912
	ds_read_b128 v[102:105], v117 offset:36864
	ds_read_b128 v[138:141], v116 offset:51200
	ds_read_b128 v[142:145], v116 offset:49152
	ds_read_b128 v[146:149], v117 offset:34816
	ds_read_b128 v[150:153], v117 offset:32768
	ds_read_b128 v[204:207], v118 offset:32768
	ds_read_b128 v[208:211], v118 offset:34816
	ds_read_b128 v[212:215], v119 offset:49152
	ds_read_b128 v[216:219], v119 offset:51200
	ds_read_b128 v[220:223], v118 offset:36864
	ds_read_b128 v[224:227], v118 offset:38912
	ds_read_b128 v[228:231], v119 offset:53248
	ds_read_b128 v[232:235], v119 offset:55296
	s_setprio 1
	s_waitcnt lgkmcnt(13)
	v_mfma_f32_16x16x32_bf16 v[0:3], v[98:101], v[90:93], v[0:3]
	s_waitcnt lgkmcnt(8)
	v_mfma_f32_16x16x32_bf16 v[60:63], v[150:153], v[142:145], v[60:63]
	v_mfma_f32_16x16x32_bf16 v[56:59], v[150:153], v[138:141], v[56:59]
	v_mfma_f32_16x16x32_bf16 v[52:55], v[150:153], v[94:97], v[52:55]
	v_mfma_f32_16x16x32_bf16 v[48:51], v[150:153], v[90:93], v[48:51]
	v_mfma_f32_16x16x32_bf16 v[44:47], v[146:149], v[142:145], v[44:47]
	v_mfma_f32_16x16x32_bf16 v[40:43], v[146:149], v[138:141], v[40:43]
	v_mfma_f32_16x16x32_bf16 v[36:39], v[146:149], v[94:97], v[36:39]
	v_mfma_f32_16x16x32_bf16 v[32:35], v[146:149], v[90:93], v[32:35]
	v_mfma_f32_16x16x32_bf16 v[28:31], v[102:105], v[142:145], v[28:31]
	v_mfma_f32_16x16x32_bf16 v[24:27], v[102:105], v[138:141], v[24:27]
	v_mfma_f32_16x16x32_bf16 v[20:23], v[102:105], v[94:97], v[20:23]
	v_mfma_f32_16x16x32_bf16 v[16:19], v[102:105], v[90:93], v[16:19]
	v_mfma_f32_16x16x32_bf16 v[12:15], v[98:101], v[142:145], v[12:15]
	v_mfma_f32_16x16x32_bf16 v[8:11], v[98:101], v[138:141], v[8:11]
	v_mfma_f32_16x16x32_bf16 v[4:7], v[98:101], v[94:97], v[4:7]
	s_waitcnt lgkmcnt(0)
	v_mfma_f32_16x16x32_bf16 v[0:3], v[224:227], v[232:235], v[0:3]
	v_mfma_f32_16x16x32_bf16 v[60:63], v[204:207], v[212:215], v[60:63]
	v_mfma_f32_16x16x32_bf16 v[56:59], v[204:207], v[216:219], v[56:59]
	v_mfma_f32_16x16x32_bf16 v[52:55], v[204:207], v[228:231], v[52:55]
	v_mfma_f32_16x16x32_bf16 v[48:51], v[204:207], v[232:235], v[48:51]
	v_mfma_f32_16x16x32_bf16 v[44:47], v[208:211], v[212:215], v[44:47]
	v_mfma_f32_16x16x32_bf16 v[40:43], v[208:211], v[216:219], v[40:43]
	v_mfma_f32_16x16x32_bf16 v[36:39], v[208:211], v[228:231], v[36:39]
	v_mfma_f32_16x16x32_bf16 v[32:35], v[208:211], v[232:235], v[32:35]
	v_mfma_f32_16x16x32_bf16 v[28:31], v[220:223], v[212:215], v[28:31]
	v_mfma_f32_16x16x32_bf16 v[24:27], v[220:223], v[216:219], v[24:27]
	v_mfma_f32_16x16x32_bf16 v[20:23], v[220:223], v[228:231], v[20:23]
	v_mfma_f32_16x16x32_bf16 v[16:19], v[220:223], v[232:235], v[16:19]
	v_mfma_f32_16x16x32_bf16 v[12:15], v[224:227], v[212:215], v[12:15]
	v_mfma_f32_16x16x32_bf16 v[8:11], v[224:227], v[216:219], v[8:11]
	v_mfma_f32_16x16x32_bf16 v[4:7], v[224:227], v[228:231], v[4:7]
	s_setprio 0
	s_barrier
	ds_write2_b32 v120, v60, v56 offset1:16
	ds_write2_b32 v120, v61, v57 offset0:132 offset1:148
	v_add_u32_e32 v56, 0x400, v120
	ds_write2_b32 v56, v62, v58 offset0:8 offset1:24
	ds_write2_b32 v56, v63, v59 offset0:140 offset1:156
	ds_write2_b32 v120, v52, v48 offset0:32 offset1:48
	ds_write2_b32 v120, v53, v49 offset0:164 offset1:180
	ds_write2_b32 v56, v54, v50 offset0:40 offset1:56
	ds_write2_b32 v56, v55, v51 offset0:172 offset1:188
	v_add_u32_e32 v48, 0x2000, v120
	ds_write2_b32 v48, v44, v40 offset0:64 offset1:80
	ds_write2_b32 v48, v45, v41 offset0:196 offset1:212
	v_add_u32_e32 v40, 0x2400, v120
	ds_write2_b32 v40, v46, v42 offset0:72 offset1:88
	ds_write2_b32 v40, v47, v43 offset0:204 offset1:220
	ds_write2_b32 v48, v36, v32 offset0:96 offset1:112
	ds_write2_b32 v48, v37, v33 offset0:228 offset1:244
	ds_write2_b32 v40, v38, v34 offset0:104 offset1:120
	ds_write2_b32 v40, v39, v35 offset0:236 offset1:252
	v_add_u32_e32 v32, 0x4000, v120
	ds_write2_b32 v32, v28, v24 offset0:128 offset1:144
	v_add_u32_e32 v24, 0x4400, v120
	ds_write2_b32 v24, v29, v25 offset0:4 offset1:20
	ds_write2_b32 v24, v30, v26 offset0:136 offset1:152
	v_add_u32_e32 v25, 0x4800, v120
	ds_write2_b32 v25, v31, v27 offset0:12 offset1:28
	ds_write2_b32 v32, v20, v16 offset0:160 offset1:176
	ds_write2_b32 v24, v21, v17 offset0:36 offset1:52
	ds_write2_b32 v24, v22, v18 offset0:168 offset1:184
	ds_write2_b32 v25, v23, v19 offset0:44 offset1:60
	v_add_u32_e32 v16, 0x6000, v120
	ds_write2_b32 v16, v12, v8 offset0:192 offset1:208
	v_add_u32_e32 v8, 0x6400, v120
	ds_write2_b32 v8, v13, v9 offset0:68 offset1:84
	ds_write2_b32 v8, v14, v10 offset0:200 offset1:216
	v_add_u32_e32 v9, 0x6800, v120
	ds_write2_b32 v9, v15, v11 offset0:76 offset1:92
	ds_write2_b32 v16, v4, v0 offset0:224 offset1:240
	ds_write2_b32 v8, v5, v1 offset0:100 offset1:116
	ds_write2_b32 v8, v6, v2 offset0:232 offset1:248
	ds_write2_b32 v9, v7, v3 offset0:108 offset1:124
	v_or_b32_e32 v0, s18, v121
	v_ashrrev_i32_e32 v1, 31, v0
	v_lshl_add_u64 v[0:1], v[0:1], 1, s[6:7]
	v_add_u32_e32 v2, s17, v128
	s_mov_b32 s12, 0
	s_waitcnt lgkmcnt(0)
	s_barrier

.LBB0_2009:
	s_and_b32 s17, s16, 0x4000
	s_xor_b32 s18, s17, 0x4000
	s_lshl_b32 s18, s18, 1
	s_add_i32 s18, s18, 32
	s_add_u32 s90, s52, s8
	s_addc_u32 s91, s53, s9
	s_add_i32 m0, s18, s82
	s_lshl_b32 s17, s17, 1
	global_load_lds_dwordx4 v184, s[90:91]
	s_add_i32 m0, s18, s83
	s_add_i32 s17, s17, 32
	global_load_lds_dwordx4 v185, s[90:91]
	s_add_i32 m0, s18, s84
	v_lshl_add_u32 v137, v113, 1, s17
	global_load_lds_dwordx4 v186, s[90:91]
	s_add_i32 m0, s18, s85
	v_lshl_add_u32 v170, v114, 1, s17
	global_load_lds_dwordx4 v187, s[90:91]
	s_add_i32 m0, s18, s86
	v_add_u32_e32 v158, v137, v135
	global_load_lds_dwordx4 v188, s[90:91]
	s_add_i32 m0, s18, s87
	v_add_u32_e32 v166, v170, v135
	global_load_lds_dwordx4 v189, s[90:91]
	s_add_i32 m0, s18, s88
	s_addk_i32 s16, 0x4000
	global_load_lds_dwordx4 v190, s[90:91]
	s_add_i32 m0, s18, s89
	s_add_u32 s8, s8, 0x80
	s_addc_u32 s9, s9, 0
	global_load_lds_dwordx4 v191, s[90:91]
	ds_read_b128 v[138:141], v158
	ds_read_b128 v[146:149], v166 offset:16384
	ds_read_b128 v[150:153], v166 offset:18432
	ds_read_b128 v[162:165], v166 offset:20480
	ds_read_b128 v[166:169], v166 offset:22528
	ds_read_b128 v[142:145], v158 offset:2048
	ds_read_b128 v[154:157], v158 offset:4096
	ds_read_b128 v[158:161], v158 offset:6144
	v_add_u32_e32 v137, v137, v136
	v_add_u32_e32 v236, v170, v136
	ds_read_b128 v[204:207], v137
	ds_read_b128 v[208:211], v236 offset:16384
	ds_read_b128 v[212:215], v236 offset:18432
	ds_read_b128 v[216:219], v236 offset:20480
	ds_read_b128 v[220:223], v236 offset:22528
	ds_read_b128 v[224:227], v137 offset:2048
	ds_read_b128 v[228:231], v137 offset:4096
	ds_read_b128 v[232:235], v137 offset:6144
	s_setprio 1
	s_waitcnt lgkmcnt(11)
	v_mfma_f32_16x16x32_bf16 v[60:63], v[138:141], v[146:149], v[60:63]
	v_mfma_f32_16x16x32_bf16 v[56:59], v[138:141], v[150:153], v[56:59]
	v_mfma_f32_16x16x32_bf16 v[52:55], v[138:141], v[162:165], v[52:55]
	v_mfma_f32_16x16x32_bf16 v[48:51], v[138:141], v[166:169], v[48:51]
	s_waitcnt lgkmcnt(10)
	v_mfma_f32_16x16x32_bf16 v[44:47], v[142:145], v[146:149], v[44:47]
	v_mfma_f32_16x16x32_bf16 v[40:43], v[142:145], v[150:153], v[40:43]
	v_mfma_f32_16x16x32_bf16 v[36:39], v[142:145], v[162:165], v[36:39]
	v_mfma_f32_16x16x32_bf16 v[32:35], v[142:145], v[166:169], v[32:35]
	s_waitcnt lgkmcnt(9)
	v_mfma_f32_16x16x32_bf16 v[28:31], v[154:157], v[146:149], v[28:31]
	v_mfma_f32_16x16x32_bf16 v[24:27], v[154:157], v[150:153], v[24:27]
	v_mfma_f32_16x16x32_bf16 v[20:23], v[154:157], v[162:165], v[20:23]
	v_mfma_f32_16x16x32_bf16 v[16:19], v[154:157], v[166:169], v[16:19]
	s_waitcnt lgkmcnt(8)
	v_mfma_f32_16x16x32_bf16 v[12:15], v[158:161], v[146:149], v[12:15]
	v_mfma_f32_16x16x32_bf16 v[8:11], v[158:161], v[150:153], v[8:11]
	v_mfma_f32_16x16x32_bf16 v[4:7], v[158:161], v[162:165], v[4:7]
	v_mfma_f32_16x16x32_bf16 v[0:3], v[158:161], v[166:169], v[0:3]
	s_waitcnt lgkmcnt(3)
	v_mfma_f32_16x16x32_bf16 v[60:63], v[204:207], v[208:211], v[60:63]
	v_mfma_f32_16x16x32_bf16 v[56:59], v[204:207], v[212:215], v[56:59]
	v_mfma_f32_16x16x32_bf16 v[52:55], v[204:207], v[216:219], v[52:55]
	v_mfma_f32_16x16x32_bf16 v[48:51], v[204:207], v[220:223], v[48:51]
	s_waitcnt lgkmcnt(2)
	v_mfma_f32_16x16x32_bf16 v[44:47], v[224:227], v[208:211], v[44:47]
	v_mfma_f32_16x16x32_bf16 v[40:43], v[224:227], v[212:215], v[40:43]
	v_mfma_f32_16x16x32_bf16 v[36:39], v[224:227], v[216:219], v[36:39]
	v_mfma_f32_16x16x32_bf16 v[32:35], v[224:227], v[220:223], v[32:35]
	s_waitcnt lgkmcnt(1)
	v_mfma_f32_16x16x32_bf16 v[28:31], v[228:231], v[208:211], v[28:31]
	v_mfma_f32_16x16x32_bf16 v[24:27], v[228:231], v[212:215], v[24:27]
	v_mfma_f32_16x16x32_bf16 v[20:23], v[228:231], v[216:219], v[20:23]
	v_mfma_f32_16x16x32_bf16 v[16:19], v[228:231], v[220:223], v[16:19]
	s_waitcnt lgkmcnt(0)
	v_mfma_f32_16x16x32_bf16 v[12:15], v[232:235], v[208:211], v[12:15]
	v_mfma_f32_16x16x32_bf16 v[8:11], v[232:235], v[212:215], v[8:11]
	v_mfma_f32_16x16x32_bf16 v[4:7], v[232:235], v[216:219], v[4:7]
	v_mfma_f32_16x16x32_bf16 v[0:3], v[232:235], v[220:223], v[0:3]
	s_setprio 0
	s_cmpk_eq_i32 s8, 0x780
	s_waitcnt vmcnt(0)
	s_barrier
	s_cbranch_scc0 .LBB0_2009
	ds_read_b128 v[88:91], v115 offset:55296
	ds_read_b128 v[92:95], v115 offset:53248
	ds_read_b128 v[96:99], v116 offset:38912
	ds_read_b128 v[100:103], v116 offset:36864
	ds_read_b128 v[138:141], v115 offset:51200
	ds_read_b128 v[142:145], v115 offset:49152
	ds_read_b128 v[146:149], v116 offset:34816
	ds_read_b128 v[150:153], v116 offset:32768
	ds_read_b128 v[204:207], v117 offset:32768
	ds_read_b128 v[208:211], v117 offset:34816
	ds_read_b128 v[212:215], v118 offset:49152
	ds_read_b128 v[216:219], v118 offset:51200
	ds_read_b128 v[220:223], v117 offset:36864
	ds_read_b128 v[224:227], v117 offset:38912
	ds_read_b128 v[228:231], v118 offset:53248
	ds_read_b128 v[232:235], v118 offset:55296
	s_setprio 1
	s_waitcnt lgkmcnt(13)
	v_mfma_f32_16x16x32_bf16 v[0:3], v[96:99], v[88:91], v[0:3]
	s_waitcnt lgkmcnt(8)
	v_mfma_f32_16x16x32_bf16 v[60:63], v[150:153], v[142:145], v[60:63]
	v_mfma_f32_16x16x32_bf16 v[56:59], v[150:153], v[138:141], v[56:59]
	v_mfma_f32_16x16x32_bf16 v[52:55], v[150:153], v[92:95], v[52:55]
	v_mfma_f32_16x16x32_bf16 v[48:51], v[150:153], v[88:91], v[48:51]
	v_mfma_f32_16x16x32_bf16 v[44:47], v[146:149], v[142:145], v[44:47]
	v_mfma_f32_16x16x32_bf16 v[40:43], v[146:149], v[138:141], v[40:43]
	v_mfma_f32_16x16x32_bf16 v[36:39], v[146:149], v[92:95], v[36:39]
	v_mfma_f32_16x16x32_bf16 v[32:35], v[146:149], v[88:91], v[32:35]
	v_mfma_f32_16x16x32_bf16 v[28:31], v[100:103], v[142:145], v[28:31]
	v_mfma_f32_16x16x32_bf16 v[24:27], v[100:103], v[138:141], v[24:27]
	v_mfma_f32_16x16x32_bf16 v[20:23], v[100:103], v[92:95], v[20:23]
	v_mfma_f32_16x16x32_bf16 v[16:19], v[100:103], v[88:91], v[16:19]
	v_mfma_f32_16x16x32_bf16 v[12:15], v[96:99], v[142:145], v[12:15]
	v_mfma_f32_16x16x32_bf16 v[8:11], v[96:99], v[138:141], v[8:11]
	v_mfma_f32_16x16x32_bf16 v[4:7], v[96:99], v[92:95], v[4:7]
	s_waitcnt lgkmcnt(0)
	v_mfma_f32_16x16x32_bf16 v[0:3], v[224:227], v[232:235], v[0:3]
	v_mfma_f32_16x16x32_bf16 v[60:63], v[204:207], v[212:215], v[60:63]
	v_mfma_f32_16x16x32_bf16 v[56:59], v[204:207], v[216:219], v[56:59]
	v_mfma_f32_16x16x32_bf16 v[52:55], v[204:207], v[228:231], v[52:55]
	v_mfma_f32_16x16x32_bf16 v[48:51], v[204:207], v[232:235], v[48:51]
	v_mfma_f32_16x16x32_bf16 v[44:47], v[208:211], v[212:215], v[44:47]
	v_mfma_f32_16x16x32_bf16 v[40:43], v[208:211], v[216:219], v[40:43]
	v_mfma_f32_16x16x32_bf16 v[36:39], v[208:211], v[228:231], v[36:39]
	v_mfma_f32_16x16x32_bf16 v[32:35], v[208:211], v[232:235], v[32:35]
	v_mfma_f32_16x16x32_bf16 v[28:31], v[220:223], v[212:215], v[28:31]
	v_mfma_f32_16x16x32_bf16 v[24:27], v[220:223], v[216:219], v[24:27]
	v_mfma_f32_16x16x32_bf16 v[20:23], v[220:223], v[228:231], v[20:23]
	v_mfma_f32_16x16x32_bf16 v[16:19], v[220:223], v[232:235], v[16:19]
	v_mfma_f32_16x16x32_bf16 v[12:15], v[224:227], v[212:215], v[12:15]
	v_mfma_f32_16x16x32_bf16 v[8:11], v[224:227], v[216:219], v[8:11]
	v_mfma_f32_16x16x32_bf16 v[4:7], v[224:227], v[228:231], v[4:7]
	s_setprio 0
	s_barrier
	ds_write2_b32 v119, v60, v56 offset1:16
	ds_write2_b32 v119, v61, v57 offset0:132 offset1:148
	v_add_u32_e32 v56, 0x400, v119
	ds_write2_b32 v56, v62, v58 offset0:8 offset1:24
	ds_write2_b32 v56, v63, v59 offset0:140 offset1:156
	ds_write2_b32 v119, v52, v48 offset0:32 offset1:48
	ds_write2_b32 v119, v53, v49 offset0:164 offset1:180
	ds_write2_b32 v56, v54, v50 offset0:40 offset1:56
	ds_write2_b32 v56, v55, v51 offset0:172 offset1:188
	v_add_u32_e32 v48, 0x2000, v119
	ds_write2_b32 v48, v44, v40 offset0:64 offset1:80
	ds_write2_b32 v48, v45, v41 offset0:196 offset1:212
	v_add_u32_e32 v40, 0x2400, v119
	ds_write2_b32 v40, v46, v42 offset0:72 offset1:88
	ds_write2_b32 v40, v47, v43 offset0:204 offset1:220
	ds_write2_b32 v48, v36, v32 offset0:96 offset1:112
	ds_write2_b32 v48, v37, v33 offset0:228 offset1:244
	ds_write2_b32 v40, v38, v34 offset0:104 offset1:120
	ds_write2_b32 v40, v39, v35 offset0:236 offset1:252
	v_add_u32_e32 v32, 0x4000, v119
	ds_write2_b32 v32, v28, v24 offset0:128 offset1:144
	v_add_u32_e32 v24, 0x4400, v119
	ds_write2_b32 v24, v29, v25 offset0:4 offset1:20
	ds_write2_b32 v24, v30, v26 offset0:136 offset1:152
	v_add_u32_e32 v25, 0x4800, v119
	ds_write2_b32 v25, v31, v27 offset0:12 offset1:28
	ds_write2_b32 v32, v20, v16 offset0:160 offset1:176
	ds_write2_b32 v24, v21, v17 offset0:36 offset1:52
	ds_write2_b32 v24, v22, v18 offset0:168 offset1:184
	ds_write2_b32 v25, v23, v19 offset0:44 offset1:60
	v_add_u32_e32 v16, 0x6000, v119
	ds_write2_b32 v16, v12, v8 offset0:192 offset1:208
	v_add_u32_e32 v8, 0x6400, v119
	ds_write2_b32 v8, v13, v9 offset0:68 offset1:84
	ds_write2_b32 v8, v14, v10 offset0:200 offset1:216
	v_add_u32_e32 v9, 0x6800, v119
	ds_write2_b32 v9, v15, v11 offset0:76 offset1:92
	ds_write2_b32 v16, v4, v0 offset0:224 offset1:240
	ds_write2_b32 v8, v5, v1 offset0:100 offset1:116
	ds_write2_b32 v8, v6, v2 offset0:232 offset1:248
	ds_write2_b32 v9, v7, v3 offset0:108 offset1:124
	v_or_b32_e32 v0, s14, v120
	v_ashrrev_i32_e32 v1, 31, v0
	v_lshl_add_u64 v[0:1], v[0:1], 1, s[6:7]
	v_add_u32_e32 v2, s15, v128
	s_mov_b32 s8, 0
	s_waitcnt lgkmcnt(0)
	s_barrier

.LBB0_2076:
	s_and_b32 s27, s26, 0x4000
	s_xor_b32 s28, s27, 0x4000
	s_lshl_b32 s28, s28, 1
	s_add_i32 s28, s28, 32
	s_add_u32 s90, s52, s16
	s_addc_u32 s91, s53, s17
	s_add_i32 m0, s28, s82
	s_lshl_b32 s27, s27, 1
	global_load_lds_dwordx4 v192, s[90:91]
	s_add_i32 m0, s28, s83
	s_add_i32 s27, s27, 32
	global_load_lds_dwordx4 v193, s[90:91]
	s_add_i32 m0, s28, s84
	v_add3_u32 v170, s27, v114, v135
	global_load_lds_dwordx4 v194, s[90:91]
	s_add_i32 m0, s28, s85
	v_add3_u32 v171, s27, v115, v135
	global_load_lds_dwordx4 v195, s[90:91]
	s_add_i32 m0, s28, s86
	v_add_u32_e32 v158, v170, v136
	global_load_lds_dwordx4 v196, s[90:91]
	s_add_i32 m0, s28, s87
	v_add_u32_e32 v166, v171, v136
	global_load_lds_dwordx4 v197, s[90:91]
	s_add_i32 m0, s28, s88
	s_addk_i32 s26, 0x4000
	global_load_lds_dwordx4 v198, s[90:91]
	s_add_i32 m0, s28, s89
	s_add_u32 s16, s16, 0x80
	s_addc_u32 s17, s17, 0
	global_load_lds_dwordx4 v199, s[90:91]
	ds_read_b128 v[138:141], v158
	ds_read_b128 v[146:149], v166 offset:16384
	ds_read_b128 v[150:153], v166 offset:18432
	ds_read_b128 v[162:165], v166 offset:20480
	ds_read_b128 v[166:169], v166 offset:22528
	ds_read_b128 v[142:145], v158 offset:2048
	ds_read_b128 v[154:157], v158 offset:4096
	ds_read_b128 v[158:161], v158 offset:6144
	v_add_u32_e32 v236, v170, v137
	v_add_u32_e32 v237, v171, v137
	ds_read_b128 v[204:207], v236
	ds_read_b128 v[208:211], v237 offset:16384
	ds_read_b128 v[212:215], v237 offset:18432
	ds_read_b128 v[216:219], v237 offset:20480
	ds_read_b128 v[220:223], v237 offset:22528
	ds_read_b128 v[224:227], v236 offset:2048
	ds_read_b128 v[228:231], v236 offset:4096
	ds_read_b128 v[232:235], v236 offset:6144
	s_setprio 1
	s_waitcnt lgkmcnt(11)
	v_mfma_f32_16x16x32_bf16 v[60:63], v[138:141], v[146:149], v[60:63]
	v_mfma_f32_16x16x32_bf16 v[56:59], v[138:141], v[150:153], v[56:59]
	v_mfma_f32_16x16x32_bf16 v[52:55], v[138:141], v[162:165], v[52:55]
	v_mfma_f32_16x16x32_bf16 v[48:51], v[138:141], v[166:169], v[48:51]
	s_waitcnt lgkmcnt(10)
	v_mfma_f32_16x16x32_bf16 v[44:47], v[142:145], v[146:149], v[44:47]
	v_mfma_f32_16x16x32_bf16 v[40:43], v[142:145], v[150:153], v[40:43]
	v_mfma_f32_16x16x32_bf16 v[36:39], v[142:145], v[162:165], v[36:39]
	v_mfma_f32_16x16x32_bf16 v[32:35], v[142:145], v[166:169], v[32:35]
	s_waitcnt lgkmcnt(9)
	v_mfma_f32_16x16x32_bf16 v[28:31], v[154:157], v[146:149], v[28:31]
	v_mfma_f32_16x16x32_bf16 v[24:27], v[154:157], v[150:153], v[24:27]
	v_mfma_f32_16x16x32_bf16 v[20:23], v[154:157], v[162:165], v[20:23]
	v_mfma_f32_16x16x32_bf16 v[16:19], v[154:157], v[166:169], v[16:19]
	s_waitcnt lgkmcnt(8)
	v_mfma_f32_16x16x32_bf16 v[12:15], v[158:161], v[146:149], v[12:15]
	v_mfma_f32_16x16x32_bf16 v[8:11], v[158:161], v[150:153], v[8:11]
	v_mfma_f32_16x16x32_bf16 v[4:7], v[158:161], v[162:165], v[4:7]
	v_mfma_f32_16x16x32_bf16 v[0:3], v[158:161], v[166:169], v[0:3]
	s_waitcnt lgkmcnt(3)
	v_mfma_f32_16x16x32_bf16 v[60:63], v[204:207], v[208:211], v[60:63]
	v_mfma_f32_16x16x32_bf16 v[56:59], v[204:207], v[212:215], v[56:59]
	v_mfma_f32_16x16x32_bf16 v[52:55], v[204:207], v[216:219], v[52:55]
	v_mfma_f32_16x16x32_bf16 v[48:51], v[204:207], v[220:223], v[48:51]
	s_waitcnt lgkmcnt(2)
	v_mfma_f32_16x16x32_bf16 v[44:47], v[224:227], v[208:211], v[44:47]
	v_mfma_f32_16x16x32_bf16 v[40:43], v[224:227], v[212:215], v[40:43]
	v_mfma_f32_16x16x32_bf16 v[36:39], v[224:227], v[216:219], v[36:39]
	v_mfma_f32_16x16x32_bf16 v[32:35], v[224:227], v[220:223], v[32:35]
	s_waitcnt lgkmcnt(1)
	v_mfma_f32_16x16x32_bf16 v[28:31], v[228:231], v[208:211], v[28:31]
	v_mfma_f32_16x16x32_bf16 v[24:27], v[228:231], v[212:215], v[24:27]
	v_mfma_f32_16x16x32_bf16 v[20:23], v[228:231], v[216:219], v[20:23]
	v_mfma_f32_16x16x32_bf16 v[16:19], v[228:231], v[220:223], v[16:19]
	s_waitcnt lgkmcnt(0)
	v_mfma_f32_16x16x32_bf16 v[12:15], v[232:235], v[208:211], v[12:15]
	v_mfma_f32_16x16x32_bf16 v[8:11], v[232:235], v[212:215], v[8:11]
	v_mfma_f32_16x16x32_bf16 v[4:7], v[232:235], v[216:219], v[4:7]
	v_mfma_f32_16x16x32_bf16 v[0:3], v[232:235], v[220:223], v[0:3]
	s_setprio 0
	s_cmpk_eq_i32 s16, 0x1f80
	s_waitcnt vmcnt(0)
	s_barrier
	s_cbranch_scc0 .LBB0_2076
	ds_read_b128 v[90:93], v118 offset:55296
	ds_read_b128 v[94:97], v118 offset:53248
	ds_read_b128 v[98:101], v119 offset:38912
	ds_read_b128 v[102:105], v119 offset:36864
	ds_read_b128 v[138:141], v118 offset:51200
	ds_read_b128 v[142:145], v118 offset:49152
	ds_read_b128 v[146:149], v119 offset:34816
	ds_read_b128 v[150:153], v119 offset:32768
	ds_read_b128 v[204:207], v120 offset:32768
	ds_read_b128 v[208:211], v120 offset:34816
	ds_read_b128 v[212:215], v121 offset:49152
	ds_read_b128 v[216:219], v121 offset:51200
	ds_read_b128 v[220:223], v120 offset:36864
	ds_read_b128 v[224:227], v120 offset:38912
	ds_read_b128 v[228:231], v121 offset:53248
	ds_read_b128 v[232:235], v121 offset:55296
	s_setprio 1
	s_waitcnt lgkmcnt(13)
	v_mfma_f32_16x16x32_bf16 v[4:7], v[98:101], v[94:97], v[4:7]
	v_mfma_f32_16x16x32_bf16 v[0:3], v[98:101], v[90:93], v[0:3]
	s_waitcnt lgkmcnt(8)
	v_mfma_f32_16x16x32_bf16 v[60:63], v[150:153], v[142:145], v[60:63]
	v_mfma_f32_16x16x32_bf16 v[56:59], v[150:153], v[138:141], v[56:59]
	v_mfma_f32_16x16x32_bf16 v[52:55], v[150:153], v[94:97], v[52:55]
	v_mfma_f32_16x16x32_bf16 v[48:51], v[150:153], v[90:93], v[48:51]
	v_mfma_f32_16x16x32_bf16 v[44:47], v[146:149], v[142:145], v[44:47]
	v_mfma_f32_16x16x32_bf16 v[40:43], v[146:149], v[138:141], v[40:43]
	v_mfma_f32_16x16x32_bf16 v[36:39], v[146:149], v[94:97], v[36:39]
	v_mfma_f32_16x16x32_bf16 v[32:35], v[146:149], v[90:93], v[32:35]
	v_mfma_f32_16x16x32_bf16 v[28:31], v[102:105], v[142:145], v[28:31]
	v_mfma_f32_16x16x32_bf16 v[24:27], v[102:105], v[138:141], v[24:27]
	v_mfma_f32_16x16x32_bf16 v[20:23], v[102:105], v[94:97], v[20:23]
	v_mfma_f32_16x16x32_bf16 v[16:19], v[102:105], v[90:93], v[16:19]
	v_mfma_f32_16x16x32_bf16 v[12:15], v[98:101], v[142:145], v[12:15]
	v_mfma_f32_16x16x32_bf16 v[8:11], v[98:101], v[138:141], v[8:11]
	s_waitcnt lgkmcnt(1)
	v_mfma_f32_16x16x32_bf16 v[4:7], v[224:227], v[228:231], v[4:7]
	s_waitcnt lgkmcnt(0)
	v_mfma_f32_16x16x32_bf16 v[0:3], v[224:227], v[232:235], v[0:3]
	v_mfma_f32_16x16x32_bf16 v[60:63], v[204:207], v[212:215], v[60:63]
	v_mfma_f32_16x16x32_bf16 v[56:59], v[204:207], v[216:219], v[56:59]
	v_mfma_f32_16x16x32_bf16 v[52:55], v[204:207], v[228:231], v[52:55]
	v_mfma_f32_16x16x32_bf16 v[48:51], v[204:207], v[232:235], v[48:51]
	v_mfma_f32_16x16x32_bf16 v[44:47], v[208:211], v[212:215], v[44:47]
	v_mfma_f32_16x16x32_bf16 v[40:43], v[208:211], v[216:219], v[40:43]
	v_mfma_f32_16x16x32_bf16 v[36:39], v[208:211], v[228:231], v[36:39]
	v_mfma_f32_16x16x32_bf16 v[32:35], v[208:211], v[232:235], v[32:35]
	v_mfma_f32_16x16x32_bf16 v[28:31], v[220:223], v[212:215], v[28:31]
	v_mfma_f32_16x16x32_bf16 v[24:27], v[220:223], v[216:219], v[24:27]
	v_mfma_f32_16x16x32_bf16 v[20:23], v[220:223], v[228:231], v[20:23]
	v_mfma_f32_16x16x32_bf16 v[16:19], v[220:223], v[232:235], v[16:19]
	v_mfma_f32_16x16x32_bf16 v[12:15], v[224:227], v[212:215], v[12:15]
	v_mfma_f32_16x16x32_bf16 v[8:11], v[224:227], v[216:219], v[8:11]
	s_setprio 0
	s_barrier
	ds_write2_b32 v116, v60, v56 offset1:16
	ds_write2_b32 v116, v61, v57 offset0:132 offset1:148
	v_add_u32_e32 v56, 0x400, v116
	ds_write2_b32 v56, v62, v58 offset0:8 offset1:24
	ds_write2_b32 v56, v63, v59 offset0:140 offset1:156
	ds_write2_b32 v116, v52, v48 offset0:32 offset1:48
	ds_write2_b32 v116, v53, v49 offset0:164 offset1:180
	ds_write2_b32 v56, v54, v50 offset0:40 offset1:56
	ds_write2_b32 v56, v55, v51 offset0:172 offset1:188
	v_add_u32_e32 v48, 0x2000, v116
	ds_write2_b32 v48, v44, v40 offset0:64 offset1:80
	ds_write2_b32 v48, v45, v41 offset0:196 offset1:212
	v_add_u32_e32 v40, 0x2400, v116
	ds_write2_b32 v40, v46, v42 offset0:72 offset1:88
	ds_write2_b32 v40, v47, v43 offset0:204 offset1:220
	ds_write2_b32 v48, v36, v32 offset0:96 offset1:112
	ds_write2_b32 v48, v37, v33 offset0:228 offset1:244
	ds_write2_b32 v40, v38, v34 offset0:104 offset1:120
	ds_write2_b32 v40, v39, v35 offset0:236 offset1:252
	v_add_u32_e32 v32, 0x4000, v116
	ds_write2_b32 v32, v28, v24 offset0:128 offset1:144
	v_add_u32_e32 v24, 0x4400, v116
	ds_write2_b32 v24, v29, v25 offset0:4 offset1:20
	ds_write2_b32 v24, v30, v26 offset0:136 offset1:152
	v_add_u32_e32 v25, 0x4800, v116
	ds_write2_b32 v25, v31, v27 offset0:12 offset1:28
	ds_write2_b32 v32, v20, v16 offset0:160 offset1:176
	ds_write2_b32 v24, v21, v17 offset0:36 offset1:52
	ds_write2_b32 v24, v22, v18 offset0:168 offset1:184
	ds_write2_b32 v25, v23, v19 offset0:44 offset1:60
	v_add_u32_e32 v16, 0x6000, v116
	ds_write2_b32 v16, v12, v8 offset0:192 offset1:208
	v_add_u32_e32 v8, 0x6400, v116
	ds_write2_b32 v8, v13, v9 offset0:68 offset1:84
	ds_write2_b32 v8, v14, v10 offset0:200 offset1:216
	v_add_u32_e32 v9, 0x6800, v116
	ds_write2_b32 v9, v15, v11 offset0:76 offset1:92
	ds_write2_b32 v16, v4, v0 offset0:224 offset1:240
	ds_write2_b32 v8, v5, v1 offset0:100 offset1:116
	ds_write2_b32 v8, v6, v2 offset0:232 offset1:248
	ds_write2_b32 v9, v7, v3 offset0:108 offset1:124
	v_or_b32_e32 v0, s25, v117
	v_ashrrev_i32_e32 v1, 31, v0
	v_lshlrev_b64 v[2:3], 2, v[0:1]
	v_lshl_add_u64 v[0:1], s[14:15], 0, v[2:3]
	v_lshl_add_u64 v[2:3], s[12:13], 0, v[2:3]
	v_add_u32_e32 v4, s24, v128
	s_mov_b32 s16, 0
	s_waitcnt lgkmcnt(0)
	s_barrier

.LBB0_2085:
	s_and_b32 s28, s27, 0x4000
	s_xor_b32 s29, s28, 0x4000
	s_lshl_b32 s29, s29, 1
	s_add_i32 s29, s29, 32
	s_add_u32 s90, s52, s16
	s_addc_u32 s91, s53, s17
	s_add_i32 m0, s29, s82
	s_lshl_b32 s28, s28, 1
	global_load_lds_dwordx4 v192, s[90:91]
	s_add_i32 m0, s29, s83
	s_add_i32 s28, s28, 32
	global_load_lds_dwordx4 v193, s[90:91]
	s_add_i32 m0, s29, s84
	v_add3_u32 v139, s28, v113, v136
	global_load_lds_dwordx4 v194, s[90:91]
	s_add_i32 m0, s29, s85
	v_add3_u32 v172, s28, v114, v136
	global_load_lds_dwordx4 v195, s[90:91]
	s_add_i32 m0, s29, s86
	v_add_u32_e32 v160, v139, v137
	global_load_lds_dwordx4 v196, s[90:91]
	s_add_i32 m0, s29, s87
	v_add_u32_e32 v168, v172, v137
	global_load_lds_dwordx4 v197, s[90:91]
	s_add_i32 m0, s29, s88
	s_addk_i32 s27, 0x4000
	global_load_lds_dwordx4 v198, s[90:91]
	s_add_i32 m0, s29, s89
	s_add_u32 s16, s16, 0x80
	s_addc_u32 s17, s17, 0
	global_load_lds_dwordx4 v199, s[90:91]
	ds_read_b128 v[140:143], v160
	ds_read_b128 v[148:151], v168 offset:16384
	ds_read_b128 v[152:155], v168 offset:18432
	ds_read_b128 v[164:167], v168 offset:20480
	ds_read_b128 v[168:171], v168 offset:22528
	ds_read_b128 v[144:147], v160 offset:2048
	ds_read_b128 v[156:159], v160 offset:4096
	ds_read_b128 v[160:163], v160 offset:6144
	v_add_u32_e32 v139, v139, v138
	v_add_u32_e32 v236, v172, v138
	ds_read_b128 v[204:207], v139
	ds_read_b128 v[208:211], v236 offset:16384
	ds_read_b128 v[212:215], v236 offset:18432
	ds_read_b128 v[216:219], v236 offset:20480
	ds_read_b128 v[220:223], v236 offset:22528
	ds_read_b128 v[224:227], v139 offset:2048
	ds_read_b128 v[228:231], v139 offset:4096
	ds_read_b128 v[232:235], v139 offset:6144
	s_setprio 1
	s_waitcnt lgkmcnt(11)
	v_mfma_f32_16x16x32_bf16 v[60:63], v[140:143], v[148:151], v[60:63]
	v_mfma_f32_16x16x32_bf16 v[56:59], v[140:143], v[152:155], v[56:59]
	v_mfma_f32_16x16x32_bf16 v[52:55], v[140:143], v[164:167], v[52:55]
	v_mfma_f32_16x16x32_bf16 v[48:51], v[140:143], v[168:171], v[48:51]
	s_waitcnt lgkmcnt(10)
	v_mfma_f32_16x16x32_bf16 v[44:47], v[144:147], v[148:151], v[44:47]
	v_mfma_f32_16x16x32_bf16 v[40:43], v[144:147], v[152:155], v[40:43]
	v_mfma_f32_16x16x32_bf16 v[36:39], v[144:147], v[164:167], v[36:39]
	v_mfma_f32_16x16x32_bf16 v[32:35], v[144:147], v[168:171], v[32:35]
	s_waitcnt lgkmcnt(9)
	v_mfma_f32_16x16x32_bf16 v[28:31], v[156:159], v[148:151], v[28:31]
	v_mfma_f32_16x16x32_bf16 v[24:27], v[156:159], v[152:155], v[24:27]
	v_mfma_f32_16x16x32_bf16 v[20:23], v[156:159], v[164:167], v[20:23]
	v_mfma_f32_16x16x32_bf16 v[16:19], v[156:159], v[168:171], v[16:19]
	s_waitcnt lgkmcnt(8)
	v_mfma_f32_16x16x32_bf16 v[12:15], v[160:163], v[148:151], v[12:15]
	v_mfma_f32_16x16x32_bf16 v[8:11], v[160:163], v[152:155], v[8:11]
	v_mfma_f32_16x16x32_bf16 v[4:7], v[160:163], v[164:167], v[4:7]
	v_mfma_f32_16x16x32_bf16 v[0:3], v[160:163], v[168:171], v[0:3]
	s_waitcnt lgkmcnt(3)
	v_mfma_f32_16x16x32_bf16 v[60:63], v[204:207], v[208:211], v[60:63]
	v_mfma_f32_16x16x32_bf16 v[56:59], v[204:207], v[212:215], v[56:59]
	v_mfma_f32_16x16x32_bf16 v[52:55], v[204:207], v[216:219], v[52:55]
	v_mfma_f32_16x16x32_bf16 v[48:51], v[204:207], v[220:223], v[48:51]
	s_waitcnt lgkmcnt(2)
	v_mfma_f32_16x16x32_bf16 v[44:47], v[224:227], v[208:211], v[44:47]
	v_mfma_f32_16x16x32_bf16 v[40:43], v[224:227], v[212:215], v[40:43]
	v_mfma_f32_16x16x32_bf16 v[36:39], v[224:227], v[216:219], v[36:39]
	v_mfma_f32_16x16x32_bf16 v[32:35], v[224:227], v[220:223], v[32:35]
	s_waitcnt lgkmcnt(1)
	v_mfma_f32_16x16x32_bf16 v[28:31], v[228:231], v[208:211], v[28:31]
	v_mfma_f32_16x16x32_bf16 v[24:27], v[228:231], v[212:215], v[24:27]
	v_mfma_f32_16x16x32_bf16 v[20:23], v[228:231], v[216:219], v[20:23]
	v_mfma_f32_16x16x32_bf16 v[16:19], v[228:231], v[220:223], v[16:19]
	s_waitcnt lgkmcnt(0)
	v_mfma_f32_16x16x32_bf16 v[12:15], v[232:235], v[208:211], v[12:15]
	v_mfma_f32_16x16x32_bf16 v[8:11], v[232:235], v[212:215], v[8:11]
	v_mfma_f32_16x16x32_bf16 v[4:7], v[232:235], v[216:219], v[4:7]
	v_mfma_f32_16x16x32_bf16 v[0:3], v[232:235], v[220:223], v[0:3]
	s_setprio 0
	s_cmpk_eq_i32 s16, 0x1f80
	s_waitcnt vmcnt(0)
	s_barrier
	s_cbranch_scc0 .LBB0_2085
	ds_read_b128 v[88:91], v117 offset:55296
	ds_read_b128 v[92:95], v117 offset:53248
	ds_read_b128 v[96:99], v118 offset:38912
	ds_read_b128 v[100:103], v118 offset:36864
	ds_read_b128 v[140:143], v117 offset:51200
	ds_read_b128 v[144:147], v117 offset:49152
	ds_read_b128 v[148:151], v118 offset:34816
	ds_read_b128 v[152:155], v118 offset:32768
	ds_read_b128 v[204:207], v119 offset:32768
	ds_read_b128 v[208:211], v119 offset:34816
	ds_read_b128 v[212:215], v120 offset:49152
	ds_read_b128 v[216:219], v120 offset:51200
	ds_read_b128 v[220:223], v119 offset:36864
	ds_read_b128 v[224:227], v119 offset:38912
	ds_read_b128 v[228:231], v120 offset:53248
	ds_read_b128 v[232:235], v120 offset:55296
	s_setprio 1
	s_waitcnt lgkmcnt(13)
	v_mfma_f32_16x16x32_bf16 v[4:7], v[96:99], v[92:95], v[4:7]
	v_mfma_f32_16x16x32_bf16 v[0:3], v[96:99], v[88:91], v[0:3]
	s_waitcnt lgkmcnt(8)
	v_mfma_f32_16x16x32_bf16 v[60:63], v[152:155], v[144:147], v[60:63]
	v_mfma_f32_16x16x32_bf16 v[56:59], v[152:155], v[140:143], v[56:59]
	v_mfma_f32_16x16x32_bf16 v[52:55], v[152:155], v[92:95], v[52:55]
	v_mfma_f32_16x16x32_bf16 v[48:51], v[152:155], v[88:91], v[48:51]
	v_mfma_f32_16x16x32_bf16 v[44:47], v[148:151], v[144:147], v[44:47]
	v_mfma_f32_16x16x32_bf16 v[40:43], v[148:151], v[140:143], v[40:43]
	v_mfma_f32_16x16x32_bf16 v[36:39], v[148:151], v[92:95], v[36:39]
	v_mfma_f32_16x16x32_bf16 v[32:35], v[148:151], v[88:91], v[32:35]
	v_mfma_f32_16x16x32_bf16 v[28:31], v[100:103], v[144:147], v[28:31]
	v_mfma_f32_16x16x32_bf16 v[24:27], v[100:103], v[140:143], v[24:27]
	v_mfma_f32_16x16x32_bf16 v[20:23], v[100:103], v[92:95], v[20:23]
	v_mfma_f32_16x16x32_bf16 v[16:19], v[100:103], v[88:91], v[16:19]
	v_mfma_f32_16x16x32_bf16 v[12:15], v[96:99], v[144:147], v[12:15]
	v_mfma_f32_16x16x32_bf16 v[8:11], v[96:99], v[140:143], v[8:11]
	s_waitcnt lgkmcnt(1)
	v_mfma_f32_16x16x32_bf16 v[4:7], v[224:227], v[228:231], v[4:7]
	s_waitcnt lgkmcnt(0)
	v_mfma_f32_16x16x32_bf16 v[0:3], v[224:227], v[232:235], v[0:3]
	v_mfma_f32_16x16x32_bf16 v[60:63], v[204:207], v[212:215], v[60:63]
	v_mfma_f32_16x16x32_bf16 v[56:59], v[204:207], v[216:219], v[56:59]
	v_mfma_f32_16x16x32_bf16 v[52:55], v[204:207], v[228:231], v[52:55]
	v_mfma_f32_16x16x32_bf16 v[48:51], v[204:207], v[232:235], v[48:51]
	v_mfma_f32_16x16x32_bf16 v[44:47], v[208:211], v[212:215], v[44:47]
	v_mfma_f32_16x16x32_bf16 v[40:43], v[208:211], v[216:219], v[40:43]
	v_mfma_f32_16x16x32_bf16 v[36:39], v[208:211], v[228:231], v[36:39]
	v_mfma_f32_16x16x32_bf16 v[32:35], v[208:211], v[232:235], v[32:35]
	v_mfma_f32_16x16x32_bf16 v[28:31], v[220:223], v[212:215], v[28:31]
	v_mfma_f32_16x16x32_bf16 v[24:27], v[220:223], v[216:219], v[24:27]
	v_mfma_f32_16x16x32_bf16 v[20:23], v[220:223], v[228:231], v[20:23]
	v_mfma_f32_16x16x32_bf16 v[16:19], v[220:223], v[232:235], v[16:19]
	v_mfma_f32_16x16x32_bf16 v[12:15], v[224:227], v[212:215], v[12:15]
	v_mfma_f32_16x16x32_bf16 v[8:11], v[224:227], v[216:219], v[8:11]
	s_setprio 0
	s_barrier
	ds_write2_b32 v115, v60, v56 offset1:16
	ds_write2_b32 v115, v61, v57 offset0:132 offset1:148
	v_add_u32_e32 v56, 0x400, v115
	ds_write2_b32 v56, v62, v58 offset0:8 offset1:24
	ds_write2_b32 v56, v63, v59 offset0:140 offset1:156
	ds_write2_b32 v115, v52, v48 offset0:32 offset1:48
	ds_write2_b32 v115, v53, v49 offset0:164 offset1:180
	ds_write2_b32 v56, v54, v50 offset0:40 offset1:56
	ds_write2_b32 v56, v55, v51 offset0:172 offset1:188
	v_add_u32_e32 v48, 0x2000, v115
	ds_write2_b32 v48, v44, v40 offset0:64 offset1:80
	ds_write2_b32 v48, v45, v41 offset0:196 offset1:212
	v_add_u32_e32 v40, 0x2400, v115
	ds_write2_b32 v40, v46, v42 offset0:72 offset1:88
	ds_write2_b32 v40, v47, v43 offset0:204 offset1:220
	ds_write2_b32 v48, v36, v32 offset0:96 offset1:112
	ds_write2_b32 v48, v37, v33 offset0:228 offset1:244
	ds_write2_b32 v40, v38, v34 offset0:104 offset1:120
	ds_write2_b32 v40, v39, v35 offset0:236 offset1:252
	v_add_u32_e32 v32, 0x4000, v115
	ds_write2_b32 v32, v28, v24 offset0:128 offset1:144
	v_add_u32_e32 v24, 0x4400, v115
	ds_write2_b32 v24, v29, v25 offset0:4 offset1:20
	ds_write2_b32 v24, v30, v26 offset0:136 offset1:152
	v_add_u32_e32 v25, 0x4800, v115
	ds_write2_b32 v25, v31, v27 offset0:12 offset1:28
	ds_write2_b32 v32, v20, v16 offset0:160 offset1:176
	ds_write2_b32 v24, v21, v17 offset0:36 offset1:52
	ds_write2_b32 v24, v22, v18 offset0:168 offset1:184
	ds_write2_b32 v25, v23, v19 offset0:44 offset1:60
	v_add_u32_e32 v16, 0x6000, v115
	ds_write2_b32 v16, v12, v8 offset0:192 offset1:208
	v_add_u32_e32 v8, 0x6400, v115
	ds_write2_b32 v8, v13, v9 offset0:68 offset1:84
	ds_write2_b32 v8, v14, v10 offset0:200 offset1:216
	v_add_u32_e32 v9, 0x6800, v115
	ds_write2_b32 v9, v15, v11 offset0:76 offset1:92
	ds_write2_b32 v16, v4, v0 offset0:224 offset1:240
	ds_write2_b32 v8, v5, v1 offset0:100 offset1:116
	ds_write2_b32 v8, v6, v2 offset0:232 offset1:248
	ds_write2_b32 v9, v7, v3 offset0:108 offset1:124
	v_or_b32_e32 v0, s25, v116
	v_ashrrev_i32_e32 v1, 31, v0
	v_lshlrev_b64 v[2:3], 2, v[0:1]
	v_lshl_add_u64 v[0:1], s[14:15], 0, v[2:3]
	v_lshl_add_u64 v[2:3], s[12:13], 0, v[2:3]
	v_add_u32_e32 v4, s26, v129
	s_mov_b32 s16, 0
	s_waitcnt lgkmcnt(0)
	s_barrier

.LBB0_2096:
	s_and_b32 s29, s28, 0x4000
	s_xor_b32 s30, s29, 0x4000
	s_lshl_b32 s30, s30, 1
	s_add_i32 s30, s30, 32
	s_add_u32 s90, s52, s16
	s_addc_u32 s91, s53, s17
	s_add_i32 m0, s30, s82
	s_lshl_b32 s29, s29, 1
	global_load_lds_dwordx4 v193, s[90:91]
	s_add_i32 m0, s30, s83
	s_add_i32 s29, s29, 32
	global_load_lds_dwordx4 v194, s[90:91]
	s_add_i32 m0, s30, s84
	v_lshlrev_b32_e32 v72, 1, v131
	global_load_lds_dwordx4 v195, s[90:91]
	s_add_i32 m0, s30, s85
	v_add3_u32 v178, s29, v129, v72
	global_load_lds_dwordx4 v196, s[90:91]
	s_add_i32 m0, s30, s86
	v_lshlrev_b32_e32 v154, 1, v121
	global_load_lds_dwordx4 v197, s[90:91]
	s_add_i32 m0, s30, s87
	v_add3_u32 v72, s29, v130, v72
	global_load_lds_dwordx4 v198, s[90:91]
	s_add_i32 m0, s30, s88
	v_add_u32_e32 v174, v178, v154
	global_load_lds_dwordx4 v199, s[90:91]
	s_add_i32 m0, s30, s89
	v_add_u32_e32 v179, v72, v154
	global_load_lds_dwordx4 v200, s[90:91]
	ds_read_b128 v[154:157], v174
	ds_read_b128 v[162:165], v179 offset:16384
	ds_read_b128 v[166:169], v179 offset:18432
	ds_read_b128 v[182:185], v179 offset:20480
	ds_read_b128 v[186:189], v179 offset:22528
	ds_read_b128 v[158:161], v174 offset:2048
	ds_read_b128 v[170:173], v174 offset:4096
	ds_read_b128 v[174:177], v174 offset:6144
	v_lshlrev_b32_e32 v236, 1, v122
	v_add_u32_e32 v237, v178, v236
	v_add_u32_e32 v72, v72, v236
	ds_read_b128 v[204:207], v237
	ds_read_b128 v[208:211], v72 offset:16384
	ds_read_b128 v[212:215], v72 offset:18432
	ds_read_b128 v[216:219], v72 offset:20480
	ds_read_b128 v[220:223], v72 offset:22528
	ds_read_b128 v[224:227], v237 offset:2048
	ds_read_b128 v[228:231], v237 offset:4096
	ds_read_b128 v[232:235], v237 offset:6144
	s_setprio 1
	s_waitcnt lgkmcnt(11)
	v_mfma_f32_16x16x32_bf16 v[60:63], v[154:157], v[162:165], v[60:63]
	v_mfma_f32_16x16x32_bf16 v[56:59], v[154:157], v[166:169], v[56:59]
	v_mfma_f32_16x16x32_bf16 v[52:55], v[154:157], v[182:185], v[52:55]
	v_mfma_f32_16x16x32_bf16 v[48:51], v[154:157], v[186:189], v[48:51]
	s_waitcnt lgkmcnt(10)
	v_mfma_f32_16x16x32_bf16 v[44:47], v[158:161], v[162:165], v[44:47]
	v_mfma_f32_16x16x32_bf16 v[40:43], v[158:161], v[166:169], v[40:43]
	v_mfma_f32_16x16x32_bf16 v[36:39], v[158:161], v[182:185], v[36:39]
	v_mfma_f32_16x16x32_bf16 v[32:35], v[158:161], v[186:189], v[32:35]
	s_waitcnt lgkmcnt(9)
	v_mfma_f32_16x16x32_bf16 v[28:31], v[170:173], v[162:165], v[28:31]
	v_mfma_f32_16x16x32_bf16 v[24:27], v[170:173], v[166:169], v[24:27]
	v_mfma_f32_16x16x32_bf16 v[20:23], v[170:173], v[182:185], v[20:23]
	v_mfma_f32_16x16x32_bf16 v[16:19], v[170:173], v[186:189], v[16:19]
	s_waitcnt lgkmcnt(8)
	v_mfma_f32_16x16x32_bf16 v[12:15], v[174:177], v[162:165], v[12:15]
	v_mfma_f32_16x16x32_bf16 v[8:11], v[174:177], v[166:169], v[8:11]
	v_mfma_f32_16x16x32_bf16 v[4:7], v[174:177], v[182:185], v[4:7]
	v_mfma_f32_16x16x32_bf16 v[0:3], v[174:177], v[186:189], v[0:3]
	s_waitcnt lgkmcnt(3)
	v_mfma_f32_16x16x32_bf16 v[60:63], v[204:207], v[208:211], v[60:63]
	v_mfma_f32_16x16x32_bf16 v[56:59], v[204:207], v[212:215], v[56:59]
	v_mfma_f32_16x16x32_bf16 v[52:55], v[204:207], v[216:219], v[52:55]
	v_mfma_f32_16x16x32_bf16 v[48:51], v[204:207], v[220:223], v[48:51]
	s_waitcnt lgkmcnt(2)
	v_mfma_f32_16x16x32_bf16 v[44:47], v[224:227], v[208:211], v[44:47]
	v_mfma_f32_16x16x32_bf16 v[40:43], v[224:227], v[212:215], v[40:43]
	v_mfma_f32_16x16x32_bf16 v[36:39], v[224:227], v[216:219], v[36:39]
	v_mfma_f32_16x16x32_bf16 v[32:35], v[224:227], v[220:223], v[32:35]
	s_waitcnt lgkmcnt(1)
	v_mfma_f32_16x16x32_bf16 v[28:31], v[228:231], v[208:211], v[28:31]
	v_mfma_f32_16x16x32_bf16 v[24:27], v[228:231], v[212:215], v[24:27]
	v_mfma_f32_16x16x32_bf16 v[20:23], v[228:231], v[216:219], v[20:23]
	v_mfma_f32_16x16x32_bf16 v[16:19], v[228:231], v[220:223], v[16:19]
	s_waitcnt lgkmcnt(0)
	v_mfma_f32_16x16x32_bf16 v[12:15], v[232:235], v[208:211], v[12:15]
	v_mfma_f32_16x16x32_bf16 v[8:11], v[232:235], v[212:215], v[8:11]
	v_mfma_f32_16x16x32_bf16 v[4:7], v[232:235], v[216:219], v[4:7]
	v_mfma_f32_16x16x32_bf16 v[0:3], v[232:235], v[220:223], v[0:3]
	s_setprio 0
	s_add_u32 s16, s16, 0x80
	s_addc_u32 s17, s17, 0
	s_addk_i32 s28, 0x4000
	s_cmpk_eq_i32 s16, 0x1f80
	s_waitcnt vmcnt(0)
	s_barrier
	s_cbranch_scc0 .LBB0_2096
	ds_read_b128 v[98:101], v71 offset:32768
	ds_read_b128 v[102:105], v71 offset:34816
	ds_read_b128 v[106:109], v138 offset:49152
	ds_read_b128 v[110:113], v138 offset:51200
	ds_read_b128 v[154:157], v71 offset:36864
	ds_read_b128 v[158:161], v71 offset:38912
	ds_read_b128 v[162:165], v138 offset:53248
	ds_read_b128 v[166:169], v138 offset:55296
	ds_read_b128 v[204:207], v139 offset:32768
	ds_read_b128 v[208:211], v139 offset:34816
	ds_read_b128 v[212:215], v140 offset:49152
	ds_read_b128 v[216:219], v140 offset:51200
	ds_read_b128 v[220:223], v139 offset:36864
	ds_read_b128 v[224:227], v139 offset:38912
	ds_read_b128 v[228:231], v140 offset:53248
	ds_read_b128 v[232:235], v140 offset:55296
	s_setprio 1
	s_waitcnt lgkmcnt(9)
	v_mfma_f32_16x16x32_bf16 v[4:7], v[158:161], v[162:165], v[4:7]
	s_waitcnt lgkmcnt(8)
	v_mfma_f32_16x16x32_bf16 v[0:3], v[158:161], v[166:169], v[0:3]
	v_mfma_f32_16x16x32_bf16 v[60:63], v[98:101], v[106:109], v[60:63]
	v_mfma_f32_16x16x32_bf16 v[56:59], v[98:101], v[110:113], v[56:59]
	v_mfma_f32_16x16x32_bf16 v[52:55], v[98:101], v[162:165], v[52:55]
	v_mfma_f32_16x16x32_bf16 v[48:51], v[98:101], v[166:169], v[48:51]
	v_mfma_f32_16x16x32_bf16 v[44:47], v[102:105], v[106:109], v[44:47]
	v_mfma_f32_16x16x32_bf16 v[40:43], v[102:105], v[110:113], v[40:43]
	v_mfma_f32_16x16x32_bf16 v[36:39], v[102:105], v[162:165], v[36:39]
	v_mfma_f32_16x16x32_bf16 v[32:35], v[102:105], v[166:169], v[32:35]
	v_mfma_f32_16x16x32_bf16 v[28:31], v[154:157], v[106:109], v[28:31]
	v_mfma_f32_16x16x32_bf16 v[24:27], v[154:157], v[110:113], v[24:27]
	v_mfma_f32_16x16x32_bf16 v[20:23], v[154:157], v[162:165], v[20:23]
	v_mfma_f32_16x16x32_bf16 v[16:19], v[154:157], v[166:169], v[16:19]
	v_mfma_f32_16x16x32_bf16 v[12:15], v[158:161], v[106:109], v[12:15]
	v_mfma_f32_16x16x32_bf16 v[8:11], v[158:161], v[110:113], v[8:11]
	s_waitcnt lgkmcnt(1)
	v_mfma_f32_16x16x32_bf16 v[4:7], v[224:227], v[228:231], v[4:7]
	s_waitcnt lgkmcnt(0)
	v_mfma_f32_16x16x32_bf16 v[0:3], v[224:227], v[232:235], v[0:3]
	v_mfma_f32_16x16x32_bf16 v[60:63], v[204:207], v[212:215], v[60:63]
	v_mfma_f32_16x16x32_bf16 v[56:59], v[204:207], v[216:219], v[56:59]
	v_mfma_f32_16x16x32_bf16 v[52:55], v[204:207], v[228:231], v[52:55]
	v_mfma_f32_16x16x32_bf16 v[48:51], v[204:207], v[232:235], v[48:51]
	v_mfma_f32_16x16x32_bf16 v[44:47], v[208:211], v[212:215], v[44:47]
	v_mfma_f32_16x16x32_bf16 v[40:43], v[208:211], v[216:219], v[40:43]
	v_mfma_f32_16x16x32_bf16 v[36:39], v[208:211], v[228:231], v[36:39]
	v_mfma_f32_16x16x32_bf16 v[32:35], v[208:211], v[232:235], v[32:35]
	v_mfma_f32_16x16x32_bf16 v[28:31], v[220:223], v[212:215], v[28:31]
	v_mfma_f32_16x16x32_bf16 v[24:27], v[220:223], v[216:219], v[24:27]
	v_mfma_f32_16x16x32_bf16 v[20:23], v[220:223], v[228:231], v[20:23]
	v_mfma_f32_16x16x32_bf16 v[16:19], v[220:223], v[232:235], v[16:19]
	v_mfma_f32_16x16x32_bf16 v[12:15], v[224:227], v[212:215], v[12:15]
	v_mfma_f32_16x16x32_bf16 v[8:11], v[224:227], v[216:219], v[8:11]
	s_setprio 0
	s_barrier
	ds_write2_b32 v136, v60, v56 offset1:16
	ds_write2_b32 v136, v61, v57 offset0:132 offset1:148
	v_add_u32_e32 v56, 0x400, v136
	ds_write2_b32 v56, v62, v58 offset0:8 offset1:24
	ds_write2_b32 v56, v63, v59 offset0:140 offset1:156
	ds_write2_b32 v136, v52, v48 offset0:32 offset1:48
	ds_write2_b32 v136, v53, v49 offset0:164 offset1:180
	ds_write2_b32 v56, v54, v50 offset0:40 offset1:56
	ds_write2_b32 v56, v55, v51 offset0:172 offset1:188
	v_add_u32_e32 v48, 0x2000, v136
	ds_write2_b32 v48, v44, v40 offset0:64 offset1:80
	ds_write2_b32 v48, v45, v41 offset0:196 offset1:212
	v_add_u32_e32 v40, 0x2400, v136
	ds_write2_b32 v40, v46, v42 offset0:72 offset1:88
	ds_write2_b32 v40, v47, v43 offset0:204 offset1:220
	ds_write2_b32 v48, v36, v32 offset0:96 offset1:112
	ds_write2_b32 v48, v37, v33 offset0:228 offset1:244
	ds_write2_b32 v40, v38, v34 offset0:104 offset1:120
	ds_write2_b32 v40, v39, v35 offset0:236 offset1:252
	v_add_u32_e32 v32, 0x4000, v136
	ds_write2_b32 v32, v28, v24 offset0:128 offset1:144
	v_add_u32_e32 v24, 0x4400, v136
	ds_write2_b32 v24, v29, v25 offset0:4 offset1:20
	ds_write2_b32 v24, v30, v26 offset0:136 offset1:152
	v_add_u32_e32 v25, 0x4800, v136
	ds_write2_b32 v25, v31, v27 offset0:12 offset1:28
	ds_write2_b32 v32, v20, v16 offset0:160 offset1:176
	ds_write2_b32 v24, v21, v17 offset0:36 offset1:52
	ds_write2_b32 v24, v22, v18 offset0:168 offset1:184
	ds_write2_b32 v25, v23, v19 offset0:44 offset1:60
	v_add_u32_e32 v16, 0x6000, v136
	ds_write2_b32 v16, v12, v8 offset0:192 offset1:208
	v_add_u32_e32 v8, 0x6400, v136
	ds_write2_b32 v8, v13, v9 offset0:68 offset1:84
	ds_write2_b32 v8, v14, v10 offset0:200 offset1:216
	v_add_u32_e32 v9, 0x6800, v136
	ds_write2_b32 v9, v15, v11 offset0:76 offset1:92
	ds_write2_b32 v16, v4, v0 offset0:224 offset1:240
	ds_write2_b32 v8, v5, v1 offset0:100 offset1:116
	ds_write2_b32 v8, v6, v2 offset0:232 offset1:248
	ds_write2_b32 v9, v7, v3 offset0:108 offset1:124
	v_or_b32_e32 v0, s26, v137
	v_lshlrev_b32_e32 v72, 2, v0
	v_lshl_add_u64 v[0:1], s[14:15], 0, v[72:73]
	v_lshl_add_u64 v[2:3], s[12:13], 0, v[72:73]
	v_add_u32_e32 v4, s27, v149
	s_mov_b32 s16, 0
	s_waitcnt lgkmcnt(0)
	s_barrier

.LBB0_2102:
	s_and_b32 s8, s13, 0x4000
	s_xor_b32 s9, s8, 0x4000
	s_lshl_b32 s9, s9, 1
	s_add_i32 s9, s9, 32
	s_add_u32 s90, s52, s6
	s_addc_u32 s91, s53, s7
	s_add_i32 m0, s9, s82
	s_lshl_b32 s8, s8, 1
	global_load_lds_dwordx4 v192, s[90:91]
	s_add_i32 m0, s9, s83
	s_add_i32 s8, s8, 32
	global_load_lds_dwordx4 v193, s[90:91]
	s_add_i32 m0, s9, s84
	v_lshlrev_b32_e32 v85, 1, v80
	global_load_lds_dwordx4 v194, s[90:91]
	s_add_i32 m0, s9, s85
	v_add3_u32 v112, s8, v81, v85
	global_load_lds_dwordx4 v195, s[90:91]
	s_add_i32 m0, s9, s86
	v_lshlrev_b32_e32 v86, 1, v121
	global_load_lds_dwordx4 v196, s[90:91]
	s_add_i32 m0, s9, s87
	v_add3_u32 v113, s8, v82, v85
	global_load_lds_dwordx4 v197, s[90:91]
	s_add_i32 m0, s9, s88
	v_add_u32_e32 v87, v112, v86
	global_load_lds_dwordx4 v198, s[90:91]
	s_add_i32 m0, s9, s89
	v_add_u32_e32 v123, v113, v86
	global_load_lds_dwordx4 v199, s[90:91]
	ds_read_b128 v[88:91], v87
	ds_read_b128 v[96:99], v123 offset:16384
	ds_read_b128 v[100:103], v123 offset:18432
	ds_read_b128 v[124:127], v123 offset:20480
	ds_read_b128 v[128:131], v123 offset:22528
	ds_read_b128 v[92:95], v87 offset:2048
	ds_read_b128 v[104:107], v87 offset:4096
	ds_read_b128 v[108:111], v87 offset:6144
	v_lshlrev_b32_e32 v87, 1, v122
	v_add_u32_e32 v236, v112, v87
	v_add_u32_e32 v112, v113, v87
	ds_read_b128 v[204:207], v236
	ds_read_b128 v[208:211], v112 offset:16384
	ds_read_b128 v[212:215], v112 offset:18432
	ds_read_b128 v[216:219], v112 offset:20480
	ds_read_b128 v[220:223], v112 offset:22528
	ds_read_b128 v[224:227], v236 offset:2048
	ds_read_b128 v[228:231], v236 offset:4096
	ds_read_b128 v[232:235], v236 offset:6144
	s_setprio 1
	s_waitcnt lgkmcnt(11)
	v_mfma_f32_16x16x32_bf16 v[60:63], v[88:91], v[96:99], v[60:63]
	v_mfma_f32_16x16x32_bf16 v[56:59], v[88:91], v[100:103], v[56:59]
	v_mfma_f32_16x16x32_bf16 v[52:55], v[88:91], v[124:127], v[52:55]
	v_mfma_f32_16x16x32_bf16 v[48:51], v[88:91], v[128:131], v[48:51]
	s_waitcnt lgkmcnt(10)
	v_mfma_f32_16x16x32_bf16 v[44:47], v[92:95], v[96:99], v[44:47]
	v_mfma_f32_16x16x32_bf16 v[40:43], v[92:95], v[100:103], v[40:43]
	v_mfma_f32_16x16x32_bf16 v[36:39], v[92:95], v[124:127], v[36:39]
	v_mfma_f32_16x16x32_bf16 v[32:35], v[92:95], v[128:131], v[32:35]
	s_waitcnt lgkmcnt(9)
	v_mfma_f32_16x16x32_bf16 v[28:31], v[104:107], v[96:99], v[28:31]
	v_mfma_f32_16x16x32_bf16 v[24:27], v[104:107], v[100:103], v[24:27]
	v_mfma_f32_16x16x32_bf16 v[20:23], v[104:107], v[124:127], v[20:23]
	v_mfma_f32_16x16x32_bf16 v[16:19], v[104:107], v[128:131], v[16:19]
	s_waitcnt lgkmcnt(8)
	v_mfma_f32_16x16x32_bf16 v[12:15], v[108:111], v[96:99], v[12:15]
	v_mfma_f32_16x16x32_bf16 v[8:11], v[108:111], v[100:103], v[8:11]
	v_mfma_f32_16x16x32_bf16 v[4:7], v[108:111], v[124:127], v[4:7]
	v_mfma_f32_16x16x32_bf16 v[0:3], v[108:111], v[128:131], v[0:3]
	s_waitcnt lgkmcnt(3)
	v_mfma_f32_16x16x32_bf16 v[60:63], v[204:207], v[208:211], v[60:63]
	v_mfma_f32_16x16x32_bf16 v[56:59], v[204:207], v[212:215], v[56:59]
	v_mfma_f32_16x16x32_bf16 v[52:55], v[204:207], v[216:219], v[52:55]
	v_mfma_f32_16x16x32_bf16 v[48:51], v[204:207], v[220:223], v[48:51]
	s_waitcnt lgkmcnt(2)
	v_mfma_f32_16x16x32_bf16 v[44:47], v[224:227], v[208:211], v[44:47]
	v_mfma_f32_16x16x32_bf16 v[40:43], v[224:227], v[212:215], v[40:43]
	v_mfma_f32_16x16x32_bf16 v[36:39], v[224:227], v[216:219], v[36:39]
	v_mfma_f32_16x16x32_bf16 v[32:35], v[224:227], v[220:223], v[32:35]
	s_waitcnt lgkmcnt(1)
	v_mfma_f32_16x16x32_bf16 v[28:31], v[228:231], v[208:211], v[28:31]
	v_mfma_f32_16x16x32_bf16 v[24:27], v[228:231], v[212:215], v[24:27]
	v_mfma_f32_16x16x32_bf16 v[20:23], v[228:231], v[216:219], v[20:23]
	v_mfma_f32_16x16x32_bf16 v[16:19], v[228:231], v[220:223], v[16:19]
	s_waitcnt lgkmcnt(0)
	v_mfma_f32_16x16x32_bf16 v[12:15], v[232:235], v[208:211], v[12:15]
	v_mfma_f32_16x16x32_bf16 v[8:11], v[232:235], v[212:215], v[8:11]
	v_mfma_f32_16x16x32_bf16 v[4:7], v[232:235], v[216:219], v[4:7]
	v_mfma_f32_16x16x32_bf16 v[0:3], v[232:235], v[220:223], v[0:3]
	s_setprio 0
	s_add_u32 s6, s6, 0x80
	s_addc_u32 s7, s7, 0
	s_addk_i32 s13, 0x4000
	s_cmpk_eq_i32 s6, 0x780
	s_waitcnt vmcnt(0)
	s_barrier
	s_cbranch_scc0 .LBB0_2102
	v_add3_u32 v84, 32, v81, v85
	v_add3_u32 v85, 32, v82, v85
	v_add_u32_e32 v88, v84, v86
	v_add_u32_e32 v86, v85, v86
	ds_read_b128 v[64:67], v88 offset:32768
	ds_read_b128 v[68:71], v88 offset:34816
	ds_read_b128 v[72:75], v86 offset:49152
	ds_read_b128 v[76:79], v86 offset:51200
	ds_read_b128 v[80:83], v88 offset:36864
	ds_read_b128 v[88:91], v88 offset:38912
	ds_read_b128 v[92:95], v86 offset:53248
	ds_read_b128 v[96:99], v86 offset:55296
	v_add_u32_e32 v84, v84, v87
	v_add_u32_e32 v236, v85, v87
	ds_read_b128 v[204:207], v84 offset:32768
	ds_read_b128 v[208:211], v84 offset:34816
	ds_read_b128 v[212:215], v236 offset:49152
	ds_read_b128 v[216:219], v236 offset:51200
	ds_read_b128 v[220:223], v84 offset:36864
	ds_read_b128 v[224:227], v84 offset:38912
	ds_read_b128 v[228:231], v236 offset:53248
	ds_read_b128 v[232:235], v236 offset:55296
	s_setprio 1
	s_waitcnt lgkmcnt(8)
	v_mfma_f32_16x16x32_bf16 v[0:3], v[88:91], v[96:99], v[0:3]
	v_mfma_f32_16x16x32_bf16 v[60:63], v[64:67], v[72:75], v[60:63]
	v_mfma_f32_16x16x32_bf16 v[56:59], v[64:67], v[76:79], v[56:59]
	v_mfma_f32_16x16x32_bf16 v[52:55], v[64:67], v[92:95], v[52:55]
	v_mfma_f32_16x16x32_bf16 v[48:51], v[64:67], v[96:99], v[48:51]
	v_mfma_f32_16x16x32_bf16 v[44:47], v[68:71], v[72:75], v[44:47]
	v_mfma_f32_16x16x32_bf16 v[40:43], v[68:71], v[76:79], v[40:43]
	v_mfma_f32_16x16x32_bf16 v[36:39], v[68:71], v[92:95], v[36:39]
	v_mfma_f32_16x16x32_bf16 v[32:35], v[68:71], v[96:99], v[32:35]
	v_mfma_f32_16x16x32_bf16 v[28:31], v[80:83], v[72:75], v[28:31]
	v_mfma_f32_16x16x32_bf16 v[24:27], v[80:83], v[76:79], v[24:27]
	v_mfma_f32_16x16x32_bf16 v[20:23], v[80:83], v[92:95], v[20:23]
	v_mfma_f32_16x16x32_bf16 v[16:19], v[80:83], v[96:99], v[16:19]
	v_mfma_f32_16x16x32_bf16 v[12:15], v[88:91], v[72:75], v[12:15]
	v_mfma_f32_16x16x32_bf16 v[8:11], v[88:91], v[76:79], v[8:11]
	v_mfma_f32_16x16x32_bf16 v[4:7], v[88:91], v[92:95], v[4:7]
	s_waitcnt lgkmcnt(0)
	v_mfma_f32_16x16x32_bf16 v[0:3], v[224:227], v[232:235], v[0:3]
	v_mfma_f32_16x16x32_bf16 v[60:63], v[204:207], v[212:215], v[60:63]
	v_mfma_f32_16x16x32_bf16 v[56:59], v[204:207], v[216:219], v[56:59]
	v_mfma_f32_16x16x32_bf16 v[52:55], v[204:207], v[228:231], v[52:55]
	v_mfma_f32_16x16x32_bf16 v[48:51], v[204:207], v[232:235], v[48:51]
	v_mfma_f32_16x16x32_bf16 v[44:47], v[208:211], v[212:215], v[44:47]
	v_mfma_f32_16x16x32_bf16 v[40:43], v[208:211], v[216:219], v[40:43]
	v_mfma_f32_16x16x32_bf16 v[36:39], v[208:211], v[228:231], v[36:39]
	v_mfma_f32_16x16x32_bf16 v[32:35], v[208:211], v[232:235], v[32:35]
	v_mfma_f32_16x16x32_bf16 v[28:31], v[220:223], v[212:215], v[28:31]
	v_mfma_f32_16x16x32_bf16 v[24:27], v[220:223], v[216:219], v[24:27]
	v_mfma_f32_16x16x32_bf16 v[20:23], v[220:223], v[228:231], v[20:23]
	v_mfma_f32_16x16x32_bf16 v[16:19], v[220:223], v[232:235], v[16:19]
	v_mfma_f32_16x16x32_bf16 v[12:15], v[224:227], v[212:215], v[12:15]
	v_mfma_f32_16x16x32_bf16 v[8:11], v[224:227], v[216:219], v[8:11]
	v_mfma_f32_16x16x32_bf16 v[4:7], v[224:227], v[228:231], v[4:7]
	s_setprio 0
	v_lshl_or_b32 v64, v114, 2, v116
	v_mul_u32_u24_e32 v64, 0x210, v64
	v_add3_u32 v64, v115, v117, v64
	s_barrier
	ds_write2_b32 v64, v60, v56 offset1:16
	ds_write2_b32 v64, v61, v57 offset0:132 offset1:148
	v_add_u32_e32 v56, 0x400, v64
	ds_write2_b32 v56, v62, v58 offset0:8 offset1:24
	ds_write2_b32 v56, v63, v59 offset0:140 offset1:156
	ds_write2_b32 v64, v52, v48 offset0:32 offset1:48
	ds_write2_b32 v64, v53, v49 offset0:164 offset1:180
	ds_write2_b32 v56, v54, v50 offset0:40 offset1:56
	ds_write2_b32 v56, v55, v51 offset0:172 offset1:188
	v_add_u32_e32 v48, 0x2000, v64
	ds_write2_b32 v48, v44, v40 offset0:64 offset1:80
	ds_write2_b32 v48, v45, v41 offset0:196 offset1:212
	v_add_u32_e32 v40, 0x2400, v64
	ds_write2_b32 v40, v46, v42 offset0:72 offset1:88
	ds_write2_b32 v40, v47, v43 offset0:204 offset1:220
	ds_write2_b32 v48, v36, v32 offset0:96 offset1:112
	ds_write2_b32 v48, v37, v33 offset0:228 offset1:244
	ds_write2_b32 v40, v38, v34 offset0:104 offset1:120
	ds_write2_b32 v40, v39, v35 offset0:236 offset1:252
	v_add_u32_e32 v32, 0x4000, v64
	ds_write2_b32 v32, v28, v24 offset0:128 offset1:144
	v_add_u32_e32 v24, 0x4400, v64
	ds_write2_b32 v24, v29, v25 offset0:4 offset1:20
	ds_write2_b32 v24, v30, v26 offset0:136 offset1:152
	v_add_u32_e32 v25, 0x4800, v64
	ds_write2_b32 v25, v31, v27 offset0:12 offset1:28
	ds_write2_b32 v32, v20, v16 offset0:160 offset1:176
	ds_write2_b32 v24, v21, v17 offset0:36 offset1:52
	ds_write2_b32 v24, v22, v18 offset0:168 offset1:184
	ds_write2_b32 v25, v23, v19 offset0:44 offset1:60
	v_add_u32_e32 v16, 0x6000, v64
	ds_write2_b32 v16, v12, v8 offset0:192 offset1:208
	v_add_u32_e32 v8, 0x6400, v64
	ds_write2_b32 v8, v13, v9 offset0:68 offset1:84
	ds_write2_b32 v8, v14, v10 offset0:200 offset1:216
	v_add_u32_e32 v9, 0x6800, v64
	ds_write2_b32 v9, v15, v11 offset0:76 offset1:92
	ds_write2_b32 v16, v4, v0 offset0:224 offset1:240
	ds_write2_b32 v8, v5, v1 offset0:100 offset1:116
	ds_write2_b32 v8, v6, v2 offset0:232 offset1:248
	ds_write2_b32 v9, v7, v3 offset0:108 offset1:124
	v_lshlrev_b32_e32 v0, 4, v180
	v_and_b32_e32 v0, 0x70, v0
	s_lshl_b32 s7, s16, 23
	v_or_b32_e32 v0, s11, v0
	s_add_u32 s8, s14, s7
	s_addc_u32 s9, s15, 0
	v_lshlrev_b32_e32 v0, 2, v0
	v_mov_b32_e32 v1, 0
	v_lshrrev_b32_e32 v2, 3, v180
	v_and_b32_e32 v4, 7, v180
	v_lshl_add_u64 v[0:1], s[8:9], 0, v[0:1]
	s_mov_b64 s[8:9], 0x11600000
	v_mul_u32_u24_e32 v3, 0x210, v2
	v_lshlrev_b32_e32 v4, 6, v4
	s_mov_b32 s6, 0
	v_lshl_add_u64 v[0:1], v[0:1], 0, s[8:9]
	v_add3_u32 v3, v3, v4, 32
	s_mov_b32 s7, 0x38e38e39
	s_mov_b32 s8, 0x1ffffee
	s_movk_i32 s9, 0xf800
	s_waitcnt lgkmcnt(0)
	s_barrier

.LBB0_2270:
	s_and_b32 s31, s30, 0x4000
	s_xor_b32 s34, s31, 0x4000
	s_lshl_b32 s34, s34, 1
	s_add_i32 s34, s34, 32
	s_add_u32 s90, s52, s8
	s_addc_u32 s91, s53, s9
	s_add_i32 m0, s34, s82
	s_lshl_b32 s31, s31, 1
	global_load_lds_dwordx4 v184, s[90:91]
	s_add_i32 m0, s34, s83
	s_add_i32 s31, s31, 32
	global_load_lds_dwordx4 v185, s[90:91]
	s_add_i32 m0, s34, s84
	v_lshl_add_u32 v64, v114, 1, s31
	global_load_lds_dwordx4 v186, s[90:91]
	s_add_i32 m0, s34, s85
	v_lshl_add_u32 v139, v115, 1, s31
	global_load_lds_dwordx4 v187, s[90:91]
	s_add_i32 m0, s34, s86
	v_add_u32_e32 v160, v64, v136
	global_load_lds_dwordx4 v188, s[90:91]
	s_add_i32 m0, s34, s87
	v_add_u32_e32 v168, v139, v136
	global_load_lds_dwordx4 v189, s[90:91]
	s_add_i32 m0, s34, s88
	s_addk_i32 s30, 0x4000
	global_load_lds_dwordx4 v190, s[90:91]
	s_add_i32 m0, s34, s89
	s_add_u32 s8, s8, 0x80
	s_addc_u32 s9, s9, 0
	global_load_lds_dwordx4 v191, s[90:91]
	ds_read_b128 v[140:143], v160
	ds_read_b128 v[148:151], v168 offset:16384
	ds_read_b128 v[152:155], v168 offset:18432
	ds_read_b128 v[164:167], v168 offset:20480
	ds_read_b128 v[168:171], v168 offset:22528
	ds_read_b128 v[144:147], v160 offset:2048
	ds_read_b128 v[156:159], v160 offset:4096
	ds_read_b128 v[160:163], v160 offset:6144
	v_add_u32_e32 v64, v64, v137
	v_add_u32_e32 v139, v139, v137
	ds_read_b128 v[204:207], v64
	ds_read_b128 v[208:211], v139 offset:16384
	ds_read_b128 v[212:215], v139 offset:18432
	ds_read_b128 v[216:219], v139 offset:20480
	ds_read_b128 v[220:223], v139 offset:22528
	ds_read_b128 v[224:227], v64 offset:2048
	ds_read_b128 v[228:231], v64 offset:4096
	ds_read_b128 v[232:235], v64 offset:6144
	s_setprio 1
	s_waitcnt lgkmcnt(11)
	v_mfma_f32_16x16x32_bf16 v[60:63], v[140:143], v[148:151], v[60:63]
	v_mfma_f32_16x16x32_bf16 v[56:59], v[140:143], v[152:155], v[56:59]
	v_mfma_f32_16x16x32_bf16 v[52:55], v[140:143], v[164:167], v[52:55]
	v_mfma_f32_16x16x32_bf16 v[48:51], v[140:143], v[168:171], v[48:51]
	s_waitcnt lgkmcnt(10)
	v_mfma_f32_16x16x32_bf16 v[44:47], v[144:147], v[148:151], v[44:47]
	v_mfma_f32_16x16x32_bf16 v[40:43], v[144:147], v[152:155], v[40:43]
	v_mfma_f32_16x16x32_bf16 v[36:39], v[144:147], v[164:167], v[36:39]
	v_mfma_f32_16x16x32_bf16 v[32:35], v[144:147], v[168:171], v[32:35]
	s_waitcnt lgkmcnt(9)
	v_mfma_f32_16x16x32_bf16 v[28:31], v[156:159], v[148:151], v[28:31]
	v_mfma_f32_16x16x32_bf16 v[24:27], v[156:159], v[152:155], v[24:27]
	v_mfma_f32_16x16x32_bf16 v[20:23], v[156:159], v[164:167], v[20:23]
	v_mfma_f32_16x16x32_bf16 v[16:19], v[156:159], v[168:171], v[16:19]
	s_waitcnt lgkmcnt(8)
	v_mfma_f32_16x16x32_bf16 v[12:15], v[160:163], v[148:151], v[12:15]
	v_mfma_f32_16x16x32_bf16 v[8:11], v[160:163], v[152:155], v[8:11]
	v_mfma_f32_16x16x32_bf16 v[4:7], v[160:163], v[164:167], v[4:7]
	v_mfma_f32_16x16x32_bf16 v[0:3], v[160:163], v[168:171], v[0:3]
	s_waitcnt lgkmcnt(3)
	v_mfma_f32_16x16x32_bf16 v[60:63], v[204:207], v[208:211], v[60:63]
	v_mfma_f32_16x16x32_bf16 v[56:59], v[204:207], v[212:215], v[56:59]
	v_mfma_f32_16x16x32_bf16 v[52:55], v[204:207], v[216:219], v[52:55]
	v_mfma_f32_16x16x32_bf16 v[48:51], v[204:207], v[220:223], v[48:51]
	s_waitcnt lgkmcnt(2)
	v_mfma_f32_16x16x32_bf16 v[44:47], v[224:227], v[208:211], v[44:47]
	v_mfma_f32_16x16x32_bf16 v[40:43], v[224:227], v[212:215], v[40:43]
	v_mfma_f32_16x16x32_bf16 v[36:39], v[224:227], v[216:219], v[36:39]
	v_mfma_f32_16x16x32_bf16 v[32:35], v[224:227], v[220:223], v[32:35]
	s_waitcnt lgkmcnt(1)
	v_mfma_f32_16x16x32_bf16 v[28:31], v[228:231], v[208:211], v[28:31]
	v_mfma_f32_16x16x32_bf16 v[24:27], v[228:231], v[212:215], v[24:27]
	v_mfma_f32_16x16x32_bf16 v[20:23], v[228:231], v[216:219], v[20:23]
	v_mfma_f32_16x16x32_bf16 v[16:19], v[228:231], v[220:223], v[16:19]
	s_waitcnt lgkmcnt(0)
	v_mfma_f32_16x16x32_bf16 v[12:15], v[232:235], v[208:211], v[12:15]
	v_mfma_f32_16x16x32_bf16 v[8:11], v[232:235], v[212:215], v[8:11]
	v_mfma_f32_16x16x32_bf16 v[4:7], v[232:235], v[216:219], v[4:7]
	v_mfma_f32_16x16x32_bf16 v[0:3], v[232:235], v[220:223], v[0:3]
	s_setprio 0
	s_cmpk_eq_i32 s8, 0x780
	s_waitcnt vmcnt(0)
	s_barrier
	s_cbranch_scc0 .LBB0_2270
	ds_read_b128 v[90:93], v116 offset:55296
	ds_read_b128 v[94:97], v116 offset:53248
	ds_read_b128 v[98:101], v117 offset:38912
	ds_read_b128 v[102:105], v117 offset:36864
	ds_read_b128 v[140:143], v116 offset:51200
	ds_read_b128 v[144:147], v116 offset:49152
	ds_read_b128 v[148:151], v117 offset:34816
	ds_read_b128 v[152:155], v117 offset:32768
	ds_read_b128 v[204:207], v118 offset:32768
	ds_read_b128 v[208:211], v118 offset:34816
	ds_read_b128 v[212:215], v119 offset:49152
	ds_read_b128 v[216:219], v119 offset:51200
	ds_read_b128 v[220:223], v118 offset:36864
	ds_read_b128 v[224:227], v118 offset:38912
	ds_read_b128 v[228:231], v119 offset:53248
	ds_read_b128 v[232:235], v119 offset:55296
	s_setprio 1
	s_waitcnt lgkmcnt(12)
	v_mfma_f32_16x16x32_bf16 v[20:23], v[102:105], v[94:97], v[20:23]
	v_mfma_f32_16x16x32_bf16 v[16:19], v[102:105], v[90:93], v[16:19]
	s_waitcnt lgkmcnt(8)
	v_mfma_f32_16x16x32_bf16 v[60:63], v[152:155], v[144:147], v[60:63]
	v_mfma_f32_16x16x32_bf16 v[56:59], v[152:155], v[140:143], v[56:59]
	v_mfma_f32_16x16x32_bf16 v[52:55], v[152:155], v[94:97], v[52:55]
	v_mfma_f32_16x16x32_bf16 v[48:51], v[152:155], v[90:93], v[48:51]
	v_mfma_f32_16x16x32_bf16 v[44:47], v[148:151], v[144:147], v[44:47]
	v_mfma_f32_16x16x32_bf16 v[40:43], v[148:151], v[140:143], v[40:43]
	v_mfma_f32_16x16x32_bf16 v[36:39], v[148:151], v[94:97], v[36:39]
	v_mfma_f32_16x16x32_bf16 v[32:35], v[148:151], v[90:93], v[32:35]
	v_mfma_f32_16x16x32_bf16 v[28:31], v[102:105], v[144:147], v[28:31]
	v_mfma_f32_16x16x32_bf16 v[24:27], v[102:105], v[140:143], v[24:27]
	v_mfma_f32_16x16x32_bf16 v[12:15], v[98:101], v[144:147], v[12:15]
	v_mfma_f32_16x16x32_bf16 v[8:11], v[98:101], v[140:143], v[8:11]
	v_mfma_f32_16x16x32_bf16 v[4:7], v[98:101], v[94:97], v[4:7]
	v_mfma_f32_16x16x32_bf16 v[0:3], v[98:101], v[90:93], v[0:3]
	s_waitcnt lgkmcnt(1)
	v_mfma_f32_16x16x32_bf16 v[20:23], v[220:223], v[228:231], v[20:23]
	s_waitcnt lgkmcnt(0)
	v_mfma_f32_16x16x32_bf16 v[16:19], v[220:223], v[232:235], v[16:19]
	v_mfma_f32_16x16x32_bf16 v[60:63], v[204:207], v[212:215], v[60:63]
	v_mfma_f32_16x16x32_bf16 v[56:59], v[204:207], v[216:219], v[56:59]
	v_mfma_f32_16x16x32_bf16 v[52:55], v[204:207], v[228:231], v[52:55]
	v_mfma_f32_16x16x32_bf16 v[48:51], v[204:207], v[232:235], v[48:51]
	v_mfma_f32_16x16x32_bf16 v[44:47], v[208:211], v[212:215], v[44:47]
	v_mfma_f32_16x16x32_bf16 v[40:43], v[208:211], v[216:219], v[40:43]
	v_mfma_f32_16x16x32_bf16 v[36:39], v[208:211], v[228:231], v[36:39]
	v_mfma_f32_16x16x32_bf16 v[32:35], v[208:211], v[232:235], v[32:35]
	v_mfma_f32_16x16x32_bf16 v[28:31], v[220:223], v[212:215], v[28:31]
	v_mfma_f32_16x16x32_bf16 v[24:27], v[220:223], v[216:219], v[24:27]
	v_mfma_f32_16x16x32_bf16 v[12:15], v[224:227], v[212:215], v[12:15]
	v_mfma_f32_16x16x32_bf16 v[8:11], v[224:227], v[216:219], v[8:11]
	v_mfma_f32_16x16x32_bf16 v[4:7], v[224:227], v[228:231], v[4:7]
	v_mfma_f32_16x16x32_bf16 v[0:3], v[224:227], v[232:235], v[0:3]
	s_setprio 0
	s_barrier
	ds_write2_b32 v120, v60, v56 offset1:16
	ds_write2_b32 v120, v61, v57 offset0:132 offset1:148
	v_add_u32_e32 v56, 0x400, v120
	ds_write2_b32 v56, v62, v58 offset0:8 offset1:24
	ds_write2_b32 v56, v63, v59 offset0:140 offset1:156
	ds_write2_b32 v120, v52, v48 offset0:32 offset1:48
	ds_write2_b32 v120, v53, v49 offset0:164 offset1:180
	ds_write2_b32 v56, v54, v50 offset0:40 offset1:56
	ds_write2_b32 v56, v55, v51 offset0:172 offset1:188
	v_add_u32_e32 v48, 0x2000, v120
	ds_write2_b32 v48, v44, v40 offset0:64 offset1:80
	ds_write2_b32 v48, v45, v41 offset0:196 offset1:212
	v_add_u32_e32 v40, 0x2400, v120
	ds_write2_b32 v40, v46, v42 offset0:72 offset1:88
	ds_write2_b32 v40, v47, v43 offset0:204 offset1:220
	ds_write2_b32 v48, v36, v32 offset0:96 offset1:112
	ds_write2_b32 v48, v37, v33 offset0:228 offset1:244
	ds_write2_b32 v40, v38, v34 offset0:104 offset1:120
	ds_write2_b32 v40, v39, v35 offset0:236 offset1:252
	v_add_u32_e32 v32, 0x4000, v120
	ds_write2_b32 v32, v28, v24 offset0:128 offset1:144
	v_add_u32_e32 v24, 0x4400, v120
	ds_write2_b32 v24, v29, v25 offset0:4 offset1:20
	ds_write2_b32 v24, v30, v26 offset0:136 offset1:152
	v_add_u32_e32 v25, 0x4800, v120
	s_cmp_gt_i32 s28, 5
	ds_write2_b32 v25, v31, v27 offset0:12 offset1:28
	ds_write2_b32 v32, v20, v16 offset0:160 offset1:176
	ds_write2_b32 v24, v21, v17 offset0:36 offset1:52
	ds_write2_b32 v24, v22, v18 offset0:168 offset1:184
	ds_write2_b32 v25, v23, v19 offset0:44 offset1:60
	v_add_u32_e32 v16, 0x6000, v120
	v_or_b32_e32 v64, s29, v121
	s_cselect_b64 s[30:31], -1, 0
	s_ashr_i32 s29, s28, 31
	ds_write2_b32 v16, v12, v8 offset0:192 offset1:208
	v_add_u32_e32 v8, 0x6400, v120
	s_cmp_gt_i32 s28, 3
	ds_write2_b32 v8, v13, v9 offset0:68 offset1:84
	ds_write2_b32 v8, v14, v10 offset0:200 offset1:216
	v_add_u32_e32 v9, 0x6800, v120
	s_cselect_b64 s[34:35], -1, 0
	s_lshl_b64 s[28:29], s[28:29], 2
	ds_write2_b32 v9, v15, v11 offset0:76 offset1:92
	ds_write2_b32 v16, v4, v0 offset0:224 offset1:240
	ds_write2_b32 v8, v5, v1 offset0:100 offset1:116
	ds_write2_b32 v8, v6, v2 offset0:232 offset1:248
	ds_write2_b32 v9, v7, v3 offset0:108 offset1:124
	v_ashrrev_i32_e32 v1, 31, v64
	v_mov_b32_e32 v0, v64
	v_lshlrev_b64 v[2:3], 1, v[64:65]
	s_add_u32 s28, s40, s28
	v_cmp_gt_u32_e64 s[8:9], s44, v64
	v_lshl_add_u64 v[16:17], s[16:17], 0, v[2:3]
	s_addc_u32 s29, s41, s29
	v_lshl_add_u64 v[18:19], s[14:15], 0, v[2:3]
	v_lshl_add_u64 v[20:21], v[0:1], 1, s[12:13]
	v_add_u32_e32 v22, s36, v129
	s_mov_b32 s50, 0
	s_waitcnt lgkmcnt(0)
	s_barrier
	s_branch .LBB0_2273

.LBB0_2292:
	s_and_b32 s24, s23, 0x4000
	s_xor_b32 s25, s24, 0x4000
	s_lshl_b32 s25, s25, 1
	s_add_i32 s25, s25, 32
	s_add_u32 s90, s52, s8
	s_addc_u32 s91, s53, s9
	s_add_i32 m0, s25, s82
	s_lshl_b32 s24, s24, 1
	global_load_lds_dwordx4 v184, s[90:91]
	s_add_i32 m0, s25, s83
	s_add_i32 s24, s24, 32
	global_load_lds_dwordx4 v185, s[90:91]
	s_add_i32 m0, s25, s84
	v_lshl_add_u32 v64, v115, 1, s24
	global_load_lds_dwordx4 v186, s[90:91]
	s_add_i32 m0, s25, s85
	v_lshl_add_u32 v141, v116, 1, s24
	global_load_lds_dwordx4 v187, s[90:91]
	s_add_i32 m0, s25, s86
	v_add_u32_e32 v162, v64, v138
	global_load_lds_dwordx4 v188, s[90:91]
	s_add_i32 m0, s25, s87
	v_add_u32_e32 v170, v141, v138
	global_load_lds_dwordx4 v189, s[90:91]
	s_add_i32 m0, s25, s88
	s_addk_i32 s23, 0x4000
	global_load_lds_dwordx4 v190, s[90:91]
	s_add_i32 m0, s25, s89
	s_add_u32 s8, s8, 0x80
	s_addc_u32 s9, s9, 0
	global_load_lds_dwordx4 v191, s[90:91]
	ds_read_b128 v[142:145], v162
	ds_read_b128 v[150:153], v170 offset:16384
	ds_read_b128 v[154:157], v170 offset:18432
	ds_read_b128 v[166:169], v170 offset:20480
	ds_read_b128 v[170:173], v170 offset:22528
	ds_read_b128 v[146:149], v162 offset:2048
	ds_read_b128 v[158:161], v162 offset:4096
	ds_read_b128 v[162:165], v162 offset:6144
	v_add_u32_e32 v64, v64, v139
	v_add_u32_e32 v141, v141, v139
	ds_read_b128 v[204:207], v64
	ds_read_b128 v[208:211], v141 offset:16384
	ds_read_b128 v[212:215], v141 offset:18432
	ds_read_b128 v[216:219], v141 offset:20480
	ds_read_b128 v[220:223], v141 offset:22528
	ds_read_b128 v[224:227], v64 offset:2048
	ds_read_b128 v[228:231], v64 offset:4096
	ds_read_b128 v[232:235], v64 offset:6144
	s_setprio 1
	s_waitcnt lgkmcnt(11)
	v_mfma_f32_16x16x32_bf16 v[60:63], v[142:145], v[150:153], v[60:63]
	v_mfma_f32_16x16x32_bf16 v[56:59], v[142:145], v[154:157], v[56:59]
	v_mfma_f32_16x16x32_bf16 v[52:55], v[142:145], v[166:169], v[52:55]
	v_mfma_f32_16x16x32_bf16 v[48:51], v[142:145], v[170:173], v[48:51]
	s_waitcnt lgkmcnt(10)
	v_mfma_f32_16x16x32_bf16 v[44:47], v[146:149], v[150:153], v[44:47]
	v_mfma_f32_16x16x32_bf16 v[40:43], v[146:149], v[154:157], v[40:43]
	v_mfma_f32_16x16x32_bf16 v[36:39], v[146:149], v[166:169], v[36:39]
	v_mfma_f32_16x16x32_bf16 v[32:35], v[146:149], v[170:173], v[32:35]
	s_waitcnt lgkmcnt(9)
	v_mfma_f32_16x16x32_bf16 v[28:31], v[158:161], v[150:153], v[28:31]
	v_mfma_f32_16x16x32_bf16 v[24:27], v[158:161], v[154:157], v[24:27]
	v_mfma_f32_16x16x32_bf16 v[20:23], v[158:161], v[166:169], v[20:23]
	v_mfma_f32_16x16x32_bf16 v[16:19], v[158:161], v[170:173], v[16:19]
	s_waitcnt lgkmcnt(8)
	v_mfma_f32_16x16x32_bf16 v[12:15], v[162:165], v[150:153], v[12:15]
	v_mfma_f32_16x16x32_bf16 v[8:11], v[162:165], v[154:157], v[8:11]
	v_mfma_f32_16x16x32_bf16 v[4:7], v[162:165], v[166:169], v[4:7]
	v_mfma_f32_16x16x32_bf16 v[0:3], v[162:165], v[170:173], v[0:3]
	s_waitcnt lgkmcnt(3)
	v_mfma_f32_16x16x32_bf16 v[60:63], v[204:207], v[208:211], v[60:63]
	v_mfma_f32_16x16x32_bf16 v[56:59], v[204:207], v[212:215], v[56:59]
	v_mfma_f32_16x16x32_bf16 v[52:55], v[204:207], v[216:219], v[52:55]
	v_mfma_f32_16x16x32_bf16 v[48:51], v[204:207], v[220:223], v[48:51]
	s_waitcnt lgkmcnt(2)
	v_mfma_f32_16x16x32_bf16 v[44:47], v[224:227], v[208:211], v[44:47]
	v_mfma_f32_16x16x32_bf16 v[40:43], v[224:227], v[212:215], v[40:43]
	v_mfma_f32_16x16x32_bf16 v[36:39], v[224:227], v[216:219], v[36:39]
	v_mfma_f32_16x16x32_bf16 v[32:35], v[224:227], v[220:223], v[32:35]
	s_waitcnt lgkmcnt(1)
	v_mfma_f32_16x16x32_bf16 v[28:31], v[228:231], v[208:211], v[28:31]
	v_mfma_f32_16x16x32_bf16 v[24:27], v[228:231], v[212:215], v[24:27]
	v_mfma_f32_16x16x32_bf16 v[20:23], v[228:231], v[216:219], v[20:23]
	v_mfma_f32_16x16x32_bf16 v[16:19], v[228:231], v[220:223], v[16:19]
	s_waitcnt lgkmcnt(0)
	v_mfma_f32_16x16x32_bf16 v[12:15], v[232:235], v[208:211], v[12:15]
	v_mfma_f32_16x16x32_bf16 v[8:11], v[232:235], v[212:215], v[8:11]
	v_mfma_f32_16x16x32_bf16 v[4:7], v[232:235], v[216:219], v[4:7]
	v_mfma_f32_16x16x32_bf16 v[0:3], v[232:235], v[220:223], v[0:3]
	s_setprio 0
	s_cmpk_eq_i32 s8, 0x780
	s_waitcnt vmcnt(0)
	s_barrier
	s_cbranch_scc0 .LBB0_2292
	ds_read_b128 v[90:93], v117 offset:55296
	ds_read_b128 v[94:97], v117 offset:53248
	ds_read_b128 v[98:101], v118 offset:38912
	ds_read_b128 v[102:105], v118 offset:36864
	ds_read_b128 v[142:145], v117 offset:51200
	ds_read_b128 v[146:149], v117 offset:49152
	ds_read_b128 v[150:153], v118 offset:34816
	ds_read_b128 v[154:157], v118 offset:32768
	ds_read_b128 v[204:207], v119 offset:32768
	ds_read_b128 v[208:211], v119 offset:34816
	ds_read_b128 v[212:215], v120 offset:49152
	ds_read_b128 v[216:219], v120 offset:51200
	ds_read_b128 v[220:223], v119 offset:36864
	ds_read_b128 v[224:227], v119 offset:38912
	ds_read_b128 v[228:231], v120 offset:53248
	ds_read_b128 v[232:235], v120 offset:55296
	s_setprio 1
	s_waitcnt lgkmcnt(12)
	v_mfma_f32_16x16x32_bf16 v[20:23], v[102:105], v[94:97], v[20:23]
	v_mfma_f32_16x16x32_bf16 v[16:19], v[102:105], v[90:93], v[16:19]
	s_waitcnt lgkmcnt(8)
	v_mfma_f32_16x16x32_bf16 v[60:63], v[154:157], v[146:149], v[60:63]
	v_mfma_f32_16x16x32_bf16 v[56:59], v[154:157], v[142:145], v[56:59]
	v_mfma_f32_16x16x32_bf16 v[52:55], v[154:157], v[94:97], v[52:55]
	v_mfma_f32_16x16x32_bf16 v[48:51], v[154:157], v[90:93], v[48:51]
	v_mfma_f32_16x16x32_bf16 v[44:47], v[150:153], v[146:149], v[44:47]
	v_mfma_f32_16x16x32_bf16 v[40:43], v[150:153], v[142:145], v[40:43]
	v_mfma_f32_16x16x32_bf16 v[36:39], v[150:153], v[94:97], v[36:39]
	v_mfma_f32_16x16x32_bf16 v[32:35], v[150:153], v[90:93], v[32:35]
	v_mfma_f32_16x16x32_bf16 v[28:31], v[102:105], v[146:149], v[28:31]
	v_mfma_f32_16x16x32_bf16 v[24:27], v[102:105], v[142:145], v[24:27]
	v_mfma_f32_16x16x32_bf16 v[12:15], v[98:101], v[146:149], v[12:15]
	v_mfma_f32_16x16x32_bf16 v[8:11], v[98:101], v[142:145], v[8:11]
	v_mfma_f32_16x16x32_bf16 v[4:7], v[98:101], v[94:97], v[4:7]
	v_mfma_f32_16x16x32_bf16 v[0:3], v[98:101], v[90:93], v[0:3]
	s_waitcnt lgkmcnt(1)
	v_mfma_f32_16x16x32_bf16 v[20:23], v[220:223], v[228:231], v[20:23]
	s_waitcnt lgkmcnt(0)
	v_mfma_f32_16x16x32_bf16 v[16:19], v[220:223], v[232:235], v[16:19]
	v_mfma_f32_16x16x32_bf16 v[60:63], v[204:207], v[212:215], v[60:63]
	v_mfma_f32_16x16x32_bf16 v[56:59], v[204:207], v[216:219], v[56:59]
	v_mfma_f32_16x16x32_bf16 v[52:55], v[204:207], v[228:231], v[52:55]
	v_mfma_f32_16x16x32_bf16 v[48:51], v[204:207], v[232:235], v[48:51]
	v_mfma_f32_16x16x32_bf16 v[44:47], v[208:211], v[212:215], v[44:47]
	v_mfma_f32_16x16x32_bf16 v[40:43], v[208:211], v[216:219], v[40:43]
	v_mfma_f32_16x16x32_bf16 v[36:39], v[208:211], v[228:231], v[36:39]
	v_mfma_f32_16x16x32_bf16 v[32:35], v[208:211], v[232:235], v[32:35]
	v_mfma_f32_16x16x32_bf16 v[28:31], v[220:223], v[212:215], v[28:31]
	v_mfma_f32_16x16x32_bf16 v[24:27], v[220:223], v[216:219], v[24:27]
	v_mfma_f32_16x16x32_bf16 v[12:15], v[224:227], v[212:215], v[12:15]
	v_mfma_f32_16x16x32_bf16 v[8:11], v[224:227], v[216:219], v[8:11]
	v_mfma_f32_16x16x32_bf16 v[4:7], v[224:227], v[228:231], v[4:7]
	v_mfma_f32_16x16x32_bf16 v[0:3], v[224:227], v[232:235], v[0:3]
	s_setprio 0
	s_barrier
	ds_write2_b32 v121, v60, v56 offset1:16
	ds_write2_b32 v121, v61, v57 offset0:132 offset1:148
	v_add_u32_e32 v56, 0x400, v121
	ds_write2_b32 v56, v62, v58 offset0:8 offset1:24
	ds_write2_b32 v56, v63, v59 offset0:140 offset1:156
	ds_write2_b32 v121, v52, v48 offset0:32 offset1:48
	ds_write2_b32 v121, v53, v49 offset0:164 offset1:180
	ds_write2_b32 v56, v54, v50 offset0:40 offset1:56
	ds_write2_b32 v56, v55, v51 offset0:172 offset1:188
	v_add_u32_e32 v48, 0x2000, v121
	ds_write2_b32 v48, v44, v40 offset0:64 offset1:80
	ds_write2_b32 v48, v45, v41 offset0:196 offset1:212
	v_add_u32_e32 v40, 0x2400, v121
	ds_write2_b32 v40, v46, v42 offset0:72 offset1:88
	ds_write2_b32 v40, v47, v43 offset0:204 offset1:220
	ds_write2_b32 v48, v36, v32 offset0:96 offset1:112
	ds_write2_b32 v48, v37, v33 offset0:228 offset1:244
	ds_write2_b32 v40, v38, v34 offset0:104 offset1:120
	ds_write2_b32 v40, v39, v35 offset0:236 offset1:252
	v_add_u32_e32 v32, 0x4000, v121
	ds_write2_b32 v32, v28, v24 offset0:128 offset1:144
	v_add_u32_e32 v24, 0x4400, v121
	s_ashr_i32 s26, s22, 7
	ds_write2_b32 v24, v29, v25 offset0:4 offset1:20
	ds_write2_b32 v24, v30, v26 offset0:136 offset1:152
	v_add_u32_e32 v25, 0x4800, v121
	s_cmp_gt_i32 s26, 5
	ds_write2_b32 v25, v31, v27 offset0:12 offset1:28
	ds_write2_b32 v32, v20, v16 offset0:160 offset1:176
	ds_write2_b32 v24, v21, v17 offset0:36 offset1:52
	ds_write2_b32 v24, v22, v18 offset0:168 offset1:184
	ds_write2_b32 v25, v23, v19 offset0:44 offset1:60
	v_add_u32_e32 v16, 0x6000, v121
	v_or_b32_e32 v64, s22, v122
	s_cselect_b64 s[22:23], -1, 0
	s_ashr_i32 s27, s26, 31
	ds_write2_b32 v16, v12, v8 offset0:192 offset1:208
	v_add_u32_e32 v8, 0x6400, v121
	s_cmp_gt_i32 s26, 3
	ds_write2_b32 v8, v13, v9 offset0:68 offset1:84
	ds_write2_b32 v8, v14, v10 offset0:200 offset1:216
	v_add_u32_e32 v9, 0x6800, v121
	s_cselect_b64 s[24:25], -1, 0
	s_lshl_b64 s[26:27], s[26:27], 2
	ds_write2_b32 v9, v15, v11 offset0:76 offset1:92
	ds_write2_b32 v16, v4, v0 offset0:224 offset1:240
	ds_write2_b32 v8, v5, v1 offset0:100 offset1:116
	ds_write2_b32 v8, v6, v2 offset0:232 offset1:248
	ds_write2_b32 v9, v7, v3 offset0:108 offset1:124
	v_ashrrev_i32_e32 v1, 31, v64
	v_mov_b32_e32 v0, v64
	v_lshlrev_b64 v[2:3], 1, v[64:65]
	s_add_u32 s26, s40, s26
	v_cmp_gt_u32_e64 s[8:9], s38, v64
	v_lshl_add_u64 v[16:17], s[16:17], 0, v[2:3]
	s_addc_u32 s27, s41, s27
	v_lshl_add_u64 v[18:19], s[14:15], 0, v[2:3]
	v_lshl_add_u64 v[20:21], v[0:1], 1, s[12:13]
	v_add_u32_e32 v22, s28, v131
	s_mov_b32 s43, 0
	s_waitcnt lgkmcnt(0)
	s_barrier
	s_branch .LBB0_2295

.LBB0_2976:
	s_and_b32 s28, s7, 0x4000
	s_xor_b32 s29, s28, 0x4000
	s_lshl_b32 s29, s29, 1
	s_add_i32 s29, s29, 32
	s_add_u32 s90, s52, s4
	s_addc_u32 s91, s53, s5
	s_add_i32 m0, s29, s82
	s_lshl_b32 s28, s28, 1
	global_load_lds_dwordx4 v184, s[90:91]
	s_add_i32 m0, s29, s83
	s_add_i32 s28, s28, 32
	global_load_lds_dwordx4 v185, s[90:91]
	s_add_i32 m0, s29, s84
	v_lshl_add_u32 v64, v114, 1, s28
	global_load_lds_dwordx4 v186, s[90:91]
	s_add_i32 m0, s29, s85
	v_lshl_add_u32 v170, v115, 1, s28
	global_load_lds_dwordx4 v187, s[90:91]
	s_add_i32 m0, s29, s86
	v_add_u32_e32 v158, v64, v136
	global_load_lds_dwordx4 v188, s[90:91]
	s_add_i32 m0, s29, s87
	v_add_u32_e32 v166, v170, v136
	global_load_lds_dwordx4 v189, s[90:91]
	s_add_i32 m0, s29, s88
	s_addk_i32 s7, 0x4000
	global_load_lds_dwordx4 v190, s[90:91]
	s_add_i32 m0, s29, s89
	s_add_u32 s4, s4, 0x80
	s_addc_u32 s5, s5, 0
	global_load_lds_dwordx4 v191, s[90:91]
	ds_read_b128 v[138:141], v158
	ds_read_b128 v[146:149], v166 offset:16384
	ds_read_b128 v[150:153], v166 offset:18432
	ds_read_b128 v[162:165], v166 offset:20480
	ds_read_b128 v[166:169], v166 offset:22528
	ds_read_b128 v[142:145], v158 offset:2048
	ds_read_b128 v[154:157], v158 offset:4096
	ds_read_b128 v[158:161], v158 offset:6144
	v_add_u32_e32 v64, v64, v137
	v_add_u32_e32 v236, v170, v137
	ds_read_b128 v[204:207], v64
	ds_read_b128 v[208:211], v236 offset:16384
	ds_read_b128 v[212:215], v236 offset:18432
	ds_read_b128 v[216:219], v236 offset:20480
	ds_read_b128 v[220:223], v236 offset:22528
	ds_read_b128 v[224:227], v64 offset:2048
	ds_read_b128 v[228:231], v64 offset:4096
	ds_read_b128 v[232:235], v64 offset:6144
	s_setprio 1
	s_waitcnt lgkmcnt(11)
	v_mfma_f32_16x16x32_bf16 v[60:63], v[138:141], v[146:149], v[60:63]
	v_mfma_f32_16x16x32_bf16 v[56:59], v[138:141], v[150:153], v[56:59]
	v_mfma_f32_16x16x32_bf16 v[52:55], v[138:141], v[162:165], v[52:55]
	v_mfma_f32_16x16x32_bf16 v[48:51], v[138:141], v[166:169], v[48:51]
	s_waitcnt lgkmcnt(10)
	v_mfma_f32_16x16x32_bf16 v[44:47], v[142:145], v[146:149], v[44:47]
	v_mfma_f32_16x16x32_bf16 v[40:43], v[142:145], v[150:153], v[40:43]
	v_mfma_f32_16x16x32_bf16 v[36:39], v[142:145], v[162:165], v[36:39]
	v_mfma_f32_16x16x32_bf16 v[32:35], v[142:145], v[166:169], v[32:35]
	s_waitcnt lgkmcnt(9)
	v_mfma_f32_16x16x32_bf16 v[28:31], v[154:157], v[146:149], v[28:31]
	v_mfma_f32_16x16x32_bf16 v[24:27], v[154:157], v[150:153], v[24:27]
	v_mfma_f32_16x16x32_bf16 v[20:23], v[154:157], v[162:165], v[20:23]
	v_mfma_f32_16x16x32_bf16 v[16:19], v[154:157], v[166:169], v[16:19]
	s_waitcnt lgkmcnt(8)
	v_mfma_f32_16x16x32_bf16 v[12:15], v[158:161], v[146:149], v[12:15]
	v_mfma_f32_16x16x32_bf16 v[8:11], v[158:161], v[150:153], v[8:11]
	v_mfma_f32_16x16x32_bf16 v[4:7], v[158:161], v[162:165], v[4:7]
	v_mfma_f32_16x16x32_bf16 v[0:3], v[158:161], v[166:169], v[0:3]
	s_waitcnt lgkmcnt(3)
	v_mfma_f32_16x16x32_bf16 v[60:63], v[204:207], v[208:211], v[60:63]
	v_mfma_f32_16x16x32_bf16 v[56:59], v[204:207], v[212:215], v[56:59]
	v_mfma_f32_16x16x32_bf16 v[52:55], v[204:207], v[216:219], v[52:55]
	v_mfma_f32_16x16x32_bf16 v[48:51], v[204:207], v[220:223], v[48:51]
	s_waitcnt lgkmcnt(2)
	v_mfma_f32_16x16x32_bf16 v[44:47], v[224:227], v[208:211], v[44:47]
	v_mfma_f32_16x16x32_bf16 v[40:43], v[224:227], v[212:215], v[40:43]
	v_mfma_f32_16x16x32_bf16 v[36:39], v[224:227], v[216:219], v[36:39]
	v_mfma_f32_16x16x32_bf16 v[32:35], v[224:227], v[220:223], v[32:35]
	s_waitcnt lgkmcnt(1)
	v_mfma_f32_16x16x32_bf16 v[28:31], v[228:231], v[208:211], v[28:31]
	v_mfma_f32_16x16x32_bf16 v[24:27], v[228:231], v[212:215], v[24:27]
	v_mfma_f32_16x16x32_bf16 v[20:23], v[228:231], v[216:219], v[20:23]
	v_mfma_f32_16x16x32_bf16 v[16:19], v[228:231], v[220:223], v[16:19]
	s_waitcnt lgkmcnt(0)
	v_mfma_f32_16x16x32_bf16 v[12:15], v[232:235], v[208:211], v[12:15]
	v_mfma_f32_16x16x32_bf16 v[8:11], v[232:235], v[212:215], v[8:11]
	v_mfma_f32_16x16x32_bf16 v[4:7], v[232:235], v[216:219], v[4:7]
	v_mfma_f32_16x16x32_bf16 v[0:3], v[232:235], v[220:223], v[0:3]
	s_setprio 0
	s_cmpk_eq_i32 s4, 0x780
	s_waitcnt vmcnt(0)
	s_barrier
	s_cbranch_scc0 .LBB0_2976
	ds_read_b128 v[90:93], v116 offset:55296
	ds_read_b128 v[94:97], v116 offset:53248
	ds_read_b128 v[98:101], v117 offset:38912
	ds_read_b128 v[102:105], v117 offset:36864
	ds_read_b128 v[138:141], v116 offset:51200
	ds_read_b128 v[142:145], v116 offset:49152
	ds_read_b128 v[146:149], v117 offset:34816
	ds_read_b128 v[150:153], v117 offset:32768
	ds_read_b128 v[204:207], v118 offset:32768
	ds_read_b128 v[208:211], v118 offset:34816
	ds_read_b128 v[212:215], v119 offset:49152
	ds_read_b128 v[216:219], v119 offset:51200
	ds_read_b128 v[220:223], v118 offset:36864
	ds_read_b128 v[224:227], v118 offset:38912
	ds_read_b128 v[228:231], v119 offset:53248
	ds_read_b128 v[232:235], v119 offset:55296
	s_setprio 1
	s_waitcnt lgkmcnt(11)
	v_mfma_f32_16x16x32_bf16 v[24:27], v[102:105], v[138:141], v[24:27]
	v_mfma_f32_16x16x32_bf16 v[20:23], v[102:105], v[94:97], v[20:23]
	v_mfma_f32_16x16x32_bf16 v[16:19], v[102:105], v[90:93], v[16:19]
	s_waitcnt lgkmcnt(8)
	v_mfma_f32_16x16x32_bf16 v[60:63], v[150:153], v[142:145], v[60:63]
	v_mfma_f32_16x16x32_bf16 v[56:59], v[150:153], v[138:141], v[56:59]
	v_mfma_f32_16x16x32_bf16 v[52:55], v[150:153], v[94:97], v[52:55]
	v_mfma_f32_16x16x32_bf16 v[48:51], v[150:153], v[90:93], v[48:51]
	v_mfma_f32_16x16x32_bf16 v[44:47], v[146:149], v[142:145], v[44:47]
	v_mfma_f32_16x16x32_bf16 v[40:43], v[146:149], v[138:141], v[40:43]
	v_mfma_f32_16x16x32_bf16 v[36:39], v[146:149], v[94:97], v[36:39]
	v_mfma_f32_16x16x32_bf16 v[32:35], v[146:149], v[90:93], v[32:35]
	v_mfma_f32_16x16x32_bf16 v[28:31], v[102:105], v[142:145], v[28:31]
	v_mfma_f32_16x16x32_bf16 v[12:15], v[98:101], v[142:145], v[12:15]
	v_mfma_f32_16x16x32_bf16 v[8:11], v[98:101], v[138:141], v[8:11]
	v_mfma_f32_16x16x32_bf16 v[4:7], v[98:101], v[94:97], v[4:7]
	v_mfma_f32_16x16x32_bf16 v[0:3], v[98:101], v[90:93], v[0:3]
	s_waitcnt lgkmcnt(3)
	v_mfma_f32_16x16x32_bf16 v[24:27], v[220:223], v[216:219], v[24:27]
	s_waitcnt lgkmcnt(1)
	v_mfma_f32_16x16x32_bf16 v[20:23], v[220:223], v[228:231], v[20:23]
	s_waitcnt lgkmcnt(0)
	v_mfma_f32_16x16x32_bf16 v[16:19], v[220:223], v[232:235], v[16:19]
	v_mfma_f32_16x16x32_bf16 v[60:63], v[204:207], v[212:215], v[60:63]
	v_mfma_f32_16x16x32_bf16 v[56:59], v[204:207], v[216:219], v[56:59]
	v_mfma_f32_16x16x32_bf16 v[52:55], v[204:207], v[228:231], v[52:55]
	v_mfma_f32_16x16x32_bf16 v[48:51], v[204:207], v[232:235], v[48:51]
	v_mfma_f32_16x16x32_bf16 v[44:47], v[208:211], v[212:215], v[44:47]
	v_mfma_f32_16x16x32_bf16 v[40:43], v[208:211], v[216:219], v[40:43]
	v_mfma_f32_16x16x32_bf16 v[36:39], v[208:211], v[228:231], v[36:39]
	v_mfma_f32_16x16x32_bf16 v[32:35], v[208:211], v[232:235], v[32:35]
	v_mfma_f32_16x16x32_bf16 v[28:31], v[220:223], v[212:215], v[28:31]
	v_mfma_f32_16x16x32_bf16 v[12:15], v[224:227], v[212:215], v[12:15]
	v_mfma_f32_16x16x32_bf16 v[8:11], v[224:227], v[216:219], v[8:11]
	v_mfma_f32_16x16x32_bf16 v[4:7], v[224:227], v[228:231], v[4:7]
	v_mfma_f32_16x16x32_bf16 v[0:3], v[224:227], v[232:235], v[0:3]
	s_setprio 0
	s_barrier
	ds_write2_b32 v120, v60, v56 offset1:16
	ds_write2_b32 v120, v61, v57 offset0:132 offset1:148
	v_add_u32_e32 v56, 0x400, v120
	ds_write2_b32 v56, v62, v58 offset0:8 offset1:24
	ds_write2_b32 v56, v63, v59 offset0:140 offset1:156
	ds_write2_b32 v120, v52, v48 offset0:32 offset1:48
	ds_write2_b32 v120, v53, v49 offset0:164 offset1:180
	ds_write2_b32 v56, v54, v50 offset0:40 offset1:56
	ds_write2_b32 v56, v55, v51 offset0:172 offset1:188
	v_add_u32_e32 v48, 0x2000, v120
	ds_write2_b32 v48, v44, v40 offset0:64 offset1:80
	ds_write2_b32 v48, v45, v41 offset0:196 offset1:212
	v_add_u32_e32 v40, 0x2400, v120
	ds_write2_b32 v40, v46, v42 offset0:72 offset1:88
	ds_write2_b32 v40, v47, v43 offset0:204 offset1:220
	ds_write2_b32 v48, v36, v32 offset0:96 offset1:112
	ds_write2_b32 v48, v37, v33 offset0:228 offset1:244
	ds_write2_b32 v40, v38, v34 offset0:104 offset1:120
	ds_write2_b32 v40, v39, v35 offset0:236 offset1:252
	v_add_u32_e32 v32, 0x4000, v120
	ds_write2_b32 v32, v28, v24 offset0:128 offset1:144
	v_add_u32_e32 v24, 0x4400, v120
	ds_write2_b32 v24, v29, v25 offset0:4 offset1:20
	ds_write2_b32 v24, v30, v26 offset0:136 offset1:152
	v_add_u32_e32 v25, 0x4800, v120
	ds_write2_b32 v25, v31, v27 offset0:12 offset1:28
	ds_write2_b32 v32, v20, v16 offset0:160 offset1:176
	ds_write2_b32 v24, v21, v17 offset0:36 offset1:52
	ds_write2_b32 v24, v22, v18 offset0:168 offset1:184
	ds_write2_b32 v25, v23, v19 offset0:44 offset1:60
	v_add_u32_e32 v16, 0x6000, v120
	ds_write2_b32 v16, v12, v8 offset0:192 offset1:208
	v_add_u32_e32 v8, 0x6400, v120
	s_cmpk_gt_u32 s6, 0x3ff
	ds_write2_b32 v8, v13, v9 offset0:68 offset1:84
	ds_write2_b32 v8, v14, v10 offset0:200 offset1:216
	v_add_u32_e32 v9, 0x6800, v120
	v_or_b32_e32 v64, s6, v121
	s_cselect_b64 s[28:29], -1, 0
	s_cmpk_gt_u32 s6, 0x7ff
	ds_write2_b32 v9, v15, v11 offset0:76 offset1:92
	ds_write2_b32 v16, v4, v0 offset0:224 offset1:240
	ds_write2_b32 v8, v5, v1 offset0:100 offset1:116
	ds_write2_b32 v8, v6, v2 offset0:232 offset1:248
	ds_write2_b32 v9, v7, v3 offset0:108 offset1:124
	s_cselect_b64 s[30:31], -1, 0
	s_cmpk_gt_u32 s6, 0xbff
	v_ashrrev_i32_e32 v1, 31, v64
	v_mov_b32_e32 v0, v64
	v_lshlrev_b64 v[2:3], 1, v[64:65]
	v_cmp_lt_i32_e64 s[4:5], s41, v64
	s_cselect_b64 s[34:35], -1, 0
	v_cmp_gt_u32_e64 s[6:7], s42, v64
	v_lshl_add_u64 v[16:17], v[64:65], 2, s[18:19]
	v_lshl_add_u64 v[18:19], s[16:17], 0, v[2:3]
	v_lshl_add_u64 v[20:21], s[14:15], 0, v[2:3]
	v_lshl_add_u64 v[22:23], s[12:13], 0, v[2:3]
	v_lshl_add_u64 v[24:25], v[0:1], 1, s[10:11]
	v_add_u32_e32 v26, s36, v129
	s_mov_b32 s44, 0
	s_waitcnt lgkmcnt(0)
	s_barrier
	s_branch .LBB0_2979

.LBB0_3008:
	s_and_b32 s22, s7, 0x4000
	s_xor_b32 s23, s22, 0x4000
	s_lshl_b32 s23, s23, 1
	s_add_i32 s23, s23, 32
	s_add_u32 s90, s52, s4
	s_addc_u32 s91, s53, s5
	s_add_i32 m0, s23, s82
	s_lshl_b32 s22, s22, 1
	global_load_lds_dwordx4 v184, s[90:91]
	s_add_i32 m0, s23, s83
	s_add_i32 s22, s22, 32
	global_load_lds_dwordx4 v185, s[90:91]
	s_add_i32 m0, s23, s84
	v_lshl_add_u32 v64, v115, 1, s22
	global_load_lds_dwordx4 v186, s[90:91]
	s_add_i32 m0, s23, s85
	v_lshl_add_u32 v168, v116, 1, s22
	global_load_lds_dwordx4 v187, s[90:91]
	s_add_i32 m0, s23, s86
	v_add_u32_e32 v156, v64, v133
	global_load_lds_dwordx4 v188, s[90:91]
	s_add_i32 m0, s23, s87
	v_add_u32_e32 v164, v168, v133
	global_load_lds_dwordx4 v189, s[90:91]
	s_add_i32 m0, s23, s88
	s_addk_i32 s7, 0x4000
	global_load_lds_dwordx4 v190, s[90:91]
	s_add_i32 m0, s23, s89
	s_add_u32 s4, s4, 0x80
	s_addc_u32 s5, s5, 0
	global_load_lds_dwordx4 v191, s[90:91]
	ds_read_b128 v[136:139], v156
	ds_read_b128 v[144:147], v164 offset:16384
	ds_read_b128 v[148:151], v164 offset:18432
	ds_read_b128 v[160:163], v164 offset:20480
	ds_read_b128 v[164:167], v164 offset:22528
	ds_read_b128 v[140:143], v156 offset:2048
	ds_read_b128 v[152:155], v156 offset:4096
	ds_read_b128 v[156:159], v156 offset:6144
	v_add_u32_e32 v64, v64, v134
	v_add_u32_e32 v236, v168, v134
	ds_read_b128 v[204:207], v64
	ds_read_b128 v[208:211], v236 offset:16384
	ds_read_b128 v[212:215], v236 offset:18432
	ds_read_b128 v[216:219], v236 offset:20480
	ds_read_b128 v[220:223], v236 offset:22528
	ds_read_b128 v[224:227], v64 offset:2048
	ds_read_b128 v[228:231], v64 offset:4096
	ds_read_b128 v[232:235], v64 offset:6144
	s_setprio 1
	s_waitcnt lgkmcnt(11)
	v_mfma_f32_16x16x32_bf16 v[60:63], v[136:139], v[144:147], v[60:63]
	v_mfma_f32_16x16x32_bf16 v[56:59], v[136:139], v[148:151], v[56:59]
	v_mfma_f32_16x16x32_bf16 v[52:55], v[136:139], v[160:163], v[52:55]
	v_mfma_f32_16x16x32_bf16 v[48:51], v[136:139], v[164:167], v[48:51]
	s_waitcnt lgkmcnt(10)
	v_mfma_f32_16x16x32_bf16 v[44:47], v[140:143], v[144:147], v[44:47]
	v_mfma_f32_16x16x32_bf16 v[40:43], v[140:143], v[148:151], v[40:43]
	v_mfma_f32_16x16x32_bf16 v[36:39], v[140:143], v[160:163], v[36:39]
	v_mfma_f32_16x16x32_bf16 v[32:35], v[140:143], v[164:167], v[32:35]
	s_waitcnt lgkmcnt(9)
	v_mfma_f32_16x16x32_bf16 v[28:31], v[152:155], v[144:147], v[28:31]
	v_mfma_f32_16x16x32_bf16 v[24:27], v[152:155], v[148:151], v[24:27]
	v_mfma_f32_16x16x32_bf16 v[20:23], v[152:155], v[160:163], v[20:23]
	v_mfma_f32_16x16x32_bf16 v[16:19], v[152:155], v[164:167], v[16:19]
	s_waitcnt lgkmcnt(8)
	v_mfma_f32_16x16x32_bf16 v[12:15], v[156:159], v[144:147], v[12:15]
	v_mfma_f32_16x16x32_bf16 v[8:11], v[156:159], v[148:151], v[8:11]
	v_mfma_f32_16x16x32_bf16 v[4:7], v[156:159], v[160:163], v[4:7]
	v_mfma_f32_16x16x32_bf16 v[0:3], v[156:159], v[164:167], v[0:3]
	s_waitcnt lgkmcnt(3)
	v_mfma_f32_16x16x32_bf16 v[60:63], v[204:207], v[208:211], v[60:63]
	v_mfma_f32_16x16x32_bf16 v[56:59], v[204:207], v[212:215], v[56:59]
	v_mfma_f32_16x16x32_bf16 v[52:55], v[204:207], v[216:219], v[52:55]
	v_mfma_f32_16x16x32_bf16 v[48:51], v[204:207], v[220:223], v[48:51]
	s_waitcnt lgkmcnt(2)
	v_mfma_f32_16x16x32_bf16 v[44:47], v[224:227], v[208:211], v[44:47]
	v_mfma_f32_16x16x32_bf16 v[40:43], v[224:227], v[212:215], v[40:43]
	v_mfma_f32_16x16x32_bf16 v[36:39], v[224:227], v[216:219], v[36:39]
	v_mfma_f32_16x16x32_bf16 v[32:35], v[224:227], v[220:223], v[32:35]
	s_waitcnt lgkmcnt(1)
	v_mfma_f32_16x16x32_bf16 v[28:31], v[228:231], v[208:211], v[28:31]
	v_mfma_f32_16x16x32_bf16 v[24:27], v[228:231], v[212:215], v[24:27]
	v_mfma_f32_16x16x32_bf16 v[20:23], v[228:231], v[216:219], v[20:23]
	v_mfma_f32_16x16x32_bf16 v[16:19], v[228:231], v[220:223], v[16:19]
	s_waitcnt lgkmcnt(0)
	v_mfma_f32_16x16x32_bf16 v[12:15], v[232:235], v[208:211], v[12:15]
	v_mfma_f32_16x16x32_bf16 v[8:11], v[232:235], v[212:215], v[8:11]
	v_mfma_f32_16x16x32_bf16 v[4:7], v[232:235], v[216:219], v[4:7]
	v_mfma_f32_16x16x32_bf16 v[0:3], v[232:235], v[220:223], v[0:3]
	s_setprio 0
	s_cmpk_eq_i32 s4, 0x780
	s_waitcnt vmcnt(0)
	s_barrier
	s_cbranch_scc0 .LBB0_3008
	ds_read_b128 v[90:93], v117 offset:55296
	ds_read_b128 v[94:97], v117 offset:53248
	ds_read_b128 v[98:101], v118 offset:38912
	ds_read_b128 v[102:105], v118 offset:36864
	ds_read_b128 v[136:139], v117 offset:51200
	ds_read_b128 v[140:143], v117 offset:49152
	ds_read_b128 v[144:147], v118 offset:34816
	ds_read_b128 v[148:151], v118 offset:32768
	ds_read_b128 v[204:207], v119 offset:32768
	ds_read_b128 v[208:211], v119 offset:34816
	ds_read_b128 v[212:215], v120 offset:49152
	ds_read_b128 v[216:219], v120 offset:51200
	ds_read_b128 v[220:223], v119 offset:36864
	ds_read_b128 v[224:227], v119 offset:38912
	ds_read_b128 v[228:231], v120 offset:53248
	ds_read_b128 v[232:235], v120 offset:55296
	s_setprio 1
	s_waitcnt lgkmcnt(11)
	v_mfma_f32_16x16x32_bf16 v[24:27], v[102:105], v[136:139], v[24:27]
	v_mfma_f32_16x16x32_bf16 v[20:23], v[102:105], v[94:97], v[20:23]
	v_mfma_f32_16x16x32_bf16 v[16:19], v[102:105], v[90:93], v[16:19]
	s_waitcnt lgkmcnt(8)
	v_mfma_f32_16x16x32_bf16 v[60:63], v[148:151], v[140:143], v[60:63]
	v_mfma_f32_16x16x32_bf16 v[56:59], v[148:151], v[136:139], v[56:59]
	v_mfma_f32_16x16x32_bf16 v[52:55], v[148:151], v[94:97], v[52:55]
	v_mfma_f32_16x16x32_bf16 v[48:51], v[148:151], v[90:93], v[48:51]
	v_mfma_f32_16x16x32_bf16 v[44:47], v[144:147], v[140:143], v[44:47]
	v_mfma_f32_16x16x32_bf16 v[40:43], v[144:147], v[136:139], v[40:43]
	v_mfma_f32_16x16x32_bf16 v[36:39], v[144:147], v[94:97], v[36:39]
	v_mfma_f32_16x16x32_bf16 v[32:35], v[144:147], v[90:93], v[32:35]
	v_mfma_f32_16x16x32_bf16 v[28:31], v[102:105], v[140:143], v[28:31]
	v_mfma_f32_16x16x32_bf16 v[12:15], v[98:101], v[140:143], v[12:15]
	v_mfma_f32_16x16x32_bf16 v[8:11], v[98:101], v[136:139], v[8:11]
	v_mfma_f32_16x16x32_bf16 v[4:7], v[98:101], v[94:97], v[4:7]
	v_mfma_f32_16x16x32_bf16 v[0:3], v[98:101], v[90:93], v[0:3]
	s_waitcnt lgkmcnt(3)
	v_mfma_f32_16x16x32_bf16 v[24:27], v[220:223], v[216:219], v[24:27]
	s_waitcnt lgkmcnt(1)
	v_mfma_f32_16x16x32_bf16 v[20:23], v[220:223], v[228:231], v[20:23]
	s_waitcnt lgkmcnt(0)
	v_mfma_f32_16x16x32_bf16 v[16:19], v[220:223], v[232:235], v[16:19]
	v_mfma_f32_16x16x32_bf16 v[60:63], v[204:207], v[212:215], v[60:63]
	v_mfma_f32_16x16x32_bf16 v[56:59], v[204:207], v[216:219], v[56:59]
	v_mfma_f32_16x16x32_bf16 v[52:55], v[204:207], v[228:231], v[52:55]
	v_mfma_f32_16x16x32_bf16 v[48:51], v[204:207], v[232:235], v[48:51]
	v_mfma_f32_16x16x32_bf16 v[44:47], v[208:211], v[212:215], v[44:47]
	v_mfma_f32_16x16x32_bf16 v[40:43], v[208:211], v[216:219], v[40:43]
	v_mfma_f32_16x16x32_bf16 v[36:39], v[208:211], v[228:231], v[36:39]
	v_mfma_f32_16x16x32_bf16 v[32:35], v[208:211], v[232:235], v[32:35]
	v_mfma_f32_16x16x32_bf16 v[28:31], v[220:223], v[212:215], v[28:31]
	v_mfma_f32_16x16x32_bf16 v[12:15], v[224:227], v[212:215], v[12:15]
	v_mfma_f32_16x16x32_bf16 v[8:11], v[224:227], v[216:219], v[8:11]
	v_mfma_f32_16x16x32_bf16 v[4:7], v[224:227], v[228:231], v[4:7]
	v_mfma_f32_16x16x32_bf16 v[0:3], v[224:227], v[232:235], v[0:3]
	s_setprio 0
	s_barrier
	ds_write2_b32 v121, v60, v56 offset1:16
	ds_write2_b32 v121, v61, v57 offset0:132 offset1:148
	v_add_u32_e32 v56, 0x400, v121
	ds_write2_b32 v56, v62, v58 offset0:8 offset1:24
	ds_write2_b32 v56, v63, v59 offset0:140 offset1:156
	ds_write2_b32 v121, v52, v48 offset0:32 offset1:48
	ds_write2_b32 v121, v53, v49 offset0:164 offset1:180
	ds_write2_b32 v56, v54, v50 offset0:40 offset1:56
	ds_write2_b32 v56, v55, v51 offset0:172 offset1:188
	v_add_u32_e32 v48, 0x2000, v121
	ds_write2_b32 v48, v44, v40 offset0:64 offset1:80
	ds_write2_b32 v48, v45, v41 offset0:196 offset1:212
	v_add_u32_e32 v40, 0x2400, v121
	ds_write2_b32 v40, v46, v42 offset0:72 offset1:88
	ds_write2_b32 v40, v47, v43 offset0:204 offset1:220
	ds_write2_b32 v48, v36, v32 offset0:96 offset1:112
	ds_write2_b32 v48, v37, v33 offset0:228 offset1:244
	ds_write2_b32 v40, v38, v34 offset0:104 offset1:120
	ds_write2_b32 v40, v39, v35 offset0:236 offset1:252
	v_add_u32_e32 v32, 0x4000, v121
	ds_write2_b32 v32, v28, v24 offset0:128 offset1:144
	v_add_u32_e32 v24, 0x4400, v121
	ds_write2_b32 v24, v29, v25 offset0:4 offset1:20
	ds_write2_b32 v24, v30, v26 offset0:136 offset1:152
	v_add_u32_e32 v25, 0x4800, v121
	ds_write2_b32 v25, v31, v27 offset0:12 offset1:28
	ds_write2_b32 v32, v20, v16 offset0:160 offset1:176
	ds_write2_b32 v24, v21, v17 offset0:36 offset1:52
	ds_write2_b32 v24, v22, v18 offset0:168 offset1:184
	ds_write2_b32 v25, v23, v19 offset0:44 offset1:60
	v_add_u32_e32 v16, 0x6000, v121
	ds_write2_b32 v16, v12, v8 offset0:192 offset1:208
	v_add_u32_e32 v8, 0x6400, v121
	s_cmpk_gt_u32 s6, 0x3ff
	ds_write2_b32 v8, v13, v9 offset0:68 offset1:84
	ds_write2_b32 v8, v14, v10 offset0:200 offset1:216
	v_add_u32_e32 v9, 0x6800, v121
	v_or_b32_e32 v64, s6, v122
	s_cselect_b64 s[22:23], -1, 0
	s_cmpk_gt_u32 s6, 0x7ff
	ds_write2_b32 v9, v15, v11 offset0:76 offset1:92
	ds_write2_b32 v16, v4, v0 offset0:224 offset1:240
	ds_write2_b32 v8, v5, v1 offset0:100 offset1:116
	ds_write2_b32 v8, v6, v2 offset0:232 offset1:248
	ds_write2_b32 v9, v7, v3 offset0:108 offset1:124
	s_cselect_b64 s[24:25], -1, 0
	s_cmpk_gt_u32 s6, 0xbff
	v_ashrrev_i32_e32 v1, 31, v64
	v_mov_b32_e32 v0, v64
	v_lshlrev_b64 v[2:3], 1, v[64:65]
	v_cmp_lt_i32_e64 s[4:5], s36, v64
	s_cselect_b64 s[26:27], -1, 0
	v_cmp_gt_u32_e64 s[6:7], s37, v64
	v_lshl_add_u64 v[16:17], v[64:65], 2, s[18:19]
	v_lshl_add_u64 v[18:19], s[16:17], 0, v[2:3]
	v_lshl_add_u64 v[20:21], s[14:15], 0, v[2:3]
	v_lshl_add_u64 v[22:23], s[12:13], 0, v[2:3]
	v_lshl_add_u64 v[24:25], v[0:1], 1, s[10:11]
	v_add_u32_e32 v26, v126, v135
	s_mov_b32 s38, 0
	s_waitcnt lgkmcnt(0)
	s_barrier
	s_branch .LBB0_3011

.LBB0_3222:
	s_and_b32 s27, s26, 0x4000
	s_xor_b32 s28, s27, 0x4000
	s_lshl_b32 s28, s28, 1
	s_add_i32 s28, s28, 32
	s_add_u32 s90, s52, s16
	s_addc_u32 s91, s53, s17
	s_add_i32 m0, s28, s82
	s_lshl_b32 s27, s27, 1
	global_load_lds_dwordx4 v184, s[90:91]
	s_add_i32 m0, s28, s83
	s_add_i32 s27, s27, 32
	global_load_lds_dwordx4 v185, s[90:91]
	s_add_i32 m0, s28, s84
	v_add3_u32 v139, s27, v114, v136
	global_load_lds_dwordx4 v186, s[90:91]
	s_add_i32 m0, s28, s85
	v_add3_u32 v172, s27, v115, v136
	global_load_lds_dwordx4 v187, s[90:91]
	s_add_i32 m0, s28, s86
	v_add_u32_e32 v160, v139, v137
	global_load_lds_dwordx4 v188, s[90:91]
	s_add_i32 m0, s28, s87
	v_add_u32_e32 v168, v172, v137
	global_load_lds_dwordx4 v189, s[90:91]
	s_add_i32 m0, s28, s88
	s_addk_i32 s26, 0x4000
	global_load_lds_dwordx4 v190, s[90:91]
	s_add_i32 m0, s28, s89
	s_add_u32 s16, s16, 0x80
	s_addc_u32 s17, s17, 0
	global_load_lds_dwordx4 v191, s[90:91]
	ds_read_b128 v[140:143], v160
	ds_read_b128 v[148:151], v168 offset:16384
	ds_read_b128 v[152:155], v168 offset:18432
	ds_read_b128 v[164:167], v168 offset:20480
	ds_read_b128 v[168:171], v168 offset:22528
	ds_read_b128 v[144:147], v160 offset:2048
	ds_read_b128 v[156:159], v160 offset:4096
	ds_read_b128 v[160:163], v160 offset:6144
	v_add_u32_e32 v139, v139, v138
	v_add_u32_e32 v236, v172, v138
	ds_read_b128 v[204:207], v139
	ds_read_b128 v[208:211], v236 offset:16384
	ds_read_b128 v[212:215], v236 offset:18432
	ds_read_b128 v[216:219], v236 offset:20480
	ds_read_b128 v[220:223], v236 offset:22528
	ds_read_b128 v[224:227], v139 offset:2048
	ds_read_b128 v[228:231], v139 offset:4096
	ds_read_b128 v[232:235], v139 offset:6144
	s_setprio 1
	s_waitcnt lgkmcnt(11)
	v_mfma_f32_16x16x32_bf16 v[60:63], v[140:143], v[148:151], v[60:63]
	v_mfma_f32_16x16x32_bf16 v[56:59], v[140:143], v[152:155], v[56:59]
	v_mfma_f32_16x16x32_bf16 v[52:55], v[140:143], v[164:167], v[52:55]
	v_mfma_f32_16x16x32_bf16 v[48:51], v[140:143], v[168:171], v[48:51]
	s_waitcnt lgkmcnt(10)
	v_mfma_f32_16x16x32_bf16 v[44:47], v[144:147], v[148:151], v[44:47]
	v_mfma_f32_16x16x32_bf16 v[40:43], v[144:147], v[152:155], v[40:43]
	v_mfma_f32_16x16x32_bf16 v[36:39], v[144:147], v[164:167], v[36:39]
	v_mfma_f32_16x16x32_bf16 v[32:35], v[144:147], v[168:171], v[32:35]
	s_waitcnt lgkmcnt(9)
	v_mfma_f32_16x16x32_bf16 v[28:31], v[156:159], v[148:151], v[28:31]
	v_mfma_f32_16x16x32_bf16 v[24:27], v[156:159], v[152:155], v[24:27]
	v_mfma_f32_16x16x32_bf16 v[20:23], v[156:159], v[164:167], v[20:23]
	v_mfma_f32_16x16x32_bf16 v[16:19], v[156:159], v[168:171], v[16:19]
	s_waitcnt lgkmcnt(8)
	v_mfma_f32_16x16x32_bf16 v[12:15], v[160:163], v[148:151], v[12:15]
	v_mfma_f32_16x16x32_bf16 v[8:11], v[160:163], v[152:155], v[8:11]
	v_mfma_f32_16x16x32_bf16 v[4:7], v[160:163], v[164:167], v[4:7]
	v_mfma_f32_16x16x32_bf16 v[0:3], v[160:163], v[168:171], v[0:3]
	s_waitcnt lgkmcnt(3)
	v_mfma_f32_16x16x32_bf16 v[60:63], v[204:207], v[208:211], v[60:63]
	v_mfma_f32_16x16x32_bf16 v[56:59], v[204:207], v[212:215], v[56:59]
	v_mfma_f32_16x16x32_bf16 v[52:55], v[204:207], v[216:219], v[52:55]
	v_mfma_f32_16x16x32_bf16 v[48:51], v[204:207], v[220:223], v[48:51]
	s_waitcnt lgkmcnt(2)
	v_mfma_f32_16x16x32_bf16 v[44:47], v[224:227], v[208:211], v[44:47]
	v_mfma_f32_16x16x32_bf16 v[40:43], v[224:227], v[212:215], v[40:43]
	v_mfma_f32_16x16x32_bf16 v[36:39], v[224:227], v[216:219], v[36:39]
	v_mfma_f32_16x16x32_bf16 v[32:35], v[224:227], v[220:223], v[32:35]
	s_waitcnt lgkmcnt(1)
	v_mfma_f32_16x16x32_bf16 v[28:31], v[228:231], v[208:211], v[28:31]
	v_mfma_f32_16x16x32_bf16 v[24:27], v[228:231], v[212:215], v[24:27]
	v_mfma_f32_16x16x32_bf16 v[20:23], v[228:231], v[216:219], v[20:23]
	v_mfma_f32_16x16x32_bf16 v[16:19], v[228:231], v[220:223], v[16:19]
	s_waitcnt lgkmcnt(0)
	v_mfma_f32_16x16x32_bf16 v[12:15], v[232:235], v[208:211], v[12:15]
	v_mfma_f32_16x16x32_bf16 v[8:11], v[232:235], v[212:215], v[8:11]
	v_mfma_f32_16x16x32_bf16 v[4:7], v[232:235], v[216:219], v[4:7]
	v_mfma_f32_16x16x32_bf16 v[0:3], v[232:235], v[220:223], v[0:3]
	s_setprio 0
	s_cmpk_eq_i32 s16, 0x780
	s_waitcnt vmcnt(0)
	s_barrier
	s_cbranch_scc0 .LBB0_3222
	ds_read_b128 v[90:93], v118 offset:55296
	ds_read_b128 v[94:97], v118 offset:53248
	ds_read_b128 v[98:101], v119 offset:38912
	ds_read_b128 v[102:105], v119 offset:36864
	ds_read_b128 v[140:143], v118 offset:51200
	ds_read_b128 v[144:147], v118 offset:49152
	ds_read_b128 v[148:151], v119 offset:34816
	ds_read_b128 v[152:155], v119 offset:32768
	ds_read_b128 v[204:207], v120 offset:32768
	ds_read_b128 v[208:211], v120 offset:34816
	ds_read_b128 v[212:215], v121 offset:49152
	ds_read_b128 v[216:219], v121 offset:51200
	ds_read_b128 v[220:223], v120 offset:36864
	ds_read_b128 v[224:227], v120 offset:38912
	ds_read_b128 v[228:231], v121 offset:53248
	ds_read_b128 v[232:235], v121 offset:55296
	s_setprio 1
	s_waitcnt lgkmcnt(13)
	v_mfma_f32_16x16x32_bf16 v[4:7], v[98:101], v[94:97], v[4:7]
	v_mfma_f32_16x16x32_bf16 v[0:3], v[98:101], v[90:93], v[0:3]
	s_waitcnt lgkmcnt(8)
	v_mfma_f32_16x16x32_bf16 v[60:63], v[152:155], v[144:147], v[60:63]
	v_mfma_f32_16x16x32_bf16 v[56:59], v[152:155], v[140:143], v[56:59]
	v_mfma_f32_16x16x32_bf16 v[52:55], v[152:155], v[94:97], v[52:55]
	v_mfma_f32_16x16x32_bf16 v[48:51], v[152:155], v[90:93], v[48:51]
	v_mfma_f32_16x16x32_bf16 v[44:47], v[148:151], v[144:147], v[44:47]
	v_mfma_f32_16x16x32_bf16 v[40:43], v[148:151], v[140:143], v[40:43]
	v_mfma_f32_16x16x32_bf16 v[36:39], v[148:151], v[94:97], v[36:39]
	v_mfma_f32_16x16x32_bf16 v[32:35], v[148:151], v[90:93], v[32:35]
	v_mfma_f32_16x16x32_bf16 v[28:31], v[102:105], v[144:147], v[28:31]
	v_mfma_f32_16x16x32_bf16 v[24:27], v[102:105], v[140:143], v[24:27]
	v_mfma_f32_16x16x32_bf16 v[20:23], v[102:105], v[94:97], v[20:23]
	v_mfma_f32_16x16x32_bf16 v[16:19], v[102:105], v[90:93], v[16:19]
	v_mfma_f32_16x16x32_bf16 v[12:15], v[98:101], v[144:147], v[12:15]
	v_mfma_f32_16x16x32_bf16 v[8:11], v[98:101], v[140:143], v[8:11]
	s_waitcnt lgkmcnt(1)
	v_mfma_f32_16x16x32_bf16 v[4:7], v[224:227], v[228:231], v[4:7]
	s_waitcnt lgkmcnt(0)
	v_mfma_f32_16x16x32_bf16 v[0:3], v[224:227], v[232:235], v[0:3]
	v_mfma_f32_16x16x32_bf16 v[60:63], v[204:207], v[212:215], v[60:63]
	v_mfma_f32_16x16x32_bf16 v[56:59], v[204:207], v[216:219], v[56:59]
	v_mfma_f32_16x16x32_bf16 v[52:55], v[204:207], v[228:231], v[52:55]
	v_mfma_f32_16x16x32_bf16 v[48:51], v[204:207], v[232:235], v[48:51]
	v_mfma_f32_16x16x32_bf16 v[44:47], v[208:211], v[212:215], v[44:47]
	v_mfma_f32_16x16x32_bf16 v[40:43], v[208:211], v[216:219], v[40:43]
	v_mfma_f32_16x16x32_bf16 v[36:39], v[208:211], v[228:231], v[36:39]
	v_mfma_f32_16x16x32_bf16 v[32:35], v[208:211], v[232:235], v[32:35]
	v_mfma_f32_16x16x32_bf16 v[28:31], v[220:223], v[212:215], v[28:31]
	v_mfma_f32_16x16x32_bf16 v[24:27], v[220:223], v[216:219], v[24:27]
	v_mfma_f32_16x16x32_bf16 v[20:23], v[220:223], v[228:231], v[20:23]
	v_mfma_f32_16x16x32_bf16 v[16:19], v[220:223], v[232:235], v[16:19]
	v_mfma_f32_16x16x32_bf16 v[12:15], v[224:227], v[212:215], v[12:15]
	v_mfma_f32_16x16x32_bf16 v[8:11], v[224:227], v[216:219], v[8:11]
	s_setprio 0
	s_barrier
	ds_write2_b32 v116, v60, v56 offset1:16
	ds_write2_b32 v116, v61, v57 offset0:132 offset1:148
	v_add_u32_e32 v56, 0x400, v116
	ds_write2_b32 v56, v62, v58 offset0:8 offset1:24
	ds_write2_b32 v56, v63, v59 offset0:140 offset1:156
	ds_write2_b32 v116, v52, v48 offset0:32 offset1:48
	ds_write2_b32 v116, v53, v49 offset0:164 offset1:180
	ds_write2_b32 v56, v54, v50 offset0:40 offset1:56
	ds_write2_b32 v56, v55, v51 offset0:172 offset1:188
	v_add_u32_e32 v48, 0x2000, v116
	ds_write2_b32 v48, v44, v40 offset0:64 offset1:80
	ds_write2_b32 v48, v45, v41 offset0:196 offset1:212
	v_add_u32_e32 v40, 0x2400, v116
	ds_write2_b32 v40, v46, v42 offset0:72 offset1:88
	ds_write2_b32 v40, v47, v43 offset0:204 offset1:220
	ds_write2_b32 v48, v36, v32 offset0:96 offset1:112
	ds_write2_b32 v48, v37, v33 offset0:228 offset1:244
	ds_write2_b32 v40, v38, v34 offset0:104 offset1:120
	ds_write2_b32 v40, v39, v35 offset0:236 offset1:252
	v_add_u32_e32 v32, 0x4000, v116
	ds_write2_b32 v32, v28, v24 offset0:128 offset1:144
	v_add_u32_e32 v24, 0x4400, v116
	ds_write2_b32 v24, v29, v25 offset0:4 offset1:20
	ds_write2_b32 v24, v30, v26 offset0:136 offset1:152
	v_add_u32_e32 v25, 0x4800, v116
	ds_write2_b32 v25, v31, v27 offset0:12 offset1:28
	ds_write2_b32 v32, v20, v16 offset0:160 offset1:176
	ds_write2_b32 v24, v21, v17 offset0:36 offset1:52
	ds_write2_b32 v24, v22, v18 offset0:168 offset1:184
	ds_write2_b32 v25, v23, v19 offset0:44 offset1:60
	v_add_u32_e32 v16, 0x6000, v116
	ds_write2_b32 v16, v12, v8 offset0:192 offset1:208
	v_add_u32_e32 v8, 0x6400, v116
	ds_write2_b32 v8, v13, v9 offset0:68 offset1:84
	ds_write2_b32 v8, v14, v10 offset0:200 offset1:216
	v_add_u32_e32 v9, 0x6800, v116
	ds_write2_b32 v9, v15, v11 offset0:76 offset1:92
	ds_write2_b32 v16, v4, v0 offset0:224 offset1:240
	ds_write2_b32 v8, v5, v1 offset0:100 offset1:116
	ds_write2_b32 v8, v6, v2 offset0:232 offset1:248
	ds_write2_b32 v9, v7, v3 offset0:108 offset1:124
	v_or_b32_e32 v0, s25, v117
	v_ashrrev_i32_e32 v1, 31, v0
	v_lshlrev_b64 v[2:3], 2, v[0:1]
	v_lshl_add_u64 v[0:1], s[14:15], 0, v[2:3]
	v_lshl_add_u64 v[2:3], s[6:7], 0, v[2:3]
	v_add_u32_e32 v4, s24, v129
	s_mov_b32 s16, 0
	s_waitcnt lgkmcnt(0)
	s_barrier

.LBB0_3231:
	s_and_b32 s23, s22, 0x4000
	s_xor_b32 s24, s23, 0x4000
	s_lshl_b32 s24, s24, 1
	s_add_i32 s24, s24, 32
	s_add_u32 s90, s52, s8
	s_addc_u32 s91, s53, s9
	s_add_i32 m0, s24, s82
	s_lshl_b32 s23, s23, 1
	global_load_lds_dwordx4 v184, s[90:91]
	s_add_i32 m0, s24, s83
	s_add_i32 s23, s23, 32
	global_load_lds_dwordx4 v185, s[90:91]
	s_add_i32 m0, s24, s84
	v_add3_u32 v170, s23, v112, v135
	global_load_lds_dwordx4 v186, s[90:91]
	s_add_i32 m0, s24, s85
	v_add3_u32 v171, s23, v113, v135
	global_load_lds_dwordx4 v187, s[90:91]
	s_add_i32 m0, s24, s86
	v_add_u32_e32 v158, v170, v136
	global_load_lds_dwordx4 v188, s[90:91]
	s_add_i32 m0, s24, s87
	v_add_u32_e32 v166, v171, v136
	global_load_lds_dwordx4 v189, s[90:91]
	s_add_i32 m0, s24, s88
	s_addk_i32 s22, 0x4000
	global_load_lds_dwordx4 v190, s[90:91]
	s_add_i32 m0, s24, s89
	s_add_u32 s8, s8, 0x80
	s_addc_u32 s9, s9, 0
	global_load_lds_dwordx4 v191, s[90:91]
	ds_read_b128 v[138:141], v158
	ds_read_b128 v[146:149], v166 offset:16384
	ds_read_b128 v[150:153], v166 offset:18432
	ds_read_b128 v[162:165], v166 offset:20480
	ds_read_b128 v[166:169], v166 offset:22528
	ds_read_b128 v[142:145], v158 offset:2048
	ds_read_b128 v[154:157], v158 offset:4096
	ds_read_b128 v[158:161], v158 offset:6144
	v_add_u32_e32 v236, v170, v137
	v_add_u32_e32 v237, v171, v137
	ds_read_b128 v[204:207], v236
	ds_read_b128 v[208:211], v237 offset:16384
	ds_read_b128 v[212:215], v237 offset:18432
	ds_read_b128 v[216:219], v237 offset:20480
	ds_read_b128 v[220:223], v237 offset:22528
	ds_read_b128 v[224:227], v236 offset:2048
	ds_read_b128 v[228:231], v236 offset:4096
	ds_read_b128 v[232:235], v236 offset:6144
	s_setprio 1
	s_waitcnt lgkmcnt(11)
	v_mfma_f32_16x16x32_bf16 v[60:63], v[138:141], v[146:149], v[60:63]
	v_mfma_f32_16x16x32_bf16 v[56:59], v[138:141], v[150:153], v[56:59]
	v_mfma_f32_16x16x32_bf16 v[52:55], v[138:141], v[162:165], v[52:55]
	v_mfma_f32_16x16x32_bf16 v[48:51], v[138:141], v[166:169], v[48:51]
	s_waitcnt lgkmcnt(10)
	v_mfma_f32_16x16x32_bf16 v[44:47], v[142:145], v[146:149], v[44:47]
	v_mfma_f32_16x16x32_bf16 v[40:43], v[142:145], v[150:153], v[40:43]
	v_mfma_f32_16x16x32_bf16 v[36:39], v[142:145], v[162:165], v[36:39]
	v_mfma_f32_16x16x32_bf16 v[32:35], v[142:145], v[166:169], v[32:35]
	s_waitcnt lgkmcnt(9)
	v_mfma_f32_16x16x32_bf16 v[28:31], v[154:157], v[146:149], v[28:31]
	v_mfma_f32_16x16x32_bf16 v[24:27], v[154:157], v[150:153], v[24:27]
	v_mfma_f32_16x16x32_bf16 v[20:23], v[154:157], v[162:165], v[20:23]
	v_mfma_f32_16x16x32_bf16 v[16:19], v[154:157], v[166:169], v[16:19]
	s_waitcnt lgkmcnt(8)
	v_mfma_f32_16x16x32_bf16 v[12:15], v[158:161], v[146:149], v[12:15]
	v_mfma_f32_16x16x32_bf16 v[8:11], v[158:161], v[150:153], v[8:11]
	v_mfma_f32_16x16x32_bf16 v[4:7], v[158:161], v[162:165], v[4:7]
	v_mfma_f32_16x16x32_bf16 v[0:3], v[158:161], v[166:169], v[0:3]
	s_waitcnt lgkmcnt(3)
	v_mfma_f32_16x16x32_bf16 v[60:63], v[204:207], v[208:211], v[60:63]
	v_mfma_f32_16x16x32_bf16 v[56:59], v[204:207], v[212:215], v[56:59]
	v_mfma_f32_16x16x32_bf16 v[52:55], v[204:207], v[216:219], v[52:55]
	v_mfma_f32_16x16x32_bf16 v[48:51], v[204:207], v[220:223], v[48:51]
	s_waitcnt lgkmcnt(2)
	v_mfma_f32_16x16x32_bf16 v[44:47], v[224:227], v[208:211], v[44:47]
	v_mfma_f32_16x16x32_bf16 v[40:43], v[224:227], v[212:215], v[40:43]
	v_mfma_f32_16x16x32_bf16 v[36:39], v[224:227], v[216:219], v[36:39]
	v_mfma_f32_16x16x32_bf16 v[32:35], v[224:227], v[220:223], v[32:35]
	s_waitcnt lgkmcnt(1)
	v_mfma_f32_16x16x32_bf16 v[28:31], v[228:231], v[208:211], v[28:31]
	v_mfma_f32_16x16x32_bf16 v[24:27], v[228:231], v[212:215], v[24:27]
	v_mfma_f32_16x16x32_bf16 v[20:23], v[228:231], v[216:219], v[20:23]
	v_mfma_f32_16x16x32_bf16 v[16:19], v[228:231], v[220:223], v[16:19]
	s_waitcnt lgkmcnt(0)
	v_mfma_f32_16x16x32_bf16 v[12:15], v[232:235], v[208:211], v[12:15]
	v_mfma_f32_16x16x32_bf16 v[8:11], v[232:235], v[212:215], v[8:11]
	v_mfma_f32_16x16x32_bf16 v[4:7], v[232:235], v[216:219], v[4:7]
	v_mfma_f32_16x16x32_bf16 v[0:3], v[232:235], v[220:223], v[0:3]
	s_setprio 0
	s_cmpk_eq_i32 s8, 0x780
	s_waitcnt vmcnt(0)
	s_barrier
	s_cbranch_scc0 .LBB0_3231
	ds_read_b128 v[88:91], v116 offset:55296
	ds_read_b128 v[92:95], v116 offset:53248
	ds_read_b128 v[96:99], v117 offset:38912
	ds_read_b128 v[100:103], v117 offset:36864
	ds_read_b128 v[138:141], v116 offset:51200
	ds_read_b128 v[142:145], v116 offset:49152
	ds_read_b128 v[146:149], v117 offset:34816
	ds_read_b128 v[150:153], v117 offset:32768
	ds_read_b128 v[204:207], v118 offset:32768
	ds_read_b128 v[208:211], v118 offset:34816
	ds_read_b128 v[212:215], v119 offset:49152
	ds_read_b128 v[216:219], v119 offset:51200
	ds_read_b128 v[220:223], v118 offset:36864
	ds_read_b128 v[224:227], v118 offset:38912
	ds_read_b128 v[228:231], v119 offset:53248
	ds_read_b128 v[232:235], v119 offset:55296
	s_setprio 1
	s_waitcnt lgkmcnt(13)
	v_mfma_f32_16x16x32_bf16 v[4:7], v[96:99], v[92:95], v[4:7]
	v_mfma_f32_16x16x32_bf16 v[0:3], v[96:99], v[88:91], v[0:3]
	s_waitcnt lgkmcnt(8)
	v_mfma_f32_16x16x32_bf16 v[60:63], v[150:153], v[142:145], v[60:63]
	v_mfma_f32_16x16x32_bf16 v[56:59], v[150:153], v[138:141], v[56:59]
	v_mfma_f32_16x16x32_bf16 v[52:55], v[150:153], v[92:95], v[52:55]
	v_mfma_f32_16x16x32_bf16 v[48:51], v[150:153], v[88:91], v[48:51]
	v_mfma_f32_16x16x32_bf16 v[44:47], v[146:149], v[142:145], v[44:47]
	v_mfma_f32_16x16x32_bf16 v[40:43], v[146:149], v[138:141], v[40:43]
	v_mfma_f32_16x16x32_bf16 v[36:39], v[146:149], v[92:95], v[36:39]
	v_mfma_f32_16x16x32_bf16 v[32:35], v[146:149], v[88:91], v[32:35]
	v_mfma_f32_16x16x32_bf16 v[28:31], v[100:103], v[142:145], v[28:31]
	v_mfma_f32_16x16x32_bf16 v[24:27], v[100:103], v[138:141], v[24:27]
	v_mfma_f32_16x16x32_bf16 v[20:23], v[100:103], v[92:95], v[20:23]
	v_mfma_f32_16x16x32_bf16 v[16:19], v[100:103], v[88:91], v[16:19]
	v_mfma_f32_16x16x32_bf16 v[12:15], v[96:99], v[142:145], v[12:15]
	v_mfma_f32_16x16x32_bf16 v[8:11], v[96:99], v[138:141], v[8:11]
	s_waitcnt lgkmcnt(1)
	v_mfma_f32_16x16x32_bf16 v[4:7], v[224:227], v[228:231], v[4:7]
	s_waitcnt lgkmcnt(0)
	v_mfma_f32_16x16x32_bf16 v[0:3], v[224:227], v[232:235], v[0:3]
	v_mfma_f32_16x16x32_bf16 v[60:63], v[204:207], v[212:215], v[60:63]
	v_mfma_f32_16x16x32_bf16 v[56:59], v[204:207], v[216:219], v[56:59]
	v_mfma_f32_16x16x32_bf16 v[52:55], v[204:207], v[228:231], v[52:55]
	v_mfma_f32_16x16x32_bf16 v[48:51], v[204:207], v[232:235], v[48:51]
	v_mfma_f32_16x16x32_bf16 v[44:47], v[208:211], v[212:215], v[44:47]
	v_mfma_f32_16x16x32_bf16 v[40:43], v[208:211], v[216:219], v[40:43]
	v_mfma_f32_16x16x32_bf16 v[36:39], v[208:211], v[228:231], v[36:39]
	v_mfma_f32_16x16x32_bf16 v[32:35], v[208:211], v[232:235], v[32:35]
	v_mfma_f32_16x16x32_bf16 v[28:31], v[220:223], v[212:215], v[28:31]
	v_mfma_f32_16x16x32_bf16 v[24:27], v[220:223], v[216:219], v[24:27]
	v_mfma_f32_16x16x32_bf16 v[20:23], v[220:223], v[228:231], v[20:23]
	v_mfma_f32_16x16x32_bf16 v[16:19], v[220:223], v[232:235], v[16:19]
	v_mfma_f32_16x16x32_bf16 v[12:15], v[224:227], v[212:215], v[12:15]
	v_mfma_f32_16x16x32_bf16 v[8:11], v[224:227], v[216:219], v[8:11]
	s_setprio 0
	s_barrier
	ds_write2_b32 v114, v60, v56 offset1:16
	ds_write2_b32 v114, v61, v57 offset0:132 offset1:148
	v_add_u32_e32 v56, 0x400, v114
	ds_write2_b32 v56, v62, v58 offset0:8 offset1:24
	ds_write2_b32 v56, v63, v59 offset0:140 offset1:156
	ds_write2_b32 v114, v52, v48 offset0:32 offset1:48
	ds_write2_b32 v114, v53, v49 offset0:164 offset1:180
	ds_write2_b32 v56, v54, v50 offset0:40 offset1:56
	ds_write2_b32 v56, v55, v51 offset0:172 offset1:188
	v_add_u32_e32 v48, 0x2000, v114
	ds_write2_b32 v48, v44, v40 offset0:64 offset1:80
	ds_write2_b32 v48, v45, v41 offset0:196 offset1:212
	v_add_u32_e32 v40, 0x2400, v114
	ds_write2_b32 v40, v46, v42 offset0:72 offset1:88
	ds_write2_b32 v40, v47, v43 offset0:204 offset1:220
	ds_write2_b32 v48, v36, v32 offset0:96 offset1:112
	ds_write2_b32 v48, v37, v33 offset0:228 offset1:244
	ds_write2_b32 v40, v38, v34 offset0:104 offset1:120
	ds_write2_b32 v40, v39, v35 offset0:236 offset1:252
	v_add_u32_e32 v32, 0x4000, v114
	ds_write2_b32 v32, v28, v24 offset0:128 offset1:144
	v_add_u32_e32 v24, 0x4400, v114
	ds_write2_b32 v24, v29, v25 offset0:4 offset1:20
	ds_write2_b32 v24, v30, v26 offset0:136 offset1:152
	v_add_u32_e32 v25, 0x4800, v114
	ds_write2_b32 v25, v31, v27 offset0:12 offset1:28
	ds_write2_b32 v32, v20, v16 offset0:160 offset1:176
	ds_write2_b32 v24, v21, v17 offset0:36 offset1:52
	ds_write2_b32 v24, v22, v18 offset0:168 offset1:184
	ds_write2_b32 v25, v23, v19 offset0:44 offset1:60
	v_add_u32_e32 v16, 0x6000, v114
	ds_write2_b32 v16, v12, v8 offset0:192 offset1:208
	v_add_u32_e32 v8, 0x6400, v114
	ds_write2_b32 v8, v13, v9 offset0:68 offset1:84
	ds_write2_b32 v8, v14, v10 offset0:200 offset1:216
	v_add_u32_e32 v9, 0x6800, v114
	ds_write2_b32 v9, v15, v11 offset0:76 offset1:92
	ds_write2_b32 v16, v4, v0 offset0:224 offset1:240
	ds_write2_b32 v8, v5, v1 offset0:100 offset1:116
	ds_write2_b32 v8, v6, v2 offset0:232 offset1:248
	ds_write2_b32 v9, v7, v3 offset0:108 offset1:124
	v_or_b32_e32 v0, s21, v115
	v_ashrrev_i32_e32 v1, 31, v0
	v_lshlrev_b64 v[2:3], 2, v[0:1]
	v_lshl_add_u64 v[0:1], s[10:11], 0, v[2:3]
	v_lshl_add_u64 v[2:3], s[6:7], 0, v[2:3]
	v_add_u32_e32 v4, s20, v128
	s_mov_b32 s8, 0
	s_waitcnt lgkmcnt(0)
	s_barrier

.LBB0_3388:
	s_and_b32 s20, s19, 0x4000
	s_xor_b32 s21, s20, 0x4000
	s_lshl_b32 s21, s21, 1
	s_add_i32 s21, s21, 32
	s_add_u32 s90, s52, s12
	s_addc_u32 s91, s53, s13
	s_add_i32 m0, s21, s82
	s_lshl_b32 s20, s20, 1
	global_load_lds_dwordx4 v184, s[90:91]
	s_add_i32 m0, s21, s83
	s_add_i32 s20, s20, 32
	global_load_lds_dwordx4 v185, s[90:91]
	s_add_i32 m0, s21, s84
	v_lshl_add_u32 v170, v114, 1, s20
	global_load_lds_dwordx4 v186, s[90:91]
	s_add_i32 m0, s21, s85
	v_lshl_add_u32 v171, v115, 1, s20
	global_load_lds_dwordx4 v187, s[90:91]
	s_add_i32 m0, s21, s86
	v_add_u32_e32 v158, v170, v136
	global_load_lds_dwordx4 v188, s[90:91]
	s_add_i32 m0, s21, s87
	v_add_u32_e32 v166, v171, v136
	global_load_lds_dwordx4 v189, s[90:91]
	s_add_i32 m0, s21, s88
	s_addk_i32 s19, 0x4000
	global_load_lds_dwordx4 v190, s[90:91]
	s_add_i32 m0, s21, s89
	s_add_u32 s12, s12, 0x80
	s_addc_u32 s13, s13, 0
	global_load_lds_dwordx4 v191, s[90:91]
	ds_read_b128 v[138:141], v158
	ds_read_b128 v[146:149], v166 offset:16384
	ds_read_b128 v[150:153], v166 offset:18432
	ds_read_b128 v[162:165], v166 offset:20480
	ds_read_b128 v[166:169], v166 offset:22528
	ds_read_b128 v[142:145], v158 offset:2048
	ds_read_b128 v[154:157], v158 offset:4096
	ds_read_b128 v[158:161], v158 offset:6144
	v_add_u32_e32 v236, v170, v137
	v_add_u32_e32 v237, v171, v137
	ds_read_b128 v[204:207], v236
	ds_read_b128 v[208:211], v237 offset:16384
	ds_read_b128 v[212:215], v237 offset:18432
	ds_read_b128 v[216:219], v237 offset:20480
	ds_read_b128 v[220:223], v237 offset:22528
	ds_read_b128 v[224:227], v236 offset:2048
	ds_read_b128 v[228:231], v236 offset:4096
	ds_read_b128 v[232:235], v236 offset:6144
	s_setprio 1
	s_waitcnt lgkmcnt(11)
	v_mfma_f32_16x16x32_bf16 v[60:63], v[138:141], v[146:149], v[60:63]
	v_mfma_f32_16x16x32_bf16 v[56:59], v[138:141], v[150:153], v[56:59]
	v_mfma_f32_16x16x32_bf16 v[52:55], v[138:141], v[162:165], v[52:55]
	v_mfma_f32_16x16x32_bf16 v[48:51], v[138:141], v[166:169], v[48:51]
	s_waitcnt lgkmcnt(10)
	v_mfma_f32_16x16x32_bf16 v[44:47], v[142:145], v[146:149], v[44:47]
	v_mfma_f32_16x16x32_bf16 v[40:43], v[142:145], v[150:153], v[40:43]
	v_mfma_f32_16x16x32_bf16 v[36:39], v[142:145], v[162:165], v[36:39]
	v_mfma_f32_16x16x32_bf16 v[32:35], v[142:145], v[166:169], v[32:35]
	s_waitcnt lgkmcnt(9)
	v_mfma_f32_16x16x32_bf16 v[28:31], v[154:157], v[146:149], v[28:31]
	v_mfma_f32_16x16x32_bf16 v[24:27], v[154:157], v[150:153], v[24:27]
	v_mfma_f32_16x16x32_bf16 v[20:23], v[154:157], v[162:165], v[20:23]
	v_mfma_f32_16x16x32_bf16 v[16:19], v[154:157], v[166:169], v[16:19]
	s_waitcnt lgkmcnt(8)
	v_mfma_f32_16x16x32_bf16 v[12:15], v[158:161], v[146:149], v[12:15]
	v_mfma_f32_16x16x32_bf16 v[8:11], v[158:161], v[150:153], v[8:11]
	v_mfma_f32_16x16x32_bf16 v[4:7], v[158:161], v[162:165], v[4:7]
	v_mfma_f32_16x16x32_bf16 v[0:3], v[158:161], v[166:169], v[0:3]
	s_waitcnt lgkmcnt(3)
	v_mfma_f32_16x16x32_bf16 v[60:63], v[204:207], v[208:211], v[60:63]
	v_mfma_f32_16x16x32_bf16 v[56:59], v[204:207], v[212:215], v[56:59]
	v_mfma_f32_16x16x32_bf16 v[52:55], v[204:207], v[216:219], v[52:55]
	v_mfma_f32_16x16x32_bf16 v[48:51], v[204:207], v[220:223], v[48:51]
	s_waitcnt lgkmcnt(2)
	v_mfma_f32_16x16x32_bf16 v[44:47], v[224:227], v[208:211], v[44:47]
	v_mfma_f32_16x16x32_bf16 v[40:43], v[224:227], v[212:215], v[40:43]
	v_mfma_f32_16x16x32_bf16 v[36:39], v[224:227], v[216:219], v[36:39]
	v_mfma_f32_16x16x32_bf16 v[32:35], v[224:227], v[220:223], v[32:35]
	s_waitcnt lgkmcnt(1)
	v_mfma_f32_16x16x32_bf16 v[28:31], v[228:231], v[208:211], v[28:31]
	v_mfma_f32_16x16x32_bf16 v[24:27], v[228:231], v[212:215], v[24:27]
	v_mfma_f32_16x16x32_bf16 v[20:23], v[228:231], v[216:219], v[20:23]
	v_mfma_f32_16x16x32_bf16 v[16:19], v[228:231], v[220:223], v[16:19]
	s_waitcnt lgkmcnt(0)
	v_mfma_f32_16x16x32_bf16 v[12:15], v[232:235], v[208:211], v[12:15]
	v_mfma_f32_16x16x32_bf16 v[8:11], v[232:235], v[212:215], v[8:11]
	v_mfma_f32_16x16x32_bf16 v[4:7], v[232:235], v[216:219], v[4:7]
	v_mfma_f32_16x16x32_bf16 v[0:3], v[232:235], v[220:223], v[0:3]
	s_setprio 0
	s_cmpk_eq_i32 s12, 0x780
	s_waitcnt vmcnt(0)
	s_barrier
	s_cbranch_scc0 .LBB0_3388
	ds_read_b128 v[90:93], v116 offset:55296
	ds_read_b128 v[94:97], v116 offset:53248
	ds_read_b128 v[98:101], v117 offset:38912
	ds_read_b128 v[102:105], v117 offset:36864
	ds_read_b128 v[138:141], v116 offset:51200
	ds_read_b128 v[142:145], v116 offset:49152
	ds_read_b128 v[146:149], v117 offset:34816
	ds_read_b128 v[150:153], v117 offset:32768
	ds_read_b128 v[204:207], v118 offset:32768
	ds_read_b128 v[208:211], v118 offset:34816
	ds_read_b128 v[212:215], v119 offset:49152
	ds_read_b128 v[216:219], v119 offset:51200
	ds_read_b128 v[220:223], v118 offset:36864
	ds_read_b128 v[224:227], v118 offset:38912
	ds_read_b128 v[228:231], v119 offset:53248
	ds_read_b128 v[232:235], v119 offset:55296
	s_setprio 1
	s_waitcnt lgkmcnt(13)
	v_mfma_f32_16x16x32_bf16 v[0:3], v[98:101], v[90:93], v[0:3]
	s_waitcnt lgkmcnt(8)
	v_mfma_f32_16x16x32_bf16 v[60:63], v[150:153], v[142:145], v[60:63]
	v_mfma_f32_16x16x32_bf16 v[56:59], v[150:153], v[138:141], v[56:59]
	v_mfma_f32_16x16x32_bf16 v[52:55], v[150:153], v[94:97], v[52:55]
	v_mfma_f32_16x16x32_bf16 v[48:51], v[150:153], v[90:93], v[48:51]
	v_mfma_f32_16x16x32_bf16 v[44:47], v[146:149], v[142:145], v[44:47]
	v_mfma_f32_16x16x32_bf16 v[40:43], v[146:149], v[138:141], v[40:43]
	v_mfma_f32_16x16x32_bf16 v[36:39], v[146:149], v[94:97], v[36:39]
	v_mfma_f32_16x16x32_bf16 v[32:35], v[146:149], v[90:93], v[32:35]
	v_mfma_f32_16x16x32_bf16 v[28:31], v[102:105], v[142:145], v[28:31]
	v_mfma_f32_16x16x32_bf16 v[24:27], v[102:105], v[138:141], v[24:27]
	v_mfma_f32_16x16x32_bf16 v[20:23], v[102:105], v[94:97], v[20:23]
	v_mfma_f32_16x16x32_bf16 v[16:19], v[102:105], v[90:93], v[16:19]
	v_mfma_f32_16x16x32_bf16 v[12:15], v[98:101], v[142:145], v[12:15]
	v_mfma_f32_16x16x32_bf16 v[8:11], v[98:101], v[138:141], v[8:11]
	v_mfma_f32_16x16x32_bf16 v[4:7], v[98:101], v[94:97], v[4:7]
	s_waitcnt lgkmcnt(0)
	v_mfma_f32_16x16x32_bf16 v[0:3], v[224:227], v[232:235], v[0:3]
	v_mfma_f32_16x16x32_bf16 v[60:63], v[204:207], v[212:215], v[60:63]
	v_mfma_f32_16x16x32_bf16 v[56:59], v[204:207], v[216:219], v[56:59]
	v_mfma_f32_16x16x32_bf16 v[52:55], v[204:207], v[228:231], v[52:55]
	v_mfma_f32_16x16x32_bf16 v[48:51], v[204:207], v[232:235], v[48:51]
	v_mfma_f32_16x16x32_bf16 v[44:47], v[208:211], v[212:215], v[44:47]
	v_mfma_f32_16x16x32_bf16 v[40:43], v[208:211], v[216:219], v[40:43]
	v_mfma_f32_16x16x32_bf16 v[36:39], v[208:211], v[228:231], v[36:39]
	v_mfma_f32_16x16x32_bf16 v[32:35], v[208:211], v[232:235], v[32:35]
	v_mfma_f32_16x16x32_bf16 v[28:31], v[220:223], v[212:215], v[28:31]
	v_mfma_f32_16x16x32_bf16 v[24:27], v[220:223], v[216:219], v[24:27]
	v_mfma_f32_16x16x32_bf16 v[20:23], v[220:223], v[228:231], v[20:23]
	v_mfma_f32_16x16x32_bf16 v[16:19], v[220:223], v[232:235], v[16:19]
	v_mfma_f32_16x16x32_bf16 v[12:15], v[224:227], v[212:215], v[12:15]
	v_mfma_f32_16x16x32_bf16 v[8:11], v[224:227], v[216:219], v[8:11]
	v_mfma_f32_16x16x32_bf16 v[4:7], v[224:227], v[228:231], v[4:7]
	s_setprio 0
	s_barrier
	ds_write2_b32 v120, v60, v56 offset1:16
	ds_write2_b32 v120, v61, v57 offset0:132 offset1:148
	v_add_u32_e32 v56, 0x400, v120
	ds_write2_b32 v56, v62, v58 offset0:8 offset1:24
	ds_write2_b32 v56, v63, v59 offset0:140 offset1:156
	ds_write2_b32 v120, v52, v48 offset0:32 offset1:48
	ds_write2_b32 v120, v53, v49 offset0:164 offset1:180
	ds_write2_b32 v56, v54, v50 offset0:40 offset1:56
	ds_write2_b32 v56, v55, v51 offset0:172 offset1:188
	v_add_u32_e32 v48, 0x2000, v120
	ds_write2_b32 v48, v44, v40 offset0:64 offset1:80
	ds_write2_b32 v48, v45, v41 offset0:196 offset1:212
	v_add_u32_e32 v40, 0x2400, v120
	ds_write2_b32 v40, v46, v42 offset0:72 offset1:88
	ds_write2_b32 v40, v47, v43 offset0:204 offset1:220
	ds_write2_b32 v48, v36, v32 offset0:96 offset1:112
	ds_write2_b32 v48, v37, v33 offset0:228 offset1:244
	ds_write2_b32 v40, v38, v34 offset0:104 offset1:120
	ds_write2_b32 v40, v39, v35 offset0:236 offset1:252
	v_add_u32_e32 v32, 0x4000, v120
	ds_write2_b32 v32, v28, v24 offset0:128 offset1:144
	v_add_u32_e32 v24, 0x4400, v120
	ds_write2_b32 v24, v29, v25 offset0:4 offset1:20
	ds_write2_b32 v24, v30, v26 offset0:136 offset1:152
	v_add_u32_e32 v25, 0x4800, v120
	ds_write2_b32 v25, v31, v27 offset0:12 offset1:28
	ds_write2_b32 v32, v20, v16 offset0:160 offset1:176
	ds_write2_b32 v24, v21, v17 offset0:36 offset1:52
	ds_write2_b32 v24, v22, v18 offset0:168 offset1:184
	ds_write2_b32 v25, v23, v19 offset0:44 offset1:60
	v_add_u32_e32 v16, 0x6000, v120
	ds_write2_b32 v16, v12, v8 offset0:192 offset1:208
	v_add_u32_e32 v8, 0x6400, v120
	ds_write2_b32 v8, v13, v9 offset0:68 offset1:84
	ds_write2_b32 v8, v14, v10 offset0:200 offset1:216
	v_add_u32_e32 v9, 0x6800, v120
	ds_write2_b32 v9, v15, v11 offset0:76 offset1:92
	ds_write2_b32 v16, v4, v0 offset0:224 offset1:240
	ds_write2_b32 v8, v5, v1 offset0:100 offset1:116
	ds_write2_b32 v8, v6, v2 offset0:232 offset1:248
	ds_write2_b32 v9, v7, v3 offset0:108 offset1:124
	v_or_b32_e32 v0, s18, v121
	v_ashrrev_i32_e32 v1, 31, v0
	v_lshl_add_u64 v[0:1], v[0:1], 1, s[6:7]
	v_add_u32_e32 v2, s17, v129
	s_mov_b32 s12, 0
	s_waitcnt lgkmcnt(0)
	s_barrier

.LBB0_3399:
	s_and_b32 s18, s17, 0x4000
	s_xor_b32 s19, s18, 0x4000
	s_lshl_b32 s19, s19, 1
	s_add_i32 s19, s19, 32
	s_add_u32 s90, s52, s8
	s_addc_u32 s91, s53, s9
	s_add_i32 m0, s19, s82
	s_lshl_b32 s18, s18, 1
	global_load_lds_dwordx4 v184, s[90:91]
	s_add_i32 m0, s19, s83
	s_add_i32 s18, s18, 32
	global_load_lds_dwordx4 v185, s[90:91]
	s_add_i32 m0, s19, s84
	v_lshl_add_u32 v168, v112, 1, s18
	global_load_lds_dwordx4 v186, s[90:91]
	s_add_i32 m0, s19, s85
	v_lshl_add_u32 v169, v113, 1, s18
	global_load_lds_dwordx4 v187, s[90:91]
	s_add_i32 m0, s19, s86
	v_add_u32_e32 v156, v168, v134
	global_load_lds_dwordx4 v188, s[90:91]
	s_add_i32 m0, s19, s87
	v_add_u32_e32 v164, v169, v134
	global_load_lds_dwordx4 v189, s[90:91]
	s_add_i32 m0, s19, s88
	s_addk_i32 s17, 0x4000
	global_load_lds_dwordx4 v190, s[90:91]
	s_add_i32 m0, s19, s89
	s_add_u32 s8, s8, 0x80
	s_addc_u32 s9, s9, 0
	global_load_lds_dwordx4 v191, s[90:91]
	ds_read_b128 v[136:139], v156
	ds_read_b128 v[144:147], v164 offset:16384
	ds_read_b128 v[148:151], v164 offset:18432
	ds_read_b128 v[160:163], v164 offset:20480
	ds_read_b128 v[164:167], v164 offset:22528
	ds_read_b128 v[140:143], v156 offset:2048
	ds_read_b128 v[152:155], v156 offset:4096
	ds_read_b128 v[156:159], v156 offset:6144
	v_add_u32_e32 v236, v168, v135
	v_add_u32_e32 v237, v169, v135
	ds_read_b128 v[204:207], v236
	ds_read_b128 v[208:211], v237 offset:16384
	ds_read_b128 v[212:215], v237 offset:18432
	ds_read_b128 v[216:219], v237 offset:20480
	ds_read_b128 v[220:223], v237 offset:22528
	ds_read_b128 v[224:227], v236 offset:2048
	ds_read_b128 v[228:231], v236 offset:4096
	ds_read_b128 v[232:235], v236 offset:6144
	s_setprio 1
	s_waitcnt lgkmcnt(11)
	v_mfma_f32_16x16x32_bf16 v[60:63], v[136:139], v[144:147], v[60:63]
	v_mfma_f32_16x16x32_bf16 v[56:59], v[136:139], v[148:151], v[56:59]
	v_mfma_f32_16x16x32_bf16 v[52:55], v[136:139], v[160:163], v[52:55]
	v_mfma_f32_16x16x32_bf16 v[48:51], v[136:139], v[164:167], v[48:51]
	s_waitcnt lgkmcnt(10)
	v_mfma_f32_16x16x32_bf16 v[44:47], v[140:143], v[144:147], v[44:47]
	v_mfma_f32_16x16x32_bf16 v[40:43], v[140:143], v[148:151], v[40:43]
	v_mfma_f32_16x16x32_bf16 v[36:39], v[140:143], v[160:163], v[36:39]
	v_mfma_f32_16x16x32_bf16 v[32:35], v[140:143], v[164:167], v[32:35]
	s_waitcnt lgkmcnt(9)
	v_mfma_f32_16x16x32_bf16 v[28:31], v[152:155], v[144:147], v[28:31]
	v_mfma_f32_16x16x32_bf16 v[24:27], v[152:155], v[148:151], v[24:27]
	v_mfma_f32_16x16x32_bf16 v[20:23], v[152:155], v[160:163], v[20:23]
	v_mfma_f32_16x16x32_bf16 v[16:19], v[152:155], v[164:167], v[16:19]
	s_waitcnt lgkmcnt(8)
	v_mfma_f32_16x16x32_bf16 v[12:15], v[156:159], v[144:147], v[12:15]
	v_mfma_f32_16x16x32_bf16 v[8:11], v[156:159], v[148:151], v[8:11]
	v_mfma_f32_16x16x32_bf16 v[4:7], v[156:159], v[160:163], v[4:7]
	v_mfma_f32_16x16x32_bf16 v[0:3], v[156:159], v[164:167], v[0:3]
	s_waitcnt lgkmcnt(3)
	v_mfma_f32_16x16x32_bf16 v[60:63], v[204:207], v[208:211], v[60:63]
	v_mfma_f32_16x16x32_bf16 v[56:59], v[204:207], v[212:215], v[56:59]
	v_mfma_f32_16x16x32_bf16 v[52:55], v[204:207], v[216:219], v[52:55]
	v_mfma_f32_16x16x32_bf16 v[48:51], v[204:207], v[220:223], v[48:51]
	s_waitcnt lgkmcnt(2)
	v_mfma_f32_16x16x32_bf16 v[44:47], v[224:227], v[208:211], v[44:47]
	v_mfma_f32_16x16x32_bf16 v[40:43], v[224:227], v[212:215], v[40:43]
	v_mfma_f32_16x16x32_bf16 v[36:39], v[224:227], v[216:219], v[36:39]
	v_mfma_f32_16x16x32_bf16 v[32:35], v[224:227], v[220:223], v[32:35]
	s_waitcnt lgkmcnt(1)
	v_mfma_f32_16x16x32_bf16 v[28:31], v[228:231], v[208:211], v[28:31]
	v_mfma_f32_16x16x32_bf16 v[24:27], v[228:231], v[212:215], v[24:27]
	v_mfma_f32_16x16x32_bf16 v[20:23], v[228:231], v[216:219], v[20:23]
	v_mfma_f32_16x16x32_bf16 v[16:19], v[228:231], v[220:223], v[16:19]
	s_waitcnt lgkmcnt(0)
	v_mfma_f32_16x16x32_bf16 v[12:15], v[232:235], v[208:211], v[12:15]
	v_mfma_f32_16x16x32_bf16 v[8:11], v[232:235], v[212:215], v[8:11]
	v_mfma_f32_16x16x32_bf16 v[4:7], v[232:235], v[216:219], v[4:7]
	v_mfma_f32_16x16x32_bf16 v[0:3], v[232:235], v[220:223], v[0:3]
	s_setprio 0
	s_cmpk_eq_i32 s8, 0x780
	s_waitcnt vmcnt(0)
	s_barrier
	s_cbranch_scc0 .LBB0_3399
	ds_read_b128 v[88:91], v114 offset:55296
	ds_read_b128 v[92:95], v114 offset:53248
	ds_read_b128 v[96:99], v115 offset:38912
	ds_read_b128 v[100:103], v115 offset:36864
	ds_read_b128 v[136:139], v114 offset:51200
	ds_read_b128 v[140:143], v114 offset:49152
	ds_read_b128 v[144:147], v115 offset:34816
	ds_read_b128 v[148:151], v115 offset:32768
	ds_read_b128 v[204:207], v116 offset:32768
	ds_read_b128 v[208:211], v116 offset:34816
	ds_read_b128 v[212:215], v117 offset:49152
	ds_read_b128 v[216:219], v117 offset:51200
	ds_read_b128 v[220:223], v116 offset:36864
	ds_read_b128 v[224:227], v116 offset:38912
	ds_read_b128 v[228:231], v117 offset:53248
	ds_read_b128 v[232:235], v117 offset:55296
	s_setprio 1
	s_waitcnt lgkmcnt(13)
	v_mfma_f32_16x16x32_bf16 v[0:3], v[96:99], v[88:91], v[0:3]
	s_waitcnt lgkmcnt(8)
	v_mfma_f32_16x16x32_bf16 v[60:63], v[148:151], v[140:143], v[60:63]
	v_mfma_f32_16x16x32_bf16 v[56:59], v[148:151], v[136:139], v[56:59]
	v_mfma_f32_16x16x32_bf16 v[52:55], v[148:151], v[92:95], v[52:55]
	v_mfma_f32_16x16x32_bf16 v[48:51], v[148:151], v[88:91], v[48:51]
	v_mfma_f32_16x16x32_bf16 v[44:47], v[144:147], v[140:143], v[44:47]
	v_mfma_f32_16x16x32_bf16 v[40:43], v[144:147], v[136:139], v[40:43]
	v_mfma_f32_16x16x32_bf16 v[36:39], v[144:147], v[92:95], v[36:39]
	v_mfma_f32_16x16x32_bf16 v[32:35], v[144:147], v[88:91], v[32:35]
	v_mfma_f32_16x16x32_bf16 v[28:31], v[100:103], v[140:143], v[28:31]
	v_mfma_f32_16x16x32_bf16 v[24:27], v[100:103], v[136:139], v[24:27]
	v_mfma_f32_16x16x32_bf16 v[20:23], v[100:103], v[92:95], v[20:23]
	v_mfma_f32_16x16x32_bf16 v[16:19], v[100:103], v[88:91], v[16:19]
	v_mfma_f32_16x16x32_bf16 v[12:15], v[96:99], v[140:143], v[12:15]
	v_mfma_f32_16x16x32_bf16 v[8:11], v[96:99], v[136:139], v[8:11]
	v_mfma_f32_16x16x32_bf16 v[4:7], v[96:99], v[92:95], v[4:7]
	s_waitcnt lgkmcnt(0)
	v_mfma_f32_16x16x32_bf16 v[0:3], v[224:227], v[232:235], v[0:3]
	v_mfma_f32_16x16x32_bf16 v[60:63], v[204:207], v[212:215], v[60:63]
	v_mfma_f32_16x16x32_bf16 v[56:59], v[204:207], v[216:219], v[56:59]
	v_mfma_f32_16x16x32_bf16 v[52:55], v[204:207], v[228:231], v[52:55]
	v_mfma_f32_16x16x32_bf16 v[48:51], v[204:207], v[232:235], v[48:51]
	v_mfma_f32_16x16x32_bf16 v[44:47], v[208:211], v[212:215], v[44:47]
	v_mfma_f32_16x16x32_bf16 v[40:43], v[208:211], v[216:219], v[40:43]
	v_mfma_f32_16x16x32_bf16 v[36:39], v[208:211], v[228:231], v[36:39]
	v_mfma_f32_16x16x32_bf16 v[32:35], v[208:211], v[232:235], v[32:35]
	v_mfma_f32_16x16x32_bf16 v[28:31], v[220:223], v[212:215], v[28:31]
	v_mfma_f32_16x16x32_bf16 v[24:27], v[220:223], v[216:219], v[24:27]
	v_mfma_f32_16x16x32_bf16 v[20:23], v[220:223], v[228:231], v[20:23]
	v_mfma_f32_16x16x32_bf16 v[16:19], v[220:223], v[232:235], v[16:19]
	v_mfma_f32_16x16x32_bf16 v[12:15], v[224:227], v[212:215], v[12:15]
	v_mfma_f32_16x16x32_bf16 v[8:11], v[224:227], v[216:219], v[8:11]
	v_mfma_f32_16x16x32_bf16 v[4:7], v[224:227], v[228:231], v[4:7]
	s_setprio 0
	s_barrier
	ds_write2_b32 v118, v60, v56 offset1:16
	ds_write2_b32 v118, v61, v57 offset0:132 offset1:148
	v_add_u32_e32 v56, 0x400, v118
	ds_write2_b32 v56, v62, v58 offset0:8 offset1:24
	ds_write2_b32 v56, v63, v59 offset0:140 offset1:156
	ds_write2_b32 v118, v52, v48 offset0:32 offset1:48
	ds_write2_b32 v118, v53, v49 offset0:164 offset1:180
	ds_write2_b32 v56, v54, v50 offset0:40 offset1:56
	ds_write2_b32 v56, v55, v51 offset0:172 offset1:188
	v_add_u32_e32 v48, 0x2000, v118
	ds_write2_b32 v48, v44, v40 offset0:64 offset1:80
	ds_write2_b32 v48, v45, v41 offset0:196 offset1:212
	v_add_u32_e32 v40, 0x2400, v118
	ds_write2_b32 v40, v46, v42 offset0:72 offset1:88
	ds_write2_b32 v40, v47, v43 offset0:204 offset1:220
	ds_write2_b32 v48, v36, v32 offset0:96 offset1:112
	ds_write2_b32 v48, v37, v33 offset0:228 offset1:244
	ds_write2_b32 v40, v38, v34 offset0:104 offset1:120
	ds_write2_b32 v40, v39, v35 offset0:236 offset1:252
	v_add_u32_e32 v32, 0x4000, v118
	ds_write2_b32 v32, v28, v24 offset0:128 offset1:144
	v_add_u32_e32 v24, 0x4400, v118
	ds_write2_b32 v24, v29, v25 offset0:4 offset1:20
	ds_write2_b32 v24, v30, v26 offset0:136 offset1:152
	v_add_u32_e32 v25, 0x4800, v118
	ds_write2_b32 v25, v31, v27 offset0:12 offset1:28
	ds_write2_b32 v32, v20, v16 offset0:160 offset1:176
	ds_write2_b32 v24, v21, v17 offset0:36 offset1:52
	ds_write2_b32 v24, v22, v18 offset0:168 offset1:184
	ds_write2_b32 v25, v23, v19 offset0:44 offset1:60
	v_add_u32_e32 v16, 0x6000, v118
	ds_write2_b32 v16, v12, v8 offset0:192 offset1:208
	v_add_u32_e32 v8, 0x6400, v118
	ds_write2_b32 v8, v13, v9 offset0:68 offset1:84
	ds_write2_b32 v8, v14, v10 offset0:200 offset1:216
	v_add_u32_e32 v9, 0x6800, v118
	ds_write2_b32 v9, v15, v11 offset0:76 offset1:92
	ds_write2_b32 v16, v4, v0 offset0:224 offset1:240
	ds_write2_b32 v8, v5, v1 offset0:100 offset1:116
	ds_write2_b32 v8, v6, v2 offset0:232 offset1:248
	ds_write2_b32 v9, v7, v3 offset0:108 offset1:124
	v_or_b32_e32 v0, s16, v119
	v_ashrrev_i32_e32 v1, 31, v0
	v_lshl_add_u64 v[0:1], v[0:1], 1, s[6:7]
	v_add_u32_e32 v2, s15, v127
	s_mov_b32 s8, 0
	s_waitcnt lgkmcnt(0)
	s_barrier

.LBB0_3463:
	s_and_b32 s27, s26, 0x4000
	s_xor_b32 s28, s27, 0x4000
	s_lshl_b32 s28, s28, 1
	s_add_i32 s28, s28, 32
	s_add_u32 s90, s52, s16
	s_addc_u32 s91, s53, s17
	s_add_i32 m0, s28, s82
	s_lshl_b32 s27, s27, 1
	global_load_lds_dwordx4 v184, s[90:91]
	s_add_i32 m0, s28, s83
	s_add_i32 s27, s27, 32
	global_load_lds_dwordx4 v185, s[90:91]
	s_add_i32 m0, s28, s84
	v_add3_u32 v139, s27, v114, v136
	global_load_lds_dwordx4 v186, s[90:91]
	s_add_i32 m0, s28, s85
	v_add3_u32 v172, s27, v115, v136
	global_load_lds_dwordx4 v187, s[90:91]
	s_add_i32 m0, s28, s86
	v_add_u32_e32 v160, v139, v137
	global_load_lds_dwordx4 v188, s[90:91]
	s_add_i32 m0, s28, s87
	v_add_u32_e32 v168, v172, v137
	global_load_lds_dwordx4 v189, s[90:91]
	s_add_i32 m0, s28, s88
	s_addk_i32 s26, 0x4000
	global_load_lds_dwordx4 v190, s[90:91]
	s_add_i32 m0, s28, s89
	s_add_u32 s16, s16, 0x80
	s_addc_u32 s17, s17, 0
	global_load_lds_dwordx4 v191, s[90:91]
	ds_read_b128 v[140:143], v160
	ds_read_b128 v[148:151], v168 offset:16384
	ds_read_b128 v[152:155], v168 offset:18432
	ds_read_b128 v[164:167], v168 offset:20480
	ds_read_b128 v[168:171], v168 offset:22528
	ds_read_b128 v[144:147], v160 offset:2048
	ds_read_b128 v[156:159], v160 offset:4096
	ds_read_b128 v[160:163], v160 offset:6144
	v_add_u32_e32 v139, v139, v138
	v_add_u32_e32 v236, v172, v138
	ds_read_b128 v[204:207], v139
	ds_read_b128 v[208:211], v236 offset:16384
	ds_read_b128 v[212:215], v236 offset:18432
	ds_read_b128 v[216:219], v236 offset:20480
	ds_read_b128 v[220:223], v236 offset:22528
	ds_read_b128 v[224:227], v139 offset:2048
	ds_read_b128 v[228:231], v139 offset:4096
	ds_read_b128 v[232:235], v139 offset:6144
	s_setprio 1
	s_waitcnt lgkmcnt(11)
	v_mfma_f32_16x16x32_bf16 v[60:63], v[140:143], v[148:151], v[60:63]
	v_mfma_f32_16x16x32_bf16 v[56:59], v[140:143], v[152:155], v[56:59]
	v_mfma_f32_16x16x32_bf16 v[52:55], v[140:143], v[164:167], v[52:55]
	v_mfma_f32_16x16x32_bf16 v[48:51], v[140:143], v[168:171], v[48:51]
	s_waitcnt lgkmcnt(10)
	v_mfma_f32_16x16x32_bf16 v[44:47], v[144:147], v[148:151], v[44:47]
	v_mfma_f32_16x16x32_bf16 v[40:43], v[144:147], v[152:155], v[40:43]
	v_mfma_f32_16x16x32_bf16 v[36:39], v[144:147], v[164:167], v[36:39]
	v_mfma_f32_16x16x32_bf16 v[32:35], v[144:147], v[168:171], v[32:35]
	s_waitcnt lgkmcnt(9)
	v_mfma_f32_16x16x32_bf16 v[28:31], v[156:159], v[148:151], v[28:31]
	v_mfma_f32_16x16x32_bf16 v[24:27], v[156:159], v[152:155], v[24:27]
	v_mfma_f32_16x16x32_bf16 v[20:23], v[156:159], v[164:167], v[20:23]
	v_mfma_f32_16x16x32_bf16 v[16:19], v[156:159], v[168:171], v[16:19]
	s_waitcnt lgkmcnt(8)
	v_mfma_f32_16x16x32_bf16 v[12:15], v[160:163], v[148:151], v[12:15]
	v_mfma_f32_16x16x32_bf16 v[8:11], v[160:163], v[152:155], v[8:11]
	v_mfma_f32_16x16x32_bf16 v[4:7], v[160:163], v[164:167], v[4:7]
	v_mfma_f32_16x16x32_bf16 v[0:3], v[160:163], v[168:171], v[0:3]
	s_waitcnt lgkmcnt(3)
	v_mfma_f32_16x16x32_bf16 v[60:63], v[204:207], v[208:211], v[60:63]
	v_mfma_f32_16x16x32_bf16 v[56:59], v[204:207], v[212:215], v[56:59]
	v_mfma_f32_16x16x32_bf16 v[52:55], v[204:207], v[216:219], v[52:55]
	v_mfma_f32_16x16x32_bf16 v[48:51], v[204:207], v[220:223], v[48:51]
	s_waitcnt lgkmcnt(2)
	v_mfma_f32_16x16x32_bf16 v[44:47], v[224:227], v[208:211], v[44:47]
	v_mfma_f32_16x16x32_bf16 v[40:43], v[224:227], v[212:215], v[40:43]
	v_mfma_f32_16x16x32_bf16 v[36:39], v[224:227], v[216:219], v[36:39]
	v_mfma_f32_16x16x32_bf16 v[32:35], v[224:227], v[220:223], v[32:35]
	s_waitcnt lgkmcnt(1)
	v_mfma_f32_16x16x32_bf16 v[28:31], v[228:231], v[208:211], v[28:31]
	v_mfma_f32_16x16x32_bf16 v[24:27], v[228:231], v[212:215], v[24:27]
	v_mfma_f32_16x16x32_bf16 v[20:23], v[228:231], v[216:219], v[20:23]
	v_mfma_f32_16x16x32_bf16 v[16:19], v[228:231], v[220:223], v[16:19]
	s_waitcnt lgkmcnt(0)
	v_mfma_f32_16x16x32_bf16 v[12:15], v[232:235], v[208:211], v[12:15]
	v_mfma_f32_16x16x32_bf16 v[8:11], v[232:235], v[212:215], v[8:11]
	v_mfma_f32_16x16x32_bf16 v[4:7], v[232:235], v[216:219], v[4:7]
	v_mfma_f32_16x16x32_bf16 v[0:3], v[232:235], v[220:223], v[0:3]
	s_setprio 0
	s_cmpk_eq_i32 s16, 0x1f80
	s_waitcnt vmcnt(0)
	s_barrier
	s_cbranch_scc0 .LBB0_3463
	ds_read_b128 v[90:93], v118 offset:55296
	ds_read_b128 v[94:97], v118 offset:53248
	ds_read_b128 v[98:101], v119 offset:38912
	ds_read_b128 v[102:105], v119 offset:36864
	ds_read_b128 v[140:143], v118 offset:51200
	ds_read_b128 v[144:147], v118 offset:49152
	ds_read_b128 v[148:151], v119 offset:34816
	ds_read_b128 v[152:155], v119 offset:32768
	ds_read_b128 v[204:207], v120 offset:32768
	ds_read_b128 v[208:211], v120 offset:34816
	ds_read_b128 v[212:215], v121 offset:49152
	ds_read_b128 v[216:219], v121 offset:51200
	ds_read_b128 v[220:223], v120 offset:36864
	ds_read_b128 v[224:227], v120 offset:38912
	ds_read_b128 v[228:231], v121 offset:53248
	ds_read_b128 v[232:235], v121 offset:55296
	s_setprio 1
	s_waitcnt lgkmcnt(13)
	v_mfma_f32_16x16x32_bf16 v[4:7], v[98:101], v[94:97], v[4:7]
	v_mfma_f32_16x16x32_bf16 v[0:3], v[98:101], v[90:93], v[0:3]
	s_waitcnt lgkmcnt(8)
	v_mfma_f32_16x16x32_bf16 v[60:63], v[152:155], v[144:147], v[60:63]
	v_mfma_f32_16x16x32_bf16 v[56:59], v[152:155], v[140:143], v[56:59]
	v_mfma_f32_16x16x32_bf16 v[52:55], v[152:155], v[94:97], v[52:55]
	v_mfma_f32_16x16x32_bf16 v[48:51], v[152:155], v[90:93], v[48:51]
	v_mfma_f32_16x16x32_bf16 v[44:47], v[148:151], v[144:147], v[44:47]
	v_mfma_f32_16x16x32_bf16 v[40:43], v[148:151], v[140:143], v[40:43]
	v_mfma_f32_16x16x32_bf16 v[36:39], v[148:151], v[94:97], v[36:39]
	v_mfma_f32_16x16x32_bf16 v[32:35], v[148:151], v[90:93], v[32:35]
	v_mfma_f32_16x16x32_bf16 v[28:31], v[102:105], v[144:147], v[28:31]
	v_mfma_f32_16x16x32_bf16 v[24:27], v[102:105], v[140:143], v[24:27]
	v_mfma_f32_16x16x32_bf16 v[20:23], v[102:105], v[94:97], v[20:23]
	v_mfma_f32_16x16x32_bf16 v[16:19], v[102:105], v[90:93], v[16:19]
	v_mfma_f32_16x16x32_bf16 v[12:15], v[98:101], v[144:147], v[12:15]
	v_mfma_f32_16x16x32_bf16 v[8:11], v[98:101], v[140:143], v[8:11]
	s_waitcnt lgkmcnt(1)
	v_mfma_f32_16x16x32_bf16 v[4:7], v[224:227], v[228:231], v[4:7]
	s_waitcnt lgkmcnt(0)
	v_mfma_f32_16x16x32_bf16 v[0:3], v[224:227], v[232:235], v[0:3]
	v_mfma_f32_16x16x32_bf16 v[60:63], v[204:207], v[212:215], v[60:63]
	v_mfma_f32_16x16x32_bf16 v[56:59], v[204:207], v[216:219], v[56:59]
	v_mfma_f32_16x16x32_bf16 v[52:55], v[204:207], v[228:231], v[52:55]
	v_mfma_f32_16x16x32_bf16 v[48:51], v[204:207], v[232:235], v[48:51]
	v_mfma_f32_16x16x32_bf16 v[44:47], v[208:211], v[212:215], v[44:47]
	v_mfma_f32_16x16x32_bf16 v[40:43], v[208:211], v[216:219], v[40:43]
	v_mfma_f32_16x16x32_bf16 v[36:39], v[208:211], v[228:231], v[36:39]
	v_mfma_f32_16x16x32_bf16 v[32:35], v[208:211], v[232:235], v[32:35]
	v_mfma_f32_16x16x32_bf16 v[28:31], v[220:223], v[212:215], v[28:31]
	v_mfma_f32_16x16x32_bf16 v[24:27], v[220:223], v[216:219], v[24:27]
	v_mfma_f32_16x16x32_bf16 v[20:23], v[220:223], v[228:231], v[20:23]
	v_mfma_f32_16x16x32_bf16 v[16:19], v[220:223], v[232:235], v[16:19]
	v_mfma_f32_16x16x32_bf16 v[12:15], v[224:227], v[212:215], v[12:15]
	v_mfma_f32_16x16x32_bf16 v[8:11], v[224:227], v[216:219], v[8:11]
	s_setprio 0
	s_barrier
	ds_write2_b32 v116, v60, v56 offset1:16
	ds_write2_b32 v116, v61, v57 offset0:132 offset1:148
	v_add_u32_e32 v56, 0x400, v116
	ds_write2_b32 v56, v62, v58 offset0:8 offset1:24
	ds_write2_b32 v56, v63, v59 offset0:140 offset1:156
	ds_write2_b32 v116, v52, v48 offset0:32 offset1:48
	ds_write2_b32 v116, v53, v49 offset0:164 offset1:180
	ds_write2_b32 v56, v54, v50 offset0:40 offset1:56
	ds_write2_b32 v56, v55, v51 offset0:172 offset1:188
	v_add_u32_e32 v48, 0x2000, v116
	ds_write2_b32 v48, v44, v40 offset0:64 offset1:80
	ds_write2_b32 v48, v45, v41 offset0:196 offset1:212
	v_add_u32_e32 v40, 0x2400, v116
	ds_write2_b32 v40, v46, v42 offset0:72 offset1:88
	ds_write2_b32 v40, v47, v43 offset0:204 offset1:220
	ds_write2_b32 v48, v36, v32 offset0:96 offset1:112
	ds_write2_b32 v48, v37, v33 offset0:228 offset1:244
	ds_write2_b32 v40, v38, v34 offset0:104 offset1:120
	ds_write2_b32 v40, v39, v35 offset0:236 offset1:252
	v_add_u32_e32 v32, 0x4000, v116
	ds_write2_b32 v32, v28, v24 offset0:128 offset1:144
	v_add_u32_e32 v24, 0x4400, v116
	ds_write2_b32 v24, v29, v25 offset0:4 offset1:20
	ds_write2_b32 v24, v30, v26 offset0:136 offset1:152
	v_add_u32_e32 v25, 0x4800, v116
	ds_write2_b32 v25, v31, v27 offset0:12 offset1:28
	ds_write2_b32 v32, v20, v16 offset0:160 offset1:176
	ds_write2_b32 v24, v21, v17 offset0:36 offset1:52
	ds_write2_b32 v24, v22, v18 offset0:168 offset1:184
	ds_write2_b32 v25, v23, v19 offset0:44 offset1:60
	v_add_u32_e32 v16, 0x6000, v116
	ds_write2_b32 v16, v12, v8 offset0:192 offset1:208
	v_add_u32_e32 v8, 0x6400, v116
	ds_write2_b32 v8, v13, v9 offset0:68 offset1:84
	ds_write2_b32 v8, v14, v10 offset0:200 offset1:216
	v_add_u32_e32 v9, 0x6800, v116
	ds_write2_b32 v9, v15, v11 offset0:76 offset1:92
	ds_write2_b32 v16, v4, v0 offset0:224 offset1:240
	ds_write2_b32 v8, v5, v1 offset0:100 offset1:116
	ds_write2_b32 v8, v6, v2 offset0:232 offset1:248
	ds_write2_b32 v9, v7, v3 offset0:108 offset1:124
	v_or_b32_e32 v0, s25, v117
	v_ashrrev_i32_e32 v1, 31, v0
	v_lshlrev_b64 v[2:3], 2, v[0:1]
	v_lshl_add_u64 v[0:1], s[14:15], 0, v[2:3]
	v_lshl_add_u64 v[2:3], s[6:7], 0, v[2:3]
	v_add_u32_e32 v4, s24, v129
	s_mov_b32 s16, 0
	s_waitcnt lgkmcnt(0)
	s_barrier

.LBB0_3472:
	s_and_b32 s23, s22, 0x4000
	s_xor_b32 s24, s23, 0x4000
	s_lshl_b32 s24, s24, 1
	s_add_i32 s24, s24, 32
	s_add_u32 s90, s52, s8
	s_addc_u32 s91, s53, s9
	s_add_i32 m0, s24, s82
	s_lshl_b32 s23, s23, 1
	global_load_lds_dwordx4 v184, s[90:91]
	s_add_i32 m0, s24, s83
	s_add_i32 s23, s23, 32
	global_load_lds_dwordx4 v185, s[90:91]
	s_add_i32 m0, s24, s84
	v_add3_u32 v170, s23, v112, v135
	global_load_lds_dwordx4 v186, s[90:91]
	s_add_i32 m0, s24, s85
	v_add3_u32 v171, s23, v113, v135
	global_load_lds_dwordx4 v187, s[90:91]
	s_add_i32 m0, s24, s86
	v_add_u32_e32 v158, v170, v136
	global_load_lds_dwordx4 v188, s[90:91]
	s_add_i32 m0, s24, s87
	v_add_u32_e32 v166, v171, v136
	global_load_lds_dwordx4 v189, s[90:91]
	s_add_i32 m0, s24, s88
	s_addk_i32 s22, 0x4000
	global_load_lds_dwordx4 v190, s[90:91]
	s_add_i32 m0, s24, s89
	s_add_u32 s8, s8, 0x80
	s_addc_u32 s9, s9, 0
	global_load_lds_dwordx4 v191, s[90:91]
	ds_read_b128 v[138:141], v158
	ds_read_b128 v[146:149], v166 offset:16384
	ds_read_b128 v[150:153], v166 offset:18432
	ds_read_b128 v[162:165], v166 offset:20480
	ds_read_b128 v[166:169], v166 offset:22528
	ds_read_b128 v[142:145], v158 offset:2048
	ds_read_b128 v[154:157], v158 offset:4096
	ds_read_b128 v[158:161], v158 offset:6144
	v_add_u32_e32 v236, v170, v137
	v_add_u32_e32 v237, v171, v137
	ds_read_b128 v[204:207], v236
	ds_read_b128 v[208:211], v237 offset:16384
	ds_read_b128 v[212:215], v237 offset:18432
	ds_read_b128 v[216:219], v237 offset:20480
	ds_read_b128 v[220:223], v237 offset:22528
	ds_read_b128 v[224:227], v236 offset:2048
	ds_read_b128 v[228:231], v236 offset:4096
	ds_read_b128 v[232:235], v236 offset:6144
	s_setprio 1
	s_waitcnt lgkmcnt(11)
	v_mfma_f32_16x16x32_bf16 v[60:63], v[138:141], v[146:149], v[60:63]
	v_mfma_f32_16x16x32_bf16 v[56:59], v[138:141], v[150:153], v[56:59]
	v_mfma_f32_16x16x32_bf16 v[52:55], v[138:141], v[162:165], v[52:55]
	v_mfma_f32_16x16x32_bf16 v[48:51], v[138:141], v[166:169], v[48:51]
	s_waitcnt lgkmcnt(10)
	v_mfma_f32_16x16x32_bf16 v[44:47], v[142:145], v[146:149], v[44:47]
	v_mfma_f32_16x16x32_bf16 v[40:43], v[142:145], v[150:153], v[40:43]
	v_mfma_f32_16x16x32_bf16 v[36:39], v[142:145], v[162:165], v[36:39]
	v_mfma_f32_16x16x32_bf16 v[32:35], v[142:145], v[166:169], v[32:35]
	s_waitcnt lgkmcnt(9)
	v_mfma_f32_16x16x32_bf16 v[28:31], v[154:157], v[146:149], v[28:31]
	v_mfma_f32_16x16x32_bf16 v[24:27], v[154:157], v[150:153], v[24:27]
	v_mfma_f32_16x16x32_bf16 v[20:23], v[154:157], v[162:165], v[20:23]
	v_mfma_f32_16x16x32_bf16 v[16:19], v[154:157], v[166:169], v[16:19]
	s_waitcnt lgkmcnt(8)
	v_mfma_f32_16x16x32_bf16 v[12:15], v[158:161], v[146:149], v[12:15]
	v_mfma_f32_16x16x32_bf16 v[8:11], v[158:161], v[150:153], v[8:11]
	v_mfma_f32_16x16x32_bf16 v[4:7], v[158:161], v[162:165], v[4:7]
	v_mfma_f32_16x16x32_bf16 v[0:3], v[158:161], v[166:169], v[0:3]
	s_waitcnt lgkmcnt(3)
	v_mfma_f32_16x16x32_bf16 v[60:63], v[204:207], v[208:211], v[60:63]
	v_mfma_f32_16x16x32_bf16 v[56:59], v[204:207], v[212:215], v[56:59]
	v_mfma_f32_16x16x32_bf16 v[52:55], v[204:207], v[216:219], v[52:55]
	v_mfma_f32_16x16x32_bf16 v[48:51], v[204:207], v[220:223], v[48:51]
	s_waitcnt lgkmcnt(2)
	v_mfma_f32_16x16x32_bf16 v[44:47], v[224:227], v[208:211], v[44:47]
	v_mfma_f32_16x16x32_bf16 v[40:43], v[224:227], v[212:215], v[40:43]
	v_mfma_f32_16x16x32_bf16 v[36:39], v[224:227], v[216:219], v[36:39]
	v_mfma_f32_16x16x32_bf16 v[32:35], v[224:227], v[220:223], v[32:35]
	s_waitcnt lgkmcnt(1)
	v_mfma_f32_16x16x32_bf16 v[28:31], v[228:231], v[208:211], v[28:31]
	v_mfma_f32_16x16x32_bf16 v[24:27], v[228:231], v[212:215], v[24:27]
	v_mfma_f32_16x16x32_bf16 v[20:23], v[228:231], v[216:219], v[20:23]
	v_mfma_f32_16x16x32_bf16 v[16:19], v[228:231], v[220:223], v[16:19]
	s_waitcnt lgkmcnt(0)
	v_mfma_f32_16x16x32_bf16 v[12:15], v[232:235], v[208:211], v[12:15]
	v_mfma_f32_16x16x32_bf16 v[8:11], v[232:235], v[212:215], v[8:11]
	v_mfma_f32_16x16x32_bf16 v[4:7], v[232:235], v[216:219], v[4:7]
	v_mfma_f32_16x16x32_bf16 v[0:3], v[232:235], v[220:223], v[0:3]
	s_setprio 0
	s_cmpk_eq_i32 s8, 0x1f80
	s_waitcnt vmcnt(0)
	s_barrier
	s_cbranch_scc0 .LBB0_3472
	ds_read_b128 v[88:91], v116 offset:55296
	ds_read_b128 v[92:95], v116 offset:53248
	ds_read_b128 v[96:99], v117 offset:38912
	ds_read_b128 v[100:103], v117 offset:36864
	ds_read_b128 v[138:141], v116 offset:51200
	ds_read_b128 v[142:145], v116 offset:49152
	ds_read_b128 v[146:149], v117 offset:34816
	ds_read_b128 v[150:153], v117 offset:32768
	ds_read_b128 v[204:207], v118 offset:32768
	ds_read_b128 v[208:211], v118 offset:34816
	ds_read_b128 v[212:215], v119 offset:49152
	ds_read_b128 v[216:219], v119 offset:51200
	ds_read_b128 v[220:223], v118 offset:36864
	ds_read_b128 v[224:227], v118 offset:38912
	ds_read_b128 v[228:231], v119 offset:53248
	ds_read_b128 v[232:235], v119 offset:55296
	s_setprio 1
	s_waitcnt lgkmcnt(13)
	v_mfma_f32_16x16x32_bf16 v[4:7], v[96:99], v[92:95], v[4:7]
	v_mfma_f32_16x16x32_bf16 v[0:3], v[96:99], v[88:91], v[0:3]
	s_waitcnt lgkmcnt(8)
	v_mfma_f32_16x16x32_bf16 v[60:63], v[150:153], v[142:145], v[60:63]
	v_mfma_f32_16x16x32_bf16 v[56:59], v[150:153], v[138:141], v[56:59]
	v_mfma_f32_16x16x32_bf16 v[52:55], v[150:153], v[92:95], v[52:55]
	v_mfma_f32_16x16x32_bf16 v[48:51], v[150:153], v[88:91], v[48:51]
	v_mfma_f32_16x16x32_bf16 v[44:47], v[146:149], v[142:145], v[44:47]
	v_mfma_f32_16x16x32_bf16 v[40:43], v[146:149], v[138:141], v[40:43]
	v_mfma_f32_16x16x32_bf16 v[36:39], v[146:149], v[92:95], v[36:39]
	v_mfma_f32_16x16x32_bf16 v[32:35], v[146:149], v[88:91], v[32:35]
	v_mfma_f32_16x16x32_bf16 v[28:31], v[100:103], v[142:145], v[28:31]
	v_mfma_f32_16x16x32_bf16 v[24:27], v[100:103], v[138:141], v[24:27]
	v_mfma_f32_16x16x32_bf16 v[20:23], v[100:103], v[92:95], v[20:23]
	v_mfma_f32_16x16x32_bf16 v[16:19], v[100:103], v[88:91], v[16:19]
	v_mfma_f32_16x16x32_bf16 v[12:15], v[96:99], v[142:145], v[12:15]
	v_mfma_f32_16x16x32_bf16 v[8:11], v[96:99], v[138:141], v[8:11]
	s_waitcnt lgkmcnt(1)
	v_mfma_f32_16x16x32_bf16 v[4:7], v[224:227], v[228:231], v[4:7]
	s_waitcnt lgkmcnt(0)
	v_mfma_f32_16x16x32_bf16 v[0:3], v[224:227], v[232:235], v[0:3]
	v_mfma_f32_16x16x32_bf16 v[60:63], v[204:207], v[212:215], v[60:63]
	v_mfma_f32_16x16x32_bf16 v[56:59], v[204:207], v[216:219], v[56:59]
	v_mfma_f32_16x16x32_bf16 v[52:55], v[204:207], v[228:231], v[52:55]
	v_mfma_f32_16x16x32_bf16 v[48:51], v[204:207], v[232:235], v[48:51]
	v_mfma_f32_16x16x32_bf16 v[44:47], v[208:211], v[212:215], v[44:47]
	v_mfma_f32_16x16x32_bf16 v[40:43], v[208:211], v[216:219], v[40:43]
	v_mfma_f32_16x16x32_bf16 v[36:39], v[208:211], v[228:231], v[36:39]
	v_mfma_f32_16x16x32_bf16 v[32:35], v[208:211], v[232:235], v[32:35]
	v_mfma_f32_16x16x32_bf16 v[28:31], v[220:223], v[212:215], v[28:31]
	v_mfma_f32_16x16x32_bf16 v[24:27], v[220:223], v[216:219], v[24:27]
	v_mfma_f32_16x16x32_bf16 v[20:23], v[220:223], v[228:231], v[20:23]
	v_mfma_f32_16x16x32_bf16 v[16:19], v[220:223], v[232:235], v[16:19]
	v_mfma_f32_16x16x32_bf16 v[12:15], v[224:227], v[212:215], v[12:15]
	v_mfma_f32_16x16x32_bf16 v[8:11], v[224:227], v[216:219], v[8:11]
	s_setprio 0
	s_barrier
	ds_write2_b32 v114, v60, v56 offset1:16
	ds_write2_b32 v114, v61, v57 offset0:132 offset1:148
	v_add_u32_e32 v56, 0x400, v114
	ds_write2_b32 v56, v62, v58 offset0:8 offset1:24
	ds_write2_b32 v56, v63, v59 offset0:140 offset1:156
	ds_write2_b32 v114, v52, v48 offset0:32 offset1:48
	ds_write2_b32 v114, v53, v49 offset0:164 offset1:180
	ds_write2_b32 v56, v54, v50 offset0:40 offset1:56
	ds_write2_b32 v56, v55, v51 offset0:172 offset1:188
	v_add_u32_e32 v48, 0x2000, v114
	ds_write2_b32 v48, v44, v40 offset0:64 offset1:80
	ds_write2_b32 v48, v45, v41 offset0:196 offset1:212
	v_add_u32_e32 v40, 0x2400, v114
	ds_write2_b32 v40, v46, v42 offset0:72 offset1:88
	ds_write2_b32 v40, v47, v43 offset0:204 offset1:220
	ds_write2_b32 v48, v36, v32 offset0:96 offset1:112
	ds_write2_b32 v48, v37, v33 offset0:228 offset1:244
	ds_write2_b32 v40, v38, v34 offset0:104 offset1:120
	ds_write2_b32 v40, v39, v35 offset0:236 offset1:252
	v_add_u32_e32 v32, 0x4000, v114
	ds_write2_b32 v32, v28, v24 offset0:128 offset1:144
	v_add_u32_e32 v24, 0x4400, v114
	ds_write2_b32 v24, v29, v25 offset0:4 offset1:20
	ds_write2_b32 v24, v30, v26 offset0:136 offset1:152
	v_add_u32_e32 v25, 0x4800, v114
	ds_write2_b32 v25, v31, v27 offset0:12 offset1:28
	ds_write2_b32 v32, v20, v16 offset0:160 offset1:176
	ds_write2_b32 v24, v21, v17 offset0:36 offset1:52
	ds_write2_b32 v24, v22, v18 offset0:168 offset1:184
	ds_write2_b32 v25, v23, v19 offset0:44 offset1:60
	v_add_u32_e32 v16, 0x6000, v114
	ds_write2_b32 v16, v12, v8 offset0:192 offset1:208
	v_add_u32_e32 v8, 0x6400, v114
	ds_write2_b32 v8, v13, v9 offset0:68 offset1:84
	ds_write2_b32 v8, v14, v10 offset0:200 offset1:216
	v_add_u32_e32 v9, 0x6800, v114
	ds_write2_b32 v9, v15, v11 offset0:76 offset1:92
	ds_write2_b32 v16, v4, v0 offset0:224 offset1:240
	ds_write2_b32 v8, v5, v1 offset0:100 offset1:116
	ds_write2_b32 v8, v6, v2 offset0:232 offset1:248
	ds_write2_b32 v9, v7, v3 offset0:108 offset1:124
	v_or_b32_e32 v0, s21, v115
	v_ashrrev_i32_e32 v1, 31, v0
	v_lshlrev_b64 v[2:3], 2, v[0:1]
	v_lshl_add_u64 v[0:1], s[10:11], 0, v[2:3]
	v_lshl_add_u64 v[2:3], s[6:7], 0, v[2:3]
	v_add_u32_e32 v4, s20, v128
	s_mov_b32 s8, 0
	s_waitcnt lgkmcnt(0)
	s_barrier
